# P3 gate-rescale epilogues pipelined, write-through dwordx4 stores, half the workgroups run mixers before attention
# speedup vs baseline: 1.0176x; 1.0176x over previous
.LBB0_23:
	s_mul_hi_i32 s30, s90, 0xcb8727c1
	s_add_i32 s30, s30, s90
	s_lshr_b32 s34, s30, 31
	s_ashr_i32 s30, s30, 12
	s_add_i32 s34, s30, s34
	s_mul_i32 s30, s34, 0xffffebe0
	s_add_i32 s91, s90, s30
	s_cmpk_gt_i32 s91, 0x8ff
	s_mov_b64 s[36:37], -1
	s_cbranch_scc0 .LBB0_37
	s_cmpk_gt_u32 s91, 0xeff
	s_cbranch_scc0 .LBB0_34
	s_cmpk_gt_u32 s91, 0x11ff
	s_cbranch_scc0 .LBB0_31
	s_cmpk_gt_u32 s91, 0x13ff
	s_cbranch_scc0 .LBB0_28
	s_add_i32 s30, s91, 0xffffec00
	s_lshr_b32 s30, s30, 3
	s_ashr_i32 s35, s34, 31
	s_lshl_b64 s[36:37], s[30:31], 14
	s_lshl_b64 s[92:93], s[34:35], 16
	s_add_u32 s36, s36, s92
	s_addc_u32 s37, s37, s93
	s_lshl_b64 s[92:93], s[36:37], 2
	s_waitcnt lgkmcnt(0)
	s_add_u32 s35, s26, s92
	s_addc_u32 s92, s27, s93
	s_lshl_b64 s[36:37], s[36:37], 1
	s_add_u32 s93, s41, s36
	s_addc_u32 s94, s42, s37
	s_and_b32 s30, s91, 7
	s_add_i32 s36, s30, 0xfffc
	s_and_b32 s36, s36, 0xffff
	s_min_u32 s36, s30, s36
	s_cmp_gt_u32 s30, 3
	s_cselect_b32 s95, 64, 0
	s_lshl_b32 s30, s36, 5
	s_lshl_b32 s36, s36, 7
	s_add_u32 s36, s35, s36
	v_or_b32_e32 v5, s95, v6
	s_addc_u32 s37, s92, 0
	v_lshl_add_u64 v[20:21], s[36:37], 0, v[2:3]
	v_lshlrev_b32_e32 v22, 9, v5
	v_mov_b32_e32 v23, v3
	v_lshl_add_u64 v[20:21], v[20:21], 0, v[22:23]
	s_movk_i32 s35, 0x1000
	v_add_co_u32_e32 v22, vcc, s35, v20
	s_movk_i32 s35, 0x3000
	s_nop 0
	v_addc_co_u32_e32 v23, vcc, 0, v21, vcc
	v_add_co_u32_e32 v24, vcc, s47, v20
	s_nop 1
	v_addc_co_u32_e32 v25, vcc, 0, v21, vcc
	v_add_co_u32_e32 v26, vcc, s35, v20
	s_movk_i32 s35, 0x5000
	s_nop 0
	v_addc_co_u32_e32 v27, vcc, 0, v21, vcc
	v_add_co_u32_e32 v28, vcc, s48, v20
	s_nop 1
	v_addc_co_u32_e32 v29, vcc, 0, v21, vcc
	global_load_dword v5, v[20:21], off
	global_load_dword v30, v[20:21], off offset:1024
	global_load_dword v31, v[20:21], off offset:2048
	global_load_dword v32, v[20:21], off offset:3072
	global_load_dword v33, v[22:23], off offset:1024
	global_load_dword v34, v[22:23], off offset:2048
	global_load_dword v35, v[22:23], off offset:3072
	global_load_dword v36, v[26:27], off offset:1024
	global_load_dword v37, v[26:27], off offset:2048
	s_nop 0
	global_load_dword v26, v[26:27], off offset:3072
	s_nop 0
	global_load_dword v27, v[24:25], off offset:-4096
	global_load_dword v38, v[24:25], off
	global_load_dword v39, v[24:25], off offset:1024
	global_load_dword v40, v[24:25], off offset:2048
	global_load_dword v41, v[24:25], off offset:3072
	global_load_dword v42, v[28:29], off offset:-4096
	global_load_dword v43, v[28:29], off
	v_add_co_u32_e32 v22, vcc, s35, v20
	s_movk_i32 s35, 0x7000
	s_nop 0
	v_addc_co_u32_e32 v23, vcc, 0, v21, vcc
	v_add_co_u32_e32 v24, vcc, s49, v20
	s_nop 1
	v_addc_co_u32_e32 v25, vcc, 0, v21, vcc
	v_add_co_u32_e32 v20, vcc, s35, v20
	global_load_dword v44, v[28:29], off offset:1024
	global_load_dword v45, v[28:29], off offset:2048
	s_nop 0
	global_load_dword v28, v[28:29], off offset:3072
	s_nop 0
	global_load_dword v29, v[24:25], off offset:-4096
	global_load_dword v46, v[24:25], off
	global_load_dword v47, v[24:25], off offset:1024
	global_load_dword v48, v[24:25], off offset:2048
	s_nop 0
	global_load_dword v24, v[24:25], off offset:3072
	v_addc_co_u32_e32 v21, vcc, 0, v21, vcc
	global_load_dword v25, v[22:23], off offset:1024
	global_load_dword v49, v[22:23], off offset:2048
	s_nop 0
	global_load_dword v22, v[22:23], off offset:3072
	s_nop 0
	global_load_dword v23, v[20:21], off
	global_load_dword v50, v[20:21], off offset:1024
	global_load_dword v51, v[20:21], off offset:2048
	s_nop 0
	global_load_dword v20, v[20:21], off offset:3072
	s_lshl_b32 s35, s95, 1
	s_add_u32 s36, s93, s35
	s_addc_u32 s37, s94, 0
	s_waitcnt vmcnt(30)
	ds_write2_b32 v7, v5, v30 offset1:66
	s_waitcnt vmcnt(28)
	ds_write2_b32 v7, v31, v32 offset0:132 offset1:198
	s_waitcnt vmcnt(21)
	ds_write2_b32 v13, v27, v33 offset0:8 offset1:74
	ds_write2_b32 v13, v34, v35 offset0:140 offset1:206
	s_waitcnt vmcnt(19)
	ds_write2_b32 v14, v38, v39 offset0:16 offset1:82
	s_waitcnt vmcnt(17)
	ds_write2_b32 v14, v40, v41 offset0:148 offset1:214
	s_waitcnt vmcnt(16)
	ds_write2_b32 v15, v42, v36 offset0:24 offset1:90
	ds_write2_b32 v15, v37, v26 offset0:156 offset1:222
	s_waitcnt vmcnt(14)
	ds_write2_b32 v16, v43, v44 offset0:32 offset1:98
	s_waitcnt vmcnt(12)
	ds_write2_b32 v16, v45, v28 offset0:164 offset1:230
	s_waitcnt vmcnt(6)
	ds_write2_b32 v17, v29, v25 offset0:40 offset1:106
	s_waitcnt vmcnt(4)
	ds_write2_b32 v17, v49, v22 offset0:172 offset1:238
	ds_write2_b32 v18, v46, v47 offset0:48 offset1:114
	ds_write2_b32 v18, v48, v24 offset0:180 offset1:246
	s_waitcnt vmcnt(2)
	ds_write2_b32 v19, v23, v50 offset0:56 offset1:122
	s_waitcnt vmcnt(0)
	ds_write2_b32 v19, v51, v20 offset0:188 offset1:254
	s_waitcnt lgkmcnt(0)
	ds_read2_b32 v[24:25], v9 offset1:8
	ds_read2_b32 v[28:29], v9 offset0:33 offset1:41
	ds_read2_b32 v[30:31], v9 offset0:66 offset1:74
	v_mov_b32_e32 v5, v3
	ds_read2_b32 v[32:33], v9 offset0:99 offset1:107
	v_lshl_add_u64 v[26:27], s[36:37], 0, v[4:5]
	s_waitcnt lgkmcnt(3)
	v_bfe_u32 v5, v24, 16, 1
	v_add3_u32 v5, v24, v5, s51
	s_waitcnt lgkmcnt(2)
	v_bfe_u32 v20, v28, 16, 1
	ds_read2_b32 v[34:35], v9 offset0:132 offset1:140
	v_lshrrev_b32_e32 v5, 16, v5
	v_add3_u32 v20, v28, v20, s51
	ds_read2_b32 v[36:37], v9 offset0:165 offset1:173
	v_and_or_b32 v20, v20, s52, v5
	s_waitcnt lgkmcnt(3)
	v_bfe_u32 v5, v30, 16, 1
	v_add3_u32 v5, v30, v5, s51
	s_waitcnt lgkmcnt(2)
	v_bfe_u32 v21, v32, 16, 1
	ds_read2_b32 v[38:39], v9 offset0:198 offset1:206
	v_lshrrev_b32_e32 v5, 16, v5
	v_add3_u32 v21, v32, v21, s51
	ds_read2_b32 v[40:41], v9 offset0:231 offset1:239
	v_and_or_b32 v21, v21, s52, v5
	s_waitcnt lgkmcnt(3)
	v_bfe_u32 v5, v34, 16, 1
	v_add3_u32 v5, v34, v5, s51
	s_waitcnt lgkmcnt(2)
	v_bfe_u32 v22, v36, 16, 1
	v_lshrrev_b32_e32 v5, 16, v5
	v_add3_u32 v22, v36, v22, s51
	v_and_or_b32 v22, v22, s52, v5
	s_waitcnt lgkmcnt(1)
	v_bfe_u32 v5, v38, 16, 1
	v_add3_u32 v5, v38, v5, s51
	s_waitcnt lgkmcnt(0)
	v_bfe_u32 v23, v40, 16, 1
	v_lshrrev_b32_e32 v5, 16, v5
	v_add3_u32 v23, v40, v23, s51
	v_and_or_b32 v23, v23, s52, v5
	v_or_b32_e32 v5, s30, v8
	v_lshlrev_b32_e32 v42, 8, v5
	v_mov_b32_e32 v43, v3
	v_lshl_add_u64 v[42:43], v[26:27], 0, v[42:43]
	v_bfe_u32 v5, v25, 16, 1
	global_store_dwordx4 v[42:43], v[20:23], off sc1
	v_add3_u32 v5, v25, v5, s51
	v_lshrrev_b32_e32 v5, 16, v5
	v_bfe_u32 v20, v29, 16, 1
	v_add3_u32 v20, v29, v20, s51
	v_and_or_b32 v20, v20, s52, v5
	v_bfe_u32 v5, v31, 16, 1
	v_add3_u32 v5, v31, v5, s51
	v_bfe_u32 v21, v33, 16, 1
	v_lshrrev_b32_e32 v5, 16, v5
	v_add3_u32 v21, v33, v21, s51
	v_and_or_b32 v21, v21, s52, v5
	v_bfe_u32 v5, v35, 16, 1
	v_add3_u32 v5, v35, v5, s51
	v_bfe_u32 v22, v37, 16, 1
	v_lshrrev_b32_e32 v5, 16, v5
	v_add3_u32 v22, v37, v22, s51
	v_and_or_b32 v22, v22, s52, v5
	v_bfe_u32 v5, v39, 16, 1
	v_add3_u32 v5, v39, v5, s51
	v_bfe_u32 v23, v41, 16, 1
	v_lshrrev_b32_e32 v5, 16, v5
	v_add3_u32 v23, v41, v23, s51
	v_and_or_b32 v23, v23, s52, v5
	v_or_b32_e32 v5, s30, v10
	v_lshlrev_b32_e32 v24, 8, v5
	v_mov_b32_e32 v25, v3
	ds_read2_b32 v[28:29], v9 offset0:16 offset1:24
	v_lshl_add_u64 v[24:25], v[26:27], 0, v[24:25]
	global_store_dwordx4 v[24:25], v[20:23], off sc1
	ds_read2_b32 v[24:25], v9 offset0:49 offset1:57
	ds_read2_b32 v[30:31], v9 offset0:82 offset1:90
	ds_read2_b32 v[32:33], v9 offset0:115 offset1:123
	s_waitcnt lgkmcnt(3)
	v_bfe_u32 v5, v28, 16, 1
	v_add3_u32 v5, v28, v5, s51
	s_waitcnt lgkmcnt(2)
	v_bfe_u32 v20, v24, 16, 1
	ds_read2_b32 v[34:35], v9 offset0:148 offset1:156
	v_lshrrev_b32_e32 v5, 16, v5
	v_add3_u32 v20, v24, v20, s51
	ds_read2_b32 v[36:37], v9 offset0:181 offset1:189
	v_and_or_b32 v20, v20, s52, v5
	s_waitcnt lgkmcnt(3)
	v_bfe_u32 v5, v30, 16, 1
	v_add3_u32 v5, v30, v5, s51
	s_waitcnt lgkmcnt(2)
	v_bfe_u32 v21, v32, 16, 1
	ds_read2_b32 v[38:39], v9 offset0:214 offset1:222
	v_lshrrev_b32_e32 v5, 16, v5
	v_add3_u32 v21, v32, v21, s51
	ds_read2_b32 v[40:41], v9 offset0:247 offset1:255
	v_and_or_b32 v21, v21, s52, v5
	s_waitcnt lgkmcnt(3)
	v_bfe_u32 v5, v34, 16, 1
	v_add3_u32 v5, v34, v5, s51
	s_waitcnt lgkmcnt(2)
	v_bfe_u32 v22, v36, 16, 1
	v_lshrrev_b32_e32 v5, 16, v5
	v_add3_u32 v22, v36, v22, s51
	v_and_or_b32 v22, v22, s52, v5
	s_waitcnt lgkmcnt(1)
	v_bfe_u32 v5, v38, 16, 1
	v_add3_u32 v5, v38, v5, s51
	s_waitcnt lgkmcnt(0)
	v_bfe_u32 v23, v40, 16, 1
	v_lshrrev_b32_e32 v5, 16, v5
	v_add3_u32 v23, v40, v23, s51
	v_and_or_b32 v23, v23, s52, v5
	v_or_b32_e32 v5, s30, v11
	v_lshlrev_b32_e32 v42, 8, v5
	v_mov_b32_e32 v43, v3
	v_lshl_add_u64 v[42:43], v[26:27], 0, v[42:43]
	v_bfe_u32 v5, v29, 16, 1
	global_store_dwordx4 v[42:43], v[20:23], off sc1
	v_add3_u32 v5, v29, v5, s51
	v_lshrrev_b32_e32 v5, 16, v5
	v_bfe_u32 v20, v25, 16, 1
	v_add3_u32 v20, v25, v20, s51
	v_and_or_b32 v20, v20, s52, v5
	v_bfe_u32 v5, v31, 16, 1
	v_add3_u32 v5, v31, v5, s51
	v_bfe_u32 v21, v33, 16, 1
	v_lshrrev_b32_e32 v5, 16, v5
	v_add3_u32 v21, v33, v21, s51
	v_and_or_b32 v21, v21, s52, v5
	v_bfe_u32 v5, v35, 16, 1
	v_add3_u32 v5, v35, v5, s51
	v_bfe_u32 v22, v37, 16, 1
	v_lshrrev_b32_e32 v5, 16, v5
	v_add3_u32 v22, v37, v22, s51
	v_and_or_b32 v22, v22, s52, v5
	v_bfe_u32 v5, v39, 16, 1
	v_add3_u32 v5, v39, v5, s51
	v_bfe_u32 v23, v41, 16, 1
	v_lshrrev_b32_e32 v5, 16, v5
	v_add3_u32 v23, v41, v23, s51
	v_and_or_b32 v23, v23, s52, v5
	v_or_b32_e32 v5, s30, v12
	v_lshlrev_b32_e32 v24, 8, v5
	v_mov_b32_e32 v25, v3
	v_lshl_add_u64 v[24:25], v[26:27], 0, v[24:25]
	global_store_dwordx4 v[24:25], v[20:23], off sc1
	s_waitcnt lgkmcnt(0)
	s_mov_b64 s[36:37], 0
.LBB0_28:
	s_andn2_b64 vcc, exec, s[36:37]
	s_cbranch_vccnz .LBB0_30
	s_ashr_i32 s35, s34, 31
	s_lshl_b64 s[36:37], s[34:35], 22
	s_waitcnt lgkmcnt(0)
	s_add_u32 s92, s28, s36
	s_addc_u32 s93, s29, s37
	s_lshl_b64 s[36:37], s[34:35], 21
	s_add_u32 s36, s39, s36
	s_mul_i32 s30, s34, 0xffffd7c0
	s_addc_u32 s35, s40, s37
	s_add_i32 s30, s45, s30
	s_add_i32 s30, s30, 0x1dc00
	s_and_b32 s37, s30, 0x1ffc0
	s_and_b32 s30, s43, 0x3e0
	s_lshl_b32 s94, s30, 2
	s_add_u32 s92, s92, s94
	v_or_b32_e32 v5, s37, v6
	s_addc_u32 s93, s93, 0
	v_lshl_add_u64 v[20:21], s[92:93], 0, v[2:3]
	v_lshlrev_b32_e32 v22, 12, v5
	v_mov_b32_e32 v23, v3
	v_lshl_add_u64 v[20:21], v[20:21], 0, v[22:23]
	v_add_co_u32_e32 v22, vcc, s47, v20
	s_lshl_b32 s37, s37, 1
	s_nop 0
	v_addc_co_u32_e32 v23, vcc, 0, v21, vcc
	v_add_co_u32_e32 v24, vcc, s48, v20
	s_add_u32 s36, s36, s37
	s_nop 0
	v_addc_co_u32_e32 v25, vcc, 0, v21, vcc
	v_add_co_u32_e32 v26, vcc, s49, v20
	s_addc_u32 s37, s35, 0
	s_nop 0
	v_addc_co_u32_e32 v27, vcc, 0, v21, vcc
	v_add_co_u32_e32 v28, vcc, s53, v20
	s_nop 1
	v_addc_co_u32_e32 v29, vcc, 0, v21, vcc
	v_add_co_u32_e32 v30, vcc, s56, v20
	s_nop 1
	v_addc_co_u32_e32 v31, vcc, 0, v21, vcc
	v_add_co_u32_e32 v32, vcc, s57, v20
	s_nop 1
	v_addc_co_u32_e32 v33, vcc, 0, v21, vcc
	v_add_co_u32_e32 v34, vcc, s58, v20
	s_nop 1
	v_addc_co_u32_e32 v35, vcc, 0, v21, vcc
	global_load_dword v5, v[20:21], off
	global_load_dword v38, v[22:23], off
	global_load_dword v39, v[24:25], off
	global_load_dword v40, v[26:27], off
	global_load_dword v41, v[28:29], off
	global_load_dword v42, v[30:31], off
	global_load_dword v43, v[32:33], off
	global_load_dword v44, v[34:35], off
	v_add_co_u32_e32 v22, vcc, s59, v20
	s_nop 1
	v_addc_co_u32_e32 v23, vcc, 0, v21, vcc
	v_add_co_u32_e32 v24, vcc, s60, v20
	s_nop 1
	v_addc_co_u32_e32 v25, vcc, 0, v21, vcc
	v_add_co_u32_e32 v26, vcc, s61, v20
	s_nop 1
	v_addc_co_u32_e32 v27, vcc, 0, v21, vcc
	v_add_co_u32_e32 v28, vcc, s62, v20
	s_nop 1
	v_addc_co_u32_e32 v29, vcc, 0, v21, vcc
	v_add_co_u32_e32 v30, vcc, s63, v20
	s_nop 1
	v_addc_co_u32_e32 v31, vcc, 0, v21, vcc
	v_add_co_u32_e32 v32, vcc, s64, v20
	s_nop 1
	v_addc_co_u32_e32 v33, vcc, 0, v21, vcc
	v_add_co_u32_e32 v34, vcc, s65, v20
	s_nop 1
	v_addc_co_u32_e32 v35, vcc, 0, v21, vcc
	v_add_co_u32_e32 v36, vcc, s66, v20
	s_nop 1
	v_addc_co_u32_e32 v37, vcc, 0, v21, vcc
	global_load_dword v45, v[22:23], off
	global_load_dword v46, v[24:25], off
	global_load_dword v47, v[26:27], off
	global_load_dword v48, v[28:29], off
	global_load_dword v49, v[30:31], off
	global_load_dword v50, v[32:33], off
	global_load_dword v51, v[34:35], off
	global_load_dword v52, v[36:37], off
	v_add_co_u32_e32 v22, vcc, s67, v20
	s_nop 1
	v_addc_co_u32_e32 v23, vcc, 0, v21, vcc
	v_add_co_u32_e32 v24, vcc, s68, v20
	s_nop 1
	v_addc_co_u32_e32 v25, vcc, 0, v21, vcc
	v_add_co_u32_e32 v26, vcc, s69, v20
	s_nop 1
	v_addc_co_u32_e32 v27, vcc, 0, v21, vcc
	v_add_co_u32_e32 v28, vcc, s70, v20
	s_nop 1
	v_addc_co_u32_e32 v29, vcc, 0, v21, vcc
	v_add_co_u32_e32 v30, vcc, s71, v20
	s_nop 1
	v_addc_co_u32_e32 v31, vcc, 0, v21, vcc
	v_add_co_u32_e32 v32, vcc, s72, v20
	s_nop 1
	v_addc_co_u32_e32 v33, vcc, 0, v21, vcc
	v_add_co_u32_e32 v34, vcc, s73, v20
	s_nop 1
	v_addc_co_u32_e32 v35, vcc, 0, v21, vcc
	v_add_co_u32_e32 v36, vcc, s74, v20
	s_nop 1
	v_addc_co_u32_e32 v37, vcc, 0, v21, vcc
	global_load_dword v53, v[22:23], off
	global_load_dword v54, v[24:25], off
	global_load_dword v55, v[26:27], off
	global_load_dword v56, v[28:29], off
	global_load_dword v57, v[30:31], off
	global_load_dword v58, v[32:33], off
	global_load_dword v59, v[34:35], off
	s_nop 0
	global_load_dword v36, v[36:37], off
	v_add_co_u32_e32 v22, vcc, s75, v20
	s_nop 1
	v_addc_co_u32_e32 v23, vcc, 0, v21, vcc
	v_add_co_u32_e32 v24, vcc, s76, v20
	s_nop 1
	v_addc_co_u32_e32 v25, vcc, 0, v21, vcc
	v_add_co_u32_e32 v26, vcc, s77, v20
	s_nop 1
	v_addc_co_u32_e32 v27, vcc, 0, v21, vcc
	v_add_co_u32_e32 v28, vcc, s78, v20
	s_nop 1
	v_addc_co_u32_e32 v29, vcc, 0, v21, vcc
	v_add_co_u32_e32 v30, vcc, s79, v20
	s_nop 1
	v_addc_co_u32_e32 v31, vcc, 0, v21, vcc
	v_add_co_u32_e32 v32, vcc, s80, v20
	s_nop 1
	v_addc_co_u32_e32 v33, vcc, 0, v21, vcc
	v_add_co_u32_e32 v34, vcc, s81, v20
	s_nop 1
	v_addc_co_u32_e32 v35, vcc, 0, v21, vcc
	v_add_co_u32_e32 v20, vcc, s82, v20
	s_nop 1
	v_addc_co_u32_e32 v21, vcc, 0, v21, vcc
	global_load_dword v22, v[22:23], off
	s_nop 0
	global_load_dword v23, v[24:25], off
	s_nop 0
	global_load_dword v24, v[26:27], off
	global_load_dword v25, v[28:29], off
	s_nop 0
	global_load_dword v26, v[30:31], off
	global_load_dword v27, v[32:33], off
	global_load_dword v28, v[34:35], off
	s_nop 0
	global_load_dword v20, v[20:21], off
	s_waitcnt vmcnt(30)
	ds_write2_b32 v7, v5, v38 offset1:66
	s_waitcnt vmcnt(28)
	ds_write2_b32 v7, v39, v40 offset0:132 offset1:198
	s_waitcnt vmcnt(26)
	ds_write2_b32 v13, v41, v42 offset0:8 offset1:74
	s_waitcnt vmcnt(24)
	ds_write2_b32 v13, v43, v44 offset0:140 offset1:206
	s_waitcnt vmcnt(22)
	ds_write2_b32 v14, v45, v46 offset0:16 offset1:82
	s_waitcnt vmcnt(20)
	ds_write2_b32 v14, v47, v48 offset0:148 offset1:214
	s_waitcnt vmcnt(18)
	ds_write2_b32 v15, v49, v50 offset0:24 offset1:90
	s_waitcnt vmcnt(16)
	ds_write2_b32 v15, v51, v52 offset0:156 offset1:222
	s_waitcnt vmcnt(14)
	ds_write2_b32 v16, v53, v54 offset0:32 offset1:98
	s_waitcnt vmcnt(12)
	ds_write2_b32 v16, v55, v56 offset0:164 offset1:230
	s_waitcnt vmcnt(10)
	ds_write2_b32 v17, v57, v58 offset0:40 offset1:106
	s_waitcnt vmcnt(8)
	ds_write2_b32 v17, v59, v36 offset0:172 offset1:238
	s_waitcnt vmcnt(6)
	ds_write2_b32 v18, v22, v23 offset0:48 offset1:114
	s_waitcnt vmcnt(4)
	ds_write2_b32 v18, v24, v25 offset0:180 offset1:246
	s_waitcnt vmcnt(2)
	ds_write2_b32 v19, v26, v27 offset0:56 offset1:122
	s_waitcnt vmcnt(0)
	ds_write2_b32 v19, v28, v20 offset0:188 offset1:254
	s_waitcnt lgkmcnt(0)
	ds_read2_b32 v[24:25], v9 offset1:8
	ds_read2_b32 v[28:29], v9 offset0:33 offset1:41
	ds_read2_b32 v[30:31], v9 offset0:66 offset1:74
	v_mov_b32_e32 v5, v3
	ds_read2_b32 v[32:33], v9 offset0:99 offset1:107
	v_lshl_add_u64 v[26:27], s[36:37], 0, v[4:5]
	s_waitcnt lgkmcnt(3)
	v_bfe_u32 v5, v24, 16, 1
	v_add3_u32 v5, v24, v5, s51
	s_waitcnt lgkmcnt(2)
	v_bfe_u32 v20, v28, 16, 1
	ds_read2_b32 v[34:35], v9 offset0:132 offset1:140
	v_lshrrev_b32_e32 v5, 16, v5
	v_add3_u32 v20, v28, v20, s51
	ds_read2_b32 v[36:37], v9 offset0:165 offset1:173
	v_and_or_b32 v20, v20, s52, v5
	s_waitcnt lgkmcnt(3)
	v_bfe_u32 v5, v30, 16, 1
	v_add3_u32 v5, v30, v5, s51
	s_waitcnt lgkmcnt(2)
	v_bfe_u32 v21, v32, 16, 1
	ds_read2_b32 v[38:39], v9 offset0:198 offset1:206
	v_lshrrev_b32_e32 v5, 16, v5
	v_add3_u32 v21, v32, v21, s51
	ds_read2_b32 v[40:41], v9 offset0:231 offset1:239
	v_and_or_b32 v21, v21, s52, v5
	s_waitcnt lgkmcnt(3)
	v_bfe_u32 v5, v34, 16, 1
	v_add3_u32 v5, v34, v5, s51
	s_waitcnt lgkmcnt(2)
	v_bfe_u32 v22, v36, 16, 1
	v_lshrrev_b32_e32 v5, 16, v5
	v_add3_u32 v22, v36, v22, s51
	v_and_or_b32 v22, v22, s52, v5
	s_waitcnt lgkmcnt(1)
	v_bfe_u32 v5, v38, 16, 1
	v_add3_u32 v5, v38, v5, s51
	s_waitcnt lgkmcnt(0)
	v_bfe_u32 v23, v40, 16, 1
	v_lshrrev_b32_e32 v5, 16, v5
	v_add3_u32 v23, v40, v23, s51
	v_and_or_b32 v23, v23, s52, v5
	v_or_b32_e32 v5, s30, v8
	v_lshlrev_b32_e32 v42, 11, v5
	v_mov_b32_e32 v43, v3
	v_lshl_add_u64 v[42:43], v[26:27], 0, v[42:43]
	v_bfe_u32 v5, v25, 16, 1
	global_store_dwordx4 v[42:43], v[20:23], off sc1
	v_add3_u32 v5, v25, v5, s51
	v_lshrrev_b32_e32 v5, 16, v5
	v_bfe_u32 v20, v29, 16, 1
	v_add3_u32 v20, v29, v20, s51
	v_and_or_b32 v20, v20, s52, v5
	v_bfe_u32 v5, v31, 16, 1
	v_add3_u32 v5, v31, v5, s51
	v_bfe_u32 v21, v33, 16, 1
	v_lshrrev_b32_e32 v5, 16, v5
	v_add3_u32 v21, v33, v21, s51
	v_and_or_b32 v21, v21, s52, v5
	v_bfe_u32 v5, v35, 16, 1
	v_add3_u32 v5, v35, v5, s51
	v_bfe_u32 v22, v37, 16, 1
	v_lshrrev_b32_e32 v5, 16, v5
	v_add3_u32 v22, v37, v22, s51
	v_and_or_b32 v22, v22, s52, v5
	v_bfe_u32 v5, v39, 16, 1
	v_add3_u32 v5, v39, v5, s51
	v_bfe_u32 v23, v41, 16, 1
	v_lshrrev_b32_e32 v5, 16, v5
	v_add3_u32 v23, v41, v23, s51
	v_and_or_b32 v23, v23, s52, v5
	v_or_b32_e32 v5, s30, v10
	v_lshlrev_b32_e32 v24, 11, v5
	v_mov_b32_e32 v25, v3
	ds_read2_b32 v[28:29], v9 offset0:16 offset1:24
	v_lshl_add_u64 v[24:25], v[26:27], 0, v[24:25]
	global_store_dwordx4 v[24:25], v[20:23], off sc1
	ds_read2_b32 v[24:25], v9 offset0:49 offset1:57
	ds_read2_b32 v[30:31], v9 offset0:82 offset1:90
	ds_read2_b32 v[32:33], v9 offset0:115 offset1:123
	s_waitcnt lgkmcnt(3)
	v_bfe_u32 v5, v28, 16, 1
	v_add3_u32 v5, v28, v5, s51
	s_waitcnt lgkmcnt(2)
	v_bfe_u32 v20, v24, 16, 1
	ds_read2_b32 v[34:35], v9 offset0:148 offset1:156
	v_lshrrev_b32_e32 v5, 16, v5
	v_add3_u32 v20, v24, v20, s51
	ds_read2_b32 v[36:37], v9 offset0:181 offset1:189
	v_and_or_b32 v20, v20, s52, v5
	s_waitcnt lgkmcnt(3)
	v_bfe_u32 v5, v30, 16, 1
	v_add3_u32 v5, v30, v5, s51
	s_waitcnt lgkmcnt(2)
	v_bfe_u32 v21, v32, 16, 1
	ds_read2_b32 v[38:39], v9 offset0:214 offset1:222
	v_lshrrev_b32_e32 v5, 16, v5
	v_add3_u32 v21, v32, v21, s51
	ds_read2_b32 v[40:41], v9 offset0:247 offset1:255
	v_and_or_b32 v21, v21, s52, v5
	s_waitcnt lgkmcnt(3)
	v_bfe_u32 v5, v34, 16, 1
	v_add3_u32 v5, v34, v5, s51
	s_waitcnt lgkmcnt(2)
	v_bfe_u32 v22, v36, 16, 1
	v_lshrrev_b32_e32 v5, 16, v5
	v_add3_u32 v22, v36, v22, s51
	v_and_or_b32 v22, v22, s52, v5
	s_waitcnt lgkmcnt(1)
	v_bfe_u32 v5, v38, 16, 1
	v_add3_u32 v5, v38, v5, s51
	s_waitcnt lgkmcnt(0)
	v_bfe_u32 v23, v40, 16, 1
	v_lshrrev_b32_e32 v5, 16, v5
	v_add3_u32 v23, v40, v23, s51
	v_and_or_b32 v23, v23, s52, v5
	v_or_b32_e32 v5, s30, v11
	v_lshlrev_b32_e32 v42, 11, v5
	v_mov_b32_e32 v43, v3
	v_lshl_add_u64 v[42:43], v[26:27], 0, v[42:43]
	v_bfe_u32 v5, v29, 16, 1
	global_store_dwordx4 v[42:43], v[20:23], off sc1
	v_add3_u32 v5, v29, v5, s51
	v_lshrrev_b32_e32 v5, 16, v5
	v_bfe_u32 v20, v25, 16, 1
	v_add3_u32 v20, v25, v20, s51
	v_and_or_b32 v20, v20, s52, v5
	v_bfe_u32 v5, v31, 16, 1
	v_add3_u32 v5, v31, v5, s51
	v_bfe_u32 v21, v33, 16, 1
	v_lshrrev_b32_e32 v5, 16, v5
	v_add3_u32 v21, v33, v21, s51
	v_and_or_b32 v21, v21, s52, v5
	v_bfe_u32 v5, v35, 16, 1
	v_add3_u32 v5, v35, v5, s51
	v_bfe_u32 v22, v37, 16, 1
	v_lshrrev_b32_e32 v5, 16, v5
	v_add3_u32 v22, v37, v22, s51
	v_and_or_b32 v22, v22, s52, v5
	v_bfe_u32 v5, v39, 16, 1
	v_add3_u32 v5, v39, v5, s51
	v_bfe_u32 v23, v41, 16, 1
	v_lshrrev_b32_e32 v5, 16, v5
	v_add3_u32 v23, v41, v23, s51
	v_and_or_b32 v23, v23, s52, v5
	v_or_b32_e32 v5, s30, v12
	v_lshlrev_b32_e32 v24, 11, v5
	v_mov_b32_e32 v25, v3
	v_lshl_add_u64 v[24:25], v[26:27], 0, v[24:25]
	global_store_dwordx4 v[24:25], v[20:23], off sc1
	s_waitcnt lgkmcnt(0)

.LBB0_31:
	s_andn2_b64 vcc, exec, s[36:37]
	s_cbranch_vccnz .LBB0_33
	s_add_i32 s30, s91, 0xfffff100
	s_lshr_b32 s35, s30, 8
	s_mul_i32 s36, s34, 3
	s_mul_hi_i32 s30, s34, 3
	s_add_u32 s36, s36, s35
	s_addc_u32 s37, s30, 0
	s_lshl_b64 s[36:37], s[36:37], 21
	s_waitcnt lgkmcnt(0)
	s_add_u32 s93, s4, s36
	s_addc_u32 s95, s5, s37
	s_mul_i32 s36, s34, 0x300000
	s_mul_hi_i32 s30, s34, 0x300000
	s_add_u32 s36, s19, s36
	s_addc_u32 s37, s38, s30
	s_lshl_b32 s30, s34, 6
	s_sub_i32 s30, s45, s30
	s_and_b32 s92, s30, 0x1c0
	s_and_b32 s30, s43, 0x3e0
	s_lshl_b32 s94, s30, 2
	s_add_u32 s94, s93, s94
	v_or_b32_e32 v5, s92, v6
	s_addc_u32 s95, s95, 0
	v_lshl_add_u64 v[20:21], s[94:95], 0, v[2:3]
	v_lshlrev_b32_e32 v22, 12, v5
	v_mov_b32_e32 v23, v3
	v_lshl_add_u64 v[20:21], v[20:21], 0, v[22:23]
	v_add_co_u32_e32 v22, vcc, s47, v20
	s_lshl_b32 s35, s35, 10
	s_nop 0
	v_addc_co_u32_e32 v23, vcc, 0, v21, vcc
	v_add_co_u32_e32 v24, vcc, s48, v20
	s_add_u32 s35, s36, s35
	s_nop 0
	v_addc_co_u32_e32 v25, vcc, 0, v21, vcc
	v_add_co_u32_e32 v26, vcc, s49, v20
	s_addc_u32 s37, s37, 0
	s_nop 0
	v_addc_co_u32_e32 v27, vcc, 0, v21, vcc
	v_add_co_u32_e32 v28, vcc, s53, v20
	s_lshl_b32 s36, s92, 1
	s_nop 0
	v_addc_co_u32_e32 v29, vcc, 0, v21, vcc
	v_add_co_u32_e32 v30, vcc, s56, v20
	s_add_u32 s36, s35, s36
	s_nop 0
	v_addc_co_u32_e32 v31, vcc, 0, v21, vcc
	v_add_co_u32_e32 v32, vcc, s57, v20
	s_addc_u32 s37, s37, 0
	s_nop 0
	v_addc_co_u32_e32 v33, vcc, 0, v21, vcc
	v_add_co_u32_e32 v34, vcc, s58, v20
	s_nop 1
	v_addc_co_u32_e32 v35, vcc, 0, v21, vcc
	global_load_dword v5, v[20:21], off
	global_load_dword v38, v[22:23], off
	global_load_dword v39, v[24:25], off
	global_load_dword v40, v[26:27], off
	global_load_dword v41, v[28:29], off
	global_load_dword v42, v[30:31], off
	global_load_dword v43, v[32:33], off
	global_load_dword v44, v[34:35], off
	v_add_co_u32_e32 v22, vcc, s59, v20
	s_nop 1
	v_addc_co_u32_e32 v23, vcc, 0, v21, vcc
	v_add_co_u32_e32 v24, vcc, s60, v20
	s_nop 1
	v_addc_co_u32_e32 v25, vcc, 0, v21, vcc
	v_add_co_u32_e32 v26, vcc, s61, v20
	s_nop 1
	v_addc_co_u32_e32 v27, vcc, 0, v21, vcc
	v_add_co_u32_e32 v28, vcc, s62, v20
	s_nop 1
	v_addc_co_u32_e32 v29, vcc, 0, v21, vcc
	v_add_co_u32_e32 v30, vcc, s63, v20
	s_nop 1
	v_addc_co_u32_e32 v31, vcc, 0, v21, vcc
	v_add_co_u32_e32 v32, vcc, s64, v20
	s_nop 1
	v_addc_co_u32_e32 v33, vcc, 0, v21, vcc
	v_add_co_u32_e32 v34, vcc, s65, v20
	s_nop 1
	v_addc_co_u32_e32 v35, vcc, 0, v21, vcc
	v_add_co_u32_e32 v36, vcc, s66, v20
	s_nop 1
	v_addc_co_u32_e32 v37, vcc, 0, v21, vcc
	global_load_dword v45, v[22:23], off
	global_load_dword v46, v[24:25], off
	global_load_dword v47, v[26:27], off
	global_load_dword v48, v[28:29], off
	global_load_dword v49, v[30:31], off
	global_load_dword v50, v[32:33], off
	global_load_dword v51, v[34:35], off
	global_load_dword v52, v[36:37], off
	v_add_co_u32_e32 v22, vcc, s67, v20
	s_nop 1
	v_addc_co_u32_e32 v23, vcc, 0, v21, vcc
	v_add_co_u32_e32 v24, vcc, s68, v20
	s_nop 1
	v_addc_co_u32_e32 v25, vcc, 0, v21, vcc
	v_add_co_u32_e32 v26, vcc, s69, v20
	s_nop 1
	v_addc_co_u32_e32 v27, vcc, 0, v21, vcc
	v_add_co_u32_e32 v28, vcc, s70, v20
	s_nop 1
	v_addc_co_u32_e32 v29, vcc, 0, v21, vcc
	v_add_co_u32_e32 v30, vcc, s71, v20
	s_nop 1
	v_addc_co_u32_e32 v31, vcc, 0, v21, vcc
	v_add_co_u32_e32 v32, vcc, s72, v20
	s_nop 1
	v_addc_co_u32_e32 v33, vcc, 0, v21, vcc
	v_add_co_u32_e32 v34, vcc, s73, v20
	s_nop 1
	v_addc_co_u32_e32 v35, vcc, 0, v21, vcc
	v_add_co_u32_e32 v36, vcc, s74, v20
	s_nop 1
	v_addc_co_u32_e32 v37, vcc, 0, v21, vcc
	global_load_dword v53, v[22:23], off
	global_load_dword v54, v[24:25], off
	global_load_dword v55, v[26:27], off
	global_load_dword v56, v[28:29], off
	global_load_dword v57, v[30:31], off
	global_load_dword v58, v[32:33], off
	global_load_dword v59, v[34:35], off
	s_nop 0
	global_load_dword v36, v[36:37], off
	v_add_co_u32_e32 v22, vcc, s75, v20
	s_nop 1
	v_addc_co_u32_e32 v23, vcc, 0, v21, vcc
	v_add_co_u32_e32 v24, vcc, s76, v20
	s_nop 1
	v_addc_co_u32_e32 v25, vcc, 0, v21, vcc
	v_add_co_u32_e32 v26, vcc, s77, v20
	s_nop 1
	v_addc_co_u32_e32 v27, vcc, 0, v21, vcc
	v_add_co_u32_e32 v28, vcc, s78, v20
	s_nop 1
	v_addc_co_u32_e32 v29, vcc, 0, v21, vcc
	v_add_co_u32_e32 v30, vcc, s79, v20
	s_nop 1
	v_addc_co_u32_e32 v31, vcc, 0, v21, vcc
	v_add_co_u32_e32 v32, vcc, s80, v20
	s_nop 1
	v_addc_co_u32_e32 v33, vcc, 0, v21, vcc
	v_add_co_u32_e32 v34, vcc, s81, v20
	s_nop 1
	v_addc_co_u32_e32 v35, vcc, 0, v21, vcc
	v_add_co_u32_e32 v20, vcc, s82, v20
	s_nop 1
	v_addc_co_u32_e32 v21, vcc, 0, v21, vcc
	global_load_dword v22, v[22:23], off
	s_nop 0
	global_load_dword v23, v[24:25], off
	s_nop 0
	global_load_dword v24, v[26:27], off
	global_load_dword v25, v[28:29], off
	s_nop 0
	global_load_dword v26, v[30:31], off
	global_load_dword v27, v[32:33], off
	global_load_dword v28, v[34:35], off
	s_nop 0
	global_load_dword v20, v[20:21], off
	s_waitcnt vmcnt(30)
	ds_write2_b32 v7, v5, v38 offset1:66
	s_waitcnt vmcnt(28)
	ds_write2_b32 v7, v39, v40 offset0:132 offset1:198
	s_waitcnt vmcnt(26)
	ds_write2_b32 v13, v41, v42 offset0:8 offset1:74
	s_waitcnt vmcnt(24)
	ds_write2_b32 v13, v43, v44 offset0:140 offset1:206
	s_waitcnt vmcnt(22)
	ds_write2_b32 v14, v45, v46 offset0:16 offset1:82
	s_waitcnt vmcnt(20)
	ds_write2_b32 v14, v47, v48 offset0:148 offset1:214
	s_waitcnt vmcnt(18)
	ds_write2_b32 v15, v49, v50 offset0:24 offset1:90
	s_waitcnt vmcnt(16)
	ds_write2_b32 v15, v51, v52 offset0:156 offset1:222
	s_waitcnt vmcnt(14)
	ds_write2_b32 v16, v53, v54 offset0:32 offset1:98
	s_waitcnt vmcnt(12)
	ds_write2_b32 v16, v55, v56 offset0:164 offset1:230
	s_waitcnt vmcnt(10)
	ds_write2_b32 v17, v57, v58 offset0:40 offset1:106
	s_waitcnt vmcnt(8)
	ds_write2_b32 v17, v59, v36 offset0:172 offset1:238
	s_waitcnt vmcnt(6)
	ds_write2_b32 v18, v22, v23 offset0:48 offset1:114
	s_waitcnt vmcnt(4)
	ds_write2_b32 v18, v24, v25 offset0:180 offset1:246
	s_waitcnt vmcnt(2)
	ds_write2_b32 v19, v26, v27 offset0:56 offset1:122
	s_waitcnt vmcnt(0)
	ds_write2_b32 v19, v28, v20 offset0:188 offset1:254
	s_waitcnt lgkmcnt(0)
	ds_read2_b32 v[24:25], v9 offset1:8
	ds_read2_b32 v[28:29], v9 offset0:33 offset1:41
	ds_read2_b32 v[30:31], v9 offset0:66 offset1:74
	v_mov_b32_e32 v5, v3
	ds_read2_b32 v[32:33], v9 offset0:99 offset1:107
	v_lshl_add_u64 v[26:27], s[36:37], 0, v[4:5]
	s_waitcnt lgkmcnt(3)
	v_bfe_u32 v5, v24, 16, 1
	v_add3_u32 v5, v24, v5, s51
	s_waitcnt lgkmcnt(2)
	v_bfe_u32 v20, v28, 16, 1
	ds_read2_b32 v[34:35], v9 offset0:132 offset1:140
	v_lshrrev_b32_e32 v5, 16, v5
	v_add3_u32 v20, v28, v20, s51
	ds_read2_b32 v[36:37], v9 offset0:165 offset1:173
	v_and_or_b32 v20, v20, s52, v5
	s_waitcnt lgkmcnt(3)
	v_bfe_u32 v5, v30, 16, 1
	v_add3_u32 v5, v30, v5, s51
	s_waitcnt lgkmcnt(2)
	v_bfe_u32 v21, v32, 16, 1
	ds_read2_b32 v[38:39], v9 offset0:198 offset1:206
	v_lshrrev_b32_e32 v5, 16, v5
	v_add3_u32 v21, v32, v21, s51
	ds_read2_b32 v[40:41], v9 offset0:231 offset1:239
	v_and_or_b32 v21, v21, s52, v5
	s_waitcnt lgkmcnt(3)
	v_bfe_u32 v5, v34, 16, 1
	v_add3_u32 v5, v34, v5, s51
	s_waitcnt lgkmcnt(2)
	v_bfe_u32 v22, v36, 16, 1
	v_lshrrev_b32_e32 v5, 16, v5
	v_add3_u32 v22, v36, v22, s51
	v_and_or_b32 v22, v22, s52, v5
	s_waitcnt lgkmcnt(1)
	v_bfe_u32 v5, v38, 16, 1
	v_add3_u32 v5, v38, v5, s51
	s_waitcnt lgkmcnt(0)
	v_bfe_u32 v23, v40, 16, 1
	v_lshrrev_b32_e32 v5, 16, v5
	v_add3_u32 v23, v40, v23, s51
	v_and_or_b32 v23, v23, s52, v5
	v_or_b32_e32 v5, s30, v8
	v_mul_u32_u24_e32 v5, 0x600, v5
	v_lshlrev_b32_e32 v42, 1, v5
	v_mov_b32_e32 v43, v3
	v_lshl_add_u64 v[42:43], v[26:27], 0, v[42:43]
	v_bfe_u32 v5, v25, 16, 1
	global_store_dwordx4 v[42:43], v[20:23], off sc1
	v_add3_u32 v5, v25, v5, s51
	v_lshrrev_b32_e32 v5, 16, v5
	v_bfe_u32 v20, v29, 16, 1
	v_add3_u32 v20, v29, v20, s51
	v_and_or_b32 v20, v20, s52, v5
	v_bfe_u32 v5, v31, 16, 1
	v_add3_u32 v5, v31, v5, s51
	v_bfe_u32 v21, v33, 16, 1
	v_lshrrev_b32_e32 v5, 16, v5
	v_add3_u32 v21, v33, v21, s51
	v_and_or_b32 v21, v21, s52, v5
	v_bfe_u32 v5, v35, 16, 1
	v_add3_u32 v5, v35, v5, s51
	v_bfe_u32 v22, v37, 16, 1
	v_lshrrev_b32_e32 v5, 16, v5
	v_add3_u32 v22, v37, v22, s51
	v_and_or_b32 v22, v22, s52, v5
	v_bfe_u32 v5, v39, 16, 1
	v_add3_u32 v5, v39, v5, s51
	v_bfe_u32 v23, v41, 16, 1
	v_lshrrev_b32_e32 v5, 16, v5
	v_add3_u32 v23, v41, v23, s51
	v_and_or_b32 v23, v23, s52, v5
	v_or_b32_e32 v5, s30, v10
	v_mul_u32_u24_e32 v5, 0x600, v5
	v_lshlrev_b32_e32 v24, 1, v5
	v_mov_b32_e32 v25, v3
	ds_read2_b32 v[28:29], v9 offset0:16 offset1:24
	v_lshl_add_u64 v[24:25], v[26:27], 0, v[24:25]
	global_store_dwordx4 v[24:25], v[20:23], off sc1
	ds_read2_b32 v[24:25], v9 offset0:49 offset1:57
	ds_read2_b32 v[30:31], v9 offset0:82 offset1:90
	ds_read2_b32 v[32:33], v9 offset0:115 offset1:123
	s_waitcnt lgkmcnt(3)
	v_bfe_u32 v5, v28, 16, 1
	v_add3_u32 v5, v28, v5, s51
	s_waitcnt lgkmcnt(2)
	v_bfe_u32 v20, v24, 16, 1
	ds_read2_b32 v[34:35], v9 offset0:148 offset1:156
	v_lshrrev_b32_e32 v5, 16, v5
	v_add3_u32 v20, v24, v20, s51
	ds_read2_b32 v[36:37], v9 offset0:181 offset1:189
	v_and_or_b32 v20, v20, s52, v5
	s_waitcnt lgkmcnt(3)
	v_bfe_u32 v5, v30, 16, 1
	v_add3_u32 v5, v30, v5, s51
	s_waitcnt lgkmcnt(2)
	v_bfe_u32 v21, v32, 16, 1
	ds_read2_b32 v[38:39], v9 offset0:214 offset1:222
	v_lshrrev_b32_e32 v5, 16, v5
	v_add3_u32 v21, v32, v21, s51
	ds_read2_b32 v[40:41], v9 offset0:247 offset1:255
	v_and_or_b32 v21, v21, s52, v5
	s_waitcnt lgkmcnt(3)
	v_bfe_u32 v5, v34, 16, 1
	v_add3_u32 v5, v34, v5, s51
	s_waitcnt lgkmcnt(2)
	v_bfe_u32 v22, v36, 16, 1
	v_lshrrev_b32_e32 v5, 16, v5
	v_add3_u32 v22, v36, v22, s51
	v_and_or_b32 v22, v22, s52, v5
	s_waitcnt lgkmcnt(1)
	v_bfe_u32 v5, v38, 16, 1
	v_add3_u32 v5, v38, v5, s51
	s_waitcnt lgkmcnt(0)
	v_bfe_u32 v23, v40, 16, 1
	v_lshrrev_b32_e32 v5, 16, v5
	v_add3_u32 v23, v40, v23, s51
	v_and_or_b32 v23, v23, s52, v5
	v_or_b32_e32 v5, s30, v11
	v_mul_u32_u24_e32 v5, 0x600, v5
	v_lshlrev_b32_e32 v42, 1, v5
	v_mov_b32_e32 v43, v3
	v_lshl_add_u64 v[42:43], v[26:27], 0, v[42:43]
	v_bfe_u32 v5, v29, 16, 1
	global_store_dwordx4 v[42:43], v[20:23], off sc1
	v_add3_u32 v5, v29, v5, s51
	v_lshrrev_b32_e32 v5, 16, v5
	v_bfe_u32 v20, v25, 16, 1
	v_add3_u32 v20, v25, v20, s51
	v_and_or_b32 v20, v20, s52, v5
	v_bfe_u32 v5, v31, 16, 1
	v_add3_u32 v5, v31, v5, s51
	v_bfe_u32 v21, v33, 16, 1
	v_lshrrev_b32_e32 v5, 16, v5
	v_add3_u32 v21, v33, v21, s51
	v_and_or_b32 v21, v21, s52, v5
	v_bfe_u32 v5, v35, 16, 1
	v_add3_u32 v5, v35, v5, s51
	v_bfe_u32 v22, v37, 16, 1
	v_lshrrev_b32_e32 v5, 16, v5
	v_add3_u32 v22, v37, v22, s51
	v_and_or_b32 v22, v22, s52, v5
	v_bfe_u32 v5, v39, 16, 1
	v_add3_u32 v5, v39, v5, s51
	v_bfe_u32 v23, v41, 16, 1
	v_lshrrev_b32_e32 v5, 16, v5
	v_add3_u32 v23, v41, v23, s51
	v_and_or_b32 v23, v23, s52, v5
	v_or_b32_e32 v5, s30, v12
	v_mul_u32_u24_e32 v5, 0x600, v5
	v_lshlrev_b32_e32 v24, 1, v5
	v_mov_b32_e32 v25, v3
	v_lshl_add_u64 v[24:25], v[26:27], 0, v[24:25]
	global_store_dwordx4 v[24:25], v[20:23], off sc1
	s_waitcnt lgkmcnt(0)

.LBB0_34:
	s_andn2_b64 vcc, exec, s[36:37]
	s_cbranch_vccnz .LBB0_36
	s_mul_i32 s35, s34, 0xc00000
	s_mul_hi_i32 s30, s34, 0xc00000
	s_waitcnt lgkmcnt(0)
	s_add_u32 s92, s6, s35
	s_addc_u32 s93, s7, s30
	s_mul_i32 s35, s34, 0xf00000
	s_mul_hi_i32 s30, s34, 0xf00000
	s_add_u32 s35, s20, s35
	s_addc_u32 s36, s21, s30
	s_add_i32 s30, s91, 0xf700
	s_and_b32 s37, s30, 0xffff
	s_mul_i32 s37, s37, 0xaaab
	s_lshr_b32 s94, s37, 16
	s_lshr_b32 s37, s37, 22
	s_mulk_i32 s37, 0x60
	s_sub_i32 s30, s30, s37
	s_lshl_b32 s30, s30, 5
	s_and_b32 s30, s30, 0xffe0
	s_and_b32 s37, s94, 0xffc0
	s_lshl_b32 s94, s30, 2
	v_or_b32_e32 v5, s37, v6
	s_add_u32 s92, s92, s94
	s_addc_u32 s93, s93, 0
	v_mul_u32_u24_e32 v5, 0xc00, v5
	v_lshl_add_u64 v[20:21], s[92:93], 0, v[2:3]
	v_lshlrev_b32_e32 v22, 2, v5
	v_mov_b32_e32 v23, v3
	v_lshl_add_u64 v[20:21], v[20:21], 0, v[22:23]
	v_add_co_u32_e32 v22, vcc, s49, v20
	s_mov_b32 s92, 0x42000
	s_nop 0
	v_addc_co_u32_e32 v23, vcc, 0, v21, vcc
	v_add_co_u32_e32 v24, vcc, s57, v20
	s_lshl_b32 s37, s37, 1
	s_nop 0
	v_addc_co_u32_e32 v25, vcc, 0, v21, vcc
	v_add_co_u32_e32 v26, vcc, s60, v20
	s_nop 1
	v_addc_co_u32_e32 v27, vcc, 0, v21, vcc
	v_add_co_u32_e32 v28, vcc, s63, v20
	s_nop 1
	v_addc_co_u32_e32 v29, vcc, 0, v21, vcc
	v_add_co_u32_e32 v30, vcc, s66, v20
	s_nop 1
	v_addc_co_u32_e32 v31, vcc, 0, v21, vcc
	v_add_co_u32_e32 v32, vcc, s69, v20
	s_nop 1
	v_addc_co_u32_e32 v33, vcc, 0, v21, vcc
	v_add_co_u32_e32 v34, vcc, s72, v20
	s_nop 1
	v_addc_co_u32_e32 v35, vcc, 0, v21, vcc
	global_load_dword v5, v[20:21], off
	global_load_dword v38, v[22:23], off
	global_load_dword v39, v[24:25], off
	global_load_dword v40, v[26:27], off
	global_load_dword v41, v[28:29], off
	global_load_dword v42, v[30:31], off
	global_load_dword v43, v[32:33], off
	global_load_dword v44, v[34:35], off
	v_add_co_u32_e32 v22, vcc, s75, v20
	s_nop 1
	v_addc_co_u32_e32 v23, vcc, 0, v21, vcc
	v_add_co_u32_e32 v24, vcc, s78, v20
	s_nop 1
	v_addc_co_u32_e32 v25, vcc, 0, v21, vcc
	v_add_co_u32_e32 v26, vcc, s81, v20
	s_nop 1
	v_addc_co_u32_e32 v27, vcc, 0, v21, vcc
	v_add_co_u32_e32 v28, vcc, s92, v20
	s_mov_b32 s92, 0x4e000
	s_nop 0
	v_addc_co_u32_e32 v29, vcc, 0, v21, vcc
	v_add_co_u32_e32 v30, vcc, s83, v20
	s_nop 1
	v_addc_co_u32_e32 v31, vcc, 0, v21, vcc
	v_add_co_u32_e32 v32, vcc, s92, v20
	s_mov_b32 s92, 0x54000
	s_nop 0
	v_addc_co_u32_e32 v33, vcc, 0, v21, vcc
	v_add_co_u32_e32 v34, vcc, s92, v20
	s_mov_b32 s92, 0x60000
	s_nop 0
	v_addc_co_u32_e32 v35, vcc, 0, v21, vcc
	v_add_co_u32_e32 v36, vcc, s84, v20
	s_nop 1
	v_addc_co_u32_e32 v37, vcc, 0, v21, vcc
	global_load_dword v45, v[22:23], off
	global_load_dword v46, v[24:25], off
	global_load_dword v47, v[26:27], off
	global_load_dword v48, v[28:29], off
	global_load_dword v49, v[30:31], off
	global_load_dword v50, v[32:33], off
	global_load_dword v51, v[34:35], off
	global_load_dword v52, v[36:37], off
	v_add_co_u32_e32 v22, vcc, s92, v20
	s_mov_b32 s92, 0x66000
	s_nop 0
	v_addc_co_u32_e32 v23, vcc, 0, v21, vcc
	v_add_co_u32_e32 v24, vcc, s92, v20
	s_mov_b32 s92, 0x72000
	s_nop 0
	v_addc_co_u32_e32 v25, vcc, 0, v21, vcc
	v_add_co_u32_e32 v26, vcc, s85, v20
	s_nop 1
	v_addc_co_u32_e32 v27, vcc, 0, v21, vcc
	v_add_co_u32_e32 v28, vcc, s92, v20
	s_mov_b32 s92, 0x78000
	s_nop 0
	v_addc_co_u32_e32 v29, vcc, 0, v21, vcc
	v_add_co_u32_e32 v30, vcc, s92, v20
	s_mov_b32 s92, 0x84000
	s_nop 0
	v_addc_co_u32_e32 v31, vcc, 0, v21, vcc
	v_add_co_u32_e32 v32, vcc, s86, v20
	s_nop 1
	v_addc_co_u32_e32 v33, vcc, 0, v21, vcc
	v_add_co_u32_e32 v34, vcc, s92, v20
	s_mov_b32 s92, 0x8a000
	s_nop 0
	v_addc_co_u32_e32 v35, vcc, 0, v21, vcc
	v_add_co_u32_e32 v36, vcc, s92, v20
	s_mov_b32 s92, 0x96000
	s_nop 0
	v_addc_co_u32_e32 v37, vcc, 0, v21, vcc
	global_load_dword v53, v[22:23], off
	global_load_dword v54, v[24:25], off
	global_load_dword v55, v[26:27], off
	global_load_dword v56, v[28:29], off
	global_load_dword v57, v[30:31], off
	global_load_dword v58, v[32:33], off
	global_load_dword v59, v[34:35], off
	s_nop 0
	global_load_dword v36, v[36:37], off
	v_add_co_u32_e32 v22, vcc, s87, v20
	s_nop 1
	v_addc_co_u32_e32 v23, vcc, 0, v21, vcc
	v_add_co_u32_e32 v24, vcc, s92, v20
	s_mov_b32 s92, 0x9c000
	s_nop 0
	v_addc_co_u32_e32 v25, vcc, 0, v21, vcc
	v_add_co_u32_e32 v26, vcc, s92, v20
	s_mov_b32 s92, 0xa8000
	s_nop 0
	v_addc_co_u32_e32 v27, vcc, 0, v21, vcc
	v_add_co_u32_e32 v28, vcc, s88, v20
	s_nop 1
	v_addc_co_u32_e32 v29, vcc, 0, v21, vcc
	v_add_co_u32_e32 v30, vcc, s92, v20
	s_mov_b32 s92, 0xae000
	s_nop 0
	v_addc_co_u32_e32 v31, vcc, 0, v21, vcc
	v_add_co_u32_e32 v32, vcc, s92, v20
	s_mov_b32 s92, 0xba000
	s_nop 0
	v_addc_co_u32_e32 v33, vcc, 0, v21, vcc
	v_add_co_u32_e32 v34, vcc, s89, v20
	s_nop 1
	v_addc_co_u32_e32 v35, vcc, 0, v21, vcc
	v_add_co_u32_e32 v20, vcc, s92, v20
	s_add_u32 s92, s35, s37
	s_nop 0
	v_addc_co_u32_e32 v21, vcc, 0, v21, vcc
	global_load_dword v22, v[22:23], off
	s_nop 0
	global_load_dword v23, v[24:25], off
	s_nop 0
	global_load_dword v24, v[26:27], off
	global_load_dword v25, v[28:29], off
	s_nop 0
	global_load_dword v26, v[30:31], off
	global_load_dword v27, v[32:33], off
	global_load_dword v28, v[34:35], off
	s_nop 0
	global_load_dword v20, v[20:21], off
	s_waitcnt vmcnt(30)
	ds_write2_b32 v7, v5, v38 offset1:66
	s_waitcnt vmcnt(28)
	ds_write2_b32 v7, v39, v40 offset0:132 offset1:198
	s_waitcnt vmcnt(26)
	ds_write2_b32 v13, v41, v42 offset0:8 offset1:74
	s_waitcnt vmcnt(24)
	ds_write2_b32 v13, v43, v44 offset0:140 offset1:206
	s_waitcnt vmcnt(22)
	ds_write2_b32 v14, v45, v46 offset0:16 offset1:82
	s_waitcnt vmcnt(20)
	ds_write2_b32 v14, v47, v48 offset0:148 offset1:214
	s_waitcnt vmcnt(18)
	ds_write2_b32 v15, v49, v50 offset0:24 offset1:90
	s_waitcnt vmcnt(16)
	ds_write2_b32 v15, v51, v52 offset0:156 offset1:222
	s_waitcnt vmcnt(14)
	ds_write2_b32 v16, v53, v54 offset0:32 offset1:98
	s_waitcnt vmcnt(12)
	ds_write2_b32 v16, v55, v56 offset0:164 offset1:230
	s_waitcnt vmcnt(10)
	ds_write2_b32 v17, v57, v58 offset0:40 offset1:106
	s_waitcnt vmcnt(8)
	ds_write2_b32 v17, v59, v36 offset0:172 offset1:238
	s_waitcnt vmcnt(6)
	ds_write2_b32 v18, v22, v23 offset0:48 offset1:114
	s_waitcnt vmcnt(4)
	ds_write2_b32 v18, v24, v25 offset0:180 offset1:246
	s_waitcnt vmcnt(2)
	ds_write2_b32 v19, v26, v27 offset0:56 offset1:122
	s_waitcnt vmcnt(0)
	ds_write2_b32 v19, v28, v20 offset0:188 offset1:254
	s_waitcnt lgkmcnt(0)
	ds_read2_b32 v[24:25], v9 offset1:8
	ds_read2_b32 v[28:29], v9 offset0:33 offset1:41
	ds_read2_b32 v[30:31], v9 offset0:66 offset1:74
	s_addc_u32 s93, s36, 0
	v_mov_b32_e32 v5, v3
	ds_read2_b32 v[32:33], v9 offset0:99 offset1:107
	v_lshl_add_u64 v[20:21], s[92:93], 0, v[4:5]
	s_mov_b64 s[36:37], 0x900000
	s_waitcnt lgkmcnt(3)
	v_bfe_u32 v5, v24, 16, 1
	v_lshl_add_u64 v[26:27], v[20:21], 0, s[36:37]
	v_add3_u32 v5, v24, v5, s51
	s_waitcnt lgkmcnt(2)
	v_bfe_u32 v20, v28, 16, 1
	ds_read2_b32 v[34:35], v9 offset0:132 offset1:140
	v_lshrrev_b32_e32 v5, 16, v5
	v_add3_u32 v20, v28, v20, s51
	ds_read2_b32 v[36:37], v9 offset0:165 offset1:173
	v_and_or_b32 v20, v20, s52, v5
	s_waitcnt lgkmcnt(3)
	v_bfe_u32 v5, v30, 16, 1
	v_add3_u32 v5, v30, v5, s51
	s_waitcnt lgkmcnt(2)
	v_bfe_u32 v21, v32, 16, 1
	ds_read2_b32 v[38:39], v9 offset0:198 offset1:206
	v_lshrrev_b32_e32 v5, 16, v5
	v_add3_u32 v21, v32, v21, s51
	ds_read2_b32 v[40:41], v9 offset0:231 offset1:239
	v_and_or_b32 v21, v21, s52, v5
	s_waitcnt lgkmcnt(3)
	v_bfe_u32 v5, v34, 16, 1
	v_add3_u32 v5, v34, v5, s51
	s_waitcnt lgkmcnt(2)
	v_bfe_u32 v22, v36, 16, 1
	v_lshrrev_b32_e32 v5, 16, v5
	v_add3_u32 v22, v36, v22, s51
	v_and_or_b32 v22, v22, s52, v5
	s_waitcnt lgkmcnt(1)
	v_bfe_u32 v5, v38, 16, 1
	v_add3_u32 v5, v38, v5, s51
	s_waitcnt lgkmcnt(0)
	v_bfe_u32 v23, v40, 16, 1
	v_lshrrev_b32_e32 v5, 16, v5
	v_add3_u32 v23, v40, v23, s51
	v_and_or_b32 v23, v23, s52, v5
	v_or_b32_e32 v5, s30, v8
	v_lshlrev_b32_e32 v42, 11, v5
	v_mov_b32_e32 v43, v3
	v_lshl_add_u64 v[42:43], v[26:27], 0, v[42:43]
	v_bfe_u32 v5, v25, 16, 1
	global_store_dwordx4 v[42:43], v[20:23], off sc1
	v_add3_u32 v5, v25, v5, s51
	v_lshrrev_b32_e32 v5, 16, v5
	v_bfe_u32 v20, v29, 16, 1
	v_add3_u32 v20, v29, v20, s51
	v_and_or_b32 v20, v20, s52, v5
	v_bfe_u32 v5, v31, 16, 1
	v_add3_u32 v5, v31, v5, s51
	v_bfe_u32 v21, v33, 16, 1
	v_lshrrev_b32_e32 v5, 16, v5
	v_add3_u32 v21, v33, v21, s51
	v_and_or_b32 v21, v21, s52, v5
	v_bfe_u32 v5, v35, 16, 1
	v_add3_u32 v5, v35, v5, s51
	v_bfe_u32 v22, v37, 16, 1
	v_lshrrev_b32_e32 v5, 16, v5
	v_add3_u32 v22, v37, v22, s51
	v_and_or_b32 v22, v22, s52, v5
	v_bfe_u32 v5, v39, 16, 1
	v_add3_u32 v5, v39, v5, s51
	v_bfe_u32 v23, v41, 16, 1
	v_lshrrev_b32_e32 v5, 16, v5
	v_add3_u32 v23, v41, v23, s51
	v_and_or_b32 v23, v23, s52, v5
	v_or_b32_e32 v5, s30, v10
	v_lshlrev_b32_e32 v24, 11, v5
	v_mov_b32_e32 v25, v3
	ds_read2_b32 v[28:29], v9 offset0:16 offset1:24
	v_lshl_add_u64 v[24:25], v[26:27], 0, v[24:25]
	global_store_dwordx4 v[24:25], v[20:23], off sc1
	ds_read2_b32 v[24:25], v9 offset0:49 offset1:57
	ds_read2_b32 v[30:31], v9 offset0:82 offset1:90
	ds_read2_b32 v[32:33], v9 offset0:115 offset1:123
	s_waitcnt lgkmcnt(3)
	v_bfe_u32 v5, v28, 16, 1
	v_add3_u32 v5, v28, v5, s51
	s_waitcnt lgkmcnt(2)
	v_bfe_u32 v20, v24, 16, 1
	ds_read2_b32 v[34:35], v9 offset0:148 offset1:156
	v_lshrrev_b32_e32 v5, 16, v5
	v_add3_u32 v20, v24, v20, s51
	ds_read2_b32 v[36:37], v9 offset0:181 offset1:189
	v_and_or_b32 v20, v20, s52, v5
	s_waitcnt lgkmcnt(3)
	v_bfe_u32 v5, v30, 16, 1
	v_add3_u32 v5, v30, v5, s51
	s_waitcnt lgkmcnt(2)
	v_bfe_u32 v21, v32, 16, 1
	ds_read2_b32 v[38:39], v9 offset0:214 offset1:222
	v_lshrrev_b32_e32 v5, 16, v5
	v_add3_u32 v21, v32, v21, s51
	ds_read2_b32 v[40:41], v9 offset0:247 offset1:255
	v_and_or_b32 v21, v21, s52, v5
	s_waitcnt lgkmcnt(3)
	v_bfe_u32 v5, v34, 16, 1
	v_add3_u32 v5, v34, v5, s51
	s_waitcnt lgkmcnt(2)
	v_bfe_u32 v22, v36, 16, 1
	v_lshrrev_b32_e32 v5, 16, v5
	v_add3_u32 v22, v36, v22, s51
	v_and_or_b32 v22, v22, s52, v5
	s_waitcnt lgkmcnt(1)
	v_bfe_u32 v5, v38, 16, 1
	v_add3_u32 v5, v38, v5, s51
	s_waitcnt lgkmcnt(0)
	v_bfe_u32 v23, v40, 16, 1
	v_lshrrev_b32_e32 v5, 16, v5
	v_add3_u32 v23, v40, v23, s51
	v_and_or_b32 v23, v23, s52, v5
	v_or_b32_e32 v5, s30, v11
	v_lshlrev_b32_e32 v42, 11, v5
	v_mov_b32_e32 v43, v3
	v_lshl_add_u64 v[42:43], v[26:27], 0, v[42:43]
	v_bfe_u32 v5, v29, 16, 1
	global_store_dwordx4 v[42:43], v[20:23], off sc1
	v_add3_u32 v5, v29, v5, s51
	v_lshrrev_b32_e32 v5, 16, v5
	v_bfe_u32 v20, v25, 16, 1
	v_add3_u32 v20, v25, v20, s51
	v_and_or_b32 v20, v20, s52, v5
	v_bfe_u32 v5, v31, 16, 1
	v_add3_u32 v5, v31, v5, s51
	v_bfe_u32 v21, v33, 16, 1
	v_lshrrev_b32_e32 v5, 16, v5
	v_add3_u32 v21, v33, v21, s51
	v_and_or_b32 v21, v21, s52, v5
	v_bfe_u32 v5, v35, 16, 1
	v_add3_u32 v5, v35, v5, s51
	v_bfe_u32 v22, v37, 16, 1
	v_lshrrev_b32_e32 v5, 16, v5
	v_add3_u32 v22, v37, v22, s51
	v_and_or_b32 v22, v22, s52, v5
	v_bfe_u32 v5, v39, 16, 1
	v_add3_u32 v5, v39, v5, s51
	v_bfe_u32 v23, v41, 16, 1
	v_lshrrev_b32_e32 v5, 16, v5
	v_add3_u32 v23, v41, v23, s51
	v_and_or_b32 v23, v23, s52, v5
	v_or_b32_e32 v5, s30, v12
	v_lshlrev_b32_e32 v24, 11, v5
	v_mov_b32_e32 v25, v3
	v_lshl_add_u64 v[24:25], v[26:27], 0, v[24:25]
	global_store_dwordx4 v[24:25], v[20:23], off sc1
	s_waitcnt lgkmcnt(0)

.LBB0_37:
	s_andn2_b64 vcc, exec, s[36:37]
	s_cbranch_vccnz .LBB0_22
	s_mul_i32 s35, s34, 0x1200000
	s_mul_hi_i32 s30, s34, 0x1200000
	s_waitcnt lgkmcnt(0)
	s_add_u32 s37, s24, s35
	s_addc_u32 s93, s25, s30
	s_mul_hi_i32 s30, s34, 0xf00000
	s_mul_i32 s34, s34, 0xf00000
	s_add_u32 s92, s20, s34
	s_mul_i32 s34, s91, 0xe39
	s_addc_u32 s30, s21, s30
	s_lshr_b32 s35, s34, 31
	s_ashr_i32 s34, s34, 19
	s_add_i32 s34, s34, s35
	s_sext_i32_i16 s35, s34
	s_mulk_i32 s34, 0x90
	s_sub_i32 s34, s91, s34
	s_sext_i32_i16 s34, s34
	s_lshl_b32 s34, s34, 5
	s_lshl_b32 s36, s35, 6
	s_ashr_i32 s35, s34, 31
	s_lshl_b64 s[94:95], s[34:35], 2
	v_or_b32_e32 v5, s36, v6
	s_add_u32 s94, s37, s94
	s_addc_u32 s95, s93, s95
	v_mul_i32_i24_e32 v22, 0x1200, v5
	v_lshl_add_u64 v[20:21], s[94:95], 0, v[2:3]
	v_ashrrev_i32_e32 v23, 31, v22
	v_lshl_add_u64 v[20:21], v[22:23], 2, v[20:21]
	s_mov_b32 s35, 0x9000
	v_add_co_u32_e32 v22, vcc, s35, v20
	s_mov_b32 s35, 0x1b000
	s_nop 0
	v_addc_co_u32_e32 v23, vcc, 0, v21, vcc
	v_add_co_u32_e32 v24, vcc, s60, v20
	s_ashr_i32 s37, s36, 31
	s_nop 0
	v_addc_co_u32_e32 v25, vcc, 0, v21, vcc
	v_add_co_u32_e32 v26, vcc, s35, v20
	s_mov_b32 s35, 0x2d000
	s_nop 0
	v_addc_co_u32_e32 v27, vcc, 0, v21, vcc
	v_add_co_u32_e32 v28, vcc, s69, v20
	s_lshl_b64 s[36:37], s[36:37], 1
	s_nop 0
	v_addc_co_u32_e32 v29, vcc, 0, v21, vcc
	v_add_co_u32_e32 v30, vcc, s35, v20
	s_mov_b32 s35, 0x3f000
	s_nop 0
	v_addc_co_u32_e32 v31, vcc, 0, v21, vcc
	v_add_co_u32_e32 v32, vcc, s78, v20
	s_add_u32 s36, s92, s36
	s_nop 0
	v_addc_co_u32_e32 v33, vcc, 0, v21, vcc
	v_add_co_u32_e32 v34, vcc, s35, v20
	s_mov_b32 s35, 0x51000
	s_nop 0
	v_addc_co_u32_e32 v35, vcc, 0, v21, vcc
	global_load_dword v5, v[20:21], off
	global_load_dword v38, v[22:23], off
	global_load_dword v39, v[24:25], off
	global_load_dword v40, v[26:27], off
	global_load_dword v41, v[28:29], off
	global_load_dword v42, v[30:31], off
	global_load_dword v43, v[32:33], off
	global_load_dword v44, v[34:35], off
	v_add_co_u32_e32 v22, vcc, s83, v20
	s_addc_u32 s37, s30, s37
	s_nop 0
	v_addc_co_u32_e32 v23, vcc, 0, v21, vcc
	v_add_co_u32_e32 v24, vcc, s35, v20
	s_mov_b32 s35, 0x63000
	s_nop 0
	v_addc_co_u32_e32 v25, vcc, 0, v21, vcc
	v_add_co_u32_e32 v26, vcc, s84, v20
	s_nop 1
	v_addc_co_u32_e32 v27, vcc, 0, v21, vcc
	v_add_co_u32_e32 v28, vcc, s35, v20
	s_mov_b32 s35, 0x75000
	s_nop 0
	v_addc_co_u32_e32 v29, vcc, 0, v21, vcc
	v_add_co_u32_e32 v30, vcc, s85, v20
	s_nop 1
	v_addc_co_u32_e32 v31, vcc, 0, v21, vcc
	v_add_co_u32_e32 v32, vcc, s35, v20
	s_mov_b32 s35, 0x87000
	s_nop 0
	v_addc_co_u32_e32 v33, vcc, 0, v21, vcc
	v_add_co_u32_e32 v34, vcc, s86, v20
	s_nop 1
	v_addc_co_u32_e32 v35, vcc, 0, v21, vcc
	v_add_co_u32_e32 v36, vcc, s35, v20
	s_mov_b32 s35, 0x99000
	s_nop 0
	v_addc_co_u32_e32 v37, vcc, 0, v21, vcc
	global_load_dword v45, v[22:23], off
	global_load_dword v46, v[24:25], off
	global_load_dword v47, v[26:27], off
	global_load_dword v48, v[28:29], off
	global_load_dword v49, v[30:31], off
	global_load_dword v50, v[32:33], off
	global_load_dword v51, v[34:35], off
	global_load_dword v52, v[36:37], off
	v_add_co_u32_e32 v22, vcc, s87, v20
	s_nop 1
	v_addc_co_u32_e32 v23, vcc, 0, v21, vcc
	v_add_co_u32_e32 v24, vcc, s35, v20
	s_mov_b32 s35, 0xab000
	s_nop 0
	v_addc_co_u32_e32 v25, vcc, 0, v21, vcc
	v_add_co_u32_e32 v26, vcc, s88, v20
	s_nop 1
	v_addc_co_u32_e32 v27, vcc, 0, v21, vcc
	v_add_co_u32_e32 v28, vcc, s35, v20
	s_mov_b32 s35, 0xbd000
	s_nop 0
	v_addc_co_u32_e32 v29, vcc, 0, v21, vcc
	v_add_co_u32_e32 v30, vcc, s89, v20
	s_nop 1
	v_addc_co_u32_e32 v31, vcc, 0, v21, vcc
	v_add_co_u32_e32 v32, vcc, s35, v20
	s_mov_b32 s35, 0xc6000
	s_nop 0
	v_addc_co_u32_e32 v33, vcc, 0, v21, vcc
	v_add_co_u32_e32 v34, vcc, s35, v20
	s_mov_b32 s35, 0xcf000
	s_nop 0
	v_addc_co_u32_e32 v35, vcc, 0, v21, vcc
	v_add_co_u32_e32 v36, vcc, s35, v20
	s_mov_b32 s35, 0xd8000
	s_nop 0
	v_addc_co_u32_e32 v37, vcc, 0, v21, vcc
	global_load_dword v53, v[22:23], off
	global_load_dword v54, v[24:25], off
	global_load_dword v55, v[26:27], off
	global_load_dword v56, v[28:29], off
	global_load_dword v57, v[30:31], off
	global_load_dword v58, v[32:33], off
	global_load_dword v59, v[34:35], off
	s_nop 0
	global_load_dword v36, v[36:37], off
	v_add_co_u32_e32 v22, vcc, s35, v20
	s_mov_b32 s35, 0xe1000
	s_nop 0
	v_addc_co_u32_e32 v23, vcc, 0, v21, vcc
	v_add_co_u32_e32 v24, vcc, s35, v20
	s_mov_b32 s35, 0xea000
	s_nop 0
	v_addc_co_u32_e32 v25, vcc, 0, v21, vcc
	v_add_co_u32_e32 v26, vcc, s35, v20
	s_mov_b32 s35, 0xf3000
	s_nop 0
	v_addc_co_u32_e32 v27, vcc, 0, v21, vcc
	v_add_co_u32_e32 v28, vcc, s35, v20
	s_mov_b32 s35, 0xfc000
	s_nop 0
	v_addc_co_u32_e32 v29, vcc, 0, v21, vcc
	v_add_co_u32_e32 v30, vcc, s35, v20
	s_mov_b32 s35, 0x105000
	s_nop 0
	v_addc_co_u32_e32 v31, vcc, 0, v21, vcc
	v_add_co_u32_e32 v32, vcc, s35, v20
	s_mov_b32 s35, 0x10e000
	s_nop 0
	v_addc_co_u32_e32 v33, vcc, 0, v21, vcc
	v_add_co_u32_e32 v34, vcc, s35, v20
	s_mov_b32 s35, 0x117000
	s_nop 0
	v_addc_co_u32_e32 v35, vcc, 0, v21, vcc
	v_add_co_u32_e32 v20, vcc, s35, v20
	s_nop 1
	v_addc_co_u32_e32 v21, vcc, 0, v21, vcc
	global_load_dword v22, v[22:23], off
	s_nop 0
	global_load_dword v23, v[24:25], off
	s_nop 0
	global_load_dword v24, v[26:27], off
	global_load_dword v25, v[28:29], off
	s_nop 0
	global_load_dword v26, v[30:31], off
	global_load_dword v27, v[32:33], off
	global_load_dword v28, v[34:35], off
	s_nop 0
	global_load_dword v20, v[20:21], off
	s_waitcnt vmcnt(30)
	ds_write2_b32 v7, v5, v38 offset1:66
	s_waitcnt vmcnt(28)
	ds_write2_b32 v7, v39, v40 offset0:132 offset1:198
	s_waitcnt vmcnt(26)
	ds_write2_b32 v13, v41, v42 offset0:8 offset1:74
	s_waitcnt vmcnt(24)
	ds_write2_b32 v13, v43, v44 offset0:140 offset1:206
	s_waitcnt vmcnt(22)
	ds_write2_b32 v14, v45, v46 offset0:16 offset1:82
	s_waitcnt vmcnt(20)
	ds_write2_b32 v14, v47, v48 offset0:148 offset1:214
	s_waitcnt vmcnt(18)
	ds_write2_b32 v15, v49, v50 offset0:24 offset1:90
	s_waitcnt vmcnt(16)
	ds_write2_b32 v15, v51, v52 offset0:156 offset1:222
	s_waitcnt vmcnt(14)
	ds_write2_b32 v16, v53, v54 offset0:32 offset1:98
	s_waitcnt vmcnt(12)
	ds_write2_b32 v16, v55, v56 offset0:164 offset1:230
	s_waitcnt vmcnt(10)
	ds_write2_b32 v17, v57, v58 offset0:40 offset1:106
	s_waitcnt vmcnt(8)
	ds_write2_b32 v17, v59, v36 offset0:172 offset1:238
	s_waitcnt vmcnt(6)
	ds_write2_b32 v18, v22, v23 offset0:48 offset1:114
	s_waitcnt vmcnt(4)
	ds_write2_b32 v18, v24, v25 offset0:180 offset1:246
	s_waitcnt vmcnt(2)
	ds_write2_b32 v19, v26, v27 offset0:56 offset1:122
	s_waitcnt vmcnt(0)
	ds_write2_b32 v19, v28, v20 offset0:188 offset1:254
	s_waitcnt lgkmcnt(0)
	ds_read2_b32 v[24:25], v9 offset1:8
	ds_read2_b32 v[28:29], v9 offset0:33 offset1:41
	ds_read2_b32 v[30:31], v9 offset0:66 offset1:74
	v_mov_b32_e32 v5, v3
	ds_read2_b32 v[32:33], v9 offset0:99 offset1:107
	v_lshl_add_u64 v[26:27], s[36:37], 0, v[4:5]
	s_waitcnt lgkmcnt(3)
	v_bfe_u32 v5, v24, 16, 1
	v_add3_u32 v5, v24, v5, s51
	s_waitcnt lgkmcnt(2)
	v_bfe_u32 v20, v28, 16, 1
	ds_read2_b32 v[34:35], v9 offset0:132 offset1:140
	v_lshrrev_b32_e32 v5, 16, v5
	v_add3_u32 v20, v28, v20, s51
	ds_read2_b32 v[36:37], v9 offset0:165 offset1:173
	v_and_or_b32 v20, v20, s52, v5
	s_waitcnt lgkmcnt(3)
	v_bfe_u32 v5, v30, 16, 1
	v_add3_u32 v5, v30, v5, s51
	s_waitcnt lgkmcnt(2)
	v_bfe_u32 v21, v32, 16, 1
	ds_read2_b32 v[38:39], v9 offset0:198 offset1:206
	v_lshrrev_b32_e32 v5, 16, v5
	v_add3_u32 v21, v32, v21, s51
	ds_read2_b32 v[40:41], v9 offset0:231 offset1:239
	v_and_or_b32 v21, v21, s52, v5
	s_waitcnt lgkmcnt(3)
	v_bfe_u32 v5, v34, 16, 1
	v_add3_u32 v5, v34, v5, s51
	s_waitcnt lgkmcnt(2)
	v_bfe_u32 v22, v36, 16, 1
	v_lshrrev_b32_e32 v5, 16, v5
	v_add3_u32 v22, v36, v22, s51
	v_and_or_b32 v22, v22, s52, v5
	s_waitcnt lgkmcnt(1)
	v_bfe_u32 v5, v38, 16, 1
	v_or_b32_e32 v42, s34, v8
	v_add3_u32 v5, v38, v5, s51
	s_waitcnt lgkmcnt(0)
	v_bfe_u32 v23, v40, 16, 1
	v_ashrrev_i32_e32 v43, 31, v42
	v_lshrrev_b32_e32 v5, 16, v5
	v_add3_u32 v23, v40, v23, s51
	v_lshlrev_b64 v[42:43], 11, v[42:43]
	v_and_or_b32 v23, v23, s52, v5
	v_lshl_add_u64 v[42:43], v[26:27], 0, v[42:43]
	v_bfe_u32 v5, v25, 16, 1
	global_store_dwordx4 v[42:43], v[20:23], off sc1
	v_add3_u32 v5, v25, v5, s51
	v_lshrrev_b32_e32 v5, 16, v5
	v_bfe_u32 v20, v29, 16, 1
	v_add3_u32 v20, v29, v20, s51
	v_and_or_b32 v20, v20, s52, v5
	v_bfe_u32 v5, v31, 16, 1
	v_add3_u32 v5, v31, v5, s51
	v_bfe_u32 v21, v33, 16, 1
	v_lshrrev_b32_e32 v5, 16, v5
	v_add3_u32 v21, v33, v21, s51
	v_and_or_b32 v21, v21, s52, v5
	v_bfe_u32 v5, v35, 16, 1
	v_add3_u32 v5, v35, v5, s51
	v_bfe_u32 v22, v37, 16, 1
	v_lshrrev_b32_e32 v5, 16, v5
	v_add3_u32 v22, v37, v22, s51
	v_and_or_b32 v22, v22, s52, v5
	v_bfe_u32 v5, v39, 16, 1
	v_or_b32_e32 v24, s34, v10
	v_add3_u32 v5, v39, v5, s51
	v_bfe_u32 v23, v41, 16, 1
	v_ashrrev_i32_e32 v25, 31, v24
	v_lshrrev_b32_e32 v5, 16, v5
	v_add3_u32 v23, v41, v23, s51
	v_lshlrev_b64 v[24:25], 11, v[24:25]
	v_and_or_b32 v23, v23, s52, v5
	ds_read2_b32 v[28:29], v9 offset0:16 offset1:24
	v_lshl_add_u64 v[24:25], v[26:27], 0, v[24:25]
	global_store_dwordx4 v[24:25], v[20:23], off sc1
	ds_read2_b32 v[24:25], v9 offset0:49 offset1:57
	ds_read2_b32 v[30:31], v9 offset0:82 offset1:90
	ds_read2_b32 v[32:33], v9 offset0:115 offset1:123
	s_waitcnt lgkmcnt(3)
	v_bfe_u32 v5, v28, 16, 1
	v_add3_u32 v5, v28, v5, s51
	s_waitcnt lgkmcnt(2)
	v_bfe_u32 v20, v24, 16, 1
	ds_read2_b32 v[34:35], v9 offset0:148 offset1:156
	v_lshrrev_b32_e32 v5, 16, v5
	v_add3_u32 v20, v24, v20, s51
	ds_read2_b32 v[36:37], v9 offset0:181 offset1:189
	v_and_or_b32 v20, v20, s52, v5
	s_waitcnt lgkmcnt(3)
	v_bfe_u32 v5, v30, 16, 1
	v_add3_u32 v5, v30, v5, s51
	s_waitcnt lgkmcnt(2)
	v_bfe_u32 v21, v32, 16, 1
	ds_read2_b32 v[38:39], v9 offset0:214 offset1:222
	v_lshrrev_b32_e32 v5, 16, v5
	v_add3_u32 v21, v32, v21, s51
	ds_read2_b32 v[40:41], v9 offset0:247 offset1:255
	v_and_or_b32 v21, v21, s52, v5
	s_waitcnt lgkmcnt(3)
	v_bfe_u32 v5, v34, 16, 1
	v_add3_u32 v5, v34, v5, s51
	s_waitcnt lgkmcnt(2)
	v_bfe_u32 v22, v36, 16, 1
	v_lshrrev_b32_e32 v5, 16, v5
	v_add3_u32 v22, v36, v22, s51
	v_and_or_b32 v22, v22, s52, v5
	s_waitcnt lgkmcnt(1)
	v_bfe_u32 v5, v38, 16, 1
	v_or_b32_e32 v42, s34, v11
	v_add3_u32 v5, v38, v5, s51
	s_waitcnt lgkmcnt(0)
	v_bfe_u32 v23, v40, 16, 1
	v_ashrrev_i32_e32 v43, 31, v42
	v_lshrrev_b32_e32 v5, 16, v5
	v_add3_u32 v23, v40, v23, s51
	v_lshlrev_b64 v[42:43], 11, v[42:43]
	v_and_or_b32 v23, v23, s52, v5
	v_lshl_add_u64 v[42:43], v[26:27], 0, v[42:43]
	v_bfe_u32 v5, v29, 16, 1
	global_store_dwordx4 v[42:43], v[20:23], off sc1
	v_add3_u32 v5, v29, v5, s51
	v_lshrrev_b32_e32 v5, 16, v5
	v_bfe_u32 v20, v25, 16, 1
	v_add3_u32 v20, v25, v20, s51
	v_and_or_b32 v20, v20, s52, v5
	v_bfe_u32 v5, v31, 16, 1
	v_add3_u32 v5, v31, v5, s51
	v_bfe_u32 v21, v33, 16, 1
	v_lshrrev_b32_e32 v5, 16, v5
	v_add3_u32 v21, v33, v21, s51
	v_and_or_b32 v21, v21, s52, v5
	v_bfe_u32 v5, v35, 16, 1
	v_add3_u32 v5, v35, v5, s51
	v_bfe_u32 v22, v37, 16, 1
	v_lshrrev_b32_e32 v5, 16, v5
	v_add3_u32 v22, v37, v22, s51
	v_and_or_b32 v22, v22, s52, v5
	v_bfe_u32 v5, v39, 16, 1
	v_or_b32_e32 v24, s34, v12
	v_add3_u32 v5, v39, v5, s51
	v_bfe_u32 v23, v41, 16, 1
	v_ashrrev_i32_e32 v25, 31, v24
	v_lshrrev_b32_e32 v5, 16, v5
	v_add3_u32 v23, v41, v23, s51
	v_lshlrev_b64 v[24:25], 11, v[24:25]
	v_and_or_b32 v23, v23, s52, v5
	v_lshl_add_u64 v[24:25], v[26:27], 0, v[24:25]
	global_store_dwordx4 v[24:25], v[20:23], off sc1
	s_waitcnt lgkmcnt(0)
	s_branch .LBB0_22

.LBB0_170:
	s_lshl_b32 s48, s71, 8
	v_or_b32_e32 v140, s57, v232
	s_or_b32 s30, s30, s48
	v_or_b32_e32 v0, s30, v234
	v_ashrrev_i32_e32 v141, 31, v140
	v_lshl_add_u64 v[2:3], v[0:1], 1, s[50:51]
	v_mul_lo_u32 v0, s82, v141
	v_mul_lo_u32 v146, s83, v140
	v_mad_u64_u32 v[134:135], s[48:49], s82, v140, 0
	v_add3_u32 v135, v135, v0, v146
	v_pk_mul_f32 v[136:137], s[80:81], v[136:137] op_sel_hi:[0,1]
	v_pk_mul_f32 v[138:139], s[80:81], v[138:139] op_sel_hi:[0,1]
	v_cndmask_b32_e64 v0, 0, 1, s[86:87]
	v_lshl_add_u64 v[134:135], v[134:135], 1, v[2:3]
	v_pk_mul_f32 v[144:145], s[80:81], v[144:145] op_sel_hi:[0,1]
	v_pk_mul_f32 v[142:143], s[80:81], v[142:143] op_sel_hi:[0,1]
	v_cvt_pk_bf16_f32 v136, v136, v137
	v_cvt_pk_bf16_f32 v137, v144, v145
	v_cvt_pk_bf16_f32 v138, v138, v139
	v_cvt_pk_bf16_f32 v139, v142, v143
	v_cmp_ne_u32_e64 s[48:49], 1, v0
	s_andn2_b64 vcc, exec, s[86:87]
	s_mov_b64 s[50:51], -1
	global_store_dwordx4 v[134:135], v[136:139], off sc1
	s_cbranch_vccnz .LBB0_174
	s_andn2_b64 vcc, exec, s[84:85]
	v_mov_b32_e32 v145, v107
	v_mov_b32_e32 v144, v106
	v_mov_b32_e32 v143, v105
	v_mov_b32_e32 v142, v104
	v_mov_b32_e32 v139, v115
	v_mov_b32_e32 v138, v114
	v_mov_b32_e32 v137, v113
	v_mov_b32_e32 v136, v112
	s_cbranch_vccnz .LBB0_173
	v_mul_f32_e32 v0, 0xbfb8aa3b, v112
	v_exp_f32_e32 v0, v0
	v_mul_f32_e32 v136, 0xbfb8aa3b, v104
	v_mul_f32_e32 v137, 0xbfb8aa3b, v113
	v_exp_f32_e32 v138, v136
	v_exp_f32_e32 v137, v137
	v_add_f32_e32 v0, 1.0, v0
	v_rcp_f32_e32 v136, v0
	v_add_f32_e32 v0, 1.0, v138
	v_rcp_f32_e32 v142, v0
	v_add_f32_e32 v0, 1.0, v137
	v_mul_f32_e32 v139, 0xbfb8aa3b, v106
	v_rcp_f32_e32 v137, v0
	v_mul_f32_e32 v0, 0xbfb8aa3b, v105
	v_mul_f32_e32 v138, 0xbfb8aa3b, v114
	v_exp_f32_e32 v139, v139
	v_mul_f32_e32 v143, 0xbfb8aa3b, v115
	v_mul_f32_e32 v144, 0xbfb8aa3b, v107
	v_exp_f32_e32 v0, v0
	v_exp_f32_e32 v138, v138
	v_exp_f32_e32 v143, v143
	v_exp_f32_e32 v145, v144
	v_add_f32_e32 v139, 1.0, v139
	v_add_f32_e32 v0, 1.0, v0
	v_add_f32_e32 v138, 1.0, v138
	v_rcp_f32_e32 v144, v139
	v_add_f32_e32 v139, 1.0, v143
	v_add_f32_e32 v143, 1.0, v145
	v_rcp_f32_e32 v138, v138
	v_rcp_f32_e32 v139, v139
	v_rcp_f32_e32 v145, v143
	v_rcp_f32_e32 v143, v0
	v_pk_mul_f32 v[136:137], v[112:113], v[136:137]
	v_pk_mul_f32 v[138:139], v[114:115], v[138:139]
	v_pk_mul_f32 v[144:145], v[106:107], v[144:145]
	v_pk_mul_f32 v[142:143], v[104:105], v[142:143]

.LBB0_177:
	s_mov_b32 s81, s80
	s_mov_b32 s50, s80
	s_mov_b32 s51, s80
	s_lshl_b32 s73, s71, 2
	v_pk_mul_f32 v[138:139], s[50:51], v[138:139]
	v_pk_mul_f32 v[136:137], s[80:81], v[136:137]
	s_and_b64 vcc, exec, s[46:47]
	v_pk_mul_f32 v[144:145], s[50:51], v[144:145]
	v_pk_mul_f32 v[142:143], s[80:81], v[142:143]
	v_cvt_pk_bf16_f32 v136, v136, v137
	v_cvt_pk_bf16_f32 v137, v138, v139
	s_nop 0
	v_cvt_pk_bf16_f32 v138, v142, v143
	v_cvt_pk_bf16_f32 v139, v144, v145
	global_store_dwordx4 v[134:135], v[136:139], off offset:256 sc1
	s_cbranch_vccnz .LBB0_181
	v_and_b32_e32 v134, 64, v230
	v_xor_b32_e32 v0, 16, v230
	v_add_u32_e32 v136, 64, v134
	v_cmp_lt_i32_e32 vcc, v0, v136
	s_nop 1
	v_cndmask_b32_e32 v0, v230, v0, vcc
	v_lshlrev_b32_e32 v0, 2, v0
	ds_bpermute_b32 v134, v0, v132
	ds_bpermute_b32 v135, v0, v133
	v_xor_b32_e32 v0, 32, v230
	v_cmp_lt_i32_e32 vcc, v0, v136
	s_waitcnt lgkmcnt(0)
	v_pk_add_f32 v[132:133], v[132:133], v[134:135]
	v_cndmask_b32_e32 v0, v230, v0, vcc
	v_lshlrev_b32_e32 v0, 2, v0
	ds_bpermute_b32 v134, v0, v132
	ds_bpermute_b32 v135, v0, v133
	s_and_saveexec_b64 s[50:51], s[38:39]
	s_cbranch_execz .LBB0_180
	s_waitcnt lgkmcnt(0)
	v_pk_add_f32 v[132:133], v[132:133], v[134:135]
	v_lshlrev_b64 v[134:135], 6, v[140:141]
	v_lshl_add_u64 v[134:135], s[66:67], 0, v[134:135]
	s_lshl_b32 s30, s73, 3
	v_lshl_add_u64 v[134:135], v[134:135], 0, s[30:31]
	s_lshl_b32 s30, s16, 3
	v_lshl_add_u64 v[134:135], v[134:135], 0, s[30:31]
	global_store_dwordx2 v[134:135], v[132:133], off

.LBB0_189:
	s_waitcnt lgkmcnt(0)
	v_or_b32_e32 v134, 16, v140
	v_ashrrev_i32_e32 v135, 31, v134
	v_mad_u64_u32 v[136:137], s[50:51], s82, v134, 0
	v_mul_lo_u32 v0, s82, v135
	v_mul_lo_u32 v141, s83, v134
	s_mov_b32 s50, s80
	s_mov_b32 s51, s80
	v_add3_u32 v137, v137, v0, v141
	v_pk_mul_f32 v[148:149], s[50:51], v[144:145]
	v_pk_mul_f32 v[144:145], s[80:81], v[142:143]
	v_lshl_add_u64 v[136:137], v[136:137], 1, v[2:3]
	v_pk_mul_f32 v[146:147], s[50:51], v[146:147]
	v_pk_mul_f32 v[138:139], s[80:81], v[138:139]
	s_and_b64 vcc, exec, s[48:49]
	v_cvt_pk_bf16_f32 v142, v138, v139
	v_cvt_pk_bf16_f32 v143, v146, v147
	v_cvt_pk_bf16_f32 v144, v144, v145
	v_cvt_pk_bf16_f32 v145, v148, v149
	s_mov_b64 s[50:51], -1
	global_store_dwordx4 v[136:137], v[142:145], off sc1
	s_cbranch_vccnz .LBB0_193
	s_andn2_b64 vcc, exec, s[84:85]
	v_mov_b32_e32 v145, v103
	v_mov_b32_e32 v144, v102
	v_mov_b32_e32 v147, v101
	v_mov_b32_e32 v146, v100
	v_mov_b32_e32 v143, v111
	v_mov_b32_e32 v142, v110
	v_mov_b32_e32 v139, v109
	v_mov_b32_e32 v138, v108
	s_cbranch_vccnz .LBB0_192
	v_mul_f32_e32 v0, 0xbfb8aa3b, v108
	v_exp_f32_e32 v0, v0
	v_mul_f32_e32 v138, 0xbfb8aa3b, v100
	v_exp_f32_e32 v141, v138
	v_mul_f32_e32 v139, 0xbfb8aa3b, v109
	v_add_f32_e32 v0, 1.0, v0
	v_rcp_f32_e32 v138, v0
	v_add_f32_e32 v0, 1.0, v141
	v_mul_f32_e32 v141, 0xbfb8aa3b, v110
	v_exp_f32_e32 v141, v141
	v_mul_f32_e32 v142, 0xbfb8aa3b, v102
	v_exp_f32_e32 v139, v139
	v_exp_f32_e32 v143, v142
	v_add_f32_e32 v141, 1.0, v141
	v_rcp_f32_e32 v146, v0
	v_add_f32_e32 v0, 1.0, v139
	v_rcp_f32_e32 v142, v141
	v_add_f32_e32 v141, 1.0, v143
	v_mul_f32_e32 v143, 0xbfb8aa3b, v111
	v_rcp_f32_e32 v139, v0
	v_mul_f32_e32 v0, 0xbfb8aa3b, v101
	v_exp_f32_e32 v143, v143
	v_mul_f32_e32 v144, 0xbfb8aa3b, v103
	v_exp_f32_e32 v0, v0
	v_exp_f32_e32 v145, v144
	v_rcp_f32_e32 v144, v141
	v_add_f32_e32 v141, 1.0, v143
	v_add_f32_e32 v0, 1.0, v0
	v_rcp_f32_e32 v143, v141
	v_add_f32_e32 v141, 1.0, v145
	v_rcp_f32_e32 v145, v141
	v_rcp_f32_e32 v147, v0
	v_pk_mul_f32 v[142:143], v[110:111], v[142:143]
	v_pk_mul_f32 v[138:139], v[108:109], v[138:139]
	v_pk_mul_f32 v[144:145], v[102:103], v[144:145]
	v_pk_mul_f32 v[146:147], v[100:101], v[146:147]

.LBB0_196:
	s_mov_b32 s50, s80
	s_mov_b32 s51, s80
	v_pk_mul_f32 v[150:151], s[50:51], v[144:145]
	v_pk_mul_f32 v[144:145], s[80:81], v[146:147]
	s_and_b64 vcc, exec, s[46:47]
	v_pk_mul_f32 v[148:149], s[50:51], v[142:143]
	v_pk_mul_f32 v[138:139], s[80:81], v[138:139]
	s_nop 0
	v_cvt_pk_bf16_f32 v142, v138, v139
	v_cvt_pk_bf16_f32 v143, v148, v149
	v_cvt_pk_bf16_f32 v144, v144, v145
	v_cvt_pk_bf16_f32 v145, v150, v151
	global_store_dwordx4 v[136:137], v[142:145], off offset:256 sc1
	s_cbranch_vccnz .LBB0_200
	v_and_b32_e32 v136, 64, v230
	v_xor_b32_e32 v0, 16, v230
	v_add_u32_e32 v138, 64, v136
	v_cmp_lt_i32_e32 vcc, v0, v138
	s_nop 1
	v_cndmask_b32_e32 v0, v230, v0, vcc
	v_lshlrev_b32_e32 v0, 2, v0
	ds_bpermute_b32 v136, v0, v132
	ds_bpermute_b32 v137, v0, v133
	v_xor_b32_e32 v0, 32, v230
	v_cmp_lt_i32_e32 vcc, v0, v138
	s_waitcnt lgkmcnt(0)
	v_pk_add_f32 v[132:133], v[132:133], v[136:137]
	v_cndmask_b32_e32 v0, v230, v0, vcc
	v_lshlrev_b32_e32 v0, 2, v0
	ds_bpermute_b32 v136, v0, v132
	ds_bpermute_b32 v137, v0, v133
	s_and_saveexec_b64 s[50:51], s[38:39]
	s_cbranch_execz .LBB0_199
	v_lshlrev_b64 v[134:135], 6, v[134:135]
	v_lshl_add_u64 v[134:135], s[66:67], 0, v[134:135]
	s_lshl_b32 s30, s73, 3
	v_lshl_add_u64 v[134:135], v[134:135], 0, s[30:31]
	s_lshl_b32 s30, s16, 3
	s_waitcnt lgkmcnt(0)
	v_pk_add_f32 v[132:133], v[132:133], v[136:137]
	v_lshl_add_u64 v[134:135], v[134:135], 0, s[30:31]
	global_store_dwordx2 v[134:135], v[132:133], off

.LBB0_208:
	v_or_b32_e32 v134, 32, v140
	v_ashrrev_i32_e32 v135, 31, v134
	s_waitcnt lgkmcnt(0)
	v_mad_u64_u32 v[136:137], s[50:51], s82, v134, 0
	v_mul_lo_u32 v0, s82, v135
	v_mul_lo_u32 v141, s83, v134
	s_mov_b32 s50, s80
	s_mov_b32 s51, s80
	v_add3_u32 v137, v137, v0, v141
	v_pk_mul_f32 v[148:149], s[50:51], v[144:145]
	v_pk_mul_f32 v[144:145], s[80:81], v[142:143]
	v_lshl_add_u64 v[136:137], v[136:137], 1, v[2:3]
	v_pk_mul_f32 v[146:147], s[50:51], v[146:147]
	v_pk_mul_f32 v[138:139], s[80:81], v[138:139]
	s_and_b64 vcc, exec, s[48:49]
	v_cvt_pk_bf16_f32 v142, v138, v139
	v_cvt_pk_bf16_f32 v143, v146, v147
	v_cvt_pk_bf16_f32 v144, v144, v145
	v_cvt_pk_bf16_f32 v145, v148, v149
	s_mov_b64 s[50:51], -1
	global_store_dwordx4 v[136:137], v[142:145], off sc1
	s_cbranch_vccnz .LBB0_212
	s_andn2_b64 vcc, exec, s[84:85]
	v_mov_b32_e32 v145, v75
	v_mov_b32_e32 v144, v74
	v_mov_b32_e32 v147, v73
	v_mov_b32_e32 v146, v72
	v_mov_b32_e32 v143, v83
	v_mov_b32_e32 v142, v82
	v_mov_b32_e32 v139, v81
	v_mov_b32_e32 v138, v80
	s_cbranch_vccnz .LBB0_211
	v_mul_f32_e32 v0, 0xbfb8aa3b, v80
	v_exp_f32_e32 v0, v0
	v_mul_f32_e32 v138, 0xbfb8aa3b, v72
	v_exp_f32_e32 v141, v138
	v_mul_f32_e32 v139, 0xbfb8aa3b, v81
	v_add_f32_e32 v0, 1.0, v0
	v_rcp_f32_e32 v138, v0
	v_add_f32_e32 v0, 1.0, v141
	v_mul_f32_e32 v141, 0xbfb8aa3b, v82
	v_exp_f32_e32 v141, v141
	v_mul_f32_e32 v142, 0xbfb8aa3b, v74
	v_exp_f32_e32 v139, v139
	v_exp_f32_e32 v143, v142
	v_add_f32_e32 v141, 1.0, v141
	v_rcp_f32_e32 v146, v0
	v_add_f32_e32 v0, 1.0, v139
	v_rcp_f32_e32 v142, v141
	v_add_f32_e32 v141, 1.0, v143
	v_mul_f32_e32 v143, 0xbfb8aa3b, v83
	v_rcp_f32_e32 v139, v0
	v_mul_f32_e32 v0, 0xbfb8aa3b, v73
	v_exp_f32_e32 v143, v143
	v_mul_f32_e32 v144, 0xbfb8aa3b, v75
	v_exp_f32_e32 v0, v0
	v_exp_f32_e32 v145, v144
	v_rcp_f32_e32 v144, v141
	v_add_f32_e32 v141, 1.0, v143
	v_add_f32_e32 v0, 1.0, v0
	v_rcp_f32_e32 v143, v141
	v_add_f32_e32 v141, 1.0, v145
	v_rcp_f32_e32 v145, v141
	v_rcp_f32_e32 v147, v0
	v_pk_mul_f32 v[142:143], v[82:83], v[142:143]
	v_pk_mul_f32 v[138:139], v[80:81], v[138:139]
	v_pk_mul_f32 v[144:145], v[74:75], v[144:145]
	v_pk_mul_f32 v[146:147], v[72:73], v[146:147]

.LBB0_227:
	v_or_b32_e32 v134, 48, v140
	v_ashrrev_i32_e32 v135, 31, v134
	s_waitcnt lgkmcnt(0)
	v_mad_u64_u32 v[136:137], s[50:51], s82, v134, 0
	v_mul_lo_u32 v0, s82, v135
	v_mul_lo_u32 v141, s83, v134
	s_mov_b32 s50, s80
	s_mov_b32 s51, s80
	v_add3_u32 v137, v137, v0, v141
	v_pk_mul_f32 v[148:149], s[50:51], v[144:145]
	v_pk_mul_f32 v[144:145], s[80:81], v[142:143]
	v_lshl_add_u64 v[136:137], v[136:137], 1, v[2:3]
	v_pk_mul_f32 v[146:147], s[50:51], v[146:147]
	v_pk_mul_f32 v[138:139], s[80:81], v[138:139]
	s_and_b64 vcc, exec, s[48:49]
	v_cvt_pk_bf16_f32 v142, v138, v139
	v_cvt_pk_bf16_f32 v143, v146, v147
	v_cvt_pk_bf16_f32 v144, v144, v145
	v_cvt_pk_bf16_f32 v145, v148, v149
	s_mov_b64 s[50:51], -1
	global_store_dwordx4 v[136:137], v[142:145], off sc1
	s_cbranch_vccnz .LBB0_231
	s_andn2_b64 vcc, exec, s[84:85]
	v_mov_b32_e32 v145, v71
	v_mov_b32_e32 v144, v70
	v_mov_b32_e32 v147, v69
	v_mov_b32_e32 v146, v68
	v_mov_b32_e32 v143, v79
	v_mov_b32_e32 v142, v78
	v_mov_b32_e32 v139, v77
	v_mov_b32_e32 v138, v76
	s_cbranch_vccnz .LBB0_230
	v_mul_f32_e32 v0, 0xbfb8aa3b, v76
	v_exp_f32_e32 v0, v0
	v_mul_f32_e32 v138, 0xbfb8aa3b, v68
	v_exp_f32_e32 v141, v138
	v_mul_f32_e32 v139, 0xbfb8aa3b, v77
	v_add_f32_e32 v0, 1.0, v0
	v_rcp_f32_e32 v138, v0
	v_add_f32_e32 v0, 1.0, v141
	v_mul_f32_e32 v141, 0xbfb8aa3b, v78
	v_exp_f32_e32 v141, v141
	v_mul_f32_e32 v142, 0xbfb8aa3b, v70
	v_exp_f32_e32 v139, v139
	v_exp_f32_e32 v143, v142
	v_add_f32_e32 v141, 1.0, v141
	v_rcp_f32_e32 v146, v0
	v_add_f32_e32 v0, 1.0, v139
	v_rcp_f32_e32 v142, v141
	v_add_f32_e32 v141, 1.0, v143
	v_mul_f32_e32 v143, 0xbfb8aa3b, v79
	v_rcp_f32_e32 v139, v0
	v_mul_f32_e32 v0, 0xbfb8aa3b, v69
	v_exp_f32_e32 v143, v143
	v_mul_f32_e32 v144, 0xbfb8aa3b, v71
	v_exp_f32_e32 v0, v0
	v_exp_f32_e32 v145, v144
	v_rcp_f32_e32 v144, v141
	v_add_f32_e32 v141, 1.0, v143
	v_add_f32_e32 v0, 1.0, v0
	v_rcp_f32_e32 v143, v141
	v_add_f32_e32 v141, 1.0, v145
	v_rcp_f32_e32 v145, v141
	v_rcp_f32_e32 v147, v0
	v_pk_mul_f32 v[142:143], v[78:79], v[142:143]
	v_pk_mul_f32 v[138:139], v[76:77], v[138:139]
	v_pk_mul_f32 v[144:145], v[70:71], v[144:145]
	v_pk_mul_f32 v[146:147], v[68:69], v[146:147]

.LBB0_249:
	v_add_u32_e32 v144, 0x80, v140
	v_ashrrev_i32_e32 v145, 31, v144
	v_mad_u64_u32 v[146:147], s[84:85], s82, v144, 0
	v_mul_lo_u32 v0, s82, v145
	v_mul_lo_u32 v141, s83, v144
	s_mov_b32 s84, s80
	s_mov_b32 s85, s80
	v_add3_u32 v147, v147, v0, v141
	v_pk_mul_f32 v[134:135], s[84:85], v[134:135]
	v_pk_mul_f32 v[132:133], s[80:81], v[132:133]
	v_lshl_add_u64 v[146:147], v[146:147], 1, v[2:3]
	v_pk_mul_f32 v[138:139], s[84:85], v[138:139]
	s_waitcnt lgkmcnt(0)
	v_pk_mul_f32 v[136:137], s[80:81], v[136:137]
	v_cvt_pk_bf16_f32 v132, v132, v133
	v_cvt_pk_bf16_f32 v133, v134, v135
	s_and_b64 vcc, exec, s[48:49]
	v_cvt_pk_bf16_f32 v134, v136, v137
	v_cvt_pk_bf16_f32 v135, v138, v139
	s_mov_b64 s[84:85], -1
	global_store_dwordx4 v[146:147], v[132:135], off sc1
	s_cbranch_vccnz .LBB0_253
	v_mov_b64_e32 v[138:139], v[42:43]
	v_mov_b64_e32 v[134:135], v[50:51]
	s_and_b64 vcc, exec, s[50:51]
	v_mov_b64_e32 v[136:137], v[40:41]
	v_mov_b64_e32 v[132:133], v[48:49]
	s_cbranch_vccnz .LBB0_252
	v_mul_f32_e32 v0, 0xbfb8aa3b, v48
	v_exp_f32_e32 v0, v0
	v_mul_f32_e32 v132, 0xbfb8aa3b, v40
	v_mul_f32_e32 v133, 0xbfb8aa3b, v49
	v_exp_f32_e32 v134, v132
	v_exp_f32_e32 v133, v133
	v_add_f32_e32 v0, 1.0, v0
	v_rcp_f32_e32 v132, v0
	v_add_f32_e32 v0, 1.0, v134
	v_rcp_f32_e32 v136, v0
	v_add_f32_e32 v0, 1.0, v133
	v_mul_f32_e32 v135, 0xbfb8aa3b, v42
	v_rcp_f32_e32 v133, v0
	v_mul_f32_e32 v0, 0xbfb8aa3b, v41
	v_mul_f32_e32 v134, 0xbfb8aa3b, v50
	v_exp_f32_e32 v135, v135
	v_mul_f32_e32 v137, 0xbfb8aa3b, v51
	v_mul_f32_e32 v138, 0xbfb8aa3b, v43
	v_exp_f32_e32 v0, v0
	v_exp_f32_e32 v134, v134
	v_exp_f32_e32 v137, v137
	v_exp_f32_e32 v139, v138
	v_add_f32_e32 v135, 1.0, v135
	v_add_f32_e32 v0, 1.0, v0
	v_add_f32_e32 v134, 1.0, v134
	v_rcp_f32_e32 v138, v135
	v_add_f32_e32 v135, 1.0, v137
	v_add_f32_e32 v137, 1.0, v139
	v_rcp_f32_e32 v134, v134
	v_rcp_f32_e32 v135, v135
	v_rcp_f32_e32 v139, v137
	v_rcp_f32_e32 v137, v0
	v_pk_mul_f32 v[132:133], v[48:49], v[132:133]
	v_pk_mul_f32 v[134:135], v[50:51], v[134:135]
	v_pk_mul_f32 v[138:139], v[42:43], v[138:139]
	v_pk_mul_f32 v[136:137], v[40:41], v[136:137]

.LBB0_256:
	s_mov_b32 s84, s80
	s_mov_b32 s85, s80
	v_pk_mul_f32 v[134:135], s[84:85], v[134:135]
	v_pk_mul_f32 v[132:133], s[80:81], v[132:133]
	s_and_b64 vcc, exec, s[46:47]
	v_pk_mul_f32 v[138:139], s[84:85], v[138:139]
	v_pk_mul_f32 v[136:137], s[80:81], v[136:137]
	v_cvt_pk_bf16_f32 v132, v132, v133
	v_cvt_pk_bf16_f32 v133, v134, v135
	s_nop 0
	v_cvt_pk_bf16_f32 v134, v136, v137
	v_cvt_pk_bf16_f32 v135, v138, v139
	global_store_dwordx4 v[146:147], v[132:135], off offset:256 sc1
	s_cbranch_vccnz .LBB0_260
	s_nop 0
	v_and_b32_e32 v132, 64, v230
	v_xor_b32_e32 v0, 16, v230
	v_add_u32_e32 v134, 64, v132
	v_cmp_lt_i32_e32 vcc, v0, v134
	s_nop 1
	v_cndmask_b32_e32 v0, v230, v0, vcc
	v_lshlrev_b32_e32 v0, 2, v0
	ds_bpermute_b32 v132, v0, v142
	ds_bpermute_b32 v133, v0, v143
	v_xor_b32_e32 v0, 32, v230
	v_cmp_lt_i32_e32 vcc, v0, v134
	s_waitcnt lgkmcnt(0)
	v_pk_add_f32 v[132:133], v[142:143], v[132:133]
	v_cndmask_b32_e32 v0, v230, v0, vcc
	v_lshlrev_b32_e32 v0, 2, v0
	ds_bpermute_b32 v134, v0, v132
	ds_bpermute_b32 v135, v0, v133
	s_and_saveexec_b64 s[84:85], s[38:39]
	s_cbranch_execz .LBB0_259
	s_waitcnt lgkmcnt(0)
	v_pk_add_f32 v[132:133], v[132:133], v[134:135]
	v_lshlrev_b64 v[134:135], 6, v[144:145]
	v_lshl_add_u64 v[134:135], s[66:67], 0, v[134:135]
	s_lshl_b32 s30, s73, 3
	v_lshl_add_u64 v[134:135], v[134:135], 0, s[30:31]
	s_lshl_b32 s30, s16, 3
	v_lshl_add_u64 v[134:135], v[134:135], 0, s[30:31]
	global_store_dwordx2 v[134:135], v[132:133], off

.LBB0_270:
	v_add_u32_e32 v144, 0x90, v140
	v_ashrrev_i32_e32 v145, 31, v144
	v_mad_u64_u32 v[146:147], s[84:85], s82, v144, 0
	v_mul_lo_u32 v0, s82, v145
	v_mul_lo_u32 v141, s83, v144
	s_mov_b32 s84, s80
	s_mov_b32 s85, s80
	v_add3_u32 v147, v147, v0, v141
	s_waitcnt lgkmcnt(0)
	v_pk_mul_f32 v[134:135], s[84:85], v[134:135]
	v_pk_mul_f32 v[132:133], s[80:81], v[132:133]
	v_lshl_add_u64 v[146:147], v[146:147], 1, v[2:3]
	v_pk_mul_f32 v[138:139], s[84:85], v[138:139]
	v_pk_mul_f32 v[136:137], s[80:81], v[136:137]
	v_cvt_pk_bf16_f32 v132, v132, v133
	v_cvt_pk_bf16_f32 v133, v134, v135
	s_and_b64 vcc, exec, s[48:49]
	v_cvt_pk_bf16_f32 v134, v136, v137
	v_cvt_pk_bf16_f32 v135, v138, v139
	s_mov_b64 s[84:85], -1
	global_store_dwordx4 v[146:147], v[132:135], off sc1
	s_cbranch_vccnz .LBB0_274
	v_mov_b64_e32 v[138:139], v[38:39]
	v_mov_b64_e32 v[134:135], v[46:47]
	s_and_b64 vcc, exec, s[50:51]
	v_mov_b64_e32 v[136:137], v[36:37]
	v_mov_b64_e32 v[132:133], v[44:45]
	s_cbranch_vccnz .LBB0_273
	v_mul_f32_e32 v0, 0xbfb8aa3b, v44
	v_exp_f32_e32 v0, v0
	v_mul_f32_e32 v132, 0xbfb8aa3b, v36
	v_mul_f32_e32 v133, 0xbfb8aa3b, v45
	v_exp_f32_e32 v134, v132
	v_exp_f32_e32 v133, v133
	v_add_f32_e32 v0, 1.0, v0
	v_rcp_f32_e32 v132, v0
	v_add_f32_e32 v0, 1.0, v134
	v_rcp_f32_e32 v136, v0
	v_add_f32_e32 v0, 1.0, v133
	v_mul_f32_e32 v135, 0xbfb8aa3b, v38
	v_rcp_f32_e32 v133, v0
	v_mul_f32_e32 v0, 0xbfb8aa3b, v37
	v_mul_f32_e32 v134, 0xbfb8aa3b, v46
	v_exp_f32_e32 v135, v135
	v_mul_f32_e32 v137, 0xbfb8aa3b, v47
	v_mul_f32_e32 v138, 0xbfb8aa3b, v39
	v_exp_f32_e32 v0, v0
	v_exp_f32_e32 v134, v134
	v_exp_f32_e32 v137, v137
	v_exp_f32_e32 v139, v138
	v_add_f32_e32 v135, 1.0, v135
	v_add_f32_e32 v0, 1.0, v0
	v_add_f32_e32 v134, 1.0, v134
	v_rcp_f32_e32 v138, v135
	v_add_f32_e32 v135, 1.0, v137
	v_add_f32_e32 v137, 1.0, v139
	v_rcp_f32_e32 v134, v134
	v_rcp_f32_e32 v135, v135
	v_rcp_f32_e32 v139, v137
	v_rcp_f32_e32 v137, v0
	v_pk_mul_f32 v[132:133], v[44:45], v[132:133]
	v_pk_mul_f32 v[134:135], v[46:47], v[134:135]
	v_pk_mul_f32 v[138:139], v[38:39], v[138:139]
	v_pk_mul_f32 v[136:137], v[36:37], v[136:137]

.LBB0_291:
	v_add_u32_e32 v144, 0xa0, v140
	v_ashrrev_i32_e32 v145, 31, v144
	v_mad_u64_u32 v[146:147], s[84:85], s82, v144, 0
	v_mul_lo_u32 v0, s82, v145
	v_mul_lo_u32 v141, s83, v144
	s_mov_b32 s84, s80
	s_mov_b32 s85, s80
	v_add3_u32 v147, v147, v0, v141
	s_waitcnt lgkmcnt(0)
	v_pk_mul_f32 v[134:135], s[84:85], v[134:135]
	v_pk_mul_f32 v[132:133], s[80:81], v[132:133]
	v_lshl_add_u64 v[146:147], v[146:147], 1, v[2:3]
	v_pk_mul_f32 v[138:139], s[84:85], v[138:139]
	v_pk_mul_f32 v[136:137], s[80:81], v[136:137]
	v_cvt_pk_bf16_f32 v132, v132, v133
	v_cvt_pk_bf16_f32 v133, v134, v135
	s_and_b64 vcc, exec, s[48:49]
	v_cvt_pk_bf16_f32 v134, v136, v137
	v_cvt_pk_bf16_f32 v135, v138, v139
	s_mov_b64 s[84:85], -1
	global_store_dwordx4 v[146:147], v[132:135], off sc1
	s_cbranch_vccnz .LBB0_295
	v_mov_b64_e32 v[138:139], v[10:11]
	v_mov_b64_e32 v[134:135], v[18:19]
	s_and_b64 vcc, exec, s[50:51]
	v_mov_b64_e32 v[136:137], v[8:9]
	v_mov_b64_e32 v[132:133], v[16:17]
	s_cbranch_vccnz .LBB0_294
	v_mul_f32_e32 v0, 0xbfb8aa3b, v16
	v_exp_f32_e32 v0, v0
	v_mul_f32_e32 v132, 0xbfb8aa3b, v8
	v_mul_f32_e32 v133, 0xbfb8aa3b, v17
	v_exp_f32_e32 v134, v132
	v_exp_f32_e32 v133, v133
	v_add_f32_e32 v0, 1.0, v0
	v_rcp_f32_e32 v132, v0
	v_add_f32_e32 v0, 1.0, v134
	v_rcp_f32_e32 v136, v0
	v_add_f32_e32 v0, 1.0, v133
	v_mul_f32_e32 v135, 0xbfb8aa3b, v10
	v_rcp_f32_e32 v133, v0
	v_mul_f32_e32 v0, 0xbfb8aa3b, v9
	v_mul_f32_e32 v134, 0xbfb8aa3b, v18
	v_exp_f32_e32 v135, v135
	v_mul_f32_e32 v137, 0xbfb8aa3b, v19
	v_mul_f32_e32 v138, 0xbfb8aa3b, v11
	v_exp_f32_e32 v0, v0
	v_exp_f32_e32 v134, v134
	v_exp_f32_e32 v137, v137
	v_exp_f32_e32 v139, v138
	v_add_f32_e32 v135, 1.0, v135
	v_add_f32_e32 v0, 1.0, v0
	v_add_f32_e32 v134, 1.0, v134
	v_rcp_f32_e32 v138, v135
	v_add_f32_e32 v135, 1.0, v137
	v_add_f32_e32 v137, 1.0, v139
	v_rcp_f32_e32 v134, v134
	v_rcp_f32_e32 v135, v135
	v_rcp_f32_e32 v139, v137
	v_rcp_f32_e32 v137, v0
	v_pk_mul_f32 v[132:133], v[16:17], v[132:133]
	v_pk_mul_f32 v[134:135], v[18:19], v[134:135]
	v_pk_mul_f32 v[138:139], v[10:11], v[138:139]
	v_pk_mul_f32 v[136:137], v[8:9], v[136:137]

.LBB0_312:
	v_add_u32_e32 v140, 0xb0, v140
	v_ashrrev_i32_e32 v141, 31, v140
	v_mul_lo_u32 v0, s82, v141
	v_mul_lo_u32 v146, s83, v140
	v_mad_u64_u32 v[144:145], s[82:83], s82, v140, 0
	s_mov_b32 s82, s80
	s_mov_b32 s83, s80
	v_add3_u32 v145, v145, v0, v146
	s_waitcnt lgkmcnt(0)
	v_pk_mul_f32 v[134:135], s[82:83], v[134:135]
	v_pk_mul_f32 v[132:133], s[80:81], v[132:133]
	v_lshl_add_u64 v[2:3], v[144:145], 1, v[2:3]
	v_pk_mul_f32 v[138:139], s[82:83], v[138:139]
	v_pk_mul_f32 v[136:137], s[80:81], v[136:137]
	v_cvt_pk_bf16_f32 v132, v132, v133
	v_cvt_pk_bf16_f32 v133, v134, v135
	s_and_b64 vcc, exec, s[48:49]
	v_cvt_pk_bf16_f32 v134, v136, v137
	v_cvt_pk_bf16_f32 v135, v138, v139
	s_mov_b64 s[48:49], -1
	global_store_dwordx4 v[2:3], v[132:135], off sc1
	s_cbranch_vccnz .LBB0_316
	v_mov_b64_e32 v[138:139], v[6:7]
	v_mov_b64_e32 v[134:135], v[14:15]
	s_and_b64 vcc, exec, s[50:51]
	v_mov_b64_e32 v[136:137], v[4:5]
	v_mov_b64_e32 v[132:133], v[12:13]
	s_cbranch_vccnz .LBB0_315
	v_mul_f32_e32 v0, 0xbfb8aa3b, v12
	v_exp_f32_e32 v0, v0
	v_mul_f32_e32 v132, 0xbfb8aa3b, v4
	v_mul_f32_e32 v133, 0xbfb8aa3b, v13
	v_exp_f32_e32 v134, v132
	v_exp_f32_e32 v133, v133
	v_add_f32_e32 v0, 1.0, v0
	v_rcp_f32_e32 v132, v0
	v_add_f32_e32 v0, 1.0, v134
	v_rcp_f32_e32 v136, v0
	v_add_f32_e32 v0, 1.0, v133
	v_mul_f32_e32 v135, 0xbfb8aa3b, v6
	v_rcp_f32_e32 v133, v0
	v_mul_f32_e32 v0, 0xbfb8aa3b, v5
	v_mul_f32_e32 v134, 0xbfb8aa3b, v14
	v_exp_f32_e32 v135, v135
	v_mul_f32_e32 v137, 0xbfb8aa3b, v15
	v_mul_f32_e32 v138, 0xbfb8aa3b, v7
	v_exp_f32_e32 v0, v0
	v_exp_f32_e32 v134, v134
	v_exp_f32_e32 v137, v137
	v_exp_f32_e32 v139, v138
	v_add_f32_e32 v135, 1.0, v135
	v_add_f32_e32 v0, 1.0, v0
	v_add_f32_e32 v134, 1.0, v134
	v_rcp_f32_e32 v138, v135
	v_add_f32_e32 v135, 1.0, v137
	v_add_f32_e32 v137, 1.0, v139
	v_rcp_f32_e32 v134, v134
	v_rcp_f32_e32 v135, v135
	v_rcp_f32_e32 v139, v137
	v_rcp_f32_e32 v137, v0
	v_pk_mul_f32 v[132:133], v[12:13], v[132:133]
	v_pk_mul_f32 v[134:135], v[14:15], v[134:135]
	v_pk_mul_f32 v[138:139], v[6:7], v[138:139]
	v_pk_mul_f32 v[136:137], v[4:5], v[136:137]

.LBB0_319:
	s_mov_b32 s48, s80
	s_mov_b32 s49, s80
	v_pk_mul_f32 v[134:135], s[48:49], v[134:135]
	v_pk_mul_f32 v[132:133], s[80:81], v[132:133]
	s_and_b64 vcc, exec, s[46:47]
	v_pk_mul_f32 v[138:139], s[48:49], v[138:139]
	v_pk_mul_f32 v[136:137], s[80:81], v[136:137]
	v_cvt_pk_bf16_f32 v132, v132, v133
	v_cvt_pk_bf16_f32 v133, v134, v135
	s_nop 0
	v_cvt_pk_bf16_f32 v134, v136, v137
	v_cvt_pk_bf16_f32 v135, v138, v139
	global_store_dwordx4 v[2:3], v[132:135], off offset:256 sc1
	s_cbranch_vccnz .LBB0_323
	v_and_b32_e32 v2, 64, v230
	v_xor_b32_e32 v0, 16, v230
	v_add_u32_e32 v132, 64, v2
	v_cmp_lt_i32_e32 vcc, v0, v132
	s_nop 1
	v_cndmask_b32_e32 v0, v230, v0, vcc
	v_lshlrev_b32_e32 v0, 2, v0
	ds_bpermute_b32 v2, v0, v142
	ds_bpermute_b32 v3, v0, v143
	v_xor_b32_e32 v0, 32, v230
	v_cmp_lt_i32_e32 vcc, v0, v132
	s_waitcnt lgkmcnt(0)
	v_pk_add_f32 v[2:3], v[142:143], v[2:3]
	v_cndmask_b32_e32 v0, v230, v0, vcc
	v_lshlrev_b32_e32 v0, 2, v0
	ds_bpermute_b32 v132, v0, v2
	ds_bpermute_b32 v133, v0, v3
	s_and_saveexec_b64 s[46:47], s[38:39]
	s_cbranch_execz .LBB0_322
	s_waitcnt lgkmcnt(0)
	v_pk_add_f32 v[2:3], v[2:3], v[132:133]
	v_lshlrev_b64 v[132:133], 6, v[140:141]
	v_lshl_add_u64 v[132:133], s[66:67], 0, v[132:133]
	s_lshl_b32 s30, s73, 3
	v_lshl_add_u64 v[132:133], v[132:133], 0, s[30:31]
	s_lshl_b32 s30, s16, 3
	v_lshl_add_u64 v[132:133], v[132:133], 0, s[30:31]
	global_store_dwordx2 v[132:133], v[2:3], off

.LBB0_324:
	s_and_b64 vcc, exec, s[48:49]
	s_cbranch_vccz .LBB0_326
	v_cndmask_b32_e64 v3, v128, v129, s[40:41]
	s_and_b32 s46, s57, 0x7c0
	v_or_b32_e32 v0, s46, v235
	v_mov_b32_dpp v3, v3 quad_perm:[1,0,3,2] row_mask:0xf bank_mask:0xf bound_ctrl:1
	v_cndmask_b32_e64 v128, v3, v128, s[40:41]
	v_cndmask_b32_e64 v3, v129, v3, s[40:41]
	v_cndmask_b32_e64 v129, v130, v131, s[40:41]
	s_ashr_i32 s46, s57, 9
	s_lshl_b32 s30, s71, 1
	v_mov_b32_dpp v129, v129 quad_perm:[1,0,3,2] row_mask:0xf bank_mask:0xf bound_ctrl:1
	v_cndmask_b32_e64 v130, v129, v130, s[40:41]
	v_cndmask_b32_e64 v129, v131, v129, s[40:41]
	v_cndmask_b32_e64 v131, v128, v130, s[42:43]
	s_and_b32 s46, s46, 0x1fffffc
	s_or_b32 s46, s46, s30
	v_mov_b32_dpp v131, v131 quad_perm:[2,3,0,1] row_mask:0xf bank_mask:0xf bound_ctrl:1
	v_cndmask_b32_e64 v128, v131, v128, s[42:43]
	v_cndmask_b32_e64 v130, v130, v131, s[42:43]
	v_cndmask_b32_e64 v131, v3, v129, s[42:43]
	v_lshl_or_b32 v2, s46, 7, v236
	v_lshlrev_b32_e32 v0, 1, v0
	v_mov_b32_dpp v131, v131 quad_perm:[2,3,0,1] row_mask:0xf bank_mask:0xf bound_ctrl:1
	v_cndmask_b32_e64 v3, v131, v3, s[42:43]
	v_cndmask_b32_e64 v129, v129, v131, s[42:43]
	v_cndmask_b32_e64 v131, v124, v125, s[40:41]
	s_and_b64 vcc, exec, s[44:45]
	s_nop 0
	v_mov_b32_dpp v131, v131 quad_perm:[1,0,3,2] row_mask:0xf bank_mask:0xf bound_ctrl:1
	v_cndmask_b32_e64 v124, v131, v124, s[40:41]
	v_cndmask_b32_e64 v125, v125, v131, s[40:41]
	v_cndmask_b32_e64 v131, v126, v127, s[40:41]
	s_nop 1
	v_mov_b32_dpp v131, v131 quad_perm:[1,0,3,2] row_mask:0xf bank_mask:0xf bound_ctrl:1
	v_cndmask_b32_e64 v126, v131, v126, s[40:41]
	v_cndmask_b32_e64 v127, v127, v131, s[40:41]
	v_cndmask_b32_e64 v131, v124, v126, s[42:43]
	s_nop 1
	v_mov_b32_dpp v131, v131 quad_perm:[2,3,0,1] row_mask:0xf bank_mask:0xf bound_ctrl:1
	s_waitcnt lgkmcnt(0)
	v_cndmask_b32_e64 v132, v131, v124, s[42:43]
	v_cndmask_b32_e64 v124, v125, v127, s[42:43]
	v_cndmask_b32_e64 v131, v126, v131, s[42:43]
	s_nop 0
	v_mov_b32_dpp v124, v124 quad_perm:[2,3,0,1] row_mask:0xf bank_mask:0xf bound_ctrl:1
	v_cndmask_b32_e64 v126, v124, v125, s[42:43]
	v_cndmask_b32_e64 v127, v127, v124, s[42:43]
	v_cvt_pk_bf16_f32 v124, v128, v3
	v_ashrrev_i32_e32 v3, 31, v2
	v_cvt_pk_bf16_f32 v125, v130, v129
	v_lshlrev_b64 v[128:129], 12, v[2:3]
	v_cndmask_b32_e64 v3, v120, v121, s[40:41]
	v_lshl_add_u64 v[128:129], s[28:29], 0, v[128:129]
	v_lshl_add_u64 v[128:129], v[128:129], 0, v[0:1]
	v_mov_b32_dpp v3, v3 quad_perm:[1,0,3,2] row_mask:0xf bank_mask:0xf bound_ctrl:1
	v_cndmask_b32_e64 v120, v3, v120, s[40:41]
	v_cndmask_b32_e64 v3, v121, v3, s[40:41]
	v_cndmask_b32_e64 v121, v122, v123, s[40:41]
	v_cvt_pk_bf16_f32 v126, v132, v126
	v_cvt_pk_bf16_f32 v127, v131, v127
	global_store_dwordx4 v[128:129], v[124:127], off sc1
	s_nop 0
	v_mov_b32_dpp v121, v121 quad_perm:[1,0,3,2] row_mask:0xf bank_mask:0xf bound_ctrl:1
	v_cndmask_b32_e64 v122, v121, v122, s[40:41]
	v_cndmask_b32_e64 v121, v123, v121, s[40:41]
	v_cndmask_b32_e64 v123, v120, v122, s[42:43]
	s_nop 1
	v_mov_b32_dpp v123, v123 quad_perm:[2,3,0,1] row_mask:0xf bank_mask:0xf bound_ctrl:1
	v_cndmask_b32_e64 v120, v123, v120, s[42:43]
	v_cndmask_b32_e64 v122, v122, v123, s[42:43]
	v_cndmask_b32_e64 v123, v3, v121, s[42:43]
	s_nop 1
	v_mov_b32_dpp v123, v123 quad_perm:[2,3,0,1] row_mask:0xf bank_mask:0xf bound_ctrl:1
	v_cndmask_b32_e64 v3, v123, v3, s[42:43]
	v_cndmask_b32_e64 v121, v121, v123, s[42:43]
	v_cndmask_b32_e64 v123, v116, v117, s[40:41]
	s_nop 1
	v_mov_b32_dpp v123, v123 quad_perm:[1,0,3,2] row_mask:0xf bank_mask:0xf bound_ctrl:1
	v_cndmask_b32_e64 v116, v123, v116, s[40:41]
	v_cndmask_b32_e64 v117, v117, v123, s[40:41]
	v_cndmask_b32_e64 v123, v118, v119, s[40:41]
	s_nop 1
	v_mov_b32_dpp v123, v123 quad_perm:[1,0,3,2] row_mask:0xf bank_mask:0xf bound_ctrl:1
	v_cndmask_b32_e64 v118, v123, v118, s[40:41]
	v_cndmask_b32_e64 v119, v119, v123, s[40:41]
	v_cndmask_b32_e64 v123, v116, v118, s[42:43]
	s_nop 1
	v_mov_b32_dpp v123, v123 quad_perm:[2,3,0,1] row_mask:0xf bank_mask:0xf bound_ctrl:1
	v_cndmask_b32_e64 v124, v123, v116, s[42:43]
	v_cndmask_b32_e64 v116, v117, v119, s[42:43]
	v_cndmask_b32_e64 v123, v118, v123, s[42:43]
	s_nop 0
	v_mov_b32_dpp v116, v116 quad_perm:[2,3,0,1] row_mask:0xf bank_mask:0xf bound_ctrl:1
	v_cndmask_b32_e64 v118, v116, v117, s[42:43]
	v_cndmask_b32_e64 v119, v119, v116, s[42:43]
	v_cvt_pk_bf16_f32 v116, v120, v3
	v_cndmask_b32_e64 v3, v112, v113, s[40:41]
	v_or_b32_e32 v120, 4, v2
	v_cvt_pk_bf16_f32 v117, v122, v121
	v_ashrrev_i32_e32 v121, 31, v120
	v_mov_b32_dpp v3, v3 quad_perm:[1,0,3,2] row_mask:0xf bank_mask:0xf bound_ctrl:1
	v_cndmask_b32_e64 v112, v3, v112, s[40:41]
	v_cndmask_b32_e64 v3, v113, v3, s[40:41]
	v_cndmask_b32_e64 v113, v114, v115, s[40:41]
	v_lshlrev_b64 v[120:121], 12, v[120:121]
	v_lshl_add_u64 v[120:121], s[28:29], 0, v[120:121]
	v_mov_b32_dpp v113, v113 quad_perm:[1,0,3,2] row_mask:0xf bank_mask:0xf bound_ctrl:1
	v_cndmask_b32_e64 v114, v113, v114, s[40:41]
	v_cndmask_b32_e64 v113, v115, v113, s[40:41]
	v_cndmask_b32_e64 v115, v112, v114, s[42:43]
	v_lshl_add_u64 v[120:121], v[120:121], 0, v[0:1]
	v_cvt_pk_bf16_f32 v118, v124, v118
	v_cvt_pk_bf16_f32 v119, v123, v119
	global_store_dwordx4 v[120:121], v[116:119], off sc1
	v_mov_b32_dpp v115, v115 quad_perm:[2,3,0,1] row_mask:0xf bank_mask:0xf bound_ctrl:1
	v_cndmask_b32_e64 v112, v115, v112, s[42:43]
	v_cndmask_b32_e64 v114, v114, v115, s[42:43]
	v_cndmask_b32_e64 v115, v3, v113, s[42:43]
	v_or_b32_e32 v116, 0x80, v2
	v_or_b32_e32 v2, 0x84, v2
	v_mov_b32_dpp v115, v115 quad_perm:[2,3,0,1] row_mask:0xf bank_mask:0xf bound_ctrl:1
	v_cndmask_b32_e64 v3, v115, v3, s[42:43]
	v_cndmask_b32_e64 v113, v113, v115, s[42:43]
	v_cndmask_b32_e64 v115, v108, v109, s[40:41]
	s_nop 1
	v_mov_b32_dpp v115, v115 quad_perm:[1,0,3,2] row_mask:0xf bank_mask:0xf bound_ctrl:1
	v_cndmask_b32_e64 v108, v115, v108, s[40:41]
	v_cndmask_b32_e64 v109, v109, v115, s[40:41]
	v_cndmask_b32_e64 v115, v110, v111, s[40:41]
	s_nop 1
	v_mov_b32_dpp v115, v115 quad_perm:[1,0,3,2] row_mask:0xf bank_mask:0xf bound_ctrl:1
	v_cndmask_b32_e64 v110, v115, v110, s[40:41]
	v_cndmask_b32_e64 v111, v111, v115, s[40:41]
	v_cndmask_b32_e64 v115, v108, v110, s[42:43]
	s_nop 1
	v_mov_b32_dpp v115, v115 quad_perm:[2,3,0,1] row_mask:0xf bank_mask:0xf bound_ctrl:1
	v_cndmask_b32_e64 v117, v115, v108, s[42:43]
	v_cndmask_b32_e64 v108, v109, v111, s[42:43]
	v_cndmask_b32_e64 v115, v110, v115, s[42:43]
	s_nop 0
	v_mov_b32_dpp v108, v108 quad_perm:[2,3,0,1] row_mask:0xf bank_mask:0xf bound_ctrl:1
	v_cndmask_b32_e64 v110, v108, v109, s[42:43]
	v_cndmask_b32_e64 v111, v111, v108, s[42:43]
	v_cvt_pk_bf16_f32 v108, v112, v3
	v_cndmask_b32_e64 v3, v104, v105, s[40:41]
	v_cvt_pk_bf16_f32 v109, v114, v113
	v_cvt_pk_bf16_f32 v110, v117, v110
	v_ashrrev_i32_e32 v117, 31, v116
	v_lshlrev_b64 v[112:113], 12, v[116:117]
	v_mov_b32_dpp v3, v3 quad_perm:[1,0,3,2] row_mask:0xf bank_mask:0xf bound_ctrl:1
	v_cndmask_b32_e64 v104, v3, v104, s[40:41]
	v_cndmask_b32_e64 v3, v105, v3, s[40:41]
	v_cndmask_b32_e64 v105, v106, v107, s[40:41]
	v_lshl_add_u64 v[112:113], s[28:29], 0, v[112:113]
	v_lshl_add_u64 v[112:113], v[112:113], 0, v[0:1]
	v_mov_b32_dpp v105, v105 quad_perm:[1,0,3,2] row_mask:0xf bank_mask:0xf bound_ctrl:1
	v_cndmask_b32_e64 v106, v105, v106, s[40:41]
	v_cndmask_b32_e64 v105, v107, v105, s[40:41]
	v_cndmask_b32_e64 v107, v104, v106, s[42:43]
	v_cvt_pk_bf16_f32 v111, v115, v111
	global_store_dwordx4 v[112:113], v[108:111], off sc1
	s_nop 0
	v_mov_b32_dpp v107, v107 quad_perm:[2,3,0,1] row_mask:0xf bank_mask:0xf bound_ctrl:1
	v_cndmask_b32_e64 v104, v107, v104, s[42:43]
	v_cndmask_b32_e64 v106, v106, v107, s[42:43]
	v_cndmask_b32_e64 v107, v3, v105, s[42:43]
	s_nop 1
	v_mov_b32_dpp v107, v107 quad_perm:[2,3,0,1] row_mask:0xf bank_mask:0xf bound_ctrl:1
	v_cndmask_b32_e64 v3, v107, v3, s[42:43]
	v_cndmask_b32_e64 v105, v105, v107, s[42:43]
	v_cndmask_b32_e64 v107, v100, v101, s[40:41]
	s_nop 1
	v_mov_b32_dpp v107, v107 quad_perm:[1,0,3,2] row_mask:0xf bank_mask:0xf bound_ctrl:1
	v_cndmask_b32_e64 v100, v107, v100, s[40:41]
	v_cndmask_b32_e64 v101, v101, v107, s[40:41]
	v_cndmask_b32_e64 v107, v102, v103, s[40:41]
	s_nop 1
	v_mov_b32_dpp v107, v107 quad_perm:[1,0,3,2] row_mask:0xf bank_mask:0xf bound_ctrl:1
	v_cndmask_b32_e64 v102, v107, v102, s[40:41]
	v_cndmask_b32_e64 v103, v103, v107, s[40:41]
	v_cndmask_b32_e64 v107, v100, v102, s[42:43]
	s_nop 1
	v_mov_b32_dpp v107, v107 quad_perm:[2,3,0,1] row_mask:0xf bank_mask:0xf bound_ctrl:1
	v_cndmask_b32_e64 v108, v107, v100, s[42:43]
	v_cndmask_b32_e64 v100, v101, v103, s[42:43]
	v_cndmask_b32_e64 v107, v102, v107, s[42:43]
	s_nop 0
	v_mov_b32_dpp v100, v100 quad_perm:[2,3,0,1] row_mask:0xf bank_mask:0xf bound_ctrl:1
	v_cndmask_b32_e64 v102, v100, v101, s[42:43]
	v_cndmask_b32_e64 v103, v103, v100, s[42:43]
	v_cvt_pk_bf16_f32 v100, v104, v3
	v_ashrrev_i32_e32 v3, 31, v2
	v_lshlrev_b64 v[2:3], 12, v[2:3]
	v_lshl_add_u64 v[2:3], s[28:29], 0, v[2:3]
	v_lshl_add_u64 v[2:3], v[2:3], 0, v[0:1]
	v_cndmask_b32_e64 v0, v96, v97, s[40:41]
	v_cvt_pk_bf16_f32 v101, v106, v105
	v_cvt_pk_bf16_f32 v102, v108, v102
	v_cvt_pk_bf16_f32 v103, v107, v103
	global_store_dwordx4 v[2:3], v[100:103], off sc1
	s_nop 0
	v_mov_b32_dpp v0, v0 quad_perm:[1,0,3,2] row_mask:0xf bank_mask:0xf bound_ctrl:1
	v_cndmask_b32_e64 v96, v0, v96, s[40:41]
	v_cndmask_b32_e64 v0, v97, v0, s[40:41]
	v_cndmask_b32_e64 v97, v98, v99, s[40:41]
	s_nop 1
	v_mov_b32_dpp v97, v97 quad_perm:[1,0,3,2] row_mask:0xf bank_mask:0xf bound_ctrl:1
	v_cndmask_b32_e64 v98, v97, v98, s[40:41]
	v_cndmask_b32_e64 v97, v99, v97, s[40:41]
	v_cndmask_b32_e64 v99, v96, v98, s[42:43]
	s_nop 1
	v_mov_b32_dpp v99, v99 quad_perm:[2,3,0,1] row_mask:0xf bank_mask:0xf bound_ctrl:1
	v_cndmask_b32_e64 v96, v99, v96, s[42:43]
	v_cndmask_b32_e64 v98, v98, v99, s[42:43]
	v_cndmask_b32_e64 v99, v0, v97, s[42:43]
	s_nop 1
	v_mov_b32_dpp v99, v99 quad_perm:[2,3,0,1] row_mask:0xf bank_mask:0xf bound_ctrl:1
	v_cndmask_b32_e64 v0, v99, v0, s[42:43]
	v_cndmask_b32_e64 v97, v97, v99, s[42:43]
	v_cndmask_b32_e64 v99, v92, v93, s[40:41]
	s_nop 1
	v_mov_b32_dpp v99, v99 quad_perm:[1,0,3,2] row_mask:0xf bank_mask:0xf bound_ctrl:1
	v_cndmask_b32_e64 v92, v99, v92, s[40:41]
	v_cndmask_b32_e64 v93, v93, v99, s[40:41]
	v_cndmask_b32_e64 v99, v94, v95, s[40:41]
	s_nop 1
	v_mov_b32_dpp v99, v99 quad_perm:[1,0,3,2] row_mask:0xf bank_mask:0xf bound_ctrl:1
	v_cndmask_b32_e64 v94, v99, v94, s[40:41]
	v_cndmask_b32_e64 v95, v95, v99, s[40:41]
	v_cndmask_b32_e64 v99, v92, v94, s[42:43]
	s_nop 1
	v_mov_b32_dpp v99, v99 quad_perm:[2,3,0,1] row_mask:0xf bank_mask:0xf bound_ctrl:1
	v_cndmask_b32_e64 v100, v99, v92, s[42:43]
	v_cndmask_b32_e64 v92, v93, v95, s[42:43]
	v_cndmask_b32_e64 v99, v94, v99, s[42:43]
	s_nop 0
	v_mov_b32_dpp v92, v92 quad_perm:[2,3,0,1] row_mask:0xf bank_mask:0xf bound_ctrl:1
	v_cndmask_b32_e64 v94, v92, v93, s[42:43]
	v_cndmask_b32_e64 v95, v95, v92, s[42:43]
	v_cvt_pk_bf16_f32 v92, v96, v0
	v_cndmask_b32_e64 v0, v88, v89, s[40:41]
	v_cvt_pk_bf16_f32 v93, v98, v97
	v_cvt_pk_bf16_f32 v94, v100, v94
	v_cvt_pk_bf16_f32 v95, v99, v95
	global_store_dwordx4 v[128:129], v[92:95], off offset:64 sc1
	s_nop 0
	v_mov_b32_dpp v0, v0 quad_perm:[1,0,3,2] row_mask:0xf bank_mask:0xf bound_ctrl:1
	v_cndmask_b32_e64 v88, v0, v88, s[40:41]
	v_cndmask_b32_e64 v0, v89, v0, s[40:41]
	v_cndmask_b32_e64 v89, v90, v91, s[40:41]
	s_nop 1
	v_mov_b32_dpp v89, v89 quad_perm:[1,0,3,2] row_mask:0xf bank_mask:0xf bound_ctrl:1
	v_cndmask_b32_e64 v90, v89, v90, s[40:41]
	v_cndmask_b32_e64 v89, v91, v89, s[40:41]
	v_cndmask_b32_e64 v91, v88, v90, s[42:43]
	s_nop 1
	v_mov_b32_dpp v91, v91 quad_perm:[2,3,0,1] row_mask:0xf bank_mask:0xf bound_ctrl:1
	v_cndmask_b32_e64 v88, v91, v88, s[42:43]
	v_cndmask_b32_e64 v90, v90, v91, s[42:43]
	v_cndmask_b32_e64 v91, v0, v89, s[42:43]
	s_nop 1
	v_mov_b32_dpp v91, v91 quad_perm:[2,3,0,1] row_mask:0xf bank_mask:0xf bound_ctrl:1
	v_cndmask_b32_e64 v0, v91, v0, s[42:43]
	v_cndmask_b32_e64 v89, v89, v91, s[42:43]
	v_cndmask_b32_e64 v91, v84, v85, s[40:41]
	s_nop 1
	v_mov_b32_dpp v91, v91 quad_perm:[1,0,3,2] row_mask:0xf bank_mask:0xf bound_ctrl:1
	v_cndmask_b32_e64 v84, v91, v84, s[40:41]
	v_cndmask_b32_e64 v85, v85, v91, s[40:41]
	v_cndmask_b32_e64 v91, v86, v87, s[40:41]
	s_nop 1
	v_mov_b32_dpp v91, v91 quad_perm:[1,0,3,2] row_mask:0xf bank_mask:0xf bound_ctrl:1
	v_cndmask_b32_e64 v86, v91, v86, s[40:41]
	v_cndmask_b32_e64 v87, v87, v91, s[40:41]
	v_cndmask_b32_e64 v91, v84, v86, s[42:43]
	s_nop 1
	v_mov_b32_dpp v91, v91 quad_perm:[2,3,0,1] row_mask:0xf bank_mask:0xf bound_ctrl:1
	v_cndmask_b32_e64 v92, v91, v84, s[42:43]
	v_cndmask_b32_e64 v84, v85, v87, s[42:43]
	v_cndmask_b32_e64 v91, v86, v91, s[42:43]
	s_nop 0
	v_mov_b32_dpp v84, v84 quad_perm:[2,3,0,1] row_mask:0xf bank_mask:0xf bound_ctrl:1
	v_cndmask_b32_e64 v86, v84, v85, s[42:43]
	v_cndmask_b32_e64 v87, v87, v84, s[42:43]
	v_cvt_pk_bf16_f32 v84, v88, v0
	v_cndmask_b32_e64 v0, v80, v81, s[40:41]
	v_cvt_pk_bf16_f32 v85, v90, v89
	v_cvt_pk_bf16_f32 v86, v92, v86
	v_cvt_pk_bf16_f32 v87, v91, v87
	global_store_dwordx4 v[120:121], v[84:87], off offset:64 sc1
	s_nop 0
	v_mov_b32_dpp v0, v0 quad_perm:[1,0,3,2] row_mask:0xf bank_mask:0xf bound_ctrl:1
	v_cndmask_b32_e64 v80, v0, v80, s[40:41]
	v_cndmask_b32_e64 v0, v81, v0, s[40:41]
	v_cndmask_b32_e64 v81, v82, v83, s[40:41]
	s_nop 1
	v_mov_b32_dpp v81, v81 quad_perm:[1,0,3,2] row_mask:0xf bank_mask:0xf bound_ctrl:1
	v_cndmask_b32_e64 v82, v81, v82, s[40:41]
	v_cndmask_b32_e64 v81, v83, v81, s[40:41]
	v_cndmask_b32_e64 v83, v80, v82, s[42:43]
	s_nop 1
	v_mov_b32_dpp v83, v83 quad_perm:[2,3,0,1] row_mask:0xf bank_mask:0xf bound_ctrl:1
	v_cndmask_b32_e64 v80, v83, v80, s[42:43]
	v_cndmask_b32_e64 v82, v82, v83, s[42:43]
	v_cndmask_b32_e64 v83, v0, v81, s[42:43]
	s_nop 1
	v_mov_b32_dpp v83, v83 quad_perm:[2,3,0,1] row_mask:0xf bank_mask:0xf bound_ctrl:1
	v_cndmask_b32_e64 v0, v83, v0, s[42:43]
	v_cndmask_b32_e64 v81, v81, v83, s[42:43]
	v_cndmask_b32_e64 v83, v76, v77, s[40:41]
	s_nop 1
	v_mov_b32_dpp v83, v83 quad_perm:[1,0,3,2] row_mask:0xf bank_mask:0xf bound_ctrl:1
	v_cndmask_b32_e64 v76, v83, v76, s[40:41]
	v_cndmask_b32_e64 v77, v77, v83, s[40:41]
	v_cndmask_b32_e64 v83, v78, v79, s[40:41]
	s_nop 1
	v_mov_b32_dpp v83, v83 quad_perm:[1,0,3,2] row_mask:0xf bank_mask:0xf bound_ctrl:1
	v_cndmask_b32_e64 v78, v83, v78, s[40:41]
	v_cndmask_b32_e64 v79, v79, v83, s[40:41]
	v_cndmask_b32_e64 v83, v76, v78, s[42:43]
	s_nop 1
	v_mov_b32_dpp v83, v83 quad_perm:[2,3,0,1] row_mask:0xf bank_mask:0xf bound_ctrl:1
	v_cndmask_b32_e64 v84, v83, v76, s[42:43]
	v_cndmask_b32_e64 v76, v77, v79, s[42:43]
	v_cndmask_b32_e64 v83, v78, v83, s[42:43]
	s_nop 0
	v_mov_b32_dpp v76, v76 quad_perm:[2,3,0,1] row_mask:0xf bank_mask:0xf bound_ctrl:1
	v_cndmask_b32_e64 v78, v76, v77, s[42:43]
	v_cndmask_b32_e64 v79, v79, v76, s[42:43]
	v_cvt_pk_bf16_f32 v76, v80, v0
	v_cndmask_b32_e64 v0, v72, v73, s[40:41]
	v_cvt_pk_bf16_f32 v77, v82, v81
	v_cvt_pk_bf16_f32 v78, v84, v78
	v_cvt_pk_bf16_f32 v79, v83, v79
	global_store_dwordx4 v[112:113], v[76:79], off offset:64 sc1
	s_nop 0
	v_mov_b32_dpp v0, v0 quad_perm:[1,0,3,2] row_mask:0xf bank_mask:0xf bound_ctrl:1
	v_cndmask_b32_e64 v72, v0, v72, s[40:41]
	v_cndmask_b32_e64 v0, v73, v0, s[40:41]
	v_cndmask_b32_e64 v73, v74, v75, s[40:41]
	s_nop 1
	v_mov_b32_dpp v73, v73 quad_perm:[1,0,3,2] row_mask:0xf bank_mask:0xf bound_ctrl:1
	v_cndmask_b32_e64 v74, v73, v74, s[40:41]
	v_cndmask_b32_e64 v73, v75, v73, s[40:41]
	v_cndmask_b32_e64 v75, v72, v74, s[42:43]
	s_nop 1
	v_mov_b32_dpp v75, v75 quad_perm:[2,3,0,1] row_mask:0xf bank_mask:0xf bound_ctrl:1
	v_cndmask_b32_e64 v72, v75, v72, s[42:43]
	v_cndmask_b32_e64 v74, v74, v75, s[42:43]
	v_cndmask_b32_e64 v75, v0, v73, s[42:43]
	s_nop 1
	v_mov_b32_dpp v75, v75 quad_perm:[2,3,0,1] row_mask:0xf bank_mask:0xf bound_ctrl:1
	v_cndmask_b32_e64 v0, v75, v0, s[42:43]
	v_cndmask_b32_e64 v73, v73, v75, s[42:43]
	v_cndmask_b32_e64 v75, v68, v69, s[40:41]
	s_nop 1
	v_mov_b32_dpp v75, v75 quad_perm:[1,0,3,2] row_mask:0xf bank_mask:0xf bound_ctrl:1
	v_cndmask_b32_e64 v68, v75, v68, s[40:41]
	v_cndmask_b32_e64 v69, v69, v75, s[40:41]
	v_cndmask_b32_e64 v75, v70, v71, s[40:41]
	s_nop 1
	v_mov_b32_dpp v75, v75 quad_perm:[1,0,3,2] row_mask:0xf bank_mask:0xf bound_ctrl:1
	v_cndmask_b32_e64 v70, v75, v70, s[40:41]
	v_cndmask_b32_e64 v71, v71, v75, s[40:41]
	v_cndmask_b32_e64 v75, v68, v70, s[42:43]
	s_nop 1
	v_mov_b32_dpp v75, v75 quad_perm:[2,3,0,1] row_mask:0xf bank_mask:0xf bound_ctrl:1
	v_cndmask_b32_e64 v76, v75, v68, s[42:43]
	v_cndmask_b32_e64 v68, v69, v71, s[42:43]
	v_cndmask_b32_e64 v75, v70, v75, s[42:43]
	s_nop 0
	v_mov_b32_dpp v68, v68 quad_perm:[2,3,0,1] row_mask:0xf bank_mask:0xf bound_ctrl:1
	v_cndmask_b32_e64 v70, v68, v69, s[42:43]
	v_cndmask_b32_e64 v71, v71, v68, s[42:43]
	v_cvt_pk_bf16_f32 v68, v72, v0
	v_cvt_pk_bf16_f32 v69, v74, v73
	v_cvt_pk_bf16_f32 v70, v76, v70
	v_cvt_pk_bf16_f32 v71, v75, v71
	global_store_dwordx4 v[2:3], v[68:71], off offset:64 sc1
	s_cbranch_vccz .LBB0_329

.LBB0_329:
	v_cndmask_b32_e64 v3, v64, v65, s[40:41]
	s_addk_i32 s57, 0x80
	s_and_b32 s44, s57, 0x7c0
	v_mov_b32_dpp v3, v3 quad_perm:[1,0,3,2] row_mask:0xf bank_mask:0xf bound_ctrl:1
	v_cndmask_b32_e64 v64, v3, v64, s[40:41]
	v_cndmask_b32_e64 v3, v65, v3, s[40:41]
	v_cndmask_b32_e64 v65, v66, v67, s[40:41]
	v_or_b32_e32 v0, s44, v235
	s_ashr_i32 s44, s57, 9
	v_mov_b32_dpp v65, v65 quad_perm:[1,0,3,2] row_mask:0xf bank_mask:0xf bound_ctrl:1
	v_cndmask_b32_e64 v66, v65, v66, s[40:41]
	v_cndmask_b32_e64 v65, v67, v65, s[40:41]
	v_cndmask_b32_e64 v67, v64, v66, s[42:43]
	s_and_b32 s44, s44, 0x1fffffc
	s_or_b32 s30, s44, s30
	v_mov_b32_dpp v67, v67 quad_perm:[2,3,0,1] row_mask:0xf bank_mask:0xf bound_ctrl:1
	v_cndmask_b32_e64 v64, v67, v64, s[42:43]
	v_cndmask_b32_e64 v66, v66, v67, s[42:43]
	v_cndmask_b32_e64 v67, v3, v65, s[42:43]
	v_lshl_or_b32 v2, s30, 7, v236
	v_lshlrev_b32_e32 v0, 1, v0
	v_mov_b32_dpp v67, v67 quad_perm:[2,3,0,1] row_mask:0xf bank_mask:0xf bound_ctrl:1
	v_cndmask_b32_e64 v3, v67, v3, s[42:43]
	v_cndmask_b32_e64 v65, v65, v67, s[42:43]
	v_cndmask_b32_e64 v67, v60, v61, s[40:41]
	s_nop 1
	v_mov_b32_dpp v67, v67 quad_perm:[1,0,3,2] row_mask:0xf bank_mask:0xf bound_ctrl:1
	v_cndmask_b32_e64 v60, v67, v60, s[40:41]
	v_cndmask_b32_e64 v61, v61, v67, s[40:41]
	v_cndmask_b32_e64 v67, v62, v63, s[40:41]
	s_nop 1
	v_mov_b32_dpp v67, v67 quad_perm:[1,0,3,2] row_mask:0xf bank_mask:0xf bound_ctrl:1
	v_cndmask_b32_e64 v62, v67, v62, s[40:41]
	v_cndmask_b32_e64 v63, v63, v67, s[40:41]
	v_cndmask_b32_e64 v67, v60, v62, s[42:43]
	s_nop 1
	v_mov_b32_dpp v67, v67 quad_perm:[2,3,0,1] row_mask:0xf bank_mask:0xf bound_ctrl:1
	v_cndmask_b32_e64 v68, v67, v60, s[42:43]
	v_cndmask_b32_e64 v60, v61, v63, s[42:43]
	v_cndmask_b32_e64 v67, v62, v67, s[42:43]
	s_nop 0
	v_mov_b32_dpp v60, v60 quad_perm:[2,3,0,1] row_mask:0xf bank_mask:0xf bound_ctrl:1
	v_cndmask_b32_e64 v62, v60, v61, s[42:43]
	v_cndmask_b32_e64 v63, v63, v60, s[42:43]
	v_cvt_pk_bf16_f32 v60, v64, v3
	v_ashrrev_i32_e32 v3, 31, v2
	v_cvt_pk_bf16_f32 v61, v66, v65
	v_lshlrev_b64 v[64:65], 12, v[2:3]
	v_cndmask_b32_e64 v3, v56, v57, s[40:41]
	v_lshl_add_u64 v[64:65], s[28:29], 0, v[64:65]
	v_lshl_add_u64 v[64:65], v[64:65], 0, v[0:1]
	v_mov_b32_dpp v3, v3 quad_perm:[1,0,3,2] row_mask:0xf bank_mask:0xf bound_ctrl:1
	v_cndmask_b32_e64 v56, v3, v56, s[40:41]
	v_cndmask_b32_e64 v3, v57, v3, s[40:41]
	v_cndmask_b32_e64 v57, v58, v59, s[40:41]
	v_cvt_pk_bf16_f32 v62, v68, v62
	v_cvt_pk_bf16_f32 v63, v67, v63
	global_store_dwordx4 v[64:65], v[60:63], off sc1
	s_nop 0
	v_mov_b32_dpp v57, v57 quad_perm:[1,0,3,2] row_mask:0xf bank_mask:0xf bound_ctrl:1
	v_cndmask_b32_e64 v58, v57, v58, s[40:41]
	v_cndmask_b32_e64 v57, v59, v57, s[40:41]
	v_cndmask_b32_e64 v59, v56, v58, s[42:43]
	s_nop 1
	v_mov_b32_dpp v59, v59 quad_perm:[2,3,0,1] row_mask:0xf bank_mask:0xf bound_ctrl:1
	v_cndmask_b32_e64 v56, v59, v56, s[42:43]
	v_cndmask_b32_e64 v58, v58, v59, s[42:43]
	v_cndmask_b32_e64 v59, v3, v57, s[42:43]
	s_nop 1
	v_mov_b32_dpp v59, v59 quad_perm:[2,3,0,1] row_mask:0xf bank_mask:0xf bound_ctrl:1
	v_cndmask_b32_e64 v3, v59, v3, s[42:43]
	v_cndmask_b32_e64 v57, v57, v59, s[42:43]
	v_cndmask_b32_e64 v59, v52, v53, s[40:41]
	s_nop 1
	v_mov_b32_dpp v59, v59 quad_perm:[1,0,3,2] row_mask:0xf bank_mask:0xf bound_ctrl:1
	v_cndmask_b32_e64 v52, v59, v52, s[40:41]
	v_cndmask_b32_e64 v53, v53, v59, s[40:41]
	v_cndmask_b32_e64 v59, v54, v55, s[40:41]
	s_nop 1
	v_mov_b32_dpp v59, v59 quad_perm:[1,0,3,2] row_mask:0xf bank_mask:0xf bound_ctrl:1
	v_cndmask_b32_e64 v54, v59, v54, s[40:41]
	v_cndmask_b32_e64 v55, v55, v59, s[40:41]
	v_cndmask_b32_e64 v59, v52, v54, s[42:43]
	s_nop 1
	v_mov_b32_dpp v59, v59 quad_perm:[2,3,0,1] row_mask:0xf bank_mask:0xf bound_ctrl:1
	v_cndmask_b32_e64 v60, v59, v52, s[42:43]
	v_cndmask_b32_e64 v52, v53, v55, s[42:43]
	v_cndmask_b32_e64 v59, v54, v59, s[42:43]
	s_nop 0
	v_mov_b32_dpp v52, v52 quad_perm:[2,3,0,1] row_mask:0xf bank_mask:0xf bound_ctrl:1
	v_cndmask_b32_e64 v54, v52, v53, s[42:43]
	v_cndmask_b32_e64 v55, v55, v52, s[42:43]
	v_cvt_pk_bf16_f32 v52, v56, v3
	v_cndmask_b32_e64 v3, v48, v49, s[40:41]
	v_or_b32_e32 v56, 4, v2
	v_cvt_pk_bf16_f32 v53, v58, v57
	v_ashrrev_i32_e32 v57, 31, v56
	v_mov_b32_dpp v3, v3 quad_perm:[1,0,3,2] row_mask:0xf bank_mask:0xf bound_ctrl:1
	v_cndmask_b32_e64 v48, v3, v48, s[40:41]
	v_cndmask_b32_e64 v3, v49, v3, s[40:41]
	v_cndmask_b32_e64 v49, v50, v51, s[40:41]
	v_lshlrev_b64 v[56:57], 12, v[56:57]
	v_lshl_add_u64 v[56:57], s[28:29], 0, v[56:57]
	v_mov_b32_dpp v49, v49 quad_perm:[1,0,3,2] row_mask:0xf bank_mask:0xf bound_ctrl:1
	v_cndmask_b32_e64 v50, v49, v50, s[40:41]
	v_cndmask_b32_e64 v49, v51, v49, s[40:41]
	v_cndmask_b32_e64 v51, v48, v50, s[42:43]
	v_lshl_add_u64 v[56:57], v[56:57], 0, v[0:1]
	v_cvt_pk_bf16_f32 v54, v60, v54
	v_cvt_pk_bf16_f32 v55, v59, v55
	global_store_dwordx4 v[56:57], v[52:55], off sc1
	v_mov_b32_dpp v51, v51 quad_perm:[2,3,0,1] row_mask:0xf bank_mask:0xf bound_ctrl:1
	v_cndmask_b32_e64 v48, v51, v48, s[42:43]
	v_cndmask_b32_e64 v50, v50, v51, s[42:43]
	v_cndmask_b32_e64 v51, v3, v49, s[42:43]
	v_or_b32_e32 v52, 0x80, v2
	v_or_b32_e32 v2, 0x84, v2
	v_mov_b32_dpp v51, v51 quad_perm:[2,3,0,1] row_mask:0xf bank_mask:0xf bound_ctrl:1
	v_cndmask_b32_e64 v3, v51, v3, s[42:43]
	v_cndmask_b32_e64 v49, v49, v51, s[42:43]
	v_cndmask_b32_e64 v51, v44, v45, s[40:41]
	s_nop 1
	v_mov_b32_dpp v51, v51 quad_perm:[1,0,3,2] row_mask:0xf bank_mask:0xf bound_ctrl:1
	v_cndmask_b32_e64 v44, v51, v44, s[40:41]
	v_cndmask_b32_e64 v45, v45, v51, s[40:41]
	v_cndmask_b32_e64 v51, v46, v47, s[40:41]
	s_nop 1
	v_mov_b32_dpp v51, v51 quad_perm:[1,0,3,2] row_mask:0xf bank_mask:0xf bound_ctrl:1
	v_cndmask_b32_e64 v46, v51, v46, s[40:41]
	v_cndmask_b32_e64 v47, v47, v51, s[40:41]
	v_cndmask_b32_e64 v51, v44, v46, s[42:43]
	s_nop 1
	v_mov_b32_dpp v51, v51 quad_perm:[2,3,0,1] row_mask:0xf bank_mask:0xf bound_ctrl:1
	v_cndmask_b32_e64 v53, v51, v44, s[42:43]
	v_cndmask_b32_e64 v44, v45, v47, s[42:43]
	v_cndmask_b32_e64 v51, v46, v51, s[42:43]
	s_nop 0
	v_mov_b32_dpp v44, v44 quad_perm:[2,3,0,1] row_mask:0xf bank_mask:0xf bound_ctrl:1
	v_cndmask_b32_e64 v46, v44, v45, s[42:43]
	v_cndmask_b32_e64 v47, v47, v44, s[42:43]
	v_cvt_pk_bf16_f32 v44, v48, v3
	v_cndmask_b32_e64 v3, v40, v41, s[40:41]
	v_cvt_pk_bf16_f32 v45, v50, v49
	v_cvt_pk_bf16_f32 v46, v53, v46
	v_ashrrev_i32_e32 v53, 31, v52
	v_lshlrev_b64 v[48:49], 12, v[52:53]
	v_mov_b32_dpp v3, v3 quad_perm:[1,0,3,2] row_mask:0xf bank_mask:0xf bound_ctrl:1
	v_cndmask_b32_e64 v40, v3, v40, s[40:41]
	v_cndmask_b32_e64 v3, v41, v3, s[40:41]
	v_cndmask_b32_e64 v41, v42, v43, s[40:41]
	v_lshl_add_u64 v[48:49], s[28:29], 0, v[48:49]
	v_lshl_add_u64 v[48:49], v[48:49], 0, v[0:1]
	v_mov_b32_dpp v41, v41 quad_perm:[1,0,3,2] row_mask:0xf bank_mask:0xf bound_ctrl:1
	v_cndmask_b32_e64 v42, v41, v42, s[40:41]
	v_cndmask_b32_e64 v41, v43, v41, s[40:41]
	v_cndmask_b32_e64 v43, v40, v42, s[42:43]
	v_cvt_pk_bf16_f32 v47, v51, v47
	global_store_dwordx4 v[48:49], v[44:47], off sc1
	s_nop 0
	v_mov_b32_dpp v43, v43 quad_perm:[2,3,0,1] row_mask:0xf bank_mask:0xf bound_ctrl:1
	v_cndmask_b32_e64 v40, v43, v40, s[42:43]
	v_cndmask_b32_e64 v42, v42, v43, s[42:43]
	v_cndmask_b32_e64 v43, v3, v41, s[42:43]
	s_nop 1
	v_mov_b32_dpp v43, v43 quad_perm:[2,3,0,1] row_mask:0xf bank_mask:0xf bound_ctrl:1
	v_cndmask_b32_e64 v3, v43, v3, s[42:43]
	v_cndmask_b32_e64 v41, v41, v43, s[42:43]
	v_cndmask_b32_e64 v43, v36, v37, s[40:41]
	s_nop 1
	v_mov_b32_dpp v43, v43 quad_perm:[1,0,3,2] row_mask:0xf bank_mask:0xf bound_ctrl:1
	v_cndmask_b32_e64 v36, v43, v36, s[40:41]
	v_cndmask_b32_e64 v37, v37, v43, s[40:41]
	v_cndmask_b32_e64 v43, v38, v39, s[40:41]
	s_nop 1
	v_mov_b32_dpp v43, v43 quad_perm:[1,0,3,2] row_mask:0xf bank_mask:0xf bound_ctrl:1
	v_cndmask_b32_e64 v38, v43, v38, s[40:41]
	v_cndmask_b32_e64 v39, v39, v43, s[40:41]
	v_cndmask_b32_e64 v43, v36, v38, s[42:43]
	s_nop 1
	v_mov_b32_dpp v43, v43 quad_perm:[2,3,0,1] row_mask:0xf bank_mask:0xf bound_ctrl:1
	v_cndmask_b32_e64 v44, v43, v36, s[42:43]
	v_cndmask_b32_e64 v36, v37, v39, s[42:43]
	v_cndmask_b32_e64 v43, v38, v43, s[42:43]
	s_nop 0
	v_mov_b32_dpp v36, v36 quad_perm:[2,3,0,1] row_mask:0xf bank_mask:0xf bound_ctrl:1
	v_cndmask_b32_e64 v38, v36, v37, s[42:43]
	v_cndmask_b32_e64 v39, v39, v36, s[42:43]
	v_cvt_pk_bf16_f32 v36, v40, v3
	v_ashrrev_i32_e32 v3, 31, v2
	v_lshlrev_b64 v[2:3], 12, v[2:3]
	v_lshl_add_u64 v[2:3], s[28:29], 0, v[2:3]
	v_cvt_pk_bf16_f32 v37, v42, v41
	v_lshl_add_u64 v[40:41], v[2:3], 0, v[0:1]
	v_cndmask_b32_e64 v0, v32, v33, s[40:41]
	v_cndmask_b32_e64 v3, v34, v35, s[40:41]
	v_cvt_pk_bf16_f32 v38, v44, v38
	v_cvt_pk_bf16_f32 v39, v43, v39
	global_store_dwordx4 v[40:41], v[36:39], off sc1
	v_mov_b32_dpp v0, v0 quad_perm:[1,0,3,2] row_mask:0xf bank_mask:0xf bound_ctrl:1
	v_mov_b32_dpp v3, v3 quad_perm:[1,0,3,2] row_mask:0xf bank_mask:0xf bound_ctrl:1
	v_cndmask_b32_e64 v2, v0, v32, s[40:41]
	v_cndmask_b32_e64 v32, v3, v34, s[40:41]
	v_cndmask_b32_e64 v0, v33, v0, s[40:41]
	v_cndmask_b32_e64 v33, v2, v32, s[42:43]
	v_cndmask_b32_e64 v3, v35, v3, s[40:41]
	s_nop 0
	v_mov_b32_dpp v33, v33 quad_perm:[2,3,0,1] row_mask:0xf bank_mask:0xf bound_ctrl:1
	v_cndmask_b32_e64 v2, v33, v2, s[42:43]
	v_cndmask_b32_e64 v32, v32, v33, s[42:43]
	v_cndmask_b32_e64 v33, v0, v3, s[42:43]
	s_nop 1
	v_mov_b32_dpp v33, v33 quad_perm:[2,3,0,1] row_mask:0xf bank_mask:0xf bound_ctrl:1
	v_cndmask_b32_e64 v0, v33, v0, s[42:43]
	v_cndmask_b32_e64 v3, v3, v33, s[42:43]
	v_cndmask_b32_e64 v33, v28, v29, s[40:41]
	s_nop 1
	v_mov_b32_dpp v33, v33 quad_perm:[1,0,3,2] row_mask:0xf bank_mask:0xf bound_ctrl:1
	v_cndmask_b32_e64 v28, v33, v28, s[40:41]
	v_cndmask_b32_e64 v29, v29, v33, s[40:41]
	v_cndmask_b32_e64 v33, v30, v31, s[40:41]
	s_nop 1
	v_mov_b32_dpp v33, v33 quad_perm:[1,0,3,2] row_mask:0xf bank_mask:0xf bound_ctrl:1
	v_cndmask_b32_e64 v30, v33, v30, s[40:41]
	v_cndmask_b32_e64 v31, v31, v33, s[40:41]
	v_cndmask_b32_e64 v33, v28, v30, s[42:43]
	s_nop 1
	v_mov_b32_dpp v33, v33 quad_perm:[2,3,0,1] row_mask:0xf bank_mask:0xf bound_ctrl:1
	v_cndmask_b32_e64 v34, v33, v28, s[42:43]
	v_cndmask_b32_e64 v28, v29, v31, s[42:43]
	v_cndmask_b32_e64 v33, v30, v33, s[42:43]
	s_nop 0
	v_mov_b32_dpp v28, v28 quad_perm:[2,3,0,1] row_mask:0xf bank_mask:0xf bound_ctrl:1
	v_cndmask_b32_e64 v30, v28, v29, s[42:43]
	v_cndmask_b32_e64 v31, v31, v28, s[42:43]
	v_cvt_pk_bf16_f32 v28, v2, v0
	v_cvt_pk_bf16_f32 v29, v32, v3
	v_cndmask_b32_e64 v0, v24, v25, s[40:41]
	v_cndmask_b32_e64 v3, v26, v27, s[40:41]
	v_cvt_pk_bf16_f32 v30, v34, v30
	v_cvt_pk_bf16_f32 v31, v33, v31
	global_store_dwordx4 v[64:65], v[28:31], off offset:64 sc1
	v_mov_b32_dpp v0, v0 quad_perm:[1,0,3,2] row_mask:0xf bank_mask:0xf bound_ctrl:1
	v_mov_b32_dpp v3, v3 quad_perm:[1,0,3,2] row_mask:0xf bank_mask:0xf bound_ctrl:1
	v_cndmask_b32_e64 v2, v0, v24, s[40:41]
	v_cndmask_b32_e64 v24, v3, v26, s[40:41]
	v_cndmask_b32_e64 v0, v25, v0, s[40:41]
	v_cndmask_b32_e64 v25, v2, v24, s[42:43]
	v_cndmask_b32_e64 v3, v27, v3, s[40:41]
	s_nop 0
	v_mov_b32_dpp v25, v25 quad_perm:[2,3,0,1] row_mask:0xf bank_mask:0xf bound_ctrl:1
	v_cndmask_b32_e64 v2, v25, v2, s[42:43]
	v_cndmask_b32_e64 v24, v24, v25, s[42:43]
	v_cndmask_b32_e64 v25, v0, v3, s[42:43]
	s_nop 1
	v_mov_b32_dpp v25, v25 quad_perm:[2,3,0,1] row_mask:0xf bank_mask:0xf bound_ctrl:1
	v_cndmask_b32_e64 v0, v25, v0, s[42:43]
	v_cndmask_b32_e64 v3, v3, v25, s[42:43]
	v_cndmask_b32_e64 v25, v20, v21, s[40:41]
	s_nop 1
	v_mov_b32_dpp v25, v25 quad_perm:[1,0,3,2] row_mask:0xf bank_mask:0xf bound_ctrl:1
	v_cndmask_b32_e64 v20, v25, v20, s[40:41]
	v_cndmask_b32_e64 v21, v21, v25, s[40:41]
	v_cndmask_b32_e64 v25, v22, v23, s[40:41]
	s_nop 1
	v_mov_b32_dpp v25, v25 quad_perm:[1,0,3,2] row_mask:0xf bank_mask:0xf bound_ctrl:1
	v_cndmask_b32_e64 v22, v25, v22, s[40:41]
	v_cndmask_b32_e64 v23, v23, v25, s[40:41]
	v_cndmask_b32_e64 v25, v20, v22, s[42:43]
	s_nop 1
	v_mov_b32_dpp v25, v25 quad_perm:[2,3,0,1] row_mask:0xf bank_mask:0xf bound_ctrl:1
	v_cndmask_b32_e64 v26, v25, v20, s[42:43]
	v_cndmask_b32_e64 v20, v21, v23, s[42:43]
	v_cndmask_b32_e64 v25, v22, v25, s[42:43]
	s_nop 0
	v_mov_b32_dpp v20, v20 quad_perm:[2,3,0,1] row_mask:0xf bank_mask:0xf bound_ctrl:1
	v_cndmask_b32_e64 v22, v20, v21, s[42:43]
	v_cndmask_b32_e64 v23, v23, v20, s[42:43]
	v_cvt_pk_bf16_f32 v20, v2, v0
	v_cvt_pk_bf16_f32 v21, v24, v3
	v_cndmask_b32_e64 v0, v16, v17, s[40:41]
	v_cndmask_b32_e64 v3, v18, v19, s[40:41]
	v_cvt_pk_bf16_f32 v22, v26, v22
	v_cvt_pk_bf16_f32 v23, v25, v23
	global_store_dwordx4 v[56:57], v[20:23], off offset:64 sc1
	v_mov_b32_dpp v0, v0 quad_perm:[1,0,3,2] row_mask:0xf bank_mask:0xf bound_ctrl:1
	v_mov_b32_dpp v3, v3 quad_perm:[1,0,3,2] row_mask:0xf bank_mask:0xf bound_ctrl:1
	v_cndmask_b32_e64 v2, v0, v16, s[40:41]
	v_cndmask_b32_e64 v16, v3, v18, s[40:41]
	v_cndmask_b32_e64 v0, v17, v0, s[40:41]
	v_cndmask_b32_e64 v17, v2, v16, s[42:43]
	v_cndmask_b32_e64 v3, v19, v3, s[40:41]
	s_nop 0
	v_mov_b32_dpp v17, v17 quad_perm:[2,3,0,1] row_mask:0xf bank_mask:0xf bound_ctrl:1
	v_cndmask_b32_e64 v2, v17, v2, s[42:43]
	v_cndmask_b32_e64 v16, v16, v17, s[42:43]
	v_cndmask_b32_e64 v17, v0, v3, s[42:43]
	s_nop 1
	v_mov_b32_dpp v17, v17 quad_perm:[2,3,0,1] row_mask:0xf bank_mask:0xf bound_ctrl:1
	v_cndmask_b32_e64 v0, v17, v0, s[42:43]
	v_cndmask_b32_e64 v3, v3, v17, s[42:43]
	v_cndmask_b32_e64 v17, v12, v13, s[40:41]
	s_nop 1
	v_mov_b32_dpp v17, v17 quad_perm:[1,0,3,2] row_mask:0xf bank_mask:0xf bound_ctrl:1
	v_cndmask_b32_e64 v12, v17, v12, s[40:41]
	v_cndmask_b32_e64 v13, v13, v17, s[40:41]
	v_cndmask_b32_e64 v17, v14, v15, s[40:41]
	s_nop 1
	v_mov_b32_dpp v17, v17 quad_perm:[1,0,3,2] row_mask:0xf bank_mask:0xf bound_ctrl:1
	v_cndmask_b32_e64 v14, v17, v14, s[40:41]
	v_cndmask_b32_e64 v15, v15, v17, s[40:41]
	v_cndmask_b32_e64 v17, v12, v14, s[42:43]
	s_nop 1
	v_mov_b32_dpp v17, v17 quad_perm:[2,3,0,1] row_mask:0xf bank_mask:0xf bound_ctrl:1
	v_cndmask_b32_e64 v18, v17, v12, s[42:43]
	v_cndmask_b32_e64 v12, v13, v15, s[42:43]
	v_cndmask_b32_e64 v17, v14, v17, s[42:43]
	s_nop 0
	v_mov_b32_dpp v12, v12 quad_perm:[2,3,0,1] row_mask:0xf bank_mask:0xf bound_ctrl:1
	v_cndmask_b32_e64 v14, v12, v13, s[42:43]
	v_cndmask_b32_e64 v15, v15, v12, s[42:43]
	v_cvt_pk_bf16_f32 v12, v2, v0
	v_cvt_pk_bf16_f32 v13, v16, v3
	v_cndmask_b32_e64 v0, v8, v9, s[40:41]
	v_cndmask_b32_e64 v3, v10, v11, s[40:41]
	v_cvt_pk_bf16_f32 v14, v18, v14
	v_cvt_pk_bf16_f32 v15, v17, v15
	global_store_dwordx4 v[48:49], v[12:15], off offset:64 sc1
	v_mov_b32_dpp v0, v0 quad_perm:[1,0,3,2] row_mask:0xf bank_mask:0xf bound_ctrl:1
	v_mov_b32_dpp v3, v3 quad_perm:[1,0,3,2] row_mask:0xf bank_mask:0xf bound_ctrl:1
	v_cndmask_b32_e64 v2, v0, v8, s[40:41]
	v_cndmask_b32_e64 v8, v3, v10, s[40:41]
	v_cndmask_b32_e64 v0, v9, v0, s[40:41]
	v_cndmask_b32_e64 v9, v2, v8, s[42:43]
	v_cndmask_b32_e64 v3, v11, v3, s[40:41]
	s_nop 0
	v_mov_b32_dpp v9, v9 quad_perm:[2,3,0,1] row_mask:0xf bank_mask:0xf bound_ctrl:1
	v_cndmask_b32_e64 v2, v9, v2, s[42:43]
	v_cndmask_b32_e64 v8, v8, v9, s[42:43]
	v_cndmask_b32_e64 v9, v0, v3, s[42:43]
	s_nop 1
	v_mov_b32_dpp v9, v9 quad_perm:[2,3,0,1] row_mask:0xf bank_mask:0xf bound_ctrl:1
	v_cndmask_b32_e64 v0, v9, v0, s[42:43]
	v_cndmask_b32_e64 v3, v3, v9, s[42:43]
	v_cndmask_b32_e64 v9, v4, v5, s[40:41]
	v_cvt_pk_bf16_f32 v2, v2, v0
	v_cvt_pk_bf16_f32 v3, v8, v3
	s_nop 1
	v_mov_b32_dpp v9, v9 quad_perm:[1,0,3,2] row_mask:0xf bank_mask:0xf bound_ctrl:1
	v_cndmask_b32_e64 v4, v9, v4, s[40:41]
	v_cndmask_b32_e64 v5, v5, v9, s[40:41]
	v_cndmask_b32_e64 v9, v6, v7, s[40:41]
	s_nop 1
	v_mov_b32_dpp v9, v9 quad_perm:[1,0,3,2] row_mask:0xf bank_mask:0xf bound_ctrl:1
	v_cndmask_b32_e64 v6, v9, v6, s[40:41]
	v_cndmask_b32_e64 v7, v7, v9, s[40:41]
	v_cndmask_b32_e64 v9, v4, v6, s[42:43]
	s_nop 1
	v_mov_b32_dpp v9, v9 quad_perm:[2,3,0,1] row_mask:0xf bank_mask:0xf bound_ctrl:1
	v_cndmask_b32_e64 v4, v9, v4, s[42:43]
	v_cndmask_b32_e64 v6, v6, v9, s[42:43]
	v_cndmask_b32_e64 v9, v5, v7, s[42:43]
	s_nop 1
	v_mov_b32_dpp v9, v9 quad_perm:[2,3,0,1] row_mask:0xf bank_mask:0xf bound_ctrl:1
	v_cndmask_b32_e64 v5, v9, v5, s[42:43]
	v_cndmask_b32_e64 v7, v7, v9, s[42:43]
	v_cvt_pk_bf16_f32 v4, v4, v5
	v_cvt_pk_bf16_f32 v5, v6, v7
	global_store_dwordx4 v[40:41], v[2:5], off offset:64 sc1
	s_andn2_b64 vcc, exec, s[76:77]
	s_mov_b64 s[44:45], -1
	s_cbranch_vccnz .LBB0_119
	s_branch .LBB0_327

.LBB0_389:
	s_andn2_b64 vcc, exec, s[26:27]
	s_cbranch_vccnz .LBB0_525
	v_readlane_b32 s98, v241, 45
	s_nop 1
	s_bfe_u32 s98, s98, 0x10003
.Lp2_again:
	s_mov_b64 s[26:27], s[96:97]
	s_load_dwordx2 s[60:61], s[26:27], 0xa8
	v_mov_b32_e32 v0, v224
	s_load_dwordx8 s[40:47], s[26:27], 0x20
	v_xor_b32_e32 v7, 2, v230
	s_waitcnt lgkmcnt(0)
	s_add_u32 s28, s60, 0x5000000
	s_addc_u32 s29, s61, 0
	s_add_u32 s50, s60, 0x8000000
	s_addc_u32 s51, s61, 0
	s_lshl_b32 s8, s86, 6
	v_and_or_b32 v0, v0, 63, s8
	v_lshlrev_b64 v[2:3], 2, v[0:1]
	v_lshl_add_u64 v[4:5], s[40:41], 0, v[2:3]
	global_load_dword v0, v[4:5], off
	v_lshl_add_u64 v[4:5], s[42:43], 0, v[2:3]
	global_load_dword v6, v[4:5], off
	v_lshl_add_u64 v[4:5], s[44:45], 0, v[2:3]
	v_lshl_add_u64 v[2:3], s[46:47], 0, v[2:3]
	global_load_dword v4, v[4:5], off
	v_xor_b32_e32 v5, 1, v230
	global_load_dword v2, v[2:3], off
	v_and_b32_e32 v3, 64, v230
	v_add_u32_e32 v3, 64, v3
	v_cmp_lt_i32_e32 vcc, v5, v3
	v_xor_b32_e32 v8, 4, v230
	v_xor_b32_e32 v9, 8, v230
	v_cndmask_b32_e32 v5, v230, v5, vcc
	v_lshlrev_b32_e32 v5, 2, v5
	v_cmp_lt_i32_e32 vcc, v7, v3
	v_xor_b32_e32 v10, 16, v230
	v_xor_b32_e32 v11, 32, v230
	v_cndmask_b32_e32 v7, v230, v7, vcc
	v_lshlrev_b32_e32 v7, 2, v7
	v_cmp_lt_i32_e32 vcc, v8, v3
	v_readlane_b32 s8, v241, 23
	v_readlane_b32 s9, v241, 24
	s_waitcnt vmcnt(0)
	v_mul_f32_e32 v12, v0, v6
	ds_bpermute_b32 v12, v5, v12
	v_mul_f32_e32 v13, v4, v2
	ds_bpermute_b32 v5, v5, v13
	s_waitcnt lgkmcnt(1)
	v_fmac_f32_e32 v12, v0, v6
	ds_bpermute_b32 v0, v7, v12
	s_waitcnt lgkmcnt(1)
	v_fmac_f32_e32 v5, v4, v2
	ds_bpermute_b32 v2, v7, v5
	v_cndmask_b32_e32 v4, v230, v8, vcc
	v_lshlrev_b32_e32 v4, 2, v4
	s_waitcnt lgkmcnt(1)
	v_add_f32_e32 v0, v12, v0
	v_cmp_lt_i32_e32 vcc, v9, v3
	s_waitcnt lgkmcnt(0)
	v_add_f32_e32 v2, v5, v2
	ds_bpermute_b32 v5, v4, v0
	ds_bpermute_b32 v4, v4, v2
	v_cndmask_b32_e32 v6, v230, v9, vcc
	v_lshlrev_b32_e32 v6, 2, v6
	v_cmp_lt_i32_e32 vcc, v10, v3
	s_waitcnt lgkmcnt(1)
	v_add_f32_e32 v0, v0, v5
	s_waitcnt lgkmcnt(0)
	v_add_f32_e32 v2, v2, v4
	ds_bpermute_b32 v4, v6, v0
	ds_bpermute_b32 v5, v6, v2
	v_cndmask_b32_e32 v6, v230, v10, vcc
	v_lshlrev_b32_e32 v148, 2, v6
	v_cmp_lt_i32_e32 vcc, v11, v3
	s_waitcnt lgkmcnt(1)
	v_add_f32_e32 v0, v0, v4
	s_waitcnt lgkmcnt(0)
	v_add_f32_e32 v2, v2, v5
	ds_bpermute_b32 v4, v148, v0
	ds_bpermute_b32 v5, v148, v2
	v_cndmask_b32_e32 v3, v230, v11, vcc
	v_lshlrev_b32_e32 v149, 2, v3
	s_andn2_b64 vcc, exec, s[8:9]
	s_waitcnt lgkmcnt(1)
	v_add_f32_e32 v0, v0, v4
	s_waitcnt lgkmcnt(0)
	v_add_f32_e32 v2, v2, v5
	ds_bpermute_b32 v3, v149, v0
	ds_bpermute_b32 v4, v149, v2
	s_cbranch_vccnz .LBB0_441
	s_cmp_eq_u32 s98, 1
	s_cbranch_scc1 .LBB0_441
	s_waitcnt lgkmcnt(1)
	v_add_f32_e32 v0, v0, v3
	v_cvt_f32_u32_e32 v3, s86
	s_waitcnt lgkmcnt(0)
	v_add_f32_e32 v2, v2, v4
	s_load_dwordx2 s[8:9], s[26:27], 0x40
	v_mul_f32_e32 v0, 0x3fb8aa3b, v0
	v_mul_f32_e32 v3, 0xbe99999a, v3
	v_mul_f32_e32 v3, 0x3fb8aa3b, v3
	v_mul_f32_e32 v2, 0x3fb8aa3b, v2
	v_exp_f32_e32 v3, v3
	v_exp_f32_e32 v0, v0
	v_exp_f32_e32 v2, v2
	s_add_u32 s40, s60, 0xd000000
	s_addc_u32 s41, s61, 0
	s_lshl_b32 s30, s86, 7
	s_lshl_b64 s[38:39], s[30:31], 2
	v_fmamk_f32 v3, v3, 0xbf19999a, v226
	v_sub_f32_e32 v0, v0, v2
	s_waitcnt lgkmcnt(0)
	s_add_u32 s42, s8, s38
	v_readlane_b32 s13, v241, 45
	v_add_f32_e32 v150, v3, v0
	v_sub_f32_e32 v151, 1.0, v3
	s_addc_u32 s43, s9, s39
	s_mov_b32 s8, s13
	v_readlane_b32 s9, v241, 46
	s_branch .LBB0_393
.LBB0_392:
	s_setprio 0
	ds_bpermute_b32 v0, v148, v162
	s_add_i32 s13, s13, s54
	s_add_i32 s8, s8, s54
	s_waitcnt lgkmcnt(0)
	v_add_f32_e32 v0, v162, v0
	ds_bpermute_b32 v2, v149, v0
	s_waitcnt lgkmcnt(0)
	v_add_f32_e32 v0, v0, v2
	ds_bpermute_b32 v2, v148, v160
	s_waitcnt lgkmcnt(0)
	v_add_f32_e32 v2, v160, v2
	ds_bpermute_b32 v3, v149, v2
	s_waitcnt lgkmcnt(0)
	v_add_f32_e32 v2, v2, v3
	v_div_scale_f32 v3, s[38:39], v0, v0, 1.0
	v_rcp_f32_e32 v36, v3
	s_nop 0
	v_fma_f32 v37, -v3, v36, 1.0
	v_fmac_f32_e32 v36, v37, v36
	v_div_scale_f32 v37, vcc, 1.0, v0, 1.0
	v_mul_f32_e32 v38, v37, v36
	v_fma_f32 v39, -v3, v38, v37
	v_fmac_f32_e32 v38, v39, v36
	v_fma_f32 v3, -v3, v38, v37
	v_div_fmas_f32 v3, v3, v36, v38
	v_div_fixup_f32 v0, v3, v0, 1.0
	v_div_scale_f32 v3, s[38:39], v2, v2, v150
	v_rcp_f32_e32 v36, v3
	s_nop 0
	v_fma_f32 v37, -v3, v36, 1.0
	v_fmac_f32_e32 v36, v37, v36
	v_div_scale_f32 v37, vcc, v150, v2, v150
	v_mul_f32_e32 v38, v37, v36
	v_fma_f32 v39, -v3, v38, v37
	v_fmac_f32_e32 v38, v39, v36
	v_fma_f32 v3, -v3, v38, v37
	v_div_fmas_f32 v3, v3, v36, v38
	v_div_fixup_f32 v2, v3, v2, v150
	v_pk_mul_f32 v[36:37], v[80:81], v[2:3] op_sel_hi:[1,0]
	v_pk_mul_f32 v[38:39], v[82:83], v[2:3] op_sel_hi:[1,0]
	v_pk_fma_f32 v[42:43], v[72:73], v[0:1], v[36:37] op_sel_hi:[1,0,1] neg_lo:[0,0,1] neg_hi:[0,0,1]
	v_pk_mul_f32 v[36:37], v[76:77], v[2:3] op_sel_hi:[1,0]
	v_pk_fma_f32 v[40:41], v[74:75], v[0:1], v[38:39] op_sel_hi:[1,0,1] neg_lo:[0,0,1] neg_hi:[0,0,1]
	v_pk_mul_f32 v[38:39], v[78:79], v[2:3] op_sel_hi:[1,0]
	v_pk_fma_f32 v[46:47], v[68:69], v[0:1], v[36:37] op_sel_hi:[1,0,1] neg_lo:[0,0,1] neg_hi:[0,0,1]
	v_pk_fma_f32 v[44:45], v[70:71], v[0:1], v[38:39] op_sel_hi:[1,0,1] neg_lo:[0,0,1] neg_hi:[0,0,1]
	v_mov_b32_e32 v38, v43
	v_mov_b32_e32 v39, v47
	v_mov_b32_e32 v36, v42
	v_mov_b32_e32 v37, v46
	v_pk_mul_f32 v[38:39], v[38:39], v[38:39]
	v_mov_b32_e32 v52, v41
	v_mov_b32_e32 v53, v45
	v_pk_fma_f32 v[36:37], v[36:37], v[36:37], v[38:39]
	v_mov_b32_e32 v38, v40
	v_mov_b32_e32 v39, v44
	v_pk_mul_f32 v[52:53], v[52:53], v[52:53]
	v_pk_mul_f32 v[56:57], v[56:57], v[2:3] op_sel_hi:[1,0]
	v_pk_fma_f32 v[38:39], v[38:39], v[38:39], v[52:53]
	v_pk_mul_f32 v[58:59], v[58:59], v[2:3] op_sel_hi:[1,0]
	v_pk_add_f32 v[36:37], v[36:37], v[38:39]
	v_pk_mul_f32 v[38:39], v[66:67], v[2:3] op_sel_hi:[1,0]
	v_pk_add_f32 v[52:53], v[36:37], v[36:37] op_sel_hi:[0,1]
	v_pk_mul_f32 v[36:37], v[64:65], v[2:3] op_sel_hi:[1,0]
	v_pk_fma_f32 v[38:39], v[62:63], v[0:1], v[38:39] op_sel_hi:[1,0,1] neg_lo:[0,0,1] neg_hi:[0,0,1]
	v_pk_fma_f32 v[36:37], v[60:61], v[0:1], v[36:37] op_sel_hi:[1,0,1] neg_lo:[0,0,1] neg_hi:[0,0,1]
	v_pk_mul_f32 v[54:55], v[38:39], v[38:39]
	v_pk_mul_f32 v[60:61], v[36:37], v[36:37]
	v_pk_fma_f32 v[32:33], v[32:33], v[0:1], v[56:57] op_sel_hi:[1,0,1] neg_lo:[0,0,1] neg_hi:[0,0,1]
	v_pk_mov_b32 v[62:63], v[60:61], v[54:55] op_sel:[1,0]
	v_mov_b32_e32 v61, v55
	v_pk_fma_f32 v[34:35], v[34:35], v[0:1], v[58:59] op_sel_hi:[1,0,1] neg_lo:[0,0,1] neg_hi:[0,0,1]
	v_mul_f32_e32 v52, v32, v32
	v_pk_add_f32 v[54:55], v[62:63], v[60:61]
	v_pk_fma_f32 v[56:57], v[32:33], v[32:33], v[52:53] op_sel_hi:[1,1,0]
	v_mul_f32_e32 v52, v34, v34
	v_pk_mul_f32 v[28:29], v[28:29], v[2:3] op_sel_hi:[1,0]
	v_pk_mul_f32 v[30:31], v[30:31], v[2:3] op_sel_hi:[1,0]
	v_pk_add_f32 v[54:55], v[54:55], v[54:55] op_sel_hi:[0,1]
	v_pk_fma_f32 v[58:59], v[34:35], v[34:35], v[52:53] op_sel_hi:[1,1,0]
	v_pk_fma_f32 v[26:27], v[26:27], v[0:1], v[30:31] op_sel_hi:[1,0,1] neg_lo:[0,0,1] neg_hi:[0,0,1]
	v_pk_fma_f32 v[24:25], v[24:25], v[0:1], v[28:29] op_sel_hi:[1,0,1] neg_lo:[0,0,1] neg_hi:[0,0,1]
	v_pk_mul_f32 v[22:23], v[22:23], v[2:3] op_sel_hi:[1,0]
	v_pk_mul_f32 v[20:21], v[20:21], v[2:3] op_sel_hi:[1,0]
	v_pk_mul_f32 v[12:13], v[12:13], v[2:3] op_sel_hi:[1,0]
	v_mul_f32_e32 v56, v24, v24
	v_mul_f32_e32 v58, v25, v25
	v_mul_f32_e32 v54, v26, v26
	v_mul_f32_e32 v52, v27, v27
	v_pk_fma_f32 v[16:17], v[16:17], v[0:1], v[20:21] op_sel_hi:[1,0,1] neg_lo:[0,0,1] neg_hi:[0,0,1]
	v_pk_fma_f32 v[20:21], v[18:19], v[0:1], v[22:23] op_sel_hi:[1,0,1] neg_lo:[0,0,1] neg_hi:[0,0,1]
	v_pk_mul_f32 v[14:15], v[14:15], v[2:3] op_sel_hi:[1,0]
	v_pk_fma_f32 v[8:9], v[8:9], v[0:1], v[12:13] op_sel_hi:[1,0,1] neg_lo:[0,0,1] neg_hi:[0,0,1]
	v_pk_add_f32 v[28:29], v[56:57], v[58:59]
	v_pk_add_f32 v[30:31], v[54:55], v[52:53]
	v_pk_mul_f32 v[18:19], v[20:21], v[20:21]
	v_pk_mul_f32 v[22:23], v[16:17], v[16:17]
	v_pk_fma_f32 v[10:11], v[10:11], v[0:1], v[14:15] op_sel_hi:[1,0,1] neg_lo:[0,0,1] neg_hi:[0,0,1]
	v_mul_f32_e32 v12, v8, v8
	v_pk_add_f32 v[28:29], v[28:29], v[30:31]
	v_pk_mov_b32 v[30:31], v[22:23], v[18:19] op_sel:[1,0]
	v_mov_b32_e32 v23, v19
	v_pk_fma_f32 v[14:15], v[8:9], v[8:9], v[12:13] op_sel_hi:[1,1,0]
	v_mul_f32_e32 v12, v10, v10
	v_pk_add_f32 v[18:19], v[30:31], v[22:23]
	v_pk_fma_f32 v[22:23], v[10:11], v[10:11], v[12:13] op_sel_hi:[1,1,0]
	v_pk_mul_f32 v[12:13], v[48:49], v[2:3] op_sel_hi:[1,0]
	v_pk_mul_f32 v[2:3], v[50:51], v[2:3] op_sel_hi:[1,0]
	v_pk_add_f32 v[28:29], v[28:29], v[28:29] op_sel_hi:[0,1]
	v_pk_add_f32 v[18:19], v[18:19], v[18:19] op_sel_hi:[0,1]
	v_pk_fma_f32 v[6:7], v[6:7], v[0:1], v[2:3] op_sel_hi:[1,0,1] neg_lo:[0,0,1] neg_hi:[0,0,1]
	v_pk_fma_f32 v[12:13], v[4:5], v[0:1], v[12:13] op_sel_hi:[1,0,1] neg_lo:[0,0,1] neg_hi:[0,0,1]
	v_mul_f32_e32 v18, v6, v6
	v_mul_f32_e32 v14, v12, v12
	v_mul_f32_e32 v22, v13, v13
	v_mul_f32_e32 v28, v7, v7
	v_pk_add_f32 v[2:3], v[14:15], v[22:23]
	v_pk_add_f32 v[4:5], v[18:19], v[28:29]
	s_nop 0
	v_pk_add_f32 v[2:3], v[2:3], v[4:5]
	s_nop 0
	v_add_f32_e32 v0, v2, v3
	ds_bpermute_b32 v2, v148, v0
	s_waitcnt lgkmcnt(0)
	v_add_f32_e32 v0, v0, v2
	ds_bpermute_b32 v2, v149, v0
	s_waitcnt lgkmcnt(0)
	v_add_f32_e32 v0, v0, v2
	v_fmamk_f32 v0, v0, 0x3c000000, v227
	v_cmp_gt_f32_e32 vcc, s7, v0
	v_mul_f32_e32 v2, 0x4f800000, v0
	s_nop 0
	v_cndmask_b32_e32 v0, v0, v2, vcc
	v_sqrt_f32_e32 v2, v0
	s_nop 0
	v_add_u32_e32 v3, -1, v2
	v_fma_f32 v4, -v3, v2, v0
	v_cmp_ge_f32_e64 s[38:39], 0, v4
	v_add_u32_e32 v4, 1, v2
	s_nop 0
	v_cndmask_b32_e64 v3, v2, v3, s[38:39]
	v_fma_f32 v2, -v4, v2, v0
	v_cmp_lt_f32_e64 s[38:39], 0, v2
	s_nop 1
	v_cndmask_b32_e64 v2, v3, v4, s[38:39]
	v_mul_f32_e32 v3, 0x37800000, v2
	v_cndmask_b32_e32 v2, v2, v3, vcc
	v_cmp_class_f32_e32 vcc, v0, v228
	s_nop 1
	v_cndmask_b32_e32 v0, v2, v0, vcc
	v_div_scale_f32 v2, s[38:39], v0, v0, v151
	v_rcp_f32_e32 v3, v2
	s_nop 0
	v_fma_f32 v4, -v2, v3, 1.0
	v_fmac_f32_e32 v3, v4, v3
	v_div_scale_f32 v4, vcc, v151, v0, v151
	v_mul_f32_e32 v5, v4, v3
	v_fma_f32 v14, -v2, v5, v4
	v_fmac_f32_e32 v5, v14, v3
	v_fma_f32 v2, -v2, v5, v4
	v_div_fmas_f32 v2, v2, v3, v5
	v_div_fixup_f32 v18, v2, v0, v151
	v_and_b32_e32 v0, 16, v153
	v_lshrrev_b32_e32 v2, 2, v153
	v_and_or_b32 v0, v2, 8, v0
	v_mov_b64_e32 v[2:3], s[50:51]
	v_mad_u64_u32 v[2:3], s[38:39], v136, s21, v[2:3]
	v_mad_i32_i24 v3, v137, s21, v3
	v_lshl_add_u64 v[2:3], v[2:3], 0, s[30:31]
	v_lshlrev_b32_e32 v0, 1, v0
	v_lshl_add_u64 v[22:23], v[2:3], 0, v[0:1]
	v_lshl_add_u64 v[14:15], v[138:139], 0, v[0:1]
	v_lshlrev_b32_e32 v0, 4, v152
	global_load_dwordx4 v[2:5], v[22:23], off offset:1024
	global_load_dwordx4 v[28:31], v0, s[42:43]
	global_load_dwordx4 v[48:51], v0, s[42:43] offset:64
	v_pk_mul_f32 v[40:41], v[40:41], v[18:19] op_sel_hi:[1,0]
	v_pk_mul_f32 v[42:43], v[42:43], v[18:19] op_sel_hi:[1,0]
	v_readlane_b32 s38, v241, 60
	s_add_i32 s9, s9, s38
	s_cmpk_gt_i32 s13, 0xff
	v_readlane_b32 s39, v241, 61
	s_waitcnt vmcnt(0)
	v_pk_mul_f32 v[30:31], v[30:31], v[40:41]
	v_pk_mul_f32 v[40:41], v[46:47], v[18:19] op_sel_hi:[1,0]
	v_pk_mul_f32 v[28:29], v[28:29], v[42:43]
	v_pk_mul_f32 v[40:41], v[48:49], v[40:41]
	v_pk_mul_f32 v[42:43], v[44:45], v[18:19] op_sel_hi:[1,0]
	s_nop 0
	v_permlane16_swap_b32_e32 v28, v40
	v_permlane16_swap_b32_e32 v29, v41
	v_lshlrev_b32_e32 v19, 16, v2
	v_and_b32_e32 v2, 0xffff0000, v2
	v_pk_mul_f32 v[42:43], v[50:51], v[42:43]
	v_mul_f32_e32 v19, v19, v28
	v_mul_f32_e32 v2, v2, v29
	v_permlane16_swap_b32_e32 v30, v42
	v_permlane16_swap_b32_e32 v31, v43
	v_cvt_pk_bf16_f32 v2, v19, v2
	v_lshlrev_b32_e32 v19, 16, v3
	v_and_b32_e32 v3, 0xffff0000, v3
	v_mul_f32_e32 v19, v19, v30
	v_mul_f32_e32 v3, v3, v31
	v_cvt_pk_bf16_f32 v3, v19, v3
	v_lshlrev_b32_e32 v19, 16, v4
	v_and_b32_e32 v4, 0xffff0000, v4
	v_mul_f32_e32 v19, v19, v40
	v_mul_f32_e32 v4, v4, v41
	v_cvt_pk_bf16_f32 v4, v19, v4
	v_lshlrev_b32_e32 v19, 16, v5
	v_and_b32_e32 v5, 0xffff0000, v5
	v_mul_f32_e32 v5, v5, v43
	v_mul_f32_e32 v19, v19, v42
	v_cvt_pk_bf16_f32 v5, v19, v5
	global_store_dwordx4 v[14:15], v[2:5], off sc1
	global_load_dwordx4 v[2:5], v[22:23], off offset:1088
	s_nop 0
	global_load_dwordx4 v[28:31], v0, s[42:43] offset:128
	global_load_dwordx4 v[40:43], v0, s[42:43] offset:192
	v_pk_mul_f32 v[36:37], v[36:37], v[18:19] op_sel_hi:[1,0]
	v_pk_mul_f32 v[32:33], v[32:33], v[18:19] op_sel_hi:[1,0]
	v_pk_mul_f32 v[38:39], v[38:39], v[18:19] op_sel_hi:[1,0]
	v_pk_mul_f32 v[34:35], v[34:35], v[18:19] op_sel_hi:[1,0]
	s_waitcnt vmcnt(2)
	v_lshlrev_b32_e32 v19, 16, v2
	s_waitcnt vmcnt(1)
	v_pk_mul_f32 v[28:29], v[28:29], v[36:37]
	s_waitcnt vmcnt(0)
	v_pk_mul_f32 v[32:33], v[40:41], v[32:33]
	v_and_b32_e32 v2, 0xffff0000, v2
	s_nop 0
	v_permlane16_swap_b32_e32 v28, v32
	v_permlane16_swap_b32_e32 v29, v33
	v_pk_mul_f32 v[30:31], v[30:31], v[38:39]
	v_pk_mul_f32 v[34:35], v[42:43], v[34:35]
	v_mul_f32_e32 v19, v19, v28
	v_mul_f32_e32 v2, v2, v29
	v_permlane16_swap_b32_e32 v30, v34
	v_permlane16_swap_b32_e32 v31, v35
	v_cvt_pk_bf16_f32 v2, v19, v2
	v_lshlrev_b32_e32 v19, 16, v3
	v_and_b32_e32 v3, 0xffff0000, v3
	v_mul_f32_e32 v19, v19, v30
	v_mul_f32_e32 v3, v3, v31
	v_cvt_pk_bf16_f32 v3, v19, v3
	v_lshlrev_b32_e32 v19, 16, v4
	v_and_b32_e32 v4, 0xffff0000, v4
	v_mul_f32_e32 v19, v19, v32
	v_mul_f32_e32 v4, v4, v33
	v_cvt_pk_bf16_f32 v4, v19, v4
	v_lshlrev_b32_e32 v19, 16, v5
	v_and_b32_e32 v5, 0xffff0000, v5
	v_mul_f32_e32 v5, v5, v35
	v_mul_f32_e32 v19, v19, v34
	v_cvt_pk_bf16_f32 v5, v19, v5
	global_store_dwordx4 v[14:15], v[2:5], off offset:64 sc1
	global_load_dwordx4 v[2:5], v[22:23], off offset:1152
	s_nop 0
	global_load_dwordx4 v[28:31], v0, s[42:43] offset:256
	global_load_dwordx4 v[32:35], v0, s[42:43] offset:320
	v_pk_mul_f32 v[24:25], v[24:25], v[18:19] op_sel_hi:[1,0]
	v_pk_mul_f32 v[16:17], v[16:17], v[18:19] op_sel_hi:[1,0]
	v_pk_mul_f32 v[26:27], v[26:27], v[18:19] op_sel_hi:[1,0]
	v_pk_mul_f32 v[20:21], v[20:21], v[18:19] op_sel_hi:[1,0]
	s_waitcnt vmcnt(2)
	v_lshlrev_b32_e32 v19, 16, v2
	s_waitcnt vmcnt(1)
	v_pk_mul_f32 v[24:25], v[24:25], v[28:29]
	s_waitcnt vmcnt(0)
	v_pk_mul_f32 v[16:17], v[16:17], v[32:33]
	v_and_b32_e32 v2, 0xffff0000, v2
	s_nop 0
	v_permlane16_swap_b32_e32 v24, v16
	v_permlane16_swap_b32_e32 v25, v17
	v_pk_mul_f32 v[26:27], v[26:27], v[30:31]
	v_pk_mul_f32 v[20:21], v[20:21], v[34:35]
	v_mul_f32_e32 v19, v19, v24
	v_mul_f32_e32 v2, v2, v25
	v_permlane16_swap_b32_e32 v26, v20
	v_permlane16_swap_b32_e32 v27, v21
	v_cvt_pk_bf16_f32 v2, v19, v2
	v_lshlrev_b32_e32 v19, 16, v3
	v_and_b32_e32 v3, 0xffff0000, v3
	v_mul_f32_e32 v19, v19, v26
	v_mul_f32_e32 v3, v3, v27
	v_cvt_pk_bf16_f32 v3, v19, v3
	v_lshlrev_b32_e32 v19, 16, v4
	v_and_b32_e32 v4, 0xffff0000, v4
	v_mul_f32_e32 v16, v19, v16
	v_mul_f32_e32 v4, v4, v17
	v_cvt_pk_bf16_f32 v4, v16, v4
	v_lshlrev_b32_e32 v16, 16, v5
	v_and_b32_e32 v5, 0xffff0000, v5
	v_mul_f32_e32 v5, v5, v21
	v_mul_f32_e32 v16, v16, v20
	v_cvt_pk_bf16_f32 v5, v16, v5
	global_store_dwordx4 v[14:15], v[2:5], off offset:128 sc1
	global_load_dwordx4 v[2:5], v[22:23], off offset:1216
	s_nop 0
	global_load_dwordx4 v[20:23], v0, s[42:43] offset:384
	global_load_dwordx4 v[24:27], v0, s[42:43] offset:448
	v_pk_mul_f32 v[8:9], v[8:9], v[18:19] op_sel_hi:[1,0]
	v_pk_mul_f32 v[12:13], v[12:13], v[18:19] op_sel_hi:[1,0]
	v_pk_mul_f32 v[10:11], v[10:11], v[18:19] op_sel_hi:[1,0]
	v_pk_mul_f32 v[6:7], v[6:7], v[18:19] op_sel_hi:[1,0]
	s_waitcnt vmcnt(2)
	v_lshlrev_b32_e32 v0, 16, v2
	s_waitcnt vmcnt(1)
	v_pk_mul_f32 v[8:9], v[8:9], v[20:21]
	s_waitcnt vmcnt(0)
	v_pk_mul_f32 v[12:13], v[12:13], v[24:25]
	v_and_b32_e32 v2, 0xffff0000, v2
	s_nop 0
	v_permlane16_swap_b32_e32 v8, v12
	v_permlane16_swap_b32_e32 v9, v13
	v_pk_mul_f32 v[10:11], v[10:11], v[22:23]
	v_pk_mul_f32 v[6:7], v[6:7], v[26:27]
	v_mul_f32_e32 v0, v0, v8
	v_mul_f32_e32 v2, v2, v9
	v_permlane16_swap_b32_e32 v10, v6
	v_permlane16_swap_b32_e32 v11, v7
	v_cvt_pk_bf16_f32 v2, v0, v2
	v_lshlrev_b32_e32 v0, 16, v3
	v_and_b32_e32 v3, 0xffff0000, v3
	v_mul_f32_e32 v0, v0, v10
	v_mul_f32_e32 v3, v3, v11
	v_cvt_pk_bf16_f32 v3, v0, v3
	v_lshlrev_b32_e32 v0, 16, v4
	v_and_b32_e32 v4, 0xffff0000, v4
	v_mul_f32_e32 v0, v0, v12
	v_mul_f32_e32 v4, v4, v13
	v_cvt_pk_bf16_f32 v4, v0, v4
	v_lshlrev_b32_e32 v0, 16, v5
	v_and_b32_e32 v5, 0xffff0000, v5
	v_mul_f32_e32 v5, v5, v7
	v_mul_f32_e32 v0, v0, v6
	v_cvt_pk_bf16_f32 v5, v0, v5
	global_store_dwordx4 v[14:15], v[2:5], off offset:192 sc1
	s_cbranch_scc1 .LBB0_441

.LBB0_417:
	s_setprio 0
	ds_bpermute_b32 v0, v148, v162
	s_waitcnt lgkmcnt(0)
	v_add_f32_e32 v0, v162, v0
	ds_bpermute_b32 v2, v149, v0
	s_waitcnt lgkmcnt(0)
	v_add_f32_e32 v0, v0, v2
	ds_bpermute_b32 v2, v148, v160
	s_waitcnt lgkmcnt(0)
	v_add_f32_e32 v2, v160, v2
	ds_bpermute_b32 v3, v149, v2
	s_waitcnt lgkmcnt(0)
	v_add_f32_e32 v2, v2, v3
	v_div_scale_f32 v3, s[38:39], v0, v0, 1.0
	v_rcp_f32_e32 v28, v3
	s_nop 0
	v_fma_f32 v29, -v3, v28, 1.0
	v_fmac_f32_e32 v28, v29, v28
	v_div_scale_f32 v29, vcc, 1.0, v0, 1.0
	v_mul_f32_e32 v30, v29, v28
	v_fma_f32 v31, -v3, v30, v29
	v_fmac_f32_e32 v30, v31, v28
	v_fma_f32 v3, -v3, v30, v29
	v_div_fmas_f32 v3, v3, v28, v30
	v_div_fixup_f32 v0, v3, v0, 1.0
	v_div_scale_f32 v3, s[38:39], v2, v2, v150
	v_rcp_f32_e32 v28, v3
	s_nop 0
	v_fma_f32 v29, -v3, v28, 1.0
	v_fmac_f32_e32 v28, v29, v28
	v_div_scale_f32 v29, vcc, v150, v2, v150
	v_mul_f32_e32 v30, v29, v28
	v_fma_f32 v31, -v3, v30, v29
	v_fmac_f32_e32 v30, v31, v28
	v_fma_f32 v3, -v3, v30, v29
	v_div_fmas_f32 v3, v3, v28, v30
	v_div_fixup_f32 v2, v3, v2, v150
	v_pk_mul_f32 v[28:29], v[80:81], v[2:3] op_sel_hi:[1,0]
	v_pk_mul_f32 v[30:31], v[82:83], v[2:3] op_sel_hi:[1,0]
	v_pk_fma_f32 v[38:39], v[72:73], v[0:1], v[28:29] op_sel_hi:[1,0,1] neg_lo:[0,0,1] neg_hi:[0,0,1]
	v_pk_mul_f32 v[28:29], v[76:77], v[2:3] op_sel_hi:[1,0]
	v_pk_fma_f32 v[36:37], v[74:75], v[0:1], v[30:31] op_sel_hi:[1,0,1] neg_lo:[0,0,1] neg_hi:[0,0,1]
	v_pk_mul_f32 v[30:31], v[78:79], v[2:3] op_sel_hi:[1,0]
	v_pk_fma_f32 v[42:43], v[68:69], v[0:1], v[28:29] op_sel_hi:[1,0,1] neg_lo:[0,0,1] neg_hi:[0,0,1]
	v_pk_fma_f32 v[40:41], v[70:71], v[0:1], v[30:31] op_sel_hi:[1,0,1] neg_lo:[0,0,1] neg_hi:[0,0,1]
	v_mov_b32_e32 v30, v39
	v_mov_b32_e32 v31, v43
	v_mov_b32_e32 v28, v38
	v_mov_b32_e32 v29, v42
	v_pk_mul_f32 v[30:31], v[30:31], v[30:31]
	v_mov_b32_e32 v32, v37
	v_mov_b32_e32 v33, v41
	v_pk_fma_f32 v[28:29], v[28:29], v[28:29], v[30:31]
	v_mov_b32_e32 v30, v36
	v_mov_b32_e32 v31, v40
	v_pk_mul_f32 v[32:33], v[32:33], v[32:33]
	v_pk_mul_f32 v[44:45], v[44:45], v[2:3] op_sel_hi:[1,0]
	v_pk_fma_f32 v[30:31], v[30:31], v[30:31], v[32:33]
	v_pk_mul_f32 v[46:47], v[46:47], v[2:3] op_sel_hi:[1,0]
	v_pk_add_f32 v[28:29], v[28:29], v[30:31]
	v_pk_mul_f32 v[30:31], v[66:67], v[2:3] op_sel_hi:[1,0]
	v_pk_add_f32 v[68:69], v[28:29], v[28:29] op_sel_hi:[0,1]
	v_pk_mul_f32 v[28:29], v[64:65], v[2:3] op_sel_hi:[1,0]
	v_pk_fma_f32 v[30:31], v[62:63], v[0:1], v[30:31] op_sel_hi:[1,0,1] neg_lo:[0,0,1] neg_hi:[0,0,1]
	v_pk_fma_f32 v[28:29], v[60:61], v[0:1], v[28:29] op_sel_hi:[1,0,1] neg_lo:[0,0,1] neg_hi:[0,0,1]
	v_pk_mul_f32 v[32:33], v[30:31], v[30:31]
	v_pk_mul_f32 v[34:35], v[28:29], v[28:29]
	v_pk_fma_f32 v[26:27], v[26:27], v[0:1], v[46:47] op_sel_hi:[1,0,1] neg_lo:[0,0,1] neg_hi:[0,0,1]
	v_pk_mov_b32 v[60:61], v[34:35], v[32:33] op_sel:[1,0]
	v_mov_b32_e32 v35, v33
	v_pk_add_f32 v[32:33], v[60:61], v[34:35]
	v_pk_mul_f32 v[34:35], v[56:57], v[2:3] op_sel_hi:[1,0]
	v_pk_add_f32 v[60:61], v[32:33], v[32:33] op_sel_hi:[0,1]
	v_pk_fma_f32 v[34:35], v[48:49], v[0:1], v[34:35] op_sel_hi:[1,0,1] neg_lo:[0,0,1] neg_hi:[0,0,1]
	v_pk_mul_f32 v[32:33], v[58:59], v[2:3] op_sel_hi:[1,0]
	v_mul_f32_e32 v48, v34, v34
	v_pk_fma_f32 v[32:33], v[50:51], v[0:1], v[32:33] op_sel_hi:[1,0,1] neg_lo:[0,0,1] neg_hi:[0,0,1]
	v_pk_fma_f32 v[48:49], v[34:35], v[34:35], v[48:49] op_sel_hi:[1,1,0]
	v_pk_fma_f32 v[24:25], v[24:25], v[0:1], v[44:45] op_sel_hi:[1,0,1] neg_lo:[0,0,1] neg_hi:[0,0,1]
	v_mul_f32_e32 v48, v32, v32
	v_pk_fma_f32 v[50:51], v[32:33], v[32:33], v[48:49] op_sel_hi:[1,1,0]
	v_pk_mul_f32 v[22:23], v[22:23], v[2:3] op_sel_hi:[1,0]
	v_pk_mul_f32 v[20:21], v[20:21], v[2:3] op_sel_hi:[1,0]
	v_pk_mul_f32 v[12:13], v[12:13], v[2:3] op_sel_hi:[1,0]
	v_mul_f32_e32 v48, v24, v24
	v_mul_f32_e32 v50, v25, v25
	v_mul_f32_e32 v60, v26, v26
	v_mul_f32_e32 v68, v27, v27
	v_pk_fma_f32 v[16:17], v[16:17], v[0:1], v[20:21] op_sel_hi:[1,0,1] neg_lo:[0,0,1] neg_hi:[0,0,1]
	v_pk_fma_f32 v[20:21], v[18:19], v[0:1], v[22:23] op_sel_hi:[1,0,1] neg_lo:[0,0,1] neg_hi:[0,0,1]
	v_pk_mul_f32 v[14:15], v[14:15], v[2:3] op_sel_hi:[1,0]
	v_pk_fma_f32 v[8:9], v[8:9], v[0:1], v[12:13] op_sel_hi:[1,0,1] neg_lo:[0,0,1] neg_hi:[0,0,1]
	v_pk_add_f32 v[44:45], v[48:49], v[50:51]
	v_pk_add_f32 v[46:47], v[60:61], v[68:69]
	v_pk_mul_f32 v[18:19], v[20:21], v[20:21]
	v_pk_mul_f32 v[22:23], v[16:17], v[16:17]
	v_pk_fma_f32 v[10:11], v[10:11], v[0:1], v[14:15] op_sel_hi:[1,0,1] neg_lo:[0,0,1] neg_hi:[0,0,1]
	v_mul_f32_e32 v12, v8, v8
	v_pk_add_f32 v[44:45], v[44:45], v[46:47]
	v_pk_mov_b32 v[46:47], v[22:23], v[18:19] op_sel:[1,0]
	v_mov_b32_e32 v23, v19
	v_pk_fma_f32 v[14:15], v[8:9], v[8:9], v[12:13] op_sel_hi:[1,1,0]
	v_mul_f32_e32 v12, v10, v10
	v_pk_add_f32 v[18:19], v[46:47], v[22:23]
	v_pk_fma_f32 v[22:23], v[10:11], v[10:11], v[12:13] op_sel_hi:[1,1,0]
	v_pk_mul_f32 v[12:13], v[52:53], v[2:3] op_sel_hi:[1,0]
	v_pk_mul_f32 v[2:3], v[54:55], v[2:3] op_sel_hi:[1,0]
	v_pk_add_f32 v[44:45], v[44:45], v[44:45] op_sel_hi:[0,1]
	v_pk_add_f32 v[18:19], v[18:19], v[18:19] op_sel_hi:[0,1]
	v_pk_fma_f32 v[6:7], v[6:7], v[0:1], v[2:3] op_sel_hi:[1,0,1] neg_lo:[0,0,1] neg_hi:[0,0,1]
	v_pk_fma_f32 v[12:13], v[4:5], v[0:1], v[12:13] op_sel_hi:[1,0,1] neg_lo:[0,0,1] neg_hi:[0,0,1]
	v_mul_f32_e32 v18, v6, v6
	v_mul_f32_e32 v14, v12, v12
	v_mul_f32_e32 v22, v13, v13
	v_mul_f32_e32 v44, v7, v7
	v_pk_add_f32 v[2:3], v[14:15], v[22:23]
	v_pk_add_f32 v[4:5], v[18:19], v[44:45]
	s_nop 0
	v_pk_add_f32 v[2:3], v[2:3], v[4:5]
	s_nop 0
	v_add_f32_e32 v0, v2, v3
	ds_bpermute_b32 v2, v148, v0
	s_waitcnt lgkmcnt(0)
	v_add_f32_e32 v0, v0, v2
	ds_bpermute_b32 v2, v149, v0
	s_waitcnt lgkmcnt(0)
	v_add_f32_e32 v0, v0, v2
	v_fmamk_f32 v0, v0, 0x3c000000, v227
	v_cmp_gt_f32_e32 vcc, s7, v0
	v_mul_f32_e32 v2, 0x4f800000, v0
	s_nop 0
	v_cndmask_b32_e32 v0, v0, v2, vcc
	v_sqrt_f32_e32 v2, v0
	s_nop 0
	v_add_u32_e32 v3, -1, v2
	v_fma_f32 v4, -v3, v2, v0
	v_cmp_ge_f32_e64 s[38:39], 0, v4
	v_add_u32_e32 v4, 1, v2
	s_nop 0
	v_cndmask_b32_e64 v3, v2, v3, s[38:39]
	v_fma_f32 v2, -v4, v2, v0
	v_cmp_lt_f32_e64 s[38:39], 0, v2
	s_nop 1
	v_cndmask_b32_e64 v2, v3, v4, s[38:39]
	v_mul_f32_e32 v3, 0x37800000, v2
	v_cndmask_b32_e32 v2, v2, v3, vcc
	v_cmp_class_f32_e32 vcc, v0, v228
	s_nop 1
	v_cndmask_b32_e32 v0, v2, v0, vcc
	v_div_scale_f32 v2, s[38:39], v0, v0, v151
	v_rcp_f32_e32 v3, v2
	s_nop 0
	v_fma_f32 v4, -v2, v3, 1.0
	v_fmac_f32_e32 v3, v4, v3
	v_div_scale_f32 v4, vcc, v151, v0, v151
	v_mul_f32_e32 v5, v4, v3
	v_fma_f32 v14, -v2, v5, v4
	v_fmac_f32_e32 v5, v14, v3
	v_fma_f32 v2, -v2, v5, v4
	v_div_fmas_f32 v2, v2, v3, v5
	v_div_fixup_f32 v18, v2, v0, v151
	v_and_b32_e32 v0, 16, v153
	v_lshrrev_b32_e32 v2, 2, v153
	v_and_or_b32 v0, v2, 8, v0
	v_mov_b64_e32 v[2:3], s[50:51]
	v_mad_u64_u32 v[2:3], s[38:39], v136, s21, v[2:3]
	v_mad_i32_i24 v3, v137, s21, v3
	v_lshl_add_u64 v[2:3], v[2:3], 0, s[30:31]
	v_lshlrev_b32_e32 v0, 1, v0
	v_lshl_add_u64 v[22:23], v[2:3], 0, v[0:1]
	v_lshl_add_u64 v[14:15], v[138:139], 0, v[0:1]
	v_lshlrev_b32_e32 v0, 4, v152
	global_load_dwordx4 v[2:5], v[22:23], off offset:1024
	global_load_dwordx4 v[44:47], v0, s[42:43]
	global_load_dwordx4 v[48:51], v0, s[42:43] offset:64
	v_pk_mul_f32 v[38:39], v[38:39], v[18:19] op_sel_hi:[1,0]
	v_pk_mul_f32 v[42:43], v[42:43], v[18:19] op_sel_hi:[1,0]
	v_pk_mul_f32 v[36:37], v[36:37], v[18:19] op_sel_hi:[1,0]
	v_pk_mul_f32 v[40:41], v[40:41], v[18:19] op_sel_hi:[1,0]
	v_mov_b32_e32 v153, v224
	s_lshl_b32 s39, s16, 7
	s_waitcnt vmcnt(0)
	v_lshlrev_b32_e32 v19, 16, v2
	v_pk_mul_f32 v[38:39], v[44:45], v[38:39]
	v_pk_mul_f32 v[42:43], v[48:49], v[42:43]
	v_and_b32_e32 v2, 0xffff0000, v2
	s_nop 0
	v_permlane16_swap_b32_e32 v38, v42
	v_permlane16_swap_b32_e32 v39, v43
	v_pk_mul_f32 v[36:37], v[46:47], v[36:37]
	v_pk_mul_f32 v[40:41], v[50:51], v[40:41]
	v_mul_f32_e32 v19, v19, v38
	v_mul_f32_e32 v2, v2, v39
	v_permlane16_swap_b32_e32 v36, v40
	v_permlane16_swap_b32_e32 v37, v41
	v_cvt_pk_bf16_f32 v2, v19, v2
	v_lshlrev_b32_e32 v19, 16, v3
	v_and_b32_e32 v3, 0xffff0000, v3
	v_mul_f32_e32 v19, v19, v36
	v_mul_f32_e32 v3, v3, v37
	v_cvt_pk_bf16_f32 v3, v19, v3
	v_lshlrev_b32_e32 v19, 16, v4
	v_and_b32_e32 v4, 0xffff0000, v4
	v_mul_f32_e32 v19, v19, v42
	v_mul_f32_e32 v4, v4, v43
	v_cvt_pk_bf16_f32 v4, v19, v4
	v_lshlrev_b32_e32 v19, 16, v5
	v_and_b32_e32 v5, 0xffff0000, v5
	v_mul_f32_e32 v5, v5, v41
	v_mul_f32_e32 v19, v19, v40
	v_cvt_pk_bf16_f32 v5, v19, v5
	global_store_dwordx4 v[14:15], v[2:5], off sc1
	global_load_dwordx4 v[2:5], v[22:23], off offset:1088
	s_nop 0
	global_load_dwordx4 v[36:39], v0, s[42:43] offset:128
	global_load_dwordx4 v[40:43], v0, s[42:43] offset:192
	v_pk_mul_f32 v[28:29], v[28:29], v[18:19] op_sel_hi:[1,0]
	v_pk_mul_f32 v[34:35], v[34:35], v[18:19] op_sel_hi:[1,0]
	v_pk_mul_f32 v[30:31], v[30:31], v[18:19] op_sel_hi:[1,0]
	v_pk_mul_f32 v[32:33], v[32:33], v[18:19] op_sel_hi:[1,0]
	s_waitcnt vmcnt(2)
	v_lshlrev_b32_e32 v19, 16, v2
	s_waitcnt vmcnt(1)
	v_pk_mul_f32 v[28:29], v[36:37], v[28:29]
	s_waitcnt vmcnt(0)
	v_pk_mul_f32 v[34:35], v[40:41], v[34:35]
	v_and_b32_e32 v2, 0xffff0000, v2
	s_nop 0
	v_permlane16_swap_b32_e32 v28, v34
	v_permlane16_swap_b32_e32 v29, v35
	v_pk_mul_f32 v[30:31], v[38:39], v[30:31]
	v_pk_mul_f32 v[32:33], v[42:43], v[32:33]
	v_mul_f32_e32 v19, v19, v28
	v_mul_f32_e32 v2, v2, v29
	v_permlane16_swap_b32_e32 v30, v32
	v_permlane16_swap_b32_e32 v31, v33
	v_cvt_pk_bf16_f32 v2, v19, v2
	v_lshlrev_b32_e32 v19, 16, v3
	v_and_b32_e32 v3, 0xffff0000, v3
	v_mul_f32_e32 v19, v19, v30
	v_mul_f32_e32 v3, v3, v31
	v_cvt_pk_bf16_f32 v3, v19, v3
	v_lshlrev_b32_e32 v19, 16, v4
	v_and_b32_e32 v4, 0xffff0000, v4
	v_mul_f32_e32 v19, v19, v34
	v_mul_f32_e32 v4, v4, v35
	v_cvt_pk_bf16_f32 v4, v19, v4
	v_lshlrev_b32_e32 v19, 16, v5
	v_and_b32_e32 v5, 0xffff0000, v5
	v_mul_f32_e32 v5, v5, v33
	v_mul_f32_e32 v19, v19, v32
	v_cvt_pk_bf16_f32 v5, v19, v5
	global_store_dwordx4 v[14:15], v[2:5], off offset:64 sc1
	global_load_dwordx4 v[2:5], v[22:23], off offset:1152
	s_nop 0
	global_load_dwordx4 v[28:31], v0, s[42:43] offset:256
	global_load_dwordx4 v[32:35], v0, s[42:43] offset:320
	v_pk_mul_f32 v[24:25], v[24:25], v[18:19] op_sel_hi:[1,0]
	v_pk_mul_f32 v[16:17], v[16:17], v[18:19] op_sel_hi:[1,0]
	v_pk_mul_f32 v[26:27], v[26:27], v[18:19] op_sel_hi:[1,0]
	v_pk_mul_f32 v[20:21], v[20:21], v[18:19] op_sel_hi:[1,0]
	s_waitcnt vmcnt(2)
	v_lshlrev_b32_e32 v19, 16, v2
	s_waitcnt vmcnt(1)
	v_pk_mul_f32 v[24:25], v[24:25], v[28:29]
	s_waitcnt vmcnt(0)
	v_pk_mul_f32 v[16:17], v[16:17], v[32:33]
	v_and_b32_e32 v2, 0xffff0000, v2
	s_nop 0
	v_permlane16_swap_b32_e32 v24, v16
	v_permlane16_swap_b32_e32 v25, v17
	v_pk_mul_f32 v[26:27], v[26:27], v[30:31]
	v_pk_mul_f32 v[20:21], v[20:21], v[34:35]
	v_mul_f32_e32 v19, v19, v24
	v_mul_f32_e32 v2, v2, v25
	v_permlane16_swap_b32_e32 v26, v20
	v_permlane16_swap_b32_e32 v27, v21
	v_cvt_pk_bf16_f32 v2, v19, v2
	v_lshlrev_b32_e32 v19, 16, v3
	v_and_b32_e32 v3, 0xffff0000, v3
	v_mul_f32_e32 v19, v19, v26
	v_mul_f32_e32 v3, v3, v27
	v_cvt_pk_bf16_f32 v3, v19, v3
	v_lshlrev_b32_e32 v19, 16, v4
	v_and_b32_e32 v4, 0xffff0000, v4
	v_mul_f32_e32 v16, v19, v16
	v_mul_f32_e32 v4, v4, v17
	v_cvt_pk_bf16_f32 v4, v16, v4
	v_lshlrev_b32_e32 v16, 16, v5
	v_and_b32_e32 v5, 0xffff0000, v5
	v_mul_f32_e32 v5, v5, v21
	v_mul_f32_e32 v16, v16, v20
	v_cvt_pk_bf16_f32 v5, v16, v5
	global_store_dwordx4 v[14:15], v[2:5], off offset:128 sc1
	global_load_dwordx4 v[2:5], v[22:23], off offset:1216
	s_nop 0
	global_load_dwordx4 v[20:23], v0, s[42:43] offset:384
	global_load_dwordx4 v[24:27], v0, s[42:43] offset:448
	v_pk_mul_f32 v[8:9], v[8:9], v[18:19] op_sel_hi:[1,0]
	v_pk_mul_f32 v[12:13], v[12:13], v[18:19] op_sel_hi:[1,0]
	v_pk_mul_f32 v[10:11], v[10:11], v[18:19] op_sel_hi:[1,0]
	v_pk_mul_f32 v[6:7], v[6:7], v[18:19] op_sel_hi:[1,0]
	s_waitcnt vmcnt(2)
	v_lshlrev_b32_e32 v0, 16, v2
	s_waitcnt vmcnt(1)
	v_pk_mul_f32 v[8:9], v[8:9], v[20:21]
	s_waitcnt vmcnt(0)
	v_pk_mul_f32 v[12:13], v[12:13], v[24:25]
	v_and_b32_e32 v2, 0xffff0000, v2
	s_nop 0
	v_permlane16_swap_b32_e32 v8, v12
	v_permlane16_swap_b32_e32 v9, v13
	v_pk_mul_f32 v[10:11], v[10:11], v[22:23]
	v_pk_mul_f32 v[6:7], v[6:7], v[26:27]
	v_mul_f32_e32 v0, v0, v8
	v_mul_f32_e32 v2, v2, v9
	v_permlane16_swap_b32_e32 v10, v6
	v_permlane16_swap_b32_e32 v11, v7
	v_cvt_pk_bf16_f32 v2, v0, v2
	v_lshlrev_b32_e32 v0, 16, v3
	v_and_b32_e32 v3, 0xffff0000, v3
	v_mul_f32_e32 v0, v0, v10
	v_mul_f32_e32 v3, v3, v11
	v_cvt_pk_bf16_f32 v3, v0, v3
	v_lshlrev_b32_e32 v0, 16, v4
	v_and_b32_e32 v4, 0xffff0000, v4
	v_mul_f32_e32 v0, v0, v12
	v_mul_f32_e32 v4, v4, v13
	v_cvt_pk_bf16_f32 v4, v0, v4
	v_lshlrev_b32_e32 v0, 16, v5
	v_and_b32_e32 v5, 0xffff0000, v5
	v_mul_f32_e32 v5, v5, v7
	v_mul_f32_e32 v0, v0, v6
	v_cvt_pk_bf16_f32 v5, v0, v5
	global_store_dwordx4 v[14:15], v[2:5], off offset:192 sc1
	s_nop 0
	v_readfirstlane_b32 s38, v153
	s_ashr_i32 s38, s38, 6
	s_lshl_b32 s62, s38, 4
	v_and_b32_e32 v2, 15, v153
	s_add_i32 s62, s62, s39
	v_or_b32_e32 v4, s62, v2
	v_ashrrev_i32_e32 v5, 31, v4
	v_lshl_add_u64 v[136:137], s[44:45], 0, v[4:5]
	v_mov_b64_e32 v[4:5], s[28:29]
	v_mad_u64_u32 v[4:5], s[62:63], v136, s23, v[4:5]
	v_mad_i32_i24 v5, v137, s23, v5
	v_lshl_add_u64 v[138:139], v[4:5], 0, s[30:31]
	v_and_b32_e32 v0, 48, v153
	v_lshl_add_u64 v[4:5], v[138:139], 0, v[0:1]
	global_load_dwordx4 v[36:39], v[4:5], off
	global_load_dwordx4 v[40:43], v[4:5], off offset:64
	global_load_dwordx4 v[44:47], v[4:5], off offset:128
	global_load_dwordx4 v[52:55], v[4:5], off offset:192
	s_cmp_lt_i32 s38, 4
	s_cbranch_scc1 .LBB0_419
	s_setprio 1

.LBB0_441:
	v_readlane_b32 s8, v241, 25
	v_readlane_b32 s9, v241, 26
	v_readlane_b32 s68, v240, 0
	v_readlane_b32 s70, v240, 2
	s_andn2_b64 vcc, exec, s[8:9]
	v_readlane_b32 s69, v240, 1
	v_readlane_b32 s71, v240, 3
	s_cbranch_vccnz .LBB0_472
	s_cmp_eq_u32 s98, 2
	s_cbranch_scc1 .Lp2_skipmix
	s_lshl_b32 s8, s86, 17
	s_add_u32 s13, s60, s8
	s_addc_u32 s16, s61, 0
	s_add_u32 s8, s13, 0x2c00000
	s_addc_u32 s9, s16, 0
	s_add_u32 s13, s13, 0x2c80000
	s_addc_u32 s16, s16, 0
	s_lshl_b32 s40, s86, 9
	s_add_u32 s42, s60, 0x2d00000
	s_mov_b32 s41, s31
	s_addc_u32 s43, s61, 0
	v_readlane_b32 s25, v241, 45
	s_branch .LBB0_444

.LBB0_447:
	s_or_b64 exec, exec, s[46:47]
	s_load_dwordx4 s[64:67], s[26:27], 0x60
	v_ashrrev_i32_e32 v35, 4, v34
	v_lshlrev_b32_e32 v36, 4, v71
	v_mov_b32_e32 v37, v1
	v_lshlrev_b32_e32 v40, 7, v35
	s_waitcnt lgkmcnt(0)
	s_add_u32 s47, s64, s44
	s_addc_u32 s46, s65, s45
	s_add_u32 s38, s66, s44
	s_addc_u32 s39, s67, s45
	s_lshl_b32 s30, s55, 15
	s_add_u32 s44, s13, s30
	s_addc_u32 s45, s16, 0
	v_lshl_add_u64 v[38:39], s[44:45], 0, v[36:37]
	v_ashrrev_i32_e32 v41, 31, v40
	v_add_u32_e32 v37, 0x200, v34
	v_lshl_add_u64 v[40:41], v[40:41], 1, v[38:39]
	v_ashrrev_i32_e32 v37, 4, v37
	global_load_dwordx4 v[50:53], v[40:41], off
	v_lshlrev_b32_e32 v40, 7, v37
	v_ashrrev_i32_e32 v41, 31, v40
	v_lshl_add_u64 v[40:41], v[40:41], 1, v[38:39]
	global_load_dwordx4 v[54:57], v[40:41], off
	v_add_u32_e32 v40, 0x400, v34
	v_ashrrev_i32_e32 v74, 4, v40
	v_lshlrev_b32_e32 v40, 7, v74
	v_ashrrev_i32_e32 v41, 31, v40
	v_lshl_add_u64 v[40:41], v[40:41], 1, v[38:39]
	global_load_dwordx4 v[58:61], v[40:41], off
	v_add_u32_e32 v40, 0x600, v34
	v_ashrrev_i32_e32 v77, 4, v40
	v_lshlrev_b32_e32 v40, 7, v77
	v_ashrrev_i32_e32 v41, 31, v40
	v_lshl_add_u64 v[38:39], v[40:41], 1, v[38:39]
	global_load_dwordx4 v[78:81], v[38:39], off
	s_lshl_b32 s44, s60, 4
	v_lshrrev_b32_e32 v38, 4, v34
	v_and_or_b32 v95, s44, 48, v71
	v_bfi_b32 v94, -4, s60, v38
	v_lshl_or_b32 v38, v95, 1, s62
	v_mul_u32_u24_e32 v38, 0xa00, v38
	v_mov_b32_e32 v39, v1
	v_lshlrev_b32_e32 v38, 1, v38
	s_lshl_b32 s30, s61, 1
	v_lshl_add_u64 v[38:39], s[50:51], 0, v[38:39]
	v_lshl_add_u64 v[38:39], v[38:39], 0, s[30:31]
	s_mov_b64 s[44:45], 0x1000
	v_bfe_u32 v76, v34, 4, 2
	v_add_u32_e32 v34, 0, v36
	v_lshl_add_u64 v[38:39], v[38:39], 0, s[44:45]
	v_mad_u64_u32 v[72:73], s[44:45], v35, s90, v[34:35]
	v_mad_u64_u32 v[82:83], s[44:45], v37, s90, v[34:35]
	v_mad_u64_u32 v[84:85], s[44:45], v74, s90, v[34:35]
	v_mad_u64_u32 v[86:87], s[44:45], v77, s90, v[34:35]
	v_lshlrev_b32_e32 v40, 3, v94
	s_and_b32 s44, s60, -4
	v_ashrrev_i32_e32 v41, 31, v40
	s_lshl_b32 s60, s61, 2
	s_add_i32 s44, s44, 8
	v_lshl_add_u64 v[42:43], v[40:41], 1, v[38:39]
	s_movk_i32 s62, 0x1000
	v_or_b32_e32 v96, s44, v76
	s_add_u32 s44, s47, s60
	v_add_co_u32_e32 v36, vcc, s62, v42
	s_addc_u32 s45, s46, 0
	global_load_dwordx4 v[46:49], v[42:43], off
	v_addc_co_u32_e32 v37, vcc, 0, v43, vcc
	v_lshlrev_b32_e32 v88, 3, v96
	s_add_u32 s38, s38, s60
	global_load_dwordx4 v[42:45], v[36:37], off offset:1024
	v_lshlrev_b64 v[34:35], 2, v[40:41]
	v_ashrrev_i32_e32 v89, 31, v88
	s_addc_u32 s39, s39, 0
	v_lshl_add_u64 v[90:91], s[44:45], 0, v[34:35]
	v_lshl_add_u64 v[92:93], s[38:39], 0, v[34:35]
	v_lshl_add_u64 v[34:35], v[88:89], 1, v[38:39]
	global_load_dwordx4 v[38:41], v[34:35], off
	v_add_co_u32_e32 v34, vcc, s62, v34
	v_lshl_add_u32 v74, v95, 2, 0
	s_nop 0
	v_addc_co_u32_e32 v35, vcc, 0, v35, vcc
	global_load_dwordx4 v[34:37], v[34:35], off offset:1024
	s_movk_i32 s60, 0x880
	s_movk_i32 s91, 0x1000
	s_waitcnt vmcnt(7)
	ds_write_b128 v72, v[50:53]
	s_waitcnt vmcnt(6)
	ds_write_b128 v82, v[54:57]
	s_waitcnt vmcnt(5)
	ds_write_b128 v84, v[58:61]
	s_waitcnt vmcnt(4)
	ds_write_b128 v86, v[78:81]
	s_waitcnt lgkmcnt(0)
	s_barrier
	global_load_dwordx4 v[54:57], v[90:91], off
	global_load_dwordx4 v[58:61], v[92:93], off
	global_load_dwordx4 v[78:81], v[90:91], off offset:16
	global_load_dwordx4 v[50:53], v[92:93], off offset:16
	v_lshl_add_u32 v72, v95, 4, 0
	v_add_u32_e32 v77, 0x11000, v72
	ds_read_b128 v[82:85], v77
	v_mad_u64_u32 v[72:73], s[46:47], v94, s60, v[74:75]
	v_lshlrev_b64 v[86:87], 2, v[88:89]
	s_waitcnt vmcnt(7)
	v_lshlrev_b32_e32 v73, 16, v46
	v_and_b32_e32 v46, 0xffff0000, v46
	v_lshlrev_b32_e32 v88, 16, v47
	v_and_b32_e32 v47, 0xffff0000, v47
	v_lshlrev_b32_e32 v89, 16, v48
	v_and_b32_e32 v48, 0xffff0000, v48
	v_lshlrev_b32_e32 v90, 16, v49
	v_and_b32_e32 v49, 0xffff0000, v49
	s_waitcnt lgkmcnt(0)
	v_sub_f32_e32 v73, v73, v82
	v_sub_f32_e32 v46, v46, v82
	v_sub_f32_e32 v88, v88, v82
	v_sub_f32_e32 v47, v47, v82
	v_sub_f32_e32 v89, v89, v82
	v_sub_f32_e32 v48, v48, v82
	v_sub_f32_e32 v90, v90, v82
	v_sub_f32_e32 v49, v49, v82
	s_waitcnt vmcnt(6)
	v_lshlrev_b32_e32 v82, 16, v42
	v_and_b32_e32 v42, 0xffff0000, v42
	v_lshlrev_b32_e32 v93, 16, v45
	v_and_b32_e32 v45, 0xffff0000, v45
	v_sub_f32_e32 v42, v42, v84
	v_lshlrev_b32_e32 v91, 16, v43
	v_sub_f32_e32 v82, v82, v84
	v_sub_f32_e32 v45, v45, v84
	v_mul_f32_e32 v42, v85, v42
	v_and_b32_e32 v43, 0xffff0000, v43
	v_mul_f32_e32 v73, v83, v73
	v_mul_f32_e32 v46, v83, v46
	v_mul_f32_e32 v88, v83, v88
	v_mul_f32_e32 v47, v83, v47
	v_mul_f32_e32 v89, v83, v89
	v_mul_f32_e32 v48, v83, v48
	v_mul_f32_e32 v90, v83, v90
	v_mul_f32_e32 v49, v83, v49
	v_sub_f32_e32 v83, v91, v84
	v_mul_f32_e32 v82, v85, v82
	v_mul_f32_e32 v45, v85, v45
	v_lshlrev_b32_e32 v92, 16, v44
	v_sub_f32_e32 v43, v43, v84
	v_mul_f32_e32 v83, v85, v83
	v_and_b32_e32 v44, 0xffff0000, v44
	v_sub_f32_e32 v91, v92, v84
	v_mul_f32_e32 v43, v85, v43
	s_waitcnt vmcnt(2)
	v_fma_f32 v42, v55, v42, v59
	v_fma_f32 v73, v54, v73, v58
	v_fma_f32 v54, v54, v82, v58
	v_fma_f32 v46, v55, v46, v59
	s_waitcnt vmcnt(0)
	v_fma_f32 v49, v49, v81, v53
	v_fmac_f32_e32 v53, v81, v45
	v_cvt_pk_bf16_f32 v45, v73, v54
	ds_write_b32 v72, v45 offset:34816
	v_cvt_pk_bf16_f32 v42, v46, v42
	v_fma_f32 v55, v56, v88, v60
	v_fma_f32 v56, v56, v83, v60
	ds_write_b32 v72, v42 offset:35088
	v_cvt_pk_bf16_f32 v42, v55, v56
	v_sub_f32_e32 v44, v44, v84
	v_sub_f32_e32 v92, v93, v84
	v_mul_f32_e32 v84, v85, v91
	v_fma_f32 v47, v57, v47, v61
	v_fmac_f32_e32 v61, v57, v43
	ds_write_b32 v72, v42 offset:35360
	v_cvt_pk_bf16_f32 v42, v47, v61
	v_mul_f32_e32 v44, v85, v44
	v_fma_f32 v43, v89, v78, v50
	v_fma_f32 v50, v78, v84, v50
	ds_write_b32 v72, v42 offset:35632
	v_cvt_pk_bf16_f32 v42, v43, v50
	v_mul_f32_e32 v91, v85, v92
	v_fma_f32 v48, v48, v79, v51
	v_fma_f32 v44, v79, v44, v51
	ds_write_b32 v72, v42 offset:35904
	v_cvt_pk_bf16_f32 v42, v48, v44
	v_fma_f32 v51, v90, v80, v52
	v_fma_f32 v52, v80, v91, v52
	ds_write_b32 v72, v42 offset:36176
	v_cvt_pk_bf16_f32 v42, v51, v52
	ds_write_b32 v72, v42 offset:36448
	v_lshl_add_u64 v[42:43], s[44:45], 0, v[86:87]
	v_cvt_pk_bf16_f32 v60, v49, v53
	global_load_dwordx4 v[54:57], v[42:43], off
	v_lshl_add_u64 v[44:45], s[38:39], 0, v[86:87]
	global_load_dwordx4 v[46:49], v[44:45], off
	global_load_dwordx4 v[50:53], v[42:43], off offset:16
	s_nop 0
	global_load_dwordx4 v[42:45], v[44:45], off offset:16
	v_mad_u64_u32 v[58:59], s[38:39], v96, s60, v[74:75]
	ds_write_b32 v72, v60 offset:36720
	v_lshlrev_b32_e32 v59, 16, v38
	v_and_b32_e32 v61, 0xffff0000, v38
	v_lshlrev_b32_e32 v73, 16, v39
	v_and_b32_e32 v74, 0xffff0000, v39
	v_lshlrev_b32_e32 v78, 16, v40
	v_and_b32_e32 v79, 0xffff0000, v40
	v_lshlrev_b32_e32 v80, 16, v41
	v_and_b32_e32 v81, 0xffff0000, v41
	ds_read_b128 v[38:41], v77
	v_lshlrev_b32_e32 v82, 16, v34
	v_and_b32_e32 v34, 0xffff0000, v34
	v_lshlrev_b32_e32 v72, 16, v37
	v_and_b32_e32 v37, 0xffff0000, v37
	s_waitcnt lgkmcnt(0)
	v_sub_f32_e32 v34, v34, v40
	v_lshlrev_b32_e32 v83, 16, v35
	v_and_b32_e32 v35, 0xffff0000, v35
	v_lshlrev_b32_e32 v60, 16, v36
	v_and_b32_e32 v36, 0xffff0000, v36
	v_sub_f32_e32 v59, v59, v38
	v_sub_f32_e32 v77, v82, v40
	v_sub_f32_e32 v61, v61, v38
	v_sub_f32_e32 v73, v73, v38
	v_sub_f32_e32 v74, v74, v38
	v_sub_f32_e32 v78, v78, v38
	v_sub_f32_e32 v79, v79, v38
	v_sub_f32_e32 v80, v80, v38
	v_sub_f32_e32 v38, v81, v38
	v_sub_f32_e32 v37, v37, v40
	v_mul_f32_e32 v34, v41, v34
	v_sub_f32_e32 v82, v83, v40
	v_sub_f32_e32 v35, v35, v40
	v_sub_f32_e32 v60, v60, v40
	v_sub_f32_e32 v36, v36, v40
	v_sub_f32_e32 v72, v72, v40
	v_mul_f32_e32 v40, v39, v59
	v_mul_f32_e32 v59, v41, v77
	v_mul_f32_e32 v61, v39, v61
	v_mul_f32_e32 v38, v39, v38
	v_mul_f32_e32 v37, v41, v37
	v_mul_f32_e32 v73, v39, v73
	v_mul_f32_e32 v77, v41, v82
	v_mul_f32_e32 v74, v39, v74
	v_mul_f32_e32 v35, v41, v35
	v_mul_f32_e32 v78, v39, v78
	v_mul_f32_e32 v60, v41, v60
	v_mul_f32_e32 v79, v39, v79
	v_mul_f32_e32 v36, v41, v36
	v_mul_f32_e32 v80, v39, v80
	v_mul_f32_e32 v72, v41, v72
	s_waitcnt vmcnt(2)
	v_fma_f32 v34, v55, v34, v47
	v_fma_f32 v39, v54, v40, v46
	v_fma_f32 v40, v54, v59, v46
	v_fma_f32 v41, v55, v61, v47
	s_waitcnt vmcnt(0)
	v_fma_f32 v38, v38, v53, v45
	v_fmac_f32_e32 v45, v53, v37
	v_cvt_pk_bf16_f32 v37, v39, v40
	ds_write_b32 v58, v37 offset:34816
	v_cvt_pk_bf16_f32 v34, v41, v34
	v_fma_f32 v46, v56, v73, v48
	v_fma_f32 v47, v56, v77, v48
	ds_write_b32 v58, v34 offset:35088
	v_cvt_pk_bf16_f32 v34, v46, v47
	v_fma_f32 v48, v57, v74, v49
	v_fmac_f32_e32 v49, v57, v35
	ds_write_b32 v58, v34 offset:35360
	v_cvt_pk_bf16_f32 v34, v48, v49
	v_fma_f32 v35, v78, v50, v42
	v_fma_f32 v42, v50, v60, v42
	ds_write_b32 v58, v34 offset:35632
	v_cvt_pk_bf16_f32 v34, v35, v42
	v_fma_f32 v50, v79, v51, v43
	v_fma_f32 v36, v51, v36, v43
	ds_write_b32 v58, v34 offset:35904
	v_cvt_pk_bf16_f32 v34, v50, v36
	v_fma_f32 v43, v80, v52, v44
	v_fma_f32 v44, v52, v72, v44
	ds_write_b32 v58, v34 offset:36176
	v_cvt_pk_bf16_f32 v34, v43, v44
	ds_write_b32 v58, v34 offset:36448
	v_cvt_pk_bf16_f32 v34, v38, v45
	ds_write_b32 v58, v34 offset:36720
	v_or_b32_e32 v34, s57, v71
	v_lshl_add_u32 v38, v76, 4, 0
	v_mad_u32_u24 v71, v34, s90, v38
	s_waitcnt lgkmcnt(0)
	s_barrier
	ds_read_b128 v[34:37], v71 offset:34816
	ds_read_b128 v[46:49], v71 offset:39168
	v_mad_u64_u32 v[88:89], s[38:39], v75, s90, v[38:39]
	ds_read_b128 v[38:41], v88
	ds_read_b128 v[50:53], v88 offset:4352
	ds_read_b128 v[58:61], v88 offset:8704
	ds_read_b128 v[76:79], v88 offset:13056
	ds_read_b128 v[80:83], v71 offset:34880
	ds_read_b128 v[84:87], v71 offset:39232
	s_waitcnt lgkmcnt(5)
	v_mfma_f32_16x16x32_bf16 v[42:45], v[34:37], v[38:41], 0
	v_mfma_f32_16x16x32_bf16 v[38:41], v[46:49], v[38:41], 0
	s_waitcnt lgkmcnt(4)
	v_mfma_f32_16x16x32_bf16 v[54:57], v[34:37], v[50:53], 0
	v_mfma_f32_16x16x32_bf16 v[50:53], v[46:49], v[50:53], 0
	s_waitcnt lgkmcnt(3)
	v_mfma_f32_16x16x32_bf16 v[72:75], v[34:37], v[58:61], 0
	v_mfma_f32_16x16x32_bf16 v[58:61], v[46:49], v[58:61], 0
	s_waitcnt lgkmcnt(2)
	v_mfma_f32_16x16x32_bf16 v[34:37], v[34:37], v[76:79], 0
	v_mfma_f32_16x16x32_bf16 v[46:49], v[46:49], v[76:79], 0
	ds_read_b128 v[76:79], v88 offset:64
	s_waitcnt lgkmcnt(0)
	v_mfma_f32_16x16x32_bf16 v[42:45], v[80:83], v[76:79], v[42:45]
	v_mfma_f32_16x16x32_bf16 v[38:41], v[84:87], v[76:79], v[38:41]
	ds_read_b128 v[76:79], v88 offset:4416
	s_waitcnt lgkmcnt(0)
	v_mfma_f32_16x16x32_bf16 v[54:57], v[80:83], v[76:79], v[54:57]
	v_mfma_f32_16x16x32_bf16 v[50:53], v[84:87], v[76:79], v[50:53]
	ds_read_b128 v[76:79], v88 offset:8768
	s_waitcnt lgkmcnt(0)
	v_mfma_f32_16x16x32_bf16 v[72:75], v[80:83], v[76:79], v[72:75]
	v_mfma_f32_16x16x32_bf16 v[58:61], v[84:87], v[76:79], v[58:61]
	ds_read_b128 v[76:79], v88 offset:13120
	s_waitcnt lgkmcnt(0)
	v_mfma_f32_16x16x32_bf16 v[34:37], v[80:83], v[76:79], v[34:37]
	ds_read_b128 v[80:83], v71 offset:34944
	v_mfma_f32_16x16x32_bf16 v[46:49], v[84:87], v[76:79], v[46:49]
	ds_read_b128 v[84:87], v71 offset:39296
	ds_read_b128 v[76:79], v88 offset:128
	s_waitcnt lgkmcnt(0)
	v_mfma_f32_16x16x32_bf16 v[42:45], v[80:83], v[76:79], v[42:45]
	v_mfma_f32_16x16x32_bf16 v[38:41], v[84:87], v[76:79], v[38:41]
	ds_read_b128 v[76:79], v88 offset:4480
	s_waitcnt lgkmcnt(0)
	v_mfma_f32_16x16x32_bf16 v[54:57], v[80:83], v[76:79], v[54:57]
	v_mfma_f32_16x16x32_bf16 v[50:53], v[84:87], v[76:79], v[50:53]
	ds_read_b128 v[76:79], v88 offset:8832
	s_waitcnt lgkmcnt(0)
	v_mfma_f32_16x16x32_bf16 v[72:75], v[80:83], v[76:79], v[72:75]
	v_mfma_f32_16x16x32_bf16 v[58:61], v[84:87], v[76:79], v[58:61]
	ds_read_b128 v[76:79], v88 offset:13184
	s_waitcnt lgkmcnt(0)
	v_mfma_f32_16x16x32_bf16 v[34:37], v[80:83], v[76:79], v[34:37]
	ds_read_b128 v[80:83], v71 offset:35008
	v_mfma_f32_16x16x32_bf16 v[46:49], v[84:87], v[76:79], v[46:49]
	ds_read_b128 v[84:87], v71 offset:39360
	ds_read_b128 v[76:79], v88 offset:192
	s_waitcnt lgkmcnt(0)
	v_mfma_f32_16x16x32_bf16 v[42:45], v[80:83], v[76:79], v[42:45]
	v_mfma_f32_16x16x32_bf16 v[38:41], v[84:87], v[76:79], v[38:41]
	ds_read_b128 v[76:79], v88 offset:4544
	s_nop 5
	v_pk_add_f32 v[42:43], v[70:71], v[42:43] op_sel_hi:[0,1]
	v_pk_add_f32 v[44:45], v[70:71], v[44:45] op_sel_hi:[0,1]
	s_waitcnt lgkmcnt(0)
	v_mfma_f32_16x16x32_bf16 v[54:57], v[80:83], v[76:79], v[54:57]
	v_add_f32_e64 v38, v70, v38
	v_add_f32_e64 v39, v70, v39
	v_mfma_f32_16x16x32_bf16 v[50:53], v[84:87], v[76:79], v[50:53]
	ds_read_b128 v[76:79], v88 offset:8896
	v_pk_add_f32 v[40:41], v[70:71], v[40:41] op_sel_hi:[0,1]
	v_permlane16_swap_b32_e32 v42, v38
	v_permlane16_swap_b32_e32 v43, v39
	v_lshlrev_b32_e32 v70, 16, v30
	v_and_b32_e32 v30, 0xffff0000, v30
	v_mul_f32_e32 v42, v70, v42
	v_lshlrev_b32_e32 v70, 16, v26
	v_mul_f32_e32 v30, v30, v43
	v_and_b32_e32 v26, 0xffff0000, v26
	v_permlane16_swap_b32_e32 v44, v40
	v_permlane16_swap_b32_e32 v45, v41
	v_mul_f32_e32 v42, v42, v70
	v_mul_f32_e32 v26, v30, v26
	v_lshlrev_b32_e32 v30, 16, v31
	v_and_b32_e32 v31, 0xffff0000, v31
	s_waitcnt lgkmcnt(0)
	v_mfma_f32_16x16x32_bf16 v[72:75], v[80:83], v[76:79], v[72:75]
	v_mul_f32_e32 v30, v30, v44
	v_mul_f32_e32 v31, v31, v45
	v_mfma_f32_16x16x32_bf16 v[58:61], v[84:87], v[76:79], v[58:61]
	ds_read_b128 v[76:79], v88 offset:13248
	v_cvt_pk_bf16_f32 v26, v42, v26
	v_lshlrev_b32_e32 v42, 16, v27
	v_and_b32_e32 v27, 0xffff0000, v27
	v_mul_f32_e32 v30, v30, v42
	v_mul_f32_e32 v27, v31, v27
	v_cvt_pk_bf16_f32 v27, v30, v27
	v_lshlrev_b32_e32 v30, 16, v32
	v_mul_f32_e32 v30, v30, v38
	v_lshlrev_b32_e32 v31, 16, v28
	v_mul_f32_e32 v30, v30, v31
	v_and_b32_e32 v31, 0xffff0000, v32
	v_mul_f32_e32 v31, v31, v39
	v_and_b32_e32 v28, 0xffff0000, v28
	v_mul_f32_e32 v28, v31, v28
	v_cvt_pk_bf16_f32 v28, v30, v28
	v_lshlrev_b32_e32 v30, 16, v33
	v_mul_f32_e32 v30, v30, v40
	v_lshlrev_b32_e32 v31, 16, v29
	v_mul_f32_e32 v30, v30, v31
	v_and_b32_e32 v31, 0xffff0000, v33
	v_mul_f32_e32 v31, v31, v41
	v_and_b32_e32 v29, 0xffff0000, v29
	v_mul_f32_e32 v29, v31, v29
	v_cvt_pk_bf16_f32 v29, v30, v29
	global_store_dwordx4 v[66:67], v[26:29], off offset:2048 sc1
	v_pk_add_f32 v[32:33], v[68:69], v[50:51] op_sel_hi:[0,1]
	v_lshlrev_b32_e32 v38, 16, v22
	v_pk_add_f32 v[28:29], v[68:69], v[54:55] op_sel_hi:[0,1]
	s_nop 1
	v_permlane16_swap_b32_e32 v28, v32
	v_permlane16_swap_b32_e32 v29, v33
	v_and_b32_e32 v22, 0xffff0000, v22
	v_pk_add_f32 v[26:27], v[68:69], v[56:57] op_sel_hi:[0,1]
	v_pk_add_f32 v[30:31], v[68:69], v[52:53] op_sel_hi:[0,1]
	v_mul_f32_e32 v28, v38, v28
	v_lshlrev_b32_e32 v38, 16, v18
	v_mul_f32_e32 v22, v22, v29
	v_and_b32_e32 v18, 0xffff0000, v18
	v_permlane16_swap_b32_e32 v26, v30
	v_permlane16_swap_b32_e32 v27, v31
	v_mul_f32_e32 v18, v22, v18
	v_lshlrev_b32_e32 v22, 16, v23
	v_and_b32_e32 v23, 0xffff0000, v23
	v_mul_f32_e32 v22, v22, v26
	v_lshlrev_b32_e32 v26, 16, v19
	v_mul_f32_e32 v23, v23, v27
	v_and_b32_e32 v19, 0xffff0000, v19
	v_mul_f32_e32 v22, v22, v26
	v_mul_f32_e32 v19, v23, v19
	v_mul_f32_e32 v28, v28, v38
	v_cvt_pk_bf16_f32 v18, v28, v18
	v_cvt_pk_bf16_f32 v19, v22, v19
	v_lshlrev_b32_e32 v22, 16, v24
	v_mul_f32_e32 v22, v22, v32
	v_lshlrev_b32_e32 v23, 16, v20
	v_mul_f32_e32 v22, v22, v23
	v_and_b32_e32 v23, 0xffff0000, v24
	v_mul_f32_e32 v23, v23, v33
	v_and_b32_e32 v20, 0xffff0000, v20
	v_mul_f32_e32 v20, v23, v20
	v_cvt_pk_bf16_f32 v20, v22, v20
	v_lshlrev_b32_e32 v22, 16, v25
	v_mul_f32_e32 v22, v22, v30
	v_lshlrev_b32_e32 v23, 16, v21
	v_mul_f32_e32 v22, v22, v23
	v_and_b32_e32 v23, 0xffff0000, v25
	v_mul_f32_e32 v23, v23, v31
	v_and_b32_e32 v21, 0xffff0000, v21
	v_mul_f32_e32 v21, v23, v21
	v_cvt_pk_bf16_f32 v21, v22, v21
	v_mov_b64_e32 v[22:23], s[28:29]
	v_mad_i64_i32 v[24:25], s[38:39], v69, s23, v[22:23]
	v_lshl_add_u64 v[24:25], v[24:25], 0, s[30:31]
	v_lshl_add_u64 v[24:25], v[24:25], 0, v[0:1]
	global_store_dwordx4 v[24:25], v[18:21], off offset:2048 sc1
	v_pk_add_f32 v[26:27], v[64:65], v[58:59] op_sel_hi:[0,1]
	v_lshlrev_b32_e32 v28, 16, v14
	v_pk_add_f32 v[20:21], v[64:65], v[72:73] op_sel_hi:[0,1]
	s_nop 1
	v_permlane16_swap_b32_e32 v20, v26
	v_permlane16_swap_b32_e32 v21, v27
	v_and_b32_e32 v14, 0xffff0000, v14
	v_pk_add_f32 v[18:19], v[64:65], v[74:75] op_sel_hi:[0,1]
	v_pk_add_f32 v[24:25], v[64:65], v[60:61] op_sel_hi:[0,1]
	v_mul_f32_e32 v20, v28, v20
	v_lshlrev_b32_e32 v28, 16, v10
	v_mul_f32_e32 v14, v14, v21
	v_and_b32_e32 v10, 0xffff0000, v10
	v_permlane16_swap_b32_e32 v18, v24
	v_permlane16_swap_b32_e32 v19, v25
	v_mul_f32_e32 v10, v14, v10
	v_lshlrev_b32_e32 v14, 16, v15
	v_and_b32_e32 v15, 0xffff0000, v15
	v_mul_f32_e32 v14, v14, v18
	v_lshlrev_b32_e32 v18, 16, v11
	v_mul_f32_e32 v15, v15, v19
	v_and_b32_e32 v11, 0xffff0000, v11
	v_mul_f32_e32 v14, v14, v18
	v_mul_f32_e32 v11, v15, v11
	v_mul_f32_e32 v20, v20, v28
	v_cvt_pk_bf16_f32 v10, v20, v10
	v_cvt_pk_bf16_f32 v11, v14, v11
	v_lshlrev_b32_e32 v14, 16, v16
	v_mul_f32_e32 v14, v14, v26
	v_lshlrev_b32_e32 v15, 16, v12
	v_mul_f32_e32 v14, v14, v15
	v_and_b32_e32 v15, 0xffff0000, v16
	v_mul_f32_e32 v15, v15, v27
	v_and_b32_e32 v12, 0xffff0000, v12
	v_mul_f32_e32 v12, v15, v12
	v_cvt_pk_bf16_f32 v12, v14, v12
	v_lshlrev_b32_e32 v14, 16, v17
	v_mul_f32_e32 v14, v14, v24
	v_lshlrev_b32_e32 v15, 16, v13
	v_mul_f32_e32 v14, v14, v15
	v_and_b32_e32 v15, 0xffff0000, v17
	v_mul_f32_e32 v15, v15, v25
	v_and_b32_e32 v13, 0xffff0000, v13
	s_waitcnt lgkmcnt(0)
	v_mfma_f32_16x16x32_bf16 v[34:37], v[80:83], v[76:79], v[34:37]
	v_mul_f32_e32 v13, v15, v13
	v_cvt_pk_bf16_f32 v13, v14, v13
	v_mad_i64_i32 v[14:15], s[38:39], v65, s23, v[22:23]
	v_mfma_f32_16x16x32_bf16 v[46:49], v[84:87], v[76:79], v[46:49]
	v_lshl_add_u64 v[14:15], v[14:15], 0, s[30:31]
	v_lshl_add_u64 v[14:15], v[14:15], 0, v[0:1]
	global_store_dwordx4 v[14:15], v[10:13], off offset:2048 sc1
	v_lshlrev_b32_e32 v18, 16, v6
	v_and_b32_e32 v6, 0xffff0000, v6
	v_pk_add_f32 v[12:13], v[62:63], v[34:35] op_sel_hi:[0,1]
	s_nop 1
	v_pk_add_f32 v[16:17], v[62:63], v[46:47] op_sel_hi:[0,1]
	s_nop 1
	v_permlane16_swap_b32_e32 v12, v16
	v_permlane16_swap_b32_e32 v13, v17
	v_pk_add_f32 v[10:11], v[62:63], v[36:37] op_sel_hi:[0,1]
	v_pk_add_f32 v[14:15], v[62:63], v[48:49] op_sel_hi:[0,1]
	v_mul_f32_e32 v12, v18, v12
	v_lshlrev_b32_e32 v18, 16, v2
	v_mul_f32_e32 v6, v6, v13
	v_and_b32_e32 v2, 0xffff0000, v2
	v_permlane16_swap_b32_e32 v10, v14
	v_permlane16_swap_b32_e32 v11, v15
	v_mul_f32_e32 v2, v6, v2
	v_lshlrev_b32_e32 v6, 16, v7
	v_and_b32_e32 v7, 0xffff0000, v7
	v_mul_f32_e32 v6, v6, v10
	v_lshlrev_b32_e32 v10, 16, v3
	v_mul_f32_e32 v7, v7, v11
	v_and_b32_e32 v3, 0xffff0000, v3
	v_mul_f32_e32 v6, v6, v10
	v_mul_f32_e32 v3, v7, v3
	v_mul_f32_e32 v12, v12, v18
	v_cvt_pk_bf16_f32 v2, v12, v2
	v_cvt_pk_bf16_f32 v3, v6, v3
	v_lshlrev_b32_e32 v6, 16, v8
	v_mul_f32_e32 v6, v6, v16
	v_lshlrev_b32_e32 v7, 16, v4
	v_mul_f32_e32 v6, v6, v7
	v_and_b32_e32 v7, 0xffff0000, v8
	v_mul_f32_e32 v7, v7, v17
	v_and_b32_e32 v4, 0xffff0000, v4
	v_mul_f32_e32 v4, v7, v4
	v_cvt_pk_bf16_f32 v4, v6, v4
	v_lshlrev_b32_e32 v6, 16, v9
	v_mul_f32_e32 v6, v6, v14
	v_lshlrev_b32_e32 v7, 16, v5
	v_mul_f32_e32 v6, v6, v7
	v_and_b32_e32 v7, 0xffff0000, v9
	v_mul_f32_e32 v7, v7, v15
	v_and_b32_e32 v5, 0xffff0000, v5
	v_mul_f32_e32 v5, v7, v5
	v_cvt_pk_bf16_f32 v5, v6, v5
	v_mad_i64_i32 v[6:7], s[38:39], v63, s23, v[22:23]
	v_lshl_add_u64 v[6:7], v[6:7], 0, s[30:31]
	v_lshl_add_u64 v[6:7], v[6:7], 0, v[0:1]
	global_store_dwordx4 v[6:7], v[2:5], off offset:2048 sc1
	s_barrier
	s_branch .LBB0_443

.LBB0_470:
	ds_read_b128 v[64:67], v62
	s_add_i32 s38, s38, -1
	v_add_u32_e32 v62, 0x110, v62
	s_cmp_gt_u32 s38, 1
	s_waitcnt lgkmcnt(0)
	v_lshlrev_b32_e32 v56, 16, v64
	v_and_b32_e32 v57, 0xffff0000, v64
	v_lshlrev_b32_e32 v54, 16, v65
	v_and_b32_e32 v55, 0xffff0000, v65
	v_lshlrev_b32_e32 v52, 16, v66
	v_and_b32_e32 v53, 0xffff0000, v66
	v_lshlrev_b32_e32 v50, 16, v67
	v_and_b32_e32 v51, 0xffff0000, v67
	v_pk_add_f32 v[48:49], v[48:49], v[56:57]
	v_pk_add_f32 v[46:47], v[46:47], v[54:55]
	v_pk_add_f32 v[36:37], v[36:37], v[52:53]
	v_pk_add_f32 v[34:35], v[34:35], v[50:51]
	s_cbranch_scc1 .LBB0_470
	v_add_u32_e32 v62, s60, v60
	v_and_b32_e32 v67, 0x7fc, v62
	v_or_b32_e32 v62, 1, v67
	v_min_u32_e32 v62, s30, v62
	v_cvt_f32_ubyte0_e32 v62, v62
	v_div_scale_f32 v63, s[38:39], v62, v62, 1.0
	v_rcp_f32_e32 v64, v63
	v_add3_u32 v66, s62, v61, v0
	v_add_u32_e32 v0, 0, v0
	s_sub_i32 s38, 1, s30
	v_fma_f32 v65, -v63, v64, 1.0
	v_fmac_f32_e32 v64, v65, v64
	v_div_scale_f32 v65, vcc, 1.0, v62, 1.0
	v_mul_f32_e32 v68, v65, v64
	v_fma_f32 v69, -v63, v68, v65
	v_fmac_f32_e32 v68, v69, v64
	v_fma_f32 v63, -v63, v68, v65
	v_div_fmas_f32 v63, v63, v64, v68
	v_div_fixup_f32 v65, v63, v62, 1.0
	v_fma_f32 v54, v65, v46, -v54
	v_add_u32_e32 v61, v0, v61
	s_mulk_i32 s38, 0x110
	v_fma_f32 v56, v65, v48, -v56
	v_fma_f32 v57, v65, v49, -v57
	v_cvt_pk_bf16_f32 v62, v56, v57
	v_fma_f32 v55, v65, v47, -v55
	v_cvt_pk_bf16_f32 v63, v54, v55
	v_fma_f32 v52, v65, v36, -v52
	v_fma_f32 v53, v65, v37, -v53
	v_cvt_pk_bf16_f32 v64, v52, v53
	v_fma_f32 v50, v65, v34, -v50
	v_fma_f32 v51, v65, v35, -v51
	v_cvt_pk_bf16_f32 v65, v50, v51
	ds_write_b128 v61, v[62:65]
	v_add_u32_e32 v54, s38, v66
	ds_read_b128 v[50:53], v66 offset:4352
	ds_read_b128 v[54:57], v54 offset:4080
	s_waitcnt lgkmcnt(1)
	v_lshlrev_b32_e32 v63, 16, v50
	s_waitcnt lgkmcnt(0)
	v_lshlrev_b32_e32 v62, 16, v54
	v_sub_f32_e32 v62, v63, v62
	v_add_f32_e32 v62, v48, v62
	v_and_b32_e32 v48, 0xffff0000, v54
	v_and_b32_e32 v50, 0xffff0000, v50
	v_sub_f32_e32 v48, v50, v48
	v_add_f32_e32 v54, v49, v48
	v_lshlrev_b32_e32 v48, 16, v55
	v_lshlrev_b32_e32 v49, 16, v51
	v_sub_f32_e32 v48, v49, v48
	v_add_f32_e32 v64, v46, v48
	v_and_b32_e32 v46, 0xffff0000, v55
	v_and_b32_e32 v48, 0xffff0000, v51
	v_sub_f32_e32 v46, v48, v46
	v_add_f32_e32 v51, v47, v46
	v_lshlrev_b32_e32 v46, 16, v56
	v_lshlrev_b32_e32 v47, 16, v52
	v_sub_f32_e32 v46, v47, v46
	v_add_f32_e32 v55, v36, v46
	v_and_b32_e32 v36, 0xffff0000, v56
	v_and_b32_e32 v46, 0xffff0000, v52
	v_sub_f32_e32 v36, v46, v36
	v_add_f32_e32 v52, v37, v36
	v_lshlrev_b32_e32 v36, 16, v57
	v_lshlrev_b32_e32 v37, 16, v53
	v_sub_f32_e32 v36, v37, v36
	v_add_f32_e32 v56, v34, v36
	v_and_b32_e32 v34, 0xffff0000, v57
	v_and_b32_e32 v53, 0xffff0000, v53
	v_sub_f32_e32 v34, v53, v34
	v_add_f32_e32 v57, v35, v34
	v_or_b32_e32 v34, 2, v67
	v_min_u32_e32 v34, s30, v34
	v_cvt_f32_ubyte0_e32 v34, v34
	v_div_scale_f32 v35, s[38:39], v34, v34, 1.0
	v_rcp_f32_e32 v36, v35
	s_sub_i32 s38, 2, s30
	s_mulk_i32 s38, 0x110
	v_fma_f32 v65, -v35, v36, 1.0
	v_fmac_f32_e32 v36, v65, v36
	v_div_scale_f32 v65, vcc, 1.0, v34, 1.0
	v_mul_f32_e32 v68, v65, v36
	v_fma_f32 v69, -v35, v68, v65
	v_fmac_f32_e32 v68, v69, v36
	v_fma_f32 v35, -v35, v68, v65
	v_div_fmas_f32 v35, v35, v36, v68
	v_div_fixup_f32 v65, v35, v34, 1.0
	v_fma_f32 v34, v65, v62, -v63
	v_fma_f32 v35, v65, v54, -v50
	v_cvt_pk_bf16_f32 v34, v34, v35
	v_fma_f32 v35, v65, v64, -v49
	v_fma_f32 v36, v65, v51, -v48
	v_cvt_pk_bf16_f32 v35, v35, v36
	v_fma_f32 v36, v65, v55, -v47
	v_fma_f32 v46, v65, v52, -v46
	v_cvt_pk_bf16_f32 v36, v36, v46
	v_fma_f32 v37, v65, v56, -v37
	v_fma_f32 v46, v65, v57, -v53
	v_cvt_pk_bf16_f32 v37, v37, v46
	ds_write_b128 v61, v[34:37] offset:272
	v_add_u32_e32 v46, s38, v66
	ds_read_b128 v[34:37], v66 offset:4624
	ds_read_b128 v[46:49], v46 offset:4080
	s_waitcnt lgkmcnt(1)
	v_lshlrev_b32_e32 v53, 16, v34
	s_waitcnt lgkmcnt(0)
	v_lshlrev_b32_e32 v50, 16, v46
	v_and_b32_e32 v46, 0xffff0000, v46
	v_and_b32_e32 v34, 0xffff0000, v34
	v_sub_f32_e32 v50, v53, v50
	v_sub_f32_e32 v46, v34, v46
	v_add_f32_e32 v50, v62, v50
	v_add_f32_e32 v54, v54, v46
	v_lshlrev_b32_e32 v46, 16, v47
	v_lshlrev_b32_e32 v62, 16, v35
	v_sub_f32_e32 v46, v62, v46
	v_add_f32_e32 v63, v64, v46
	v_and_b32_e32 v46, 0xffff0000, v47
	v_and_b32_e32 v35, 0xffff0000, v35
	v_sub_f32_e32 v46, v35, v46
	v_add_f32_e32 v51, v51, v46
	v_lshlrev_b32_e32 v46, 16, v48
	v_lshlrev_b32_e32 v47, 16, v36
	v_sub_f32_e32 v46, v47, v46
	v_add_f32_e32 v55, v55, v46
	v_and_b32_e32 v46, 0xffff0000, v48
	v_and_b32_e32 v36, 0xffff0000, v36
	v_sub_f32_e32 v46, v36, v46
	v_add_f32_e32 v52, v52, v46
	v_lshlrev_b32_e32 v46, 16, v49
	v_lshlrev_b32_e32 v48, 16, v37
	v_sub_f32_e32 v46, v48, v46
	v_add_f32_e32 v56, v56, v46
	v_and_b32_e32 v46, 0xffff0000, v49
	v_and_b32_e32 v37, 0xffff0000, v37
	v_sub_f32_e32 v46, v37, v46
	v_add_f32_e32 v57, v57, v46
	v_or_b32_e32 v46, 3, v67
	v_min_u32_e32 v46, s30, v46
	v_cvt_f32_ubyte0_e32 v46, v46
	v_div_scale_f32 v49, s[38:39], v46, v46, 1.0
	v_rcp_f32_e32 v64, v49
	s_sub_i32 s38, 3, s30
	s_mulk_i32 s38, 0x110
	v_fma_f32 v65, -v49, v64, 1.0
	v_fmac_f32_e32 v64, v65, v64
	v_div_scale_f32 v65, vcc, 1.0, v46, 1.0
	v_mul_f32_e32 v68, v65, v64
	v_fma_f32 v69, -v49, v68, v65
	v_fmac_f32_e32 v68, v69, v64
	v_fma_f32 v49, -v49, v68, v65
	v_div_fmas_f32 v49, v49, v64, v68
	v_div_fixup_f32 v46, v49, v46, 1.0
	v_fma_f32 v49, v46, v50, -v53
	v_fma_f32 v34, v46, v54, -v34
	v_fma_f32 v35, v46, v51, -v35
	v_fma_f32 v47, v46, v55, -v47
	v_fma_f32 v36, v46, v52, -v36
	v_fma_f32 v37, v46, v57, -v37
	v_cvt_pk_bf16_f32 v34, v49, v34
	v_fma_f32 v49, v46, v63, -v62
	v_cvt_pk_bf16_f32 v35, v49, v35
	v_cvt_pk_bf16_f32 v36, v47, v36
	v_fma_f32 v47, v46, v56, -v48
	v_cvt_pk_bf16_f32 v37, v47, v37
	ds_write_b128 v61, v[34:37] offset:544
	v_add_u32_e32 v46, s38, v66
	ds_read_b128 v[34:37], v66 offset:4896
	ds_read_b128 v[46:49], v46 offset:4080
	s_waitcnt lgkmcnt(1)
	v_lshlrev_b32_e32 v61, 16, v34
	s_waitcnt lgkmcnt(0)
	v_lshlrev_b32_e32 v53, 16, v46
	v_and_b32_e32 v46, 0xffff0000, v46
	v_and_b32_e32 v34, 0xffff0000, v34
	v_sub_f32_e32 v53, v61, v53
	v_sub_f32_e32 v46, v34, v46
	v_add_f32_e32 v50, v50, v53
	v_add_f32_e32 v46, v54, v46
	v_lshlrev_b32_e32 v53, 16, v47
	v_lshlrev_b32_e32 v54, 16, v35
	v_and_b32_e32 v47, 0xffff0000, v47
	v_and_b32_e32 v35, 0xffff0000, v35
	v_sub_f32_e32 v47, v35, v47
	v_add_f32_e32 v47, v51, v47
	v_lshlrev_b32_e32 v51, 16, v48
	v_lshlrev_b32_e32 v62, 16, v36
	v_and_b32_e32 v48, 0xffff0000, v48
	v_and_b32_e32 v36, 0xffff0000, v36
	v_sub_f32_e32 v51, v62, v51
	v_sub_f32_e32 v48, v36, v48
	v_add_f32_e32 v51, v55, v51
	v_add_f32_e32 v48, v52, v48
	v_lshlrev_b32_e32 v52, 16, v49
	v_lshlrev_b32_e32 v55, 16, v37
	v_sub_f32_e32 v52, v55, v52
	v_add_f32_e32 v52, v56, v52
	v_add_u32_e32 v56, 4, v67
	v_and_b32_e32 v49, 0xffff0000, v49
	v_and_b32_e32 v37, 0xffff0000, v37
	v_min_u32_e32 v56, s30, v56
	v_sub_f32_e32 v49, v37, v49
	v_cvt_f32_ubyte0_e32 v56, v56
	v_sub_f32_e32 v53, v54, v53
	v_add_f32_e32 v49, v57, v49
	v_div_scale_f32 v57, s[38:39], v56, v56, 1.0
	v_add_f32_e32 v53, v63, v53
	v_rcp_f32_e32 v63, v57
	s_nop 0
	v_fma_f32 v64, -v57, v63, 1.0
	v_fmac_f32_e32 v63, v64, v63
	v_div_scale_f32 v64, vcc, 1.0, v56, 1.0
	v_mul_f32_e32 v65, v64, v63
	v_fma_f32 v66, -v57, v65, v64
	v_fmac_f32_e32 v65, v66, v63
	v_fma_f32 v57, -v57, v65, v64
	v_div_fmas_f32 v57, v57, v63, v65
	v_div_fixup_f32 v56, v57, v56, 1.0
	v_fma_f32 v34, v56, v46, -v34
	v_fma_f32 v46, v56, v53, -v54
	v_fma_f32 v35, v56, v47, -v35
	v_fma_f32 v50, v56, v50, -v61
	v_cvt_pk_bf16_f32 v34, v50, v34
	v_cvt_pk_bf16_f32 v35, v46, v35
	v_fma_f32 v46, v56, v51, -v62
	v_fma_f32 v36, v56, v48, -v36
	v_cvt_pk_bf16_f32 v36, v46, v36
	v_fma_f32 v46, v56, v52, -v55
	v_fma_f32 v37, v56, v49, -v37
	v_cvt_pk_bf16_f32 v37, v46, v37
	v_or_b32_e32 v46, 3, v60
	v_mad_u64_u32 v[46:47], s[38:39], v46, s90, v[0:1]
	ds_write_b128 v46, v[34:37]
	v_or_b32_e32 v34, s57, v59
	v_lshl_add_u32 v0, v58, 4, 0
	v_or_b32_e32 v50, s56, v59
	v_mad_u32_u24 v100, v34, s90, v0
	v_mad_u64_u32 v[98:99], s[38:39], v50, s90, v[0:1]
	s_waitcnt lgkmcnt(0)
	s_barrier
	ds_read_b128 v[34:37], v100 offset:34816
	ds_read_b128 v[46:49], v100 offset:39168
	ds_read_b128 v[50:53], v98
	ds_read_b128 v[54:57], v98 offset:4352
	ds_read_b128 v[58:61], v98 offset:8704
	ds_read_b128 v[62:65], v98 offset:13056
	s_waitcnt lgkmcnt(3)
	v_mfma_f32_16x16x32_bf16 v[66:69], v[34:37], v[50:53], 0
	v_lshlrev_b32_e32 v0, 16, v30
	v_and_b32_e32 v30, 0xffff0000, v30
	v_mfma_f32_16x16x32_bf16 v[50:53], v[46:49], v[50:53], 0
	s_waitcnt lgkmcnt(2)
	v_mfma_f32_16x16x32_bf16 v[70:73], v[34:37], v[54:57], 0
	v_mfma_f32_16x16x32_bf16 v[54:57], v[46:49], v[54:57], 0
	s_waitcnt lgkmcnt(1)
	v_mfma_f32_16x16x32_bf16 v[74:77], v[34:37], v[58:61], 0
	v_mfma_f32_16x16x32_bf16 v[58:61], v[46:49], v[58:61], 0
	s_waitcnt lgkmcnt(0)
	v_mfma_f32_16x16x32_bf16 v[34:37], v[34:37], v[62:65], 0
	v_mfma_f32_16x16x32_bf16 v[46:49], v[46:49], v[62:65], 0
	ds_read_b128 v[62:65], v100 offset:34880
	ds_read_b128 v[78:81], v100 offset:39232
	ds_read_b128 v[82:85], v98 offset:64
	ds_read_b128 v[86:89], v98 offset:4416
	ds_read_b128 v[90:93], v98 offset:8768
	ds_read_b128 v[94:97], v98 offset:13120
	s_waitcnt lgkmcnt(3)
	v_mfma_f32_16x16x32_bf16 v[66:69], v[62:65], v[82:85], v[66:69]
	v_mfma_f32_16x16x32_bf16 v[50:53], v[78:81], v[82:85], v[50:53]
	s_waitcnt lgkmcnt(2)
	v_mfma_f32_16x16x32_bf16 v[70:73], v[62:65], v[86:89], v[70:73]
	v_mfma_f32_16x16x32_bf16 v[54:57], v[78:81], v[86:89], v[54:57]
	s_waitcnt lgkmcnt(1)
	v_mfma_f32_16x16x32_bf16 v[74:77], v[62:65], v[90:93], v[74:77]
	v_mfma_f32_16x16x32_bf16 v[58:61], v[78:81], v[90:93], v[58:61]
	s_waitcnt lgkmcnt(0)
	v_mfma_f32_16x16x32_bf16 v[34:37], v[62:65], v[94:97], v[34:37]
	v_mfma_f32_16x16x32_bf16 v[46:49], v[78:81], v[94:97], v[46:49]
	ds_read_b128 v[62:65], v100 offset:34944
	ds_read_b128 v[78:81], v100 offset:39296
	ds_read_b128 v[82:85], v98 offset:128
	ds_read_b128 v[86:89], v98 offset:4480
	ds_read_b128 v[90:93], v98 offset:8832
	ds_read_b128 v[94:97], v98 offset:13184
	s_waitcnt lgkmcnt(3)
	v_mfma_f32_16x16x32_bf16 v[66:69], v[62:65], v[82:85], v[66:69]
	v_mfma_f32_16x16x32_bf16 v[50:53], v[78:81], v[82:85], v[50:53]
	s_waitcnt lgkmcnt(2)
	v_mfma_f32_16x16x32_bf16 v[70:73], v[62:65], v[86:89], v[70:73]
	v_mfma_f32_16x16x32_bf16 v[54:57], v[78:81], v[86:89], v[54:57]
	s_waitcnt lgkmcnt(1)
	v_mfma_f32_16x16x32_bf16 v[74:77], v[62:65], v[90:93], v[74:77]
	v_mfma_f32_16x16x32_bf16 v[58:61], v[78:81], v[90:93], v[58:61]
	s_waitcnt lgkmcnt(0)
	v_mfma_f32_16x16x32_bf16 v[34:37], v[62:65], v[94:97], v[34:37]
	v_mfma_f32_16x16x32_bf16 v[46:49], v[78:81], v[94:97], v[46:49]
	ds_read_b128 v[62:65], v100 offset:35008
	ds_read_b128 v[78:81], v100 offset:39360
	ds_read_b128 v[82:85], v98 offset:192
	ds_read_b128 v[86:89], v98 offset:4544
	ds_read_b128 v[90:93], v98 offset:8896
	ds_read_b128 v[94:97], v98 offset:13248
	s_waitcnt lgkmcnt(3)
	v_mfma_f32_16x16x32_bf16 v[66:69], v[62:65], v[82:85], v[66:69]
	v_mfma_f32_16x16x32_bf16 v[50:53], v[78:81], v[82:85], v[50:53]
	s_waitcnt lgkmcnt(2)
	v_mfma_f32_16x16x32_bf16 v[70:73], v[62:65], v[86:89], v[70:73]
	s_waitcnt lgkmcnt(1)
	v_mfma_f32_16x16x32_bf16 v[74:77], v[62:65], v[90:93], v[74:77]
	s_nop 3
	v_add_f32_e64 v50, v6, v50
	v_add_f32_e64 v51, v7, v51
	v_pk_add_f32 v[52:53], v[8:9], v[52:53]
	v_pk_mul_f32 v[50:51], v[2:3], v[50:51]
	s_waitcnt lgkmcnt(0)
	v_mfma_f32_16x16x32_bf16 v[34:37], v[62:65], v[94:97], v[34:37]
	v_add_f32_e64 v64, v14, v66
	v_add_f32_e64 v65, v15, v67
	v_pk_add_f32 v[62:63], v[16:17], v[68:69]
	v_pk_mul_f32 v[64:65], v[10:11], v[64:65]
	v_pk_mul_f32 v[62:63], v[12:13], v[62:63]
	s_nop 0
	v_permlane16_swap_b32_e32 v64, v50
	v_permlane16_swap_b32_e32 v65, v51
	v_pk_mul_f32 v[52:53], v[4:5], v[52:53]
	v_mul_f32_e32 v0, v0, v64
	v_mul_f32_e32 v30, v30, v65
	v_permlane16_swap_b32_e32 v62, v52
	v_permlane16_swap_b32_e32 v63, v53
	v_cvt_pk_bf16_f32 v30, v0, v30
	v_lshlrev_b32_e32 v0, 16, v31
	v_and_b32_e32 v31, 0xffff0000, v31
	v_mul_f32_e32 v0, v0, v62
	v_mul_f32_e32 v31, v31, v63
	v_cvt_pk_bf16_f32 v31, v0, v31
	v_lshlrev_b32_e32 v0, 16, v32
	v_and_b32_e32 v32, 0xffff0000, v32
	v_mfma_f32_16x16x32_bf16 v[54:57], v[78:81], v[86:89], v[54:57]
	v_mul_f32_e32 v0, v0, v50
	v_mul_f32_e32 v32, v32, v51
	v_cvt_pk_bf16_f32 v32, v0, v32
	v_lshlrev_b32_e32 v0, 16, v33
	v_and_b32_e32 v33, 0xffff0000, v33
	v_mul_f32_e32 v33, v33, v53
	v_mul_f32_e32 v0, v0, v52
	v_cvt_pk_bf16_f32 v33, v0, v33
	global_store_dwordx4 v[44:45], v[30:33], off offset:1024 sc1
	s_nop 0
	v_pk_add_f32 v[50:51], v[6:7], v[54:55]
	v_pk_add_f32 v[44:45], v[8:9], v[56:57]
	v_pk_add_f32 v[32:33], v[14:15], v[70:71]
	v_pk_mul_f32 v[50:51], v[2:3], v[50:51]
	v_pk_mul_f32 v[32:33], v[10:11], v[32:33]
	v_pk_add_f32 v[30:31], v[16:17], v[72:73]
	s_nop 0
	v_permlane16_swap_b32_e32 v32, v50
	v_permlane16_swap_b32_e32 v33, v51
	v_lshlrev_b32_e32 v0, 16, v26
	v_and_b32_e32 v26, 0xffff0000, v26
	v_pk_mul_f32 v[30:31], v[12:13], v[30:31]
	v_pk_mul_f32 v[44:45], v[4:5], v[44:45]
	v_mul_f32_e32 v0, v0, v32
	v_mul_f32_e32 v26, v26, v33
	v_permlane16_swap_b32_e32 v30, v44
	v_permlane16_swap_b32_e32 v31, v45
	v_cvt_pk_bf16_f32 v26, v0, v26
	v_lshlrev_b32_e32 v0, 16, v27
	v_and_b32_e32 v27, 0xffff0000, v27
	v_mul_f32_e32 v0, v0, v30
	v_mul_f32_e32 v27, v27, v31
	v_cvt_pk_bf16_f32 v27, v0, v27
	v_lshlrev_b32_e32 v0, 16, v28
	v_and_b32_e32 v28, 0xffff0000, v28
	v_mfma_f32_16x16x32_bf16 v[58:61], v[78:81], v[90:93], v[58:61]
	v_mul_f32_e32 v0, v0, v50
	v_mul_f32_e32 v28, v28, v51
	v_cvt_pk_bf16_f32 v28, v0, v28
	v_lshlrev_b32_e32 v0, 16, v29
	v_and_b32_e32 v29, 0xffff0000, v29
	v_mul_f32_e32 v29, v29, v45
	v_mul_f32_e32 v0, v0, v44
	v_cvt_pk_bf16_f32 v29, v0, v29
	global_store_dwordx4 v[42:43], v[26:29], off offset:1024 sc1
	s_nop 0
	v_pk_add_f32 v[32:33], v[6:7], v[58:59]
	v_pk_add_f32 v[30:31], v[8:9], v[60:61]
	v_pk_add_f32 v[28:29], v[14:15], v[74:75]
	v_pk_mul_f32 v[32:33], v[2:3], v[32:33]
	v_pk_mul_f32 v[28:29], v[10:11], v[28:29]
	v_pk_add_f32 v[26:27], v[16:17], v[76:77]
	s_nop 0
	v_permlane16_swap_b32_e32 v28, v32
	v_permlane16_swap_b32_e32 v29, v33
	v_lshlrev_b32_e32 v0, 16, v22
	v_and_b32_e32 v22, 0xffff0000, v22
	v_pk_mul_f32 v[26:27], v[12:13], v[26:27]
	v_pk_mul_f32 v[30:31], v[4:5], v[30:31]
	v_mul_f32_e32 v0, v0, v28
	v_mul_f32_e32 v22, v22, v29
	v_mfma_f32_16x16x32_bf16 v[46:49], v[78:81], v[94:97], v[46:49]
	v_permlane16_swap_b32_e32 v26, v30
	v_permlane16_swap_b32_e32 v27, v31
	v_cvt_pk_bf16_f32 v22, v0, v22
	v_lshlrev_b32_e32 v0, 16, v23
	v_and_b32_e32 v23, 0xffff0000, v23
	v_mul_f32_e32 v0, v0, v26
	v_mul_f32_e32 v23, v23, v27
	v_cvt_pk_bf16_f32 v23, v0, v23
	v_lshlrev_b32_e32 v0, 16, v24
	v_and_b32_e32 v24, 0xffff0000, v24
	v_mul_f32_e32 v0, v0, v32
	v_mul_f32_e32 v24, v24, v33
	v_cvt_pk_bf16_f32 v24, v0, v24
	v_lshlrev_b32_e32 v0, 16, v25
	v_and_b32_e32 v25, 0xffff0000, v25
	v_pk_add_f32 v[14:15], v[14:15], v[34:35]
	v_pk_add_f32 v[8:9], v[8:9], v[48:49]
	v_pk_add_f32 v[6:7], v[6:7], v[46:47]
	v_mul_f32_e32 v0, v0, v30
	v_mul_f32_e32 v25, v25, v31
	v_pk_mul_f32 v[10:11], v[10:11], v[14:15]
	v_pk_mul_f32 v[8:9], v[4:5], v[8:9]
	v_pk_mul_f32 v[4:5], v[2:3], v[6:7]
	v_cvt_pk_bf16_f32 v25, v0, v25
	v_pk_add_f32 v[16:17], v[16:17], v[36:37]
	s_nop 0
	v_permlane16_swap_b32_e32 v10, v4
	v_permlane16_swap_b32_e32 v11, v5
	v_lshlrev_b32_e32 v0, 16, v18
	v_and_b32_e32 v2, 0xffff0000, v18
	v_pk_mul_f32 v[12:13], v[12:13], v[16:17]
	v_mul_f32_e32 v0, v0, v10
	v_mul_f32_e32 v2, v2, v11
	global_store_dwordx4 v[40:41], v[22:25], off offset:1024 sc1
	v_permlane16_swap_b32_e32 v12, v8
	v_permlane16_swap_b32_e32 v13, v9
	v_cvt_pk_bf16_f32 v2, v0, v2
	v_lshlrev_b32_e32 v0, 16, v19
	v_and_b32_e32 v3, 0xffff0000, v19
	v_mul_f32_e32 v0, v0, v12
	v_mul_f32_e32 v3, v3, v13
	v_cvt_pk_bf16_f32 v3, v0, v3
	v_lshlrev_b32_e32 v0, 16, v20
	v_mul_f32_e32 v0, v0, v4
	v_and_b32_e32 v4, 0xffff0000, v20
	v_mul_f32_e32 v4, v4, v5
	v_and_b32_e32 v5, 0xffff0000, v21
	v_cvt_pk_bf16_f32 v4, v0, v4
	v_lshlrev_b32_e32 v0, 16, v21
	v_mul_f32_e32 v5, v5, v9
	v_mul_f32_e32 v0, v0, v8
	v_cvt_pk_bf16_f32 v5, v0, v5
	global_store_dwordx4 v[38:39], v[2:5], off offset:1024 sc1
	s_barrier
	s_branch .LBB0_443
.Lp2_skipmix:
	s_mov_b32 s98, 0
.LBB0_472:
	s_cmp_eq_u32 s98, 1
	s_cbranch_scc0 .Lp2_seam
	s_mov_b32 s98, 2
	s_branch .Lp2_again

.LBB0_540:
	v_lshl_or_b32 v90, s69, 8, v161
	v_ashrrev_i32_e32 v91, 31, v90
	v_lshl_add_u64 v[90:91], v[90:91], 2, s[28:29]
	global_load_dwordx4 v[102:105], v[90:91], off
	global_load_dwordx4 v[98:101], v[90:91], off offset:16
	global_load_dwordx4 v[94:97], v[90:91], off offset:512
	s_nop 0
	global_load_dwordx4 v[90:93], v[90:91], off offset:528
	s_mul_i32 s43, s70, 12
	s_add_i32 s60, s43, s69
	s_ashr_i32 s61, s60, 31
	s_lshl_b64 s[60:61], s[60:61], 17
	v_lshl_add_u64 v[158:159], v[152:153], 0, s[60:61]
	s_movk_i32 s43, 0x2000
	s_waitcnt vmcnt(0)
	v_pk_add_f32 v[144:145], v[144:145], v[104:105]
	v_pk_add_f32 v[142:143], v[142:143], v[102:103]
	v_pk_add_f32 v[138:139], v[138:139], v[98:99]
	v_pk_add_f32 v[130:131], v[130:131], v[90:91]
	v_pk_add_f32 v[140:141], v[140:141], v[100:101]
	v_mul_f32_e32 v142, 0xbfb8aa3b, v142
	v_mul_f32_e32 v138, 0xbfb8aa3b, v138
	v_mul_f32_e32 v143, 0xbfb8aa3b, v143
	v_mul_f32_e32 v144, 0xbfb8aa3b, v144
	v_mul_f32_e32 v145, 0xbfb8aa3b, v145
	v_mul_f32_e32 v130, 0xbfb8aa3b, v130
	v_mul_f32_e32 v139, 0xbfb8aa3b, v139
	v_mul_f32_e32 v140, 0xbfb8aa3b, v140
	v_mul_f32_e32 v141, 0xbfb8aa3b, v141
	v_mul_f32_e32 v131, 0xbfb8aa3b, v131
	v_exp_f32_e32 v142, v142
	v_exp_f32_e32 v138, v138
	v_exp_f32_e32 v143, v143
	v_exp_f32_e32 v144, v144
	v_exp_f32_e32 v145, v145
	v_exp_f32_e32 v130, v130
	v_exp_f32_e32 v139, v139
	v_exp_f32_e32 v140, v140
	v_exp_f32_e32 v141, v141
	v_exp_f32_e32 v131, v131
	v_pk_add_f32 v[132:133], v[132:133], v[92:93]
	v_pk_add_f32 v[136:137], v[136:137], v[96:97]
	v_mul_f32_e32 v132, 0xbfb8aa3b, v132
	v_mul_f32_e32 v133, 0xbfb8aa3b, v133
	v_pk_add_f32 v[134:135], v[134:135], v[94:95]
	v_exp_f32_e32 v132, v132
	v_exp_f32_e32 v163, v133
	v_add_f32_e32 v133, 1.0, v142
	v_add_f32_e32 v138, 1.0, v138
	v_add_f32_e32 v142, 1.0, v143
	v_add_f32_e32 v143, 1.0, v144
	v_add_f32_e32 v144, 1.0, v145
	v_add_f32_e32 v130, 1.0, v130
	v_mul_f32_e32 v134, 0xbfb8aa3b, v134
	v_mul_f32_e32 v135, 0xbfb8aa3b, v135
	v_mul_f32_e32 v136, 0xbfb8aa3b, v136
	v_mul_f32_e32 v137, 0xbfb8aa3b, v137
	v_add_f32_e32 v139, 1.0, v139
	v_add_f32_e32 v140, 1.0, v140
	v_add_f32_e32 v141, 1.0, v141
	v_add_f32_e32 v131, 1.0, v131
	v_rcp_f32_e32 v133, v133
	v_rcp_f32_e32 v138, v138
	v_rcp_f32_e32 v142, v142
	v_rcp_f32_e32 v143, v143
	v_rcp_f32_e32 v144, v144
	v_rcp_f32_e32 v130, v130
	v_pk_add_f32 v[126:127], v[126:127], v[102:103]
	v_pk_add_f32 v[122:123], v[122:123], v[98:99]
	v_exp_f32_e32 v134, v134
	v_exp_f32_e32 v135, v135
	v_exp_f32_e32 v136, v136
	v_exp_f32_e32 v137, v137
	v_rcp_f32_e32 v139, v139
	v_rcp_f32_e32 v140, v140
	v_rcp_f32_e32 v141, v141
	v_rcp_f32_e32 v131, v131
	v_mul_f32_e32 v122, 0xbfb8aa3b, v122
	v_mul_f32_e32 v127, 0xbfb8aa3b, v127
	v_exp_f32_e32 v122, v122
	v_exp_f32_e32 v127, v127
	v_add_f32_e32 v132, 1.0, v132
	v_rcp_f32_e32 v145, v132
	v_max_f32_e32 v132, 0x219392ef, v133
	v_max_f32_e32 v133, 0x219392ef, v138
	v_max_f32_e32 v138, 0x219392ef, v142
	v_max_f32_e32 v142, 0x219392ef, v143
	v_max_f32_e32 v143, 0x219392ef, v144
	v_max_f32_e32 v144, 0x219392ef, v130
	v_cvt_pk_bf16_f32 v130, v132, v138
	v_add_f32_e32 v134, 1.0, v134
	v_add_f32_e32 v135, 1.0, v135
	v_add_f32_e32 v136, 1.0, v136
	v_max_f32_e32 v139, 0x219392ef, v139
	v_max_f32_e32 v140, 0x219392ef, v140
	v_max_f32_e32 v141, 0x219392ef, v141
	v_max_f32_e32 v164, 0x219392ef, v131
	v_cvt_pk_bf16_f32 v131, v142, v143
	v_cvt_pk_bf16_f32 v132, v133, v139
	v_cvt_pk_bf16_f32 v133, v140, v141
	global_store_dwordx4 v[158:159], v[130:133], off sc1
	v_rcp_f32_e32 v134, v134
	v_rcp_f32_e32 v135, v135
	v_add_f32_e32 v130, 1.0, v137
	v_rcp_f32_e32 v136, v136
	v_rcp_f32_e32 v130, v130
	v_add_f32_e32 v131, 1.0, v163
	v_add_f32_e32 v122, 1.0, v122
	v_add_f32_e32 v127, 1.0, v127
	v_mul_f32_e32 v123, 0xbfb8aa3b, v123
	v_rcp_f32_e32 v131, v131
	v_rcp_f32_e32 v122, v122
	v_rcp_f32_e32 v127, v127
	v_exp_f32_e32 v123, v123
	v_max_f32_e32 v134, 0x219392ef, v134
	v_max_f32_e32 v135, 0x219392ef, v135
	v_max_f32_e32 v132, 0x219392ef, v136
	v_max_f32_e32 v133, 0x219392ef, v145
	v_max_f32_e32 v136, 0x219392ef, v130
	v_cvt_pk_bf16_f32 v130, v134, v135
	v_pk_add_f32 v[128:129], v[128:129], v[104:105]
	v_max_f32_e32 v137, 0x219392ef, v131
	v_cvt_pk_bf16_f32 v131, v132, v136
	v_cvt_pk_bf16_f32 v132, v144, v164
	v_cvt_pk_bf16_f32 v133, v133, v137
	global_store_dwordx4 v[158:159], v[130:133], off offset:1024 sc1
	v_add_f32_e32 v123, 1.0, v123
	v_rcp_f32_e32 v123, v123
	v_max_f32_e32 v130, 0x219392ef, v122
	v_max_f32_e32 v122, 0x219392ef, v127
	v_mul_f32_e32 v127, 0xbfb8aa3b, v128
	v_exp_f32_e32 v127, v127
	v_pk_add_f32 v[124:125], v[124:125], v[100:101]
	v_mul_f32_e32 v126, 0xbfb8aa3b, v126
	v_mul_f32_e32 v124, 0xbfb8aa3b, v124
	v_max_f32_e32 v128, 0x219392ef, v123
	v_add_f32_e32 v123, 1.0, v127
	v_mul_f32_e32 v127, 0xbfb8aa3b, v129
	v_mul_f32_e32 v125, 0xbfb8aa3b, v125
	v_pk_add_f32 v[118:119], v[118:119], v[94:95]
	v_pk_add_f32 v[114:115], v[114:115], v[90:91]
	v_exp_f32_e32 v126, v126
	v_exp_f32_e32 v124, v124
	v_exp_f32_e32 v127, v127
	v_exp_f32_e32 v125, v125
	v_mul_f32_e32 v114, 0xbfb8aa3b, v114
	v_mul_f32_e32 v119, 0xbfb8aa3b, v119
	v_exp_f32_e32 v114, v114
	v_exp_f32_e32 v119, v119
	v_add_f32_e32 v126, 1.0, v126
	v_add_f32_e32 v124, 1.0, v124
	v_add_f32_e32 v127, 1.0, v127
	v_add_f32_e32 v125, 1.0, v125
	v_rcp_f32_e32 v126, v126
	v_rcp_f32_e32 v123, v123
	v_rcp_f32_e32 v124, v124
	v_rcp_f32_e32 v127, v127
	v_rcp_f32_e32 v125, v125
	v_add_f32_e32 v114, 1.0, v114
	v_add_f32_e32 v119, 1.0, v119
	v_mul_f32_e32 v115, 0xbfb8aa3b, v115
	v_rcp_f32_e32 v114, v114
	v_rcp_f32_e32 v119, v119
	v_exp_f32_e32 v115, v115
	v_max_f32_e32 v126, 0x219392ef, v126
	v_max_f32_e32 v123, 0x219392ef, v123
	v_max_f32_e32 v129, 0x219392ef, v124
	v_max_f32_e32 v124, 0x219392ef, v127
	v_max_f32_e32 v125, 0x219392ef, v125
	v_cvt_pk_bf16_f32 v122, v126, v122
	v_pk_add_f32 v[120:121], v[120:121], v[96:97]
	v_cvt_pk_bf16_f32 v123, v123, v124
	v_cvt_pk_bf16_f32 v124, v130, v128
	v_cvt_pk_bf16_f32 v125, v129, v125
	global_store_dwordx4 v[158:159], v[122:125], off offset:2048 sc1
	v_add_f32_e32 v115, 1.0, v115
	v_rcp_f32_e32 v115, v115
	v_max_f32_e32 v122, 0x219392ef, v114
	v_max_f32_e32 v114, 0x219392ef, v119
	v_mul_f32_e32 v119, 0xbfb8aa3b, v120
	v_exp_f32_e32 v119, v119
	v_pk_add_f32 v[116:117], v[116:117], v[92:93]
	v_pk_add_f32 v[112:113], v[112:113], v[104:105]
	v_mul_f32_e32 v118, 0xbfb8aa3b, v118
	v_mul_f32_e32 v116, 0xbfb8aa3b, v116
	v_max_f32_e32 v120, 0x219392ef, v115
	v_add_f32_e32 v115, 1.0, v119
	v_mul_f32_e32 v119, 0xbfb8aa3b, v121
	v_mul_f32_e32 v117, 0xbfb8aa3b, v117
	v_pk_add_f32 v[110:111], v[110:111], v[102:103]
	v_pk_add_f32 v[108:109], v[108:109], v[100:101]
	v_mul_f32_e32 v112, 0xbfb8aa3b, v112
	v_exp_f32_e32 v118, v118
	v_exp_f32_e32 v116, v116
	v_exp_f32_e32 v119, v119
	v_exp_f32_e32 v117, v117
	v_mul_f32_e32 v110, 0xbfb8aa3b, v110
	v_pk_add_f32 v[106:107], v[106:107], v[98:99]
	v_mul_f32_e32 v111, 0xbfb8aa3b, v111
	v_exp_f32_e32 v112, v112
	v_mul_f32_e32 v108, 0xbfb8aa3b, v108
	v_mul_f32_e32 v113, 0xbfb8aa3b, v113
	v_mul_f32_e32 v109, 0xbfb8aa3b, v109
	v_exp_f32_e32 v110, v110
	v_mul_f32_e32 v106, 0xbfb8aa3b, v106
	v_exp_f32_e32 v111, v111
	v_exp_f32_e32 v108, v108
	v_exp_f32_e32 v113, v113
	v_exp_f32_e32 v109, v109
	v_exp_f32_e32 v106, v106
	v_mul_f32_e32 v107, 0xbfb8aa3b, v107
	v_exp_f32_e32 v107, v107
	v_pk_add_f32 v[86:87], v[86:87], v[94:95]
	v_pk_add_f32 v[82:83], v[82:83], v[90:91]
	v_add_f32_e32 v118, 1.0, v118
	v_rcp_f32_e32 v115, v115
	v_add_f32_e32 v116, 1.0, v116
	v_add_f32_e32 v119, 1.0, v119
	v_add_f32_e32 v117, 1.0, v117
	v_add_f32_e32 v112, 1.0, v112
	v_mul_f32_e32 v82, 0xbfb8aa3b, v82
	v_mul_f32_e32 v87, 0xbfb8aa3b, v87
	v_rcp_f32_e32 v118, v118
	v_rcp_f32_e32 v116, v116
	v_rcp_f32_e32 v119, v119
	v_rcp_f32_e32 v117, v117
	v_add_f32_e32 v110, 1.0, v110
	v_add_f32_e32 v111, 1.0, v111
	v_rcp_f32_e32 v112, v112
	v_add_f32_e32 v108, 1.0, v108
	v_add_f32_e32 v113, 1.0, v113
	v_add_f32_e32 v109, 1.0, v109
	v_exp_f32_e32 v82, v82
	v_exp_f32_e32 v87, v87
	v_rcp_f32_e32 v110, v110
	v_add_f32_e32 v106, 1.0, v106
	v_rcp_f32_e32 v111, v111
	v_rcp_f32_e32 v108, v108
	v_rcp_f32_e32 v113, v113
	v_rcp_f32_e32 v109, v109
	v_rcp_f32_e32 v106, v106
	v_add_f32_e32 v107, 1.0, v107
	v_max_f32_e32 v115, 0x219392ef, v115
	v_rcp_f32_e32 v107, v107
	v_max_f32_e32 v118, 0x219392ef, v118
	v_max_f32_e32 v121, 0x219392ef, v116
	v_max_f32_e32 v116, 0x219392ef, v119
	v_max_f32_e32 v117, 0x219392ef, v117
	v_cvt_pk_bf16_f32 v114, v118, v114
	v_cvt_pk_bf16_f32 v115, v115, v116
	v_max_f32_e32 v112, 0x219392ef, v112
	v_add_f32_e32 v82, 1.0, v82
	v_add_f32_e32 v87, 1.0, v87
	v_mul_f32_e32 v83, 0xbfb8aa3b, v83
	v_cvt_pk_bf16_f32 v116, v122, v120
	v_cvt_pk_bf16_f32 v117, v121, v117
	global_store_dwordx4 v[158:159], v[114:117], off offset:3072 sc1
	v_max_f32_e32 v110, 0x219392ef, v110
	v_max_f32_e32 v111, 0x219392ef, v111
	v_max_f32_e32 v114, 0x219392ef, v108
	v_max_f32_e32 v113, 0x219392ef, v113
	v_max_f32_e32 v115, 0x219392ef, v109
	v_cvt_pk_bf16_f32 v108, v110, v111
	v_cvt_pk_bf16_f32 v109, v112, v113
	v_add_co_u32_e32 v112, vcc, s91, v158
	v_rcp_f32_e32 v82, v82
	v_rcp_f32_e32 v87, v87
	v_exp_f32_e32 v83, v83
	v_max_f32_e32 v106, 0x219392ef, v106
	v_addc_co_u32_e32 v113, vcc, 0, v159, vcc
	v_max_f32_e32 v107, 0x219392ef, v107
	v_cvt_pk_bf16_f32 v110, v106, v107
	v_add_co_u32_e32 v106, vcc, s43, v158
	v_pk_add_f32 v[88:89], v[88:89], v[96:97]
	s_nop 0
	v_addc_co_u32_e32 v107, vcc, 0, v159, vcc
	v_cvt_pk_bf16_f32 v111, v114, v115
	global_store_dwordx4 v[106:107], v[108:111], off offset:-4096 sc1
	v_add_f32_e32 v83, 1.0, v83
	v_rcp_f32_e32 v83, v83
	v_max_f32_e32 v108, 0x219392ef, v82
	v_max_f32_e32 v82, 0x219392ef, v87
	v_mul_f32_e32 v87, 0xbfb8aa3b, v88
	v_exp_f32_e32 v87, v87
	v_pk_add_f32 v[84:85], v[84:85], v[92:93]
	v_mul_f32_e32 v86, 0xbfb8aa3b, v86
	v_mul_f32_e32 v84, 0xbfb8aa3b, v84
	v_max_f32_e32 v88, 0x219392ef, v83
	v_add_f32_e32 v83, 1.0, v87
	v_mul_f32_e32 v87, 0xbfb8aa3b, v89
	v_mul_f32_e32 v85, 0xbfb8aa3b, v85
	v_pk_add_f32 v[78:79], v[78:79], v[102:103]
	v_pk_add_f32 v[74:75], v[74:75], v[98:99]
	v_exp_f32_e32 v86, v86
	v_exp_f32_e32 v84, v84
	v_exp_f32_e32 v87, v87
	v_exp_f32_e32 v85, v85
	v_mul_f32_e32 v74, 0xbfb8aa3b, v74
	v_mul_f32_e32 v79, 0xbfb8aa3b, v79
	v_exp_f32_e32 v74, v74
	v_exp_f32_e32 v79, v79
	v_add_f32_e32 v86, 1.0, v86
	v_add_f32_e32 v84, 1.0, v84
	v_add_f32_e32 v87, 1.0, v87
	v_add_f32_e32 v85, 1.0, v85
	v_rcp_f32_e32 v86, v86
	v_rcp_f32_e32 v83, v83
	v_rcp_f32_e32 v84, v84
	v_rcp_f32_e32 v87, v87
	v_rcp_f32_e32 v85, v85
	v_add_f32_e32 v74, 1.0, v74
	v_add_f32_e32 v79, 1.0, v79
	v_mul_f32_e32 v75, 0xbfb8aa3b, v75
	v_rcp_f32_e32 v74, v74
	v_rcp_f32_e32 v79, v79
	v_exp_f32_e32 v75, v75
	v_max_f32_e32 v86, 0x219392ef, v86
	v_max_f32_e32 v83, 0x219392ef, v83
	v_max_f32_e32 v89, 0x219392ef, v84
	v_max_f32_e32 v84, 0x219392ef, v87
	v_max_f32_e32 v85, 0x219392ef, v85
	v_cvt_pk_bf16_f32 v82, v86, v82
	v_pk_add_f32 v[80:81], v[80:81], v[104:105]
	v_cvt_pk_bf16_f32 v83, v83, v84
	v_cvt_pk_bf16_f32 v84, v108, v88
	v_cvt_pk_bf16_f32 v85, v89, v85
	global_store_dwordx4 v[112:113], v[82:85], off offset:1024 sc1
	v_add_f32_e32 v75, 1.0, v75
	v_rcp_f32_e32 v75, v75
	v_max_f32_e32 v82, 0x219392ef, v74
	v_max_f32_e32 v74, 0x219392ef, v79
	v_mul_f32_e32 v79, 0xbfb8aa3b, v80
	v_exp_f32_e32 v79, v79
	v_pk_add_f32 v[76:77], v[76:77], v[100:101]
	v_mul_f32_e32 v78, 0xbfb8aa3b, v78
	v_mul_f32_e32 v76, 0xbfb8aa3b, v76
	v_max_f32_e32 v80, 0x219392ef, v75
	v_add_f32_e32 v75, 1.0, v79
	v_mul_f32_e32 v79, 0xbfb8aa3b, v81
	v_mul_f32_e32 v77, 0xbfb8aa3b, v77
	v_pk_add_f32 v[70:71], v[70:71], v[94:95]
	v_pk_add_f32 v[66:67], v[66:67], v[90:91]
	v_exp_f32_e32 v78, v78
	v_exp_f32_e32 v76, v76
	v_exp_f32_e32 v79, v79
	v_exp_f32_e32 v77, v77
	v_mul_f32_e32 v66, 0xbfb8aa3b, v66
	v_mul_f32_e32 v71, 0xbfb8aa3b, v71
	v_exp_f32_e32 v66, v66
	v_exp_f32_e32 v71, v71
	v_add_f32_e32 v78, 1.0, v78
	v_add_f32_e32 v76, 1.0, v76
	v_add_f32_e32 v79, 1.0, v79
	v_add_f32_e32 v77, 1.0, v77
	v_rcp_f32_e32 v78, v78
	v_rcp_f32_e32 v75, v75
	v_rcp_f32_e32 v76, v76
	v_rcp_f32_e32 v79, v79
	v_rcp_f32_e32 v77, v77
	v_add_f32_e32 v66, 1.0, v66
	v_add_f32_e32 v71, 1.0, v71
	v_mul_f32_e32 v67, 0xbfb8aa3b, v67
	v_rcp_f32_e32 v66, v66
	v_rcp_f32_e32 v71, v71
	v_exp_f32_e32 v67, v67
	v_max_f32_e32 v78, 0x219392ef, v78
	v_max_f32_e32 v75, 0x219392ef, v75
	v_max_f32_e32 v81, 0x219392ef, v76
	v_max_f32_e32 v76, 0x219392ef, v79
	v_max_f32_e32 v77, 0x219392ef, v77
	v_cvt_pk_bf16_f32 v74, v78, v74
	v_pk_add_f32 v[72:73], v[72:73], v[96:97]
	v_cvt_pk_bf16_f32 v75, v75, v76
	v_cvt_pk_bf16_f32 v76, v82, v80
	v_cvt_pk_bf16_f32 v77, v81, v77
	global_store_dwordx4 v[112:113], v[74:77], off offset:2048 sc1
	v_add_f32_e32 v67, 1.0, v67
	v_rcp_f32_e32 v67, v67
	v_max_f32_e32 v74, 0x219392ef, v66
	v_max_f32_e32 v66, 0x219392ef, v71
	v_mul_f32_e32 v71, 0xbfb8aa3b, v72
	v_exp_f32_e32 v71, v71
	v_pk_add_f32 v[68:69], v[68:69], v[92:93]
	v_mul_f32_e32 v70, 0xbfb8aa3b, v70
	v_mul_f32_e32 v68, 0xbfb8aa3b, v68
	v_max_f32_e32 v72, 0x219392ef, v67
	v_add_f32_e32 v67, 1.0, v71
	v_mul_f32_e32 v71, 0xbfb8aa3b, v73
	v_mul_f32_e32 v69, 0xbfb8aa3b, v69
	v_pk_add_f32 v[62:63], v[62:63], v[102:103]
	v_pk_add_f32 v[58:59], v[58:59], v[98:99]
	v_exp_f32_e32 v70, v70
	v_exp_f32_e32 v68, v68
	v_exp_f32_e32 v71, v71
	v_exp_f32_e32 v69, v69
	v_mul_f32_e32 v58, 0xbfb8aa3b, v58
	v_mul_f32_e32 v63, 0xbfb8aa3b, v63
	v_exp_f32_e32 v58, v58
	v_exp_f32_e32 v63, v63
	v_add_f32_e32 v70, 1.0, v70
	v_add_f32_e32 v68, 1.0, v68
	v_add_f32_e32 v71, 1.0, v71
	v_add_f32_e32 v69, 1.0, v69
	v_rcp_f32_e32 v70, v70
	v_rcp_f32_e32 v67, v67
	v_rcp_f32_e32 v68, v68
	v_rcp_f32_e32 v71, v71
	v_rcp_f32_e32 v69, v69
	v_add_f32_e32 v58, 1.0, v58
	v_add_f32_e32 v63, 1.0, v63
	v_mul_f32_e32 v59, 0xbfb8aa3b, v59
	v_rcp_f32_e32 v58, v58
	v_rcp_f32_e32 v63, v63
	v_exp_f32_e32 v59, v59
	v_max_f32_e32 v70, 0x219392ef, v70
	v_max_f32_e32 v67, 0x219392ef, v67
	v_max_f32_e32 v73, 0x219392ef, v68
	v_max_f32_e32 v68, 0x219392ef, v71
	v_max_f32_e32 v69, 0x219392ef, v69
	v_cvt_pk_bf16_f32 v66, v70, v66
	v_pk_add_f32 v[64:65], v[64:65], v[104:105]
	v_cvt_pk_bf16_f32 v67, v67, v68
	v_cvt_pk_bf16_f32 v68, v74, v72
	v_cvt_pk_bf16_f32 v69, v73, v69
	global_store_dwordx4 v[112:113], v[66:69], off offset:3072 sc1
	v_add_f32_e32 v59, 1.0, v59
	v_rcp_f32_e32 v59, v59
	v_max_f32_e32 v66, 0x219392ef, v58
	v_max_f32_e32 v58, 0x219392ef, v63
	v_mul_f32_e32 v63, 0xbfb8aa3b, v64
	v_exp_f32_e32 v63, v63
	v_pk_add_f32 v[60:61], v[60:61], v[100:101]
	v_mul_f32_e32 v62, 0xbfb8aa3b, v62
	v_mul_f32_e32 v60, 0xbfb8aa3b, v60
	v_max_f32_e32 v64, 0x219392ef, v59
	v_add_f32_e32 v59, 1.0, v63
	v_mul_f32_e32 v63, 0xbfb8aa3b, v65
	v_mul_f32_e32 v61, 0xbfb8aa3b, v61
	v_pk_add_f32 v[54:55], v[54:55], v[94:95]
	v_pk_add_f32 v[50:51], v[50:51], v[90:91]
	v_exp_f32_e32 v62, v62
	v_exp_f32_e32 v60, v60
	v_exp_f32_e32 v63, v63
	v_exp_f32_e32 v61, v61
	v_mul_f32_e32 v50, 0xbfb8aa3b, v50
	v_mul_f32_e32 v55, 0xbfb8aa3b, v55
	v_exp_f32_e32 v50, v50
	v_exp_f32_e32 v55, v55
	v_add_f32_e32 v62, 1.0, v62
	v_add_f32_e32 v60, 1.0, v60
	v_add_f32_e32 v63, 1.0, v63
	v_add_f32_e32 v61, 1.0, v61
	v_rcp_f32_e32 v62, v62
	v_rcp_f32_e32 v59, v59
	v_rcp_f32_e32 v60, v60
	v_rcp_f32_e32 v63, v63
	v_rcp_f32_e32 v61, v61
	v_add_f32_e32 v50, 1.0, v50
	v_add_f32_e32 v55, 1.0, v55
	v_mul_f32_e32 v51, 0xbfb8aa3b, v51
	v_rcp_f32_e32 v50, v50
	v_rcp_f32_e32 v55, v55
	v_exp_f32_e32 v51, v51
	v_max_f32_e32 v62, 0x219392ef, v62
	v_max_f32_e32 v59, 0x219392ef, v59
	v_max_f32_e32 v65, 0x219392ef, v60
	v_max_f32_e32 v60, 0x219392ef, v63
	v_max_f32_e32 v61, 0x219392ef, v61
	v_cvt_pk_bf16_f32 v58, v62, v58
	v_pk_add_f32 v[56:57], v[56:57], v[96:97]
	v_cvt_pk_bf16_f32 v59, v59, v60
	v_cvt_pk_bf16_f32 v60, v66, v64
	v_cvt_pk_bf16_f32 v61, v65, v61
	global_store_dwordx4 v[106:107], v[58:61], off sc1
	v_add_f32_e32 v51, 1.0, v51
	v_rcp_f32_e32 v51, v51
	v_max_f32_e32 v58, 0x219392ef, v50
	v_max_f32_e32 v50, 0x219392ef, v55
	v_mul_f32_e32 v55, 0xbfb8aa3b, v56
	v_exp_f32_e32 v55, v55
	v_pk_add_f32 v[52:53], v[52:53], v[92:93]
	v_mul_f32_e32 v54, 0xbfb8aa3b, v54
	v_mul_f32_e32 v52, 0xbfb8aa3b, v52
	v_max_f32_e32 v56, 0x219392ef, v51
	v_add_f32_e32 v51, 1.0, v55
	v_mul_f32_e32 v55, 0xbfb8aa3b, v57
	v_mul_f32_e32 v53, 0xbfb8aa3b, v53
	v_pk_add_f32 v[46:47], v[46:47], v[102:103]
	v_pk_add_f32 v[42:43], v[42:43], v[98:99]
	v_exp_f32_e32 v54, v54
	v_exp_f32_e32 v52, v52
	v_exp_f32_e32 v55, v55
	v_exp_f32_e32 v53, v53
	v_mul_f32_e32 v42, 0xbfb8aa3b, v42
	v_mul_f32_e32 v47, 0xbfb8aa3b, v47
	v_exp_f32_e32 v42, v42
	v_exp_f32_e32 v47, v47
	v_add_f32_e32 v54, 1.0, v54
	v_add_f32_e32 v52, 1.0, v52
	v_add_f32_e32 v55, 1.0, v55
	v_add_f32_e32 v53, 1.0, v53
	v_rcp_f32_e32 v54, v54
	v_rcp_f32_e32 v51, v51
	v_rcp_f32_e32 v52, v52
	v_rcp_f32_e32 v55, v55
	v_rcp_f32_e32 v53, v53
	v_add_f32_e32 v42, 1.0, v42
	v_add_f32_e32 v47, 1.0, v47
	v_mul_f32_e32 v43, 0xbfb8aa3b, v43
	v_rcp_f32_e32 v42, v42
	v_rcp_f32_e32 v47, v47
	v_exp_f32_e32 v43, v43
	v_max_f32_e32 v54, 0x219392ef, v54
	v_max_f32_e32 v51, 0x219392ef, v51
	v_max_f32_e32 v57, 0x219392ef, v52
	v_max_f32_e32 v52, 0x219392ef, v55
	v_max_f32_e32 v53, 0x219392ef, v53
	v_cvt_pk_bf16_f32 v50, v54, v50
	v_pk_add_f32 v[48:49], v[48:49], v[104:105]
	v_cvt_pk_bf16_f32 v51, v51, v52
	v_cvt_pk_bf16_f32 v52, v58, v56
	v_cvt_pk_bf16_f32 v53, v57, v53
	global_store_dwordx4 v[106:107], v[50:53], off offset:1024 sc1
	v_add_f32_e32 v43, 1.0, v43
	v_rcp_f32_e32 v43, v43
	v_max_f32_e32 v50, 0x219392ef, v42
	v_max_f32_e32 v42, 0x219392ef, v47
	v_mul_f32_e32 v47, 0xbfb8aa3b, v48
	v_exp_f32_e32 v47, v47
	v_pk_add_f32 v[44:45], v[44:45], v[100:101]
	v_mul_f32_e32 v46, 0xbfb8aa3b, v46
	v_mul_f32_e32 v44, 0xbfb8aa3b, v44
	v_max_f32_e32 v48, 0x219392ef, v43
	v_add_f32_e32 v43, 1.0, v47
	v_mul_f32_e32 v47, 0xbfb8aa3b, v49
	v_mul_f32_e32 v45, 0xbfb8aa3b, v45
	v_pk_add_f32 v[38:39], v[38:39], v[94:95]
	v_pk_add_f32 v[34:35], v[34:35], v[90:91]
	v_exp_f32_e32 v46, v46
	v_exp_f32_e32 v44, v44
	v_exp_f32_e32 v47, v47
	v_exp_f32_e32 v45, v45
	v_mul_f32_e32 v34, 0xbfb8aa3b, v34
	v_mul_f32_e32 v39, 0xbfb8aa3b, v39
	v_exp_f32_e32 v34, v34
	v_exp_f32_e32 v39, v39
	v_add_f32_e32 v46, 1.0, v46
	v_add_f32_e32 v44, 1.0, v44
	v_add_f32_e32 v47, 1.0, v47
	v_add_f32_e32 v45, 1.0, v45
	v_rcp_f32_e32 v46, v46
	v_rcp_f32_e32 v43, v43
	v_rcp_f32_e32 v44, v44
	v_rcp_f32_e32 v47, v47
	v_rcp_f32_e32 v45, v45
	v_add_f32_e32 v34, 1.0, v34
	v_add_f32_e32 v39, 1.0, v39
	v_mul_f32_e32 v35, 0xbfb8aa3b, v35
	v_rcp_f32_e32 v34, v34
	v_rcp_f32_e32 v39, v39
	v_exp_f32_e32 v35, v35
	v_max_f32_e32 v46, 0x219392ef, v46
	v_max_f32_e32 v43, 0x219392ef, v43
	v_max_f32_e32 v49, 0x219392ef, v44
	v_max_f32_e32 v44, 0x219392ef, v47
	v_max_f32_e32 v45, 0x219392ef, v45
	v_cvt_pk_bf16_f32 v42, v46, v42
	v_pk_add_f32 v[40:41], v[40:41], v[96:97]
	v_cvt_pk_bf16_f32 v43, v43, v44
	v_cvt_pk_bf16_f32 v44, v50, v48
	v_cvt_pk_bf16_f32 v45, v49, v45
	global_store_dwordx4 v[106:107], v[42:45], off offset:2048 sc1
	v_add_f32_e32 v35, 1.0, v35
	v_rcp_f32_e32 v35, v35
	v_max_f32_e32 v42, 0x219392ef, v34
	v_max_f32_e32 v34, 0x219392ef, v39
	v_mul_f32_e32 v39, 0xbfb8aa3b, v40
	v_exp_f32_e32 v39, v39
	v_pk_add_f32 v[36:37], v[36:37], v[92:93]
	v_mul_f32_e32 v38, 0xbfb8aa3b, v38
	v_mul_f32_e32 v36, 0xbfb8aa3b, v36
	v_max_f32_e32 v40, 0x219392ef, v35
	v_add_f32_e32 v35, 1.0, v39
	v_mul_f32_e32 v39, 0xbfb8aa3b, v41
	v_mul_f32_e32 v37, 0xbfb8aa3b, v37
	v_pk_add_f32 v[30:31], v[30:31], v[102:103]
	v_pk_add_f32 v[26:27], v[26:27], v[98:99]
	v_exp_f32_e32 v38, v38
	v_exp_f32_e32 v36, v36
	v_exp_f32_e32 v39, v39
	v_exp_f32_e32 v37, v37
	v_mul_f32_e32 v26, 0xbfb8aa3b, v26
	v_mul_f32_e32 v31, 0xbfb8aa3b, v31
	v_exp_f32_e32 v26, v26
	v_exp_f32_e32 v31, v31
	v_add_f32_e32 v38, 1.0, v38
	v_add_f32_e32 v36, 1.0, v36
	v_add_f32_e32 v39, 1.0, v39
	v_add_f32_e32 v37, 1.0, v37
	v_rcp_f32_e32 v38, v38
	v_rcp_f32_e32 v35, v35
	v_rcp_f32_e32 v36, v36
	v_rcp_f32_e32 v39, v39
	v_rcp_f32_e32 v37, v37
	v_add_f32_e32 v26, 1.0, v26
	v_add_f32_e32 v31, 1.0, v31
	v_mul_f32_e32 v27, 0xbfb8aa3b, v27
	v_rcp_f32_e32 v26, v26
	v_rcp_f32_e32 v31, v31
	v_exp_f32_e32 v27, v27
	v_max_f32_e32 v38, 0x219392ef, v38
	v_max_f32_e32 v35, 0x219392ef, v35
	v_max_f32_e32 v41, 0x219392ef, v36
	v_max_f32_e32 v36, 0x219392ef, v39
	v_max_f32_e32 v37, 0x219392ef, v37
	v_cvt_pk_bf16_f32 v34, v38, v34
	v_pk_add_f32 v[32:33], v[32:33], v[104:105]
	v_cvt_pk_bf16_f32 v35, v35, v36
	v_cvt_pk_bf16_f32 v36, v42, v40
	v_cvt_pk_bf16_f32 v37, v41, v37
	global_store_dwordx4 v[106:107], v[34:37], off offset:3072 sc1
	v_add_f32_e32 v27, 1.0, v27
	v_rcp_f32_e32 v27, v27
	v_max_f32_e32 v34, 0x219392ef, v26
	v_max_f32_e32 v26, 0x219392ef, v31
	v_mul_f32_e32 v31, 0xbfb8aa3b, v32
	v_exp_f32_e32 v31, v31
	v_mul_f32_e32 v30, 0xbfb8aa3b, v30
	v_exp_f32_e32 v30, v30
	v_pk_add_f32 v[28:29], v[28:29], v[100:101]
	v_max_f32_e32 v32, 0x219392ef, v27
	v_mul_f32_e32 v28, 0xbfb8aa3b, v28
	v_add_f32_e32 v27, 1.0, v31
	v_mul_f32_e32 v31, 0xbfb8aa3b, v33
	v_mul_f32_e32 v29, 0xbfb8aa3b, v29
	v_pk_add_f32 v[22:23], v[22:23], v[94:95]
	v_pk_add_f32 v[18:19], v[18:19], v[90:91]
	v_exp_f32_e32 v28, v28
	v_exp_f32_e32 v31, v31
	v_exp_f32_e32 v29, v29
	v_mul_f32_e32 v18, 0xbfb8aa3b, v18
	v_mul_f32_e32 v23, 0xbfb8aa3b, v23
	v_exp_f32_e32 v18, v18
	v_exp_f32_e32 v23, v23
	v_add_f32_e32 v30, 1.0, v30
	v_rcp_f32_e32 v30, v30
	v_add_f32_e32 v28, 1.0, v28
	v_add_f32_e32 v31, 1.0, v31
	v_add_f32_e32 v29, 1.0, v29
	v_rcp_f32_e32 v27, v27
	v_rcp_f32_e32 v28, v28
	v_rcp_f32_e32 v31, v31
	v_rcp_f32_e32 v29, v29
	v_add_f32_e32 v18, 1.0, v18
	v_add_f32_e32 v23, 1.0, v23
	v_mul_f32_e32 v19, 0xbfb8aa3b, v19
	v_rcp_f32_e32 v18, v18
	v_rcp_f32_e32 v23, v23
	v_exp_f32_e32 v19, v19
	v_max_f32_e32 v30, 0x219392ef, v30
	s_movk_i32 s43, 0x3000
	v_cvt_pk_bf16_f32 v26, v30, v26
	v_add_co_u32_e32 v30, vcc, s43, v158
	v_max_f32_e32 v27, 0x219392ef, v27
	v_max_f32_e32 v33, 0x219392ef, v28
	v_max_f32_e32 v28, 0x219392ef, v31
	v_max_f32_e32 v29, 0x219392ef, v29
	v_addc_co_u32_e32 v31, vcc, 0, v159, vcc
	v_pk_add_f32 v[24:25], v[24:25], v[96:97]
	v_cvt_pk_bf16_f32 v27, v27, v28
	v_cvt_pk_bf16_f32 v28, v34, v32
	v_cvt_pk_bf16_f32 v29, v33, v29
	global_store_dwordx4 v[30:31], v[26:29], off sc1
	v_add_f32_e32 v19, 1.0, v19
	v_rcp_f32_e32 v19, v19
	v_max_f32_e32 v26, 0x219392ef, v18
	v_max_f32_e32 v18, 0x219392ef, v23
	v_mul_f32_e32 v23, 0xbfb8aa3b, v24
	v_exp_f32_e32 v23, v23
	v_pk_add_f32 v[20:21], v[20:21], v[92:93]
	v_mul_f32_e32 v22, 0xbfb8aa3b, v22
	v_mul_f32_e32 v20, 0xbfb8aa3b, v20
	v_max_f32_e32 v24, 0x219392ef, v19
	v_add_f32_e32 v19, 1.0, v23
	v_mul_f32_e32 v23, 0xbfb8aa3b, v25
	v_mul_f32_e32 v21, 0xbfb8aa3b, v21
	v_pk_add_f32 v[14:15], v[14:15], v[102:103]
	v_pk_add_f32 v[10:11], v[10:11], v[98:99]
	v_exp_f32_e32 v22, v22
	v_exp_f32_e32 v20, v20
	v_exp_f32_e32 v23, v23
	v_exp_f32_e32 v21, v21
	v_mul_f32_e32 v10, 0xbfb8aa3b, v10
	v_mul_f32_e32 v15, 0xbfb8aa3b, v15
	v_exp_f32_e32 v10, v10
	v_exp_f32_e32 v15, v15
	v_add_f32_e32 v22, 1.0, v22
	v_add_f32_e32 v20, 1.0, v20
	v_add_f32_e32 v23, 1.0, v23
	v_add_f32_e32 v21, 1.0, v21
	v_rcp_f32_e32 v22, v22
	v_rcp_f32_e32 v19, v19
	v_rcp_f32_e32 v20, v20
	v_rcp_f32_e32 v23, v23
	v_rcp_f32_e32 v21, v21
	v_add_f32_e32 v10, 1.0, v10
	v_add_f32_e32 v15, 1.0, v15
	v_mul_f32_e32 v11, 0xbfb8aa3b, v11
	v_rcp_f32_e32 v10, v10
	v_rcp_f32_e32 v15, v15
	v_exp_f32_e32 v11, v11
	v_max_f32_e32 v22, 0x219392ef, v22
	v_max_f32_e32 v19, 0x219392ef, v19
	v_max_f32_e32 v25, 0x219392ef, v20
	v_max_f32_e32 v20, 0x219392ef, v23
	v_max_f32_e32 v21, 0x219392ef, v21
	v_cvt_pk_bf16_f32 v18, v22, v18
	v_pk_add_f32 v[16:17], v[16:17], v[104:105]
	v_cvt_pk_bf16_f32 v19, v19, v20
	v_cvt_pk_bf16_f32 v20, v26, v24
	v_cvt_pk_bf16_f32 v21, v25, v21
	global_store_dwordx4 v[30:31], v[18:21], off offset:1024 sc1
	v_add_f32_e32 v11, 1.0, v11
	v_rcp_f32_e32 v11, v11
	v_max_f32_e32 v18, 0x219392ef, v10
	v_max_f32_e32 v10, 0x219392ef, v15
	v_mul_f32_e32 v15, 0xbfb8aa3b, v16
	v_exp_f32_e32 v15, v15
	v_pk_add_f32 v[12:13], v[12:13], v[100:101]
	v_mul_f32_e32 v14, 0xbfb8aa3b, v14
	v_mul_f32_e32 v12, 0xbfb8aa3b, v12
	v_max_f32_e32 v16, 0x219392ef, v11
	v_add_f32_e32 v11, 1.0, v15
	v_mul_f32_e32 v15, 0xbfb8aa3b, v17
	v_mul_f32_e32 v13, 0xbfb8aa3b, v13
	v_pk_add_f32 v[6:7], v[6:7], v[94:95]
	v_pk_add_f32 v[2:3], v[2:3], v[90:91]
	v_exp_f32_e32 v14, v14
	v_exp_f32_e32 v12, v12
	v_exp_f32_e32 v15, v15
	v_exp_f32_e32 v13, v13
	v_mul_f32_e32 v2, 0xbfb8aa3b, v2
	v_mul_f32_e32 v7, 0xbfb8aa3b, v7
	v_exp_f32_e32 v2, v2
	v_exp_f32_e32 v7, v7
	v_add_f32_e32 v14, 1.0, v14
	v_add_f32_e32 v12, 1.0, v12
	v_add_f32_e32 v15, 1.0, v15
	v_add_f32_e32 v13, 1.0, v13
	v_rcp_f32_e32 v14, v14
	v_rcp_f32_e32 v11, v11
	v_rcp_f32_e32 v12, v12
	v_rcp_f32_e32 v15, v15
	v_rcp_f32_e32 v13, v13
	v_add_f32_e32 v2, 1.0, v2
	v_add_f32_e32 v7, 1.0, v7
	v_mul_f32_e32 v3, 0xbfb8aa3b, v3
	v_rcp_f32_e32 v2, v2
	v_rcp_f32_e32 v7, v7
	v_exp_f32_e32 v3, v3
	v_max_f32_e32 v14, 0x219392ef, v14
	v_max_f32_e32 v11, 0x219392ef, v11
	v_max_f32_e32 v17, 0x219392ef, v12
	v_max_f32_e32 v12, 0x219392ef, v15
	v_max_f32_e32 v13, 0x219392ef, v13
	v_cvt_pk_bf16_f32 v10, v14, v10
	v_pk_add_f32 v[8:9], v[8:9], v[96:97]
	v_cvt_pk_bf16_f32 v11, v11, v12
	v_cvt_pk_bf16_f32 v12, v18, v16
	v_cvt_pk_bf16_f32 v13, v17, v13
	global_store_dwordx4 v[30:31], v[10:13], off offset:2048 sc1
	v_add_f32_e32 v3, 1.0, v3
	v_rcp_f32_e32 v3, v3
	v_max_f32_e32 v10, 0x219392ef, v2
	v_max_f32_e32 v2, 0x219392ef, v7
	v_mul_f32_e32 v7, 0xbfb8aa3b, v8
	v_exp_f32_e32 v7, v7
	v_pk_add_f32 v[4:5], v[4:5], v[92:93]
	v_max_f32_e32 v8, 0x219392ef, v3
	v_mul_f32_e32 v4, 0xbfb8aa3b, v4
	v_add_f32_e32 v3, 1.0, v7
	v_mul_f32_e32 v7, 0xbfb8aa3b, v9
	v_mul_f32_e32 v5, 0xbfb8aa3b, v5
	v_mul_f32_e32 v6, 0xbfb8aa3b, v6
	v_exp_f32_e32 v4, v4
	v_exp_f32_e32 v7, v7
	v_exp_f32_e32 v5, v5
	v_exp_f32_e32 v6, v6
	v_add_f32_e32 v4, 1.0, v4
	v_add_f32_e32 v7, 1.0, v7
	v_add_f32_e32 v5, 1.0, v5
	v_add_f32_e32 v6, 1.0, v6
	v_rcp_f32_e32 v3, v3
	v_rcp_f32_e32 v4, v4
	v_rcp_f32_e32 v7, v7
	v_rcp_f32_e32 v5, v5
	v_rcp_f32_e32 v6, v6
	v_max_f32_e32 v3, 0x219392ef, v3
	v_max_f32_e32 v9, 0x219392ef, v4
	v_max_f32_e32 v4, 0x219392ef, v7
	v_max_f32_e32 v5, 0x219392ef, v5
	s_andn2_b64 vcc, exec, s[38:39]
	s_mov_b64 s[38:39], -1
	v_max_f32_e32 v6, 0x219392ef, v6
	v_cvt_pk_bf16_f32 v2, v6, v2
	v_cvt_pk_bf16_f32 v3, v3, v4
	v_cvt_pk_bf16_f32 v4, v10, v8
	v_cvt_pk_bf16_f32 v5, v9, v5
	global_store_dwordx4 v[30:31], v[2:5], off offset:3072 sc1
	s_cbranch_vccnz .LBB0_533
	s_andn2_b64 vcc, exec, s[26:27]
	s_cbranch_vccnz .LBB0_532
	s_barrier
	s_branch .LBB0_532

.LBB0_619:
	s_cmp_gt_i32 s73, 1
	s_cselect_b64 s[60:61], -1, 0
	s_mov_b64 s[62:63], -1
	s_and_b64 vcc, exec, s[60:61]
	s_mul_i32 s47, s75, 12
	s_cbranch_vccz .LBB0_622
	s_add_i32 s62, s74, s47
	s_add_i32 s62, s62, 8
	s_ashr_i32 s63, s62, 31
	s_lshl_b64 s[62:63], s[62:63], 17
	s_add_u32 s62, s62, 0x1000
	s_addc_u32 s63, s63, 0
	v_lshl_add_u64 v[158:159], v[148:149], 0, s[62:63]
	s_mov_b64 s[62:63], 0x2000
	global_load_dwordx4 v[164:167], v[158:159], off offset:-4096
	global_load_dwordx4 v[168:171], v[158:159], off offset:-3072
	global_load_dwordx4 v[172:175], v[158:159], off offset:-2048
	global_load_dwordx4 v[176:179], v[158:159], off offset:-1024
	global_load_dwordx4 v[180:183], v[158:159], off
	global_load_dwordx4 v[184:187], v[158:159], off offset:1024
	global_load_dwordx4 v[188:191], v[158:159], off offset:2048
	global_load_dwordx4 v[192:195], v[158:159], off offset:3072
	v_lshl_add_u64 v[158:159], v[158:159], 0, s[62:63]
	v_lshl_add_u32 v132, s75, 8, v160
	v_lshl_or_b32 v2, s74, 8, v162
	v_ashrrev_i32_e32 v133, 31, v132
	v_ashrrev_i32_e32 v3, 31, v2
	v_lshlrev_b64 v[132:133], 11, v[132:133]
	v_lshlrev_b64 v[134:135], 1, v[2:3]
	v_lshl_add_u64 v[2:3], s[28:29], 0, v[132:133]
	v_lshl_add_u64 v[2:3], v[2:3], 0, v[134:135]
	global_load_dwordx4 v[206:209], v[158:159], off offset:-4096
	global_load_dwordx4 v[210:213], v[158:159], off offset:-3072
	global_load_dwordx4 v[214:217], v[158:159], off offset:-2048
	global_load_dwordx4 v[218:221], v[158:159], off offset:-1024
	global_load_dwordx4 v[154:157], v[158:159], off
	global_load_dwordx4 v[232:235], v[158:159], off offset:1024
	s_mov_b64 s[62:63], 0x8000
	s_mov_b64 s[64:65], 0x28000
	s_waitcnt vmcnt(13)
	v_lshlrev_b32_e32 v132, 16, v164
	v_and_b32_e32 v133, 0xffff0000, v164
	v_lshlrev_b32_e32 v134, 16, v165
	v_and_b32_e32 v135, 0xffff0000, v165
	v_pk_mul_f32 v[132:133], v[128:129], v[132:133]
	v_pk_mul_f32 v[134:135], v[130:131], v[134:135]
	v_cvt_pk_bf16_f32 v136, v132, v133
	v_cvt_pk_bf16_f32 v137, v134, v135
	v_lshlrev_b32_e32 v132, 16, v166
	v_and_b32_e32 v133, 0xffff0000, v166
	v_lshlrev_b32_e32 v134, 16, v167
	v_and_b32_e32 v135, 0xffff0000, v167
	v_pk_mul_f32 v[132:133], v[124:125], v[132:133]
	v_pk_mul_f32 v[134:135], v[126:127], v[134:135]
	v_cvt_pk_bf16_f32 v138, v132, v133
	v_cvt_pk_bf16_f32 v139, v134, v135
	global_store_dwordx4 v[2:3], v[136:139], off sc1
	global_load_dwordx4 v[164:167], v[158:159], off offset:2048
	s_waitcnt vmcnt(14)
	v_lshlrev_b32_e32 v132, 16, v168
	v_and_b32_e32 v133, 0xffff0000, v168
	v_lshlrev_b32_e32 v134, 16, v169
	v_and_b32_e32 v135, 0xffff0000, v169
	v_pk_mul_f32 v[132:133], v[96:97], v[132:133]
	v_pk_mul_f32 v[134:135], v[98:99], v[134:135]
	v_cvt_pk_bf16_f32 v136, v132, v133
	v_cvt_pk_bf16_f32 v137, v134, v135
	v_lshlrev_b32_e32 v132, 16, v170
	v_and_b32_e32 v133, 0xffff0000, v170
	v_lshlrev_b32_e32 v134, 16, v171
	v_and_b32_e32 v135, 0xffff0000, v171
	v_pk_mul_f32 v[132:133], v[92:93], v[132:133]
	v_pk_mul_f32 v[134:135], v[94:95], v[134:135]
	v_cvt_pk_bf16_f32 v138, v132, v133
	v_cvt_pk_bf16_f32 v139, v134, v135
	global_store_dwordx4 v[2:3], v[136:139], off offset:256 sc1
	v_lshl_add_u64 v[2:3], v[2:3], 0, s[62:63]
	global_load_dwordx4 v[168:171], v[158:159], off offset:3072
	s_waitcnt vmcnt(15)
	v_lshlrev_b32_e32 v132, 16, v172
	v_and_b32_e32 v133, 0xffff0000, v172
	v_lshlrev_b32_e32 v134, 16, v173
	v_and_b32_e32 v135, 0xffff0000, v173
	v_pk_mul_f32 v[132:133], v[120:121], v[132:133]
	v_pk_mul_f32 v[134:135], v[122:123], v[134:135]
	v_cvt_pk_bf16_f32 v136, v132, v133
	v_cvt_pk_bf16_f32 v137, v134, v135
	v_lshlrev_b32_e32 v132, 16, v174
	v_and_b32_e32 v133, 0xffff0000, v174
	v_lshlrev_b32_e32 v134, 16, v175
	v_and_b32_e32 v135, 0xffff0000, v175
	v_pk_mul_f32 v[132:133], v[116:117], v[132:133]
	v_pk_mul_f32 v[134:135], v[118:119], v[134:135]
	v_cvt_pk_bf16_f32 v138, v132, v133
	v_cvt_pk_bf16_f32 v139, v134, v135
	global_store_dwordx4 v[2:3], v[136:139], off sc1
	s_waitcnt vmcnt(15)
	v_lshlrev_b32_e32 v132, 16, v176
	v_and_b32_e32 v133, 0xffff0000, v176
	v_lshlrev_b32_e32 v134, 16, v177
	v_and_b32_e32 v135, 0xffff0000, v177
	v_pk_mul_f32 v[132:133], v[88:89], v[132:133]
	v_pk_mul_f32 v[134:135], v[90:91], v[134:135]
	v_cvt_pk_bf16_f32 v136, v132, v133
	v_cvt_pk_bf16_f32 v137, v134, v135
	v_lshlrev_b32_e32 v132, 16, v178
	v_and_b32_e32 v133, 0xffff0000, v178
	v_lshlrev_b32_e32 v134, 16, v179
	v_and_b32_e32 v135, 0xffff0000, v179
	v_pk_mul_f32 v[132:133], v[84:85], v[132:133]
	v_pk_mul_f32 v[134:135], v[86:87], v[134:135]
	v_cvt_pk_bf16_f32 v138, v132, v133
	v_cvt_pk_bf16_f32 v139, v134, v135
	global_store_dwordx4 v[2:3], v[136:139], off offset:256 sc1
	v_lshl_add_u64 v[2:3], v[2:3], 0, s[62:63]
	s_waitcnt vmcnt(15)
	v_lshlrev_b32_e32 v132, 16, v180
	v_and_b32_e32 v133, 0xffff0000, v180
	v_lshlrev_b32_e32 v134, 16, v181
	v_and_b32_e32 v135, 0xffff0000, v181
	v_pk_mul_f32 v[132:133], v[112:113], v[132:133]
	v_pk_mul_f32 v[134:135], v[114:115], v[134:135]
	v_cvt_pk_bf16_f32 v136, v132, v133
	v_cvt_pk_bf16_f32 v137, v134, v135
	v_lshlrev_b32_e32 v132, 16, v182
	v_and_b32_e32 v133, 0xffff0000, v182
	v_lshlrev_b32_e32 v134, 16, v183
	v_and_b32_e32 v135, 0xffff0000, v183
	v_pk_mul_f32 v[132:133], v[108:109], v[132:133]
	v_pk_mul_f32 v[134:135], v[110:111], v[134:135]
	v_cvt_pk_bf16_f32 v138, v132, v133
	v_cvt_pk_bf16_f32 v139, v134, v135
	global_store_dwordx4 v[2:3], v[136:139], off sc1
	s_waitcnt vmcnt(15)
	v_lshlrev_b32_e32 v132, 16, v184
	v_and_b32_e32 v133, 0xffff0000, v184
	v_lshlrev_b32_e32 v134, 16, v185
	v_and_b32_e32 v135, 0xffff0000, v185
	v_pk_mul_f32 v[132:133], v[80:81], v[132:133]
	v_pk_mul_f32 v[134:135], v[82:83], v[134:135]
	v_cvt_pk_bf16_f32 v136, v132, v133
	v_cvt_pk_bf16_f32 v137, v134, v135
	v_lshlrev_b32_e32 v132, 16, v186
	v_and_b32_e32 v133, 0xffff0000, v186
	v_lshlrev_b32_e32 v134, 16, v187
	v_and_b32_e32 v135, 0xffff0000, v187
	v_pk_mul_f32 v[132:133], v[76:77], v[132:133]
	v_pk_mul_f32 v[134:135], v[78:79], v[134:135]
	v_cvt_pk_bf16_f32 v138, v132, v133
	v_cvt_pk_bf16_f32 v139, v134, v135
	global_store_dwordx4 v[2:3], v[136:139], off offset:256 sc1
	v_lshl_add_u64 v[2:3], v[2:3], 0, s[62:63]
	s_waitcnt vmcnt(15)
	v_lshlrev_b32_e32 v132, 16, v188
	v_and_b32_e32 v133, 0xffff0000, v188
	v_lshlrev_b32_e32 v134, 16, v189
	v_and_b32_e32 v135, 0xffff0000, v189
	v_pk_mul_f32 v[132:133], v[104:105], v[132:133]
	v_pk_mul_f32 v[134:135], v[106:107], v[134:135]
	v_cvt_pk_bf16_f32 v136, v132, v133
	v_cvt_pk_bf16_f32 v137, v134, v135
	v_lshlrev_b32_e32 v132, 16, v190
	v_and_b32_e32 v133, 0xffff0000, v190
	v_lshlrev_b32_e32 v134, 16, v191
	v_and_b32_e32 v135, 0xffff0000, v191
	v_pk_mul_f32 v[132:133], v[100:101], v[132:133]
	v_pk_mul_f32 v[134:135], v[102:103], v[134:135]
	v_cvt_pk_bf16_f32 v138, v132, v133
	v_cvt_pk_bf16_f32 v139, v134, v135
	global_store_dwordx4 v[2:3], v[136:139], off sc1
	s_waitcnt vmcnt(15)
	v_lshlrev_b32_e32 v132, 16, v192
	v_and_b32_e32 v133, 0xffff0000, v192
	v_lshlrev_b32_e32 v134, 16, v193
	v_and_b32_e32 v135, 0xffff0000, v193
	v_pk_mul_f32 v[132:133], v[72:73], v[132:133]
	v_pk_mul_f32 v[134:135], v[74:75], v[134:135]
	v_cvt_pk_bf16_f32 v136, v132, v133
	v_cvt_pk_bf16_f32 v137, v134, v135
	v_lshlrev_b32_e32 v132, 16, v194
	v_and_b32_e32 v133, 0xffff0000, v194
	v_lshlrev_b32_e32 v134, 16, v195
	v_and_b32_e32 v135, 0xffff0000, v195
	v_pk_mul_f32 v[132:133], v[68:69], v[132:133]
	v_pk_mul_f32 v[134:135], v[70:71], v[134:135]
	v_cvt_pk_bf16_f32 v138, v132, v133
	v_cvt_pk_bf16_f32 v139, v134, v135
	global_store_dwordx4 v[2:3], v[136:139], off offset:256 sc1
	v_lshl_add_u64 v[2:3], v[2:3], 0, s[64:65]
	s_waitcnt vmcnt(15)
	v_lshlrev_b32_e32 v132, 16, v206
	v_and_b32_e32 v133, 0xffff0000, v206
	v_lshlrev_b32_e32 v134, 16, v207
	v_and_b32_e32 v135, 0xffff0000, v207
	v_pk_mul_f32 v[132:133], v[64:65], v[132:133]
	v_pk_mul_f32 v[134:135], v[66:67], v[134:135]
	v_cvt_pk_bf16_f32 v136, v132, v133
	v_cvt_pk_bf16_f32 v137, v134, v135
	v_lshlrev_b32_e32 v132, 16, v208
	v_and_b32_e32 v133, 0xffff0000, v208
	v_lshlrev_b32_e32 v134, 16, v209
	v_and_b32_e32 v135, 0xffff0000, v209
	v_pk_mul_f32 v[132:133], v[60:61], v[132:133]
	v_pk_mul_f32 v[134:135], v[62:63], v[134:135]
	v_cvt_pk_bf16_f32 v138, v132, v133
	v_cvt_pk_bf16_f32 v139, v134, v135
	global_store_dwordx4 v[2:3], v[136:139], off sc1
	s_waitcnt vmcnt(15)
	v_lshlrev_b32_e32 v132, 16, v210
	v_and_b32_e32 v133, 0xffff0000, v210
	v_lshlrev_b32_e32 v134, 16, v211
	v_and_b32_e32 v135, 0xffff0000, v211
	v_pk_mul_f32 v[132:133], v[32:33], v[132:133]
	v_pk_mul_f32 v[134:135], v[34:35], v[134:135]
	v_cvt_pk_bf16_f32 v136, v132, v133
	v_cvt_pk_bf16_f32 v137, v134, v135
	v_lshlrev_b32_e32 v132, 16, v212
	v_and_b32_e32 v133, 0xffff0000, v212
	v_lshlrev_b32_e32 v134, 16, v213
	v_and_b32_e32 v135, 0xffff0000, v213
	v_pk_mul_f32 v[132:133], v[28:29], v[132:133]
	v_pk_mul_f32 v[134:135], v[30:31], v[134:135]
	v_cvt_pk_bf16_f32 v138, v132, v133
	v_cvt_pk_bf16_f32 v139, v134, v135
	global_store_dwordx4 v[2:3], v[136:139], off offset:256 sc1
	v_lshl_add_u64 v[2:3], v[2:3], 0, s[62:63]
	s_waitcnt vmcnt(15)
	v_lshlrev_b32_e32 v132, 16, v214
	v_and_b32_e32 v133, 0xffff0000, v214
	v_lshlrev_b32_e32 v134, 16, v215
	v_and_b32_e32 v135, 0xffff0000, v215
	v_pk_mul_f32 v[132:133], v[56:57], v[132:133]
	v_pk_mul_f32 v[134:135], v[58:59], v[134:135]
	v_cvt_pk_bf16_f32 v136, v132, v133
	v_cvt_pk_bf16_f32 v137, v134, v135
	v_lshlrev_b32_e32 v132, 16, v216
	v_and_b32_e32 v133, 0xffff0000, v216
	v_lshlrev_b32_e32 v134, 16, v217
	v_and_b32_e32 v135, 0xffff0000, v217
	v_pk_mul_f32 v[132:133], v[52:53], v[132:133]
	v_pk_mul_f32 v[134:135], v[54:55], v[134:135]
	v_cvt_pk_bf16_f32 v138, v132, v133
	v_cvt_pk_bf16_f32 v139, v134, v135
	global_store_dwordx4 v[2:3], v[136:139], off sc1
	s_waitcnt vmcnt(15)
	v_lshlrev_b32_e32 v132, 16, v218
	v_and_b32_e32 v133, 0xffff0000, v218
	v_lshlrev_b32_e32 v134, 16, v219
	v_and_b32_e32 v135, 0xffff0000, v219
	v_pk_mul_f32 v[132:133], v[24:25], v[132:133]
	v_pk_mul_f32 v[134:135], v[26:27], v[134:135]
	v_cvt_pk_bf16_f32 v136, v132, v133
	v_cvt_pk_bf16_f32 v137, v134, v135
	v_lshlrev_b32_e32 v132, 16, v220
	v_and_b32_e32 v133, 0xffff0000, v220
	v_lshlrev_b32_e32 v134, 16, v221
	v_and_b32_e32 v135, 0xffff0000, v221
	v_pk_mul_f32 v[132:133], v[20:21], v[132:133]
	v_pk_mul_f32 v[134:135], v[22:23], v[134:135]
	v_cvt_pk_bf16_f32 v138, v132, v133
	v_cvt_pk_bf16_f32 v139, v134, v135
	global_store_dwordx4 v[2:3], v[136:139], off offset:256 sc1
	v_lshl_add_u64 v[2:3], v[2:3], 0, s[62:63]
	s_waitcnt vmcnt(15)
	v_lshlrev_b32_e32 v132, 16, v154
	v_and_b32_e32 v133, 0xffff0000, v154
	v_lshlrev_b32_e32 v134, 16, v155
	v_and_b32_e32 v135, 0xffff0000, v155
	v_pk_mul_f32 v[132:133], v[48:49], v[132:133]
	v_pk_mul_f32 v[134:135], v[50:51], v[134:135]
	v_cvt_pk_bf16_f32 v136, v132, v133
	v_cvt_pk_bf16_f32 v137, v134, v135
	v_lshlrev_b32_e32 v132, 16, v156
	v_and_b32_e32 v133, 0xffff0000, v156
	v_lshlrev_b32_e32 v134, 16, v157
	v_and_b32_e32 v135, 0xffff0000, v157
	v_pk_mul_f32 v[132:133], v[44:45], v[132:133]
	v_pk_mul_f32 v[134:135], v[46:47], v[134:135]
	v_cvt_pk_bf16_f32 v138, v132, v133
	v_cvt_pk_bf16_f32 v139, v134, v135
	global_store_dwordx4 v[2:3], v[136:139], off sc1
	s_waitcnt vmcnt(15)
	v_lshlrev_b32_e32 v132, 16, v232
	v_and_b32_e32 v133, 0xffff0000, v232
	v_lshlrev_b32_e32 v134, 16, v233
	v_and_b32_e32 v135, 0xffff0000, v233
	v_pk_mul_f32 v[132:133], v[16:17], v[132:133]
	v_pk_mul_f32 v[134:135], v[18:19], v[134:135]
	v_cvt_pk_bf16_f32 v136, v132, v133
	v_cvt_pk_bf16_f32 v137, v134, v135
	v_lshlrev_b32_e32 v132, 16, v234
	v_and_b32_e32 v133, 0xffff0000, v234
	v_lshlrev_b32_e32 v134, 16, v235
	v_and_b32_e32 v135, 0xffff0000, v235
	v_pk_mul_f32 v[132:133], v[12:13], v[132:133]
	v_pk_mul_f32 v[134:135], v[14:15], v[134:135]
	v_cvt_pk_bf16_f32 v138, v132, v133
	v_cvt_pk_bf16_f32 v139, v134, v135
	global_store_dwordx4 v[2:3], v[136:139], off offset:256 sc1
	v_lshl_add_u64 v[2:3], v[2:3], 0, s[62:63]
	s_waitcnt vmcnt(14)
	v_lshlrev_b32_e32 v132, 16, v164
	v_and_b32_e32 v133, 0xffff0000, v164
	v_lshlrev_b32_e32 v134, 16, v165
	v_and_b32_e32 v135, 0xffff0000, v165
	v_pk_mul_f32 v[132:133], v[40:41], v[132:133]
	v_pk_mul_f32 v[134:135], v[42:43], v[134:135]
	v_cvt_pk_bf16_f32 v136, v132, v133
	v_cvt_pk_bf16_f32 v137, v134, v135
	v_lshlrev_b32_e32 v132, 16, v166
	v_and_b32_e32 v133, 0xffff0000, v166
	v_lshlrev_b32_e32 v134, 16, v167
	v_and_b32_e32 v135, 0xffff0000, v167
	v_pk_mul_f32 v[132:133], v[36:37], v[132:133]
	v_pk_mul_f32 v[134:135], v[38:39], v[134:135]
	v_cvt_pk_bf16_f32 v138, v132, v133
	v_cvt_pk_bf16_f32 v139, v134, v135
	global_store_dwordx4 v[2:3], v[136:139], off sc1
	s_waitcnt vmcnt(13)
	v_lshlrev_b32_e32 v132, 16, v168
	v_and_b32_e32 v133, 0xffff0000, v168
	v_lshlrev_b32_e32 v134, 16, v169
	v_and_b32_e32 v135, 0xffff0000, v169
	v_pk_mul_f32 v[132:133], v[8:9], v[132:133]
	v_pk_mul_f32 v[134:135], v[10:11], v[134:135]
	v_cvt_pk_bf16_f32 v136, v132, v133
	v_cvt_pk_bf16_f32 v137, v134, v135
	v_lshlrev_b32_e32 v132, 16, v170
	v_and_b32_e32 v133, 0xffff0000, v170
	v_lshlrev_b32_e32 v134, 16, v171
	v_and_b32_e32 v135, 0xffff0000, v171
	v_pk_mul_f32 v[132:133], v[4:5], v[132:133]
	v_pk_mul_f32 v[134:135], v[6:7], v[134:135]
	v_cvt_pk_bf16_f32 v138, v132, v133
	v_cvt_pk_bf16_f32 v139, v134, v135
	global_store_dwordx4 v[2:3], v[136:139], off offset:256 sc1
	s_cbranch_execz .LBB0_623

.LBB0_623:
	s_lshl_b32 s62, s73, 2
	s_add_i32 s62, s62, s74
	s_add_i32 s62, s62, s47
	s_ashr_i32 s63, s62, 31
	s_lshl_b64 s[64:65], s[62:63], 17
	s_add_i32 s62, s62, 4
	s_ashr_i32 s63, s62, 31
	s_lshl_b64 s[62:63], s[62:63], 17
	s_add_u32 s64, s64, 0x1000
	s_addc_u32 s65, s65, 0
	s_add_u32 s62, s62, 0x1000
	s_addc_u32 s63, s63, 0
	v_lshl_add_u64 v[2:3], v[148:149], 0, s[64:65]
	v_lshl_add_u64 v[158:159], v[148:149], 0, s[62:63]
	s_mov_b64 s[62:63], 0x2000
	s_movk_i32 s91, 0x1000
	global_load_dwordx4 v[164:167], v[2:3], off offset:-4096
	global_load_dwordx4 v[168:171], v[158:159], off offset:-4096
	global_load_dwordx4 v[172:175], v[2:3], off offset:-3072
	global_load_dwordx4 v[176:179], v[158:159], off offset:-3072
	global_load_dwordx4 v[180:183], v[2:3], off offset:-2048
	global_load_dwordx4 v[184:187], v[158:159], off offset:-2048
	global_load_dwordx4 v[188:191], v[2:3], off offset:-1024
	global_load_dwordx4 v[192:195], v[158:159], off offset:-1024
	global_load_dwordx4 v[206:209], v[2:3], off
	global_load_dwordx4 v[210:213], v[158:159], off
	global_load_dwordx4 v[214:217], v[2:3], off offset:1024
	global_load_dwordx4 v[218:221], v[158:159], off offset:1024
	global_load_dwordx4 v[154:157], v[2:3], off offset:2048
	global_load_dwordx4 v[232:235], v[158:159], off offset:2048
	s_waitcnt vmcnt(12)
	v_lshlrev_b32_e32 v132, 16, v168
	v_and_b32_e32 v133, 0xffff0000, v168
	v_lshlrev_b32_e32 v136, 16, v169
	v_and_b32_e32 v137, 0xffff0000, v169
	v_rcp_f32_e32 v132, v132
	v_rcp_f32_e32 v133, v133
	v_rcp_f32_e32 v136, v136
	v_rcp_f32_e32 v137, v137
	v_lshlrev_b32_e32 v134, 16, v164
	v_and_b32_e32 v135, 0xffff0000, v164
	v_lshlrev_b32_e32 v138, 16, v165
	v_and_b32_e32 v139, 0xffff0000, v165
	v_pk_mul_f32 v[132:133], v[132:133], v[134:135]
	v_pk_mul_f32 v[136:137], v[136:137], v[138:139]
	v_pk_mul_f32 v[128:129], v[128:129], v[132:133]
	v_pk_mul_f32 v[130:131], v[130:131], v[136:137]
	v_lshlrev_b32_e32 v132, 16, v170
	v_and_b32_e32 v133, 0xffff0000, v170
	v_lshlrev_b32_e32 v136, 16, v171
	v_and_b32_e32 v137, 0xffff0000, v171
	v_rcp_f32_e32 v132, v132
	v_rcp_f32_e32 v133, v133
	v_rcp_f32_e32 v136, v136
	v_rcp_f32_e32 v137, v137
	v_lshlrev_b32_e32 v134, 16, v166
	v_and_b32_e32 v135, 0xffff0000, v166
	v_lshlrev_b32_e32 v138, 16, v167
	v_and_b32_e32 v139, 0xffff0000, v167
	v_pk_mul_f32 v[132:133], v[132:133], v[134:135]
	v_pk_mul_f32 v[136:137], v[136:137], v[138:139]
	v_pk_mul_f32 v[124:125], v[124:125], v[132:133]
	v_pk_mul_f32 v[126:127], v[126:127], v[136:137]
	global_load_dwordx4 v[164:167], v[2:3], off offset:3072
	global_load_dwordx4 v[168:171], v[158:159], off offset:3072
	v_lshl_add_u64 v[2:3], v[2:3], 0, s[62:63]
	v_lshl_add_u64 v[158:159], v[158:159], 0, s[62:63]
	s_waitcnt vmcnt(12)
	v_lshlrev_b32_e32 v132, 16, v176
	v_and_b32_e32 v133, 0xffff0000, v176
	v_lshlrev_b32_e32 v136, 16, v177
	v_and_b32_e32 v137, 0xffff0000, v177
	v_rcp_f32_e32 v132, v132
	v_rcp_f32_e32 v133, v133
	v_rcp_f32_e32 v136, v136
	v_rcp_f32_e32 v137, v137
	v_lshlrev_b32_e32 v134, 16, v172
	v_and_b32_e32 v135, 0xffff0000, v172
	v_lshlrev_b32_e32 v138, 16, v173
	v_and_b32_e32 v139, 0xffff0000, v173
	v_pk_mul_f32 v[132:133], v[132:133], v[134:135]
	v_pk_mul_f32 v[136:137], v[136:137], v[138:139]
	v_pk_mul_f32 v[96:97], v[96:97], v[132:133]
	v_pk_mul_f32 v[98:99], v[98:99], v[136:137]
	v_lshlrev_b32_e32 v132, 16, v178
	v_and_b32_e32 v133, 0xffff0000, v178
	v_lshlrev_b32_e32 v136, 16, v179
	v_and_b32_e32 v137, 0xffff0000, v179
	v_rcp_f32_e32 v132, v132
	v_rcp_f32_e32 v133, v133
	v_rcp_f32_e32 v136, v136
	v_rcp_f32_e32 v137, v137
	v_lshlrev_b32_e32 v134, 16, v174
	v_and_b32_e32 v135, 0xffff0000, v174
	v_lshlrev_b32_e32 v138, 16, v175
	v_and_b32_e32 v139, 0xffff0000, v175
	v_pk_mul_f32 v[132:133], v[132:133], v[134:135]
	v_pk_mul_f32 v[136:137], v[136:137], v[138:139]
	v_pk_mul_f32 v[92:93], v[92:93], v[132:133]
	v_pk_mul_f32 v[94:95], v[94:95], v[136:137]
	global_load_dwordx4 v[172:175], v[2:3], off offset:-4096
	global_load_dwordx4 v[176:179], v[158:159], off offset:-4096
	s_waitcnt vmcnt(12)
	v_lshlrev_b32_e32 v132, 16, v184
	v_and_b32_e32 v133, 0xffff0000, v184
	v_lshlrev_b32_e32 v136, 16, v185
	v_and_b32_e32 v137, 0xffff0000, v185
	v_rcp_f32_e32 v132, v132
	v_rcp_f32_e32 v133, v133
	v_rcp_f32_e32 v136, v136
	v_rcp_f32_e32 v137, v137
	v_lshlrev_b32_e32 v134, 16, v180
	v_and_b32_e32 v135, 0xffff0000, v180
	v_lshlrev_b32_e32 v138, 16, v181
	v_and_b32_e32 v139, 0xffff0000, v181
	v_pk_mul_f32 v[132:133], v[132:133], v[134:135]
	v_pk_mul_f32 v[136:137], v[136:137], v[138:139]
	v_pk_mul_f32 v[120:121], v[120:121], v[132:133]
	v_pk_mul_f32 v[122:123], v[122:123], v[136:137]
	v_lshlrev_b32_e32 v132, 16, v186
	v_and_b32_e32 v133, 0xffff0000, v186
	v_lshlrev_b32_e32 v136, 16, v187
	v_and_b32_e32 v137, 0xffff0000, v187
	v_rcp_f32_e32 v132, v132
	v_rcp_f32_e32 v133, v133
	v_rcp_f32_e32 v136, v136
	v_rcp_f32_e32 v137, v137
	v_lshlrev_b32_e32 v134, 16, v182
	v_and_b32_e32 v135, 0xffff0000, v182
	v_lshlrev_b32_e32 v138, 16, v183
	v_and_b32_e32 v139, 0xffff0000, v183
	v_pk_mul_f32 v[132:133], v[132:133], v[134:135]
	v_pk_mul_f32 v[136:137], v[136:137], v[138:139]
	v_pk_mul_f32 v[116:117], v[116:117], v[132:133]
	v_pk_mul_f32 v[118:119], v[118:119], v[136:137]
	global_load_dwordx4 v[180:183], v[2:3], off offset:-3072
	global_load_dwordx4 v[184:187], v[158:159], off offset:-3072
	s_waitcnt vmcnt(12)
	v_lshlrev_b32_e32 v132, 16, v192
	v_and_b32_e32 v133, 0xffff0000, v192
	v_lshlrev_b32_e32 v136, 16, v193
	v_and_b32_e32 v137, 0xffff0000, v193
	v_rcp_f32_e32 v132, v132
	v_rcp_f32_e32 v133, v133
	v_rcp_f32_e32 v136, v136
	v_rcp_f32_e32 v137, v137
	v_lshlrev_b32_e32 v134, 16, v188
	v_and_b32_e32 v135, 0xffff0000, v188
	v_lshlrev_b32_e32 v138, 16, v189
	v_and_b32_e32 v139, 0xffff0000, v189
	v_pk_mul_f32 v[132:133], v[132:133], v[134:135]
	v_pk_mul_f32 v[136:137], v[136:137], v[138:139]
	v_pk_mul_f32 v[88:89], v[88:89], v[132:133]
	v_pk_mul_f32 v[90:91], v[90:91], v[136:137]
	v_lshlrev_b32_e32 v132, 16, v194
	v_and_b32_e32 v133, 0xffff0000, v194
	v_lshlrev_b32_e32 v136, 16, v195
	v_and_b32_e32 v137, 0xffff0000, v195
	v_rcp_f32_e32 v132, v132
	v_rcp_f32_e32 v133, v133
	v_rcp_f32_e32 v136, v136
	v_rcp_f32_e32 v137, v137
	v_lshlrev_b32_e32 v134, 16, v190
	v_and_b32_e32 v135, 0xffff0000, v190
	v_lshlrev_b32_e32 v138, 16, v191
	v_and_b32_e32 v139, 0xffff0000, v191
	v_pk_mul_f32 v[132:133], v[132:133], v[134:135]
	v_pk_mul_f32 v[136:137], v[136:137], v[138:139]
	v_pk_mul_f32 v[84:85], v[84:85], v[132:133]
	v_pk_mul_f32 v[86:87], v[86:87], v[136:137]
	global_load_dwordx4 v[188:191], v[2:3], off offset:-2048
	global_load_dwordx4 v[192:195], v[158:159], off offset:-2048
	s_waitcnt vmcnt(12)
	v_lshlrev_b32_e32 v132, 16, v210
	v_and_b32_e32 v133, 0xffff0000, v210
	v_lshlrev_b32_e32 v136, 16, v211
	v_and_b32_e32 v137, 0xffff0000, v211
	v_rcp_f32_e32 v132, v132
	v_rcp_f32_e32 v133, v133
	v_rcp_f32_e32 v136, v136
	v_rcp_f32_e32 v137, v137
	v_lshlrev_b32_e32 v134, 16, v206
	v_and_b32_e32 v135, 0xffff0000, v206
	v_lshlrev_b32_e32 v138, 16, v207
	v_and_b32_e32 v139, 0xffff0000, v207
	v_pk_mul_f32 v[132:133], v[132:133], v[134:135]
	v_pk_mul_f32 v[136:137], v[136:137], v[138:139]
	v_pk_mul_f32 v[112:113], v[112:113], v[132:133]
	v_pk_mul_f32 v[114:115], v[114:115], v[136:137]
	v_lshlrev_b32_e32 v132, 16, v212
	v_and_b32_e32 v133, 0xffff0000, v212
	v_lshlrev_b32_e32 v136, 16, v213
	v_and_b32_e32 v137, 0xffff0000, v213
	v_rcp_f32_e32 v132, v132
	v_rcp_f32_e32 v133, v133
	v_rcp_f32_e32 v136, v136
	v_rcp_f32_e32 v137, v137
	v_lshlrev_b32_e32 v134, 16, v208
	v_and_b32_e32 v135, 0xffff0000, v208
	v_lshlrev_b32_e32 v138, 16, v209
	v_and_b32_e32 v139, 0xffff0000, v209
	v_pk_mul_f32 v[132:133], v[132:133], v[134:135]
	v_pk_mul_f32 v[136:137], v[136:137], v[138:139]
	v_pk_mul_f32 v[108:109], v[108:109], v[132:133]
	v_pk_mul_f32 v[110:111], v[110:111], v[136:137]
	global_load_dwordx4 v[206:209], v[2:3], off offset:-1024
	global_load_dwordx4 v[210:213], v[158:159], off offset:-1024
	s_waitcnt vmcnt(12)
	v_lshlrev_b32_e32 v132, 16, v218
	v_and_b32_e32 v133, 0xffff0000, v218
	v_lshlrev_b32_e32 v136, 16, v219
	v_and_b32_e32 v137, 0xffff0000, v219
	v_rcp_f32_e32 v132, v132
	v_rcp_f32_e32 v133, v133
	v_rcp_f32_e32 v136, v136
	v_rcp_f32_e32 v137, v137
	v_lshlrev_b32_e32 v134, 16, v214
	v_and_b32_e32 v135, 0xffff0000, v214
	v_lshlrev_b32_e32 v138, 16, v215
	v_and_b32_e32 v139, 0xffff0000, v215
	v_pk_mul_f32 v[132:133], v[132:133], v[134:135]
	v_pk_mul_f32 v[136:137], v[136:137], v[138:139]
	v_pk_mul_f32 v[80:81], v[80:81], v[132:133]
	v_pk_mul_f32 v[82:83], v[82:83], v[136:137]
	v_lshlrev_b32_e32 v132, 16, v220
	v_and_b32_e32 v133, 0xffff0000, v220
	v_lshlrev_b32_e32 v136, 16, v221
	v_and_b32_e32 v137, 0xffff0000, v221
	v_rcp_f32_e32 v132, v132
	v_rcp_f32_e32 v133, v133
	v_rcp_f32_e32 v136, v136
	v_rcp_f32_e32 v137, v137
	v_lshlrev_b32_e32 v134, 16, v216
	v_and_b32_e32 v135, 0xffff0000, v216
	v_lshlrev_b32_e32 v138, 16, v217
	v_and_b32_e32 v139, 0xffff0000, v217
	v_pk_mul_f32 v[132:133], v[132:133], v[134:135]
	v_pk_mul_f32 v[136:137], v[136:137], v[138:139]
	v_pk_mul_f32 v[76:77], v[76:77], v[132:133]
	v_pk_mul_f32 v[78:79], v[78:79], v[136:137]
	global_load_dwordx4 v[214:217], v[2:3], off
	global_load_dwordx4 v[218:221], v[158:159], off
	s_waitcnt vmcnt(12)
	v_lshlrev_b32_e32 v132, 16, v232
	v_and_b32_e32 v133, 0xffff0000, v232
	v_lshlrev_b32_e32 v136, 16, v233
	v_and_b32_e32 v137, 0xffff0000, v233
	v_rcp_f32_e32 v132, v132
	v_rcp_f32_e32 v133, v133
	v_rcp_f32_e32 v136, v136
	v_rcp_f32_e32 v137, v137
	v_lshlrev_b32_e32 v134, 16, v154
	v_and_b32_e32 v135, 0xffff0000, v154
	v_lshlrev_b32_e32 v138, 16, v155
	v_and_b32_e32 v139, 0xffff0000, v155
	v_pk_mul_f32 v[132:133], v[132:133], v[134:135]
	v_pk_mul_f32 v[136:137], v[136:137], v[138:139]
	v_pk_mul_f32 v[104:105], v[104:105], v[132:133]
	v_pk_mul_f32 v[106:107], v[106:107], v[136:137]
	v_lshlrev_b32_e32 v132, 16, v234
	v_and_b32_e32 v133, 0xffff0000, v234
	v_lshlrev_b32_e32 v136, 16, v235
	v_and_b32_e32 v137, 0xffff0000, v235
	v_rcp_f32_e32 v132, v132
	v_rcp_f32_e32 v133, v133
	v_rcp_f32_e32 v136, v136
	v_rcp_f32_e32 v137, v137
	v_lshlrev_b32_e32 v134, 16, v156
	v_and_b32_e32 v135, 0xffff0000, v156
	v_lshlrev_b32_e32 v138, 16, v157
	v_and_b32_e32 v139, 0xffff0000, v157
	v_pk_mul_f32 v[132:133], v[132:133], v[134:135]
	v_pk_mul_f32 v[136:137], v[136:137], v[138:139]
	v_pk_mul_f32 v[100:101], v[100:101], v[132:133]
	v_pk_mul_f32 v[102:103], v[102:103], v[136:137]
	global_load_dwordx4 v[154:157], v[2:3], off offset:1024
	global_load_dwordx4 v[232:235], v[158:159], off offset:1024
	s_waitcnt vmcnt(12)
	v_lshlrev_b32_e32 v132, 16, v168
	v_and_b32_e32 v133, 0xffff0000, v168
	v_lshlrev_b32_e32 v136, 16, v169
	v_and_b32_e32 v137, 0xffff0000, v169
	v_rcp_f32_e32 v132, v132
	v_rcp_f32_e32 v133, v133
	v_rcp_f32_e32 v136, v136
	v_rcp_f32_e32 v137, v137
	v_lshlrev_b32_e32 v134, 16, v164
	v_and_b32_e32 v135, 0xffff0000, v164
	v_lshlrev_b32_e32 v138, 16, v165
	v_and_b32_e32 v139, 0xffff0000, v165
	v_pk_mul_f32 v[132:133], v[132:133], v[134:135]
	v_pk_mul_f32 v[136:137], v[136:137], v[138:139]
	v_pk_mul_f32 v[72:73], v[72:73], v[132:133]
	v_pk_mul_f32 v[74:75], v[74:75], v[136:137]
	v_lshlrev_b32_e32 v132, 16, v170
	v_and_b32_e32 v133, 0xffff0000, v170
	v_lshlrev_b32_e32 v136, 16, v171
	v_and_b32_e32 v137, 0xffff0000, v171
	v_rcp_f32_e32 v132, v132
	v_rcp_f32_e32 v133, v133
	v_rcp_f32_e32 v136, v136
	v_rcp_f32_e32 v137, v137
	v_lshlrev_b32_e32 v134, 16, v166
	v_and_b32_e32 v135, 0xffff0000, v166
	v_lshlrev_b32_e32 v138, 16, v167
	v_and_b32_e32 v139, 0xffff0000, v167
	v_pk_mul_f32 v[132:133], v[132:133], v[134:135]
	v_pk_mul_f32 v[136:137], v[136:137], v[138:139]
	v_pk_mul_f32 v[68:69], v[68:69], v[132:133]
	v_pk_mul_f32 v[70:71], v[70:71], v[136:137]
	global_load_dwordx4 v[164:167], v[2:3], off offset:2048
	global_load_dwordx4 v[168:171], v[158:159], off offset:2048
	s_waitcnt vmcnt(12)
	v_lshlrev_b32_e32 v132, 16, v176
	v_and_b32_e32 v133, 0xffff0000, v176
	v_lshlrev_b32_e32 v136, 16, v177
	v_and_b32_e32 v137, 0xffff0000, v177
	v_rcp_f32_e32 v132, v132
	v_rcp_f32_e32 v133, v133
	v_rcp_f32_e32 v136, v136
	v_rcp_f32_e32 v137, v137
	v_lshlrev_b32_e32 v134, 16, v172
	v_and_b32_e32 v135, 0xffff0000, v172
	v_lshlrev_b32_e32 v138, 16, v173
	v_and_b32_e32 v139, 0xffff0000, v173
	v_pk_mul_f32 v[132:133], v[132:133], v[134:135]
	v_pk_mul_f32 v[136:137], v[136:137], v[138:139]
	v_pk_mul_f32 v[64:65], v[64:65], v[132:133]
	v_pk_mul_f32 v[66:67], v[66:67], v[136:137]
	v_lshlrev_b32_e32 v132, 16, v178
	v_and_b32_e32 v133, 0xffff0000, v178
	v_lshlrev_b32_e32 v136, 16, v179
	v_and_b32_e32 v137, 0xffff0000, v179
	v_rcp_f32_e32 v132, v132
	v_rcp_f32_e32 v133, v133
	v_rcp_f32_e32 v136, v136
	v_rcp_f32_e32 v137, v137
	v_lshlrev_b32_e32 v134, 16, v174
	v_and_b32_e32 v135, 0xffff0000, v174
	v_lshlrev_b32_e32 v138, 16, v175
	v_and_b32_e32 v139, 0xffff0000, v175
	v_pk_mul_f32 v[132:133], v[132:133], v[134:135]
	v_pk_mul_f32 v[136:137], v[136:137], v[138:139]
	v_pk_mul_f32 v[60:61], v[60:61], v[132:133]
	v_pk_mul_f32 v[62:63], v[62:63], v[136:137]
	global_load_dwordx4 v[172:175], v[2:3], off offset:3072
	global_load_dwordx4 v[176:179], v[158:159], off offset:3072
	s_waitcnt vmcnt(12)
	v_lshlrev_b32_e32 v132, 16, v184
	v_and_b32_e32 v133, 0xffff0000, v184
	v_lshlrev_b32_e32 v136, 16, v185
	v_and_b32_e32 v137, 0xffff0000, v185
	v_rcp_f32_e32 v132, v132
	v_rcp_f32_e32 v133, v133
	v_rcp_f32_e32 v136, v136
	v_rcp_f32_e32 v137, v137
	v_lshlrev_b32_e32 v134, 16, v180
	v_and_b32_e32 v135, 0xffff0000, v180
	v_lshlrev_b32_e32 v138, 16, v181
	v_and_b32_e32 v139, 0xffff0000, v181
	v_pk_mul_f32 v[132:133], v[132:133], v[134:135]
	v_pk_mul_f32 v[136:137], v[136:137], v[138:139]
	v_pk_mul_f32 v[32:33], v[32:33], v[132:133]
	v_pk_mul_f32 v[34:35], v[34:35], v[136:137]
	v_lshlrev_b32_e32 v132, 16, v186
	v_and_b32_e32 v133, 0xffff0000, v186
	v_lshlrev_b32_e32 v136, 16, v187
	v_and_b32_e32 v137, 0xffff0000, v187
	v_rcp_f32_e32 v132, v132
	v_rcp_f32_e32 v133, v133
	v_rcp_f32_e32 v136, v136
	v_rcp_f32_e32 v137, v137
	v_lshlrev_b32_e32 v134, 16, v182
	v_and_b32_e32 v135, 0xffff0000, v182
	v_lshlrev_b32_e32 v138, 16, v183
	v_and_b32_e32 v139, 0xffff0000, v183
	v_pk_mul_f32 v[132:133], v[132:133], v[134:135]
	v_pk_mul_f32 v[136:137], v[136:137], v[138:139]
	v_pk_mul_f32 v[28:29], v[28:29], v[132:133]
	v_pk_mul_f32 v[30:31], v[30:31], v[136:137]
	s_waitcnt vmcnt(10)
	v_lshlrev_b32_e32 v132, 16, v192
	v_and_b32_e32 v133, 0xffff0000, v192
	v_lshlrev_b32_e32 v136, 16, v193
	v_and_b32_e32 v137, 0xffff0000, v193
	v_rcp_f32_e32 v132, v132
	v_rcp_f32_e32 v133, v133
	v_rcp_f32_e32 v136, v136
	v_rcp_f32_e32 v137, v137
	v_lshlrev_b32_e32 v134, 16, v188
	v_and_b32_e32 v135, 0xffff0000, v188
	v_lshlrev_b32_e32 v138, 16, v189
	v_and_b32_e32 v139, 0xffff0000, v189
	v_pk_mul_f32 v[132:133], v[132:133], v[134:135]
	v_pk_mul_f32 v[136:137], v[136:137], v[138:139]
	v_pk_mul_f32 v[56:57], v[56:57], v[132:133]
	v_pk_mul_f32 v[58:59], v[58:59], v[136:137]
	v_lshlrev_b32_e32 v132, 16, v194
	v_and_b32_e32 v133, 0xffff0000, v194
	v_lshlrev_b32_e32 v136, 16, v195
	v_and_b32_e32 v137, 0xffff0000, v195
	v_rcp_f32_e32 v132, v132
	v_rcp_f32_e32 v133, v133
	v_rcp_f32_e32 v136, v136
	v_rcp_f32_e32 v137, v137
	v_lshlrev_b32_e32 v134, 16, v190
	v_and_b32_e32 v135, 0xffff0000, v190
	v_lshlrev_b32_e32 v138, 16, v191
	v_and_b32_e32 v139, 0xffff0000, v191
	v_pk_mul_f32 v[132:133], v[132:133], v[134:135]
	v_pk_mul_f32 v[136:137], v[136:137], v[138:139]
	v_pk_mul_f32 v[52:53], v[52:53], v[132:133]
	v_pk_mul_f32 v[54:55], v[54:55], v[136:137]
	s_waitcnt vmcnt(8)
	v_lshlrev_b32_e32 v132, 16, v210
	v_and_b32_e32 v133, 0xffff0000, v210
	v_lshlrev_b32_e32 v136, 16, v211
	v_and_b32_e32 v137, 0xffff0000, v211
	v_rcp_f32_e32 v132, v132
	v_rcp_f32_e32 v133, v133
	v_rcp_f32_e32 v136, v136
	v_rcp_f32_e32 v137, v137
	v_lshlrev_b32_e32 v134, 16, v206
	v_and_b32_e32 v135, 0xffff0000, v206
	v_lshlrev_b32_e32 v138, 16, v207
	v_and_b32_e32 v139, 0xffff0000, v207
	v_pk_mul_f32 v[132:133], v[132:133], v[134:135]
	v_pk_mul_f32 v[136:137], v[136:137], v[138:139]
	v_pk_mul_f32 v[24:25], v[24:25], v[132:133]
	v_pk_mul_f32 v[26:27], v[26:27], v[136:137]
	v_lshlrev_b32_e32 v132, 16, v212
	v_and_b32_e32 v133, 0xffff0000, v212
	v_lshlrev_b32_e32 v136, 16, v213
	v_and_b32_e32 v137, 0xffff0000, v213
	v_rcp_f32_e32 v132, v132
	v_rcp_f32_e32 v133, v133
	v_rcp_f32_e32 v136, v136
	v_rcp_f32_e32 v137, v137
	v_lshlrev_b32_e32 v134, 16, v208
	v_and_b32_e32 v135, 0xffff0000, v208
	v_lshlrev_b32_e32 v138, 16, v209
	v_and_b32_e32 v139, 0xffff0000, v209
	v_pk_mul_f32 v[132:133], v[132:133], v[134:135]
	v_pk_mul_f32 v[136:137], v[136:137], v[138:139]
	v_pk_mul_f32 v[20:21], v[20:21], v[132:133]
	v_pk_mul_f32 v[22:23], v[22:23], v[136:137]
	s_waitcnt vmcnt(6)
	v_lshlrev_b32_e32 v132, 16, v218
	v_and_b32_e32 v133, 0xffff0000, v218
	v_lshlrev_b32_e32 v136, 16, v219
	v_and_b32_e32 v137, 0xffff0000, v219
	v_rcp_f32_e32 v132, v132
	v_rcp_f32_e32 v133, v133
	v_rcp_f32_e32 v136, v136
	v_rcp_f32_e32 v137, v137
	v_lshlrev_b32_e32 v134, 16, v214
	v_and_b32_e32 v135, 0xffff0000, v214
	v_lshlrev_b32_e32 v138, 16, v215
	v_and_b32_e32 v139, 0xffff0000, v215
	v_pk_mul_f32 v[132:133], v[132:133], v[134:135]
	v_pk_mul_f32 v[136:137], v[136:137], v[138:139]
	v_pk_mul_f32 v[48:49], v[48:49], v[132:133]
	v_pk_mul_f32 v[50:51], v[50:51], v[136:137]
	v_lshlrev_b32_e32 v132, 16, v220
	v_and_b32_e32 v133, 0xffff0000, v220
	v_lshlrev_b32_e32 v136, 16, v221
	v_and_b32_e32 v137, 0xffff0000, v221
	v_rcp_f32_e32 v132, v132
	v_rcp_f32_e32 v133, v133
	v_rcp_f32_e32 v136, v136
	v_rcp_f32_e32 v137, v137
	v_lshlrev_b32_e32 v134, 16, v216
	v_and_b32_e32 v135, 0xffff0000, v216
	v_lshlrev_b32_e32 v138, 16, v217
	v_and_b32_e32 v139, 0xffff0000, v217
	v_pk_mul_f32 v[132:133], v[132:133], v[134:135]
	v_pk_mul_f32 v[136:137], v[136:137], v[138:139]
	v_pk_mul_f32 v[44:45], v[44:45], v[132:133]
	v_pk_mul_f32 v[46:47], v[46:47], v[136:137]
	s_waitcnt vmcnt(4)
	v_lshlrev_b32_e32 v132, 16, v232
	v_and_b32_e32 v133, 0xffff0000, v232
	v_lshlrev_b32_e32 v136, 16, v233
	v_and_b32_e32 v137, 0xffff0000, v233
	v_rcp_f32_e32 v132, v132
	v_rcp_f32_e32 v133, v133
	v_rcp_f32_e32 v136, v136
	v_rcp_f32_e32 v137, v137
	v_lshlrev_b32_e32 v134, 16, v154
	v_and_b32_e32 v135, 0xffff0000, v154
	v_lshlrev_b32_e32 v138, 16, v155
	v_and_b32_e32 v139, 0xffff0000, v155
	v_pk_mul_f32 v[132:133], v[132:133], v[134:135]
	v_pk_mul_f32 v[136:137], v[136:137], v[138:139]
	v_pk_mul_f32 v[16:17], v[16:17], v[132:133]
	v_pk_mul_f32 v[18:19], v[18:19], v[136:137]
	v_lshlrev_b32_e32 v132, 16, v234
	v_and_b32_e32 v133, 0xffff0000, v234
	v_lshlrev_b32_e32 v136, 16, v235
	v_and_b32_e32 v137, 0xffff0000, v235
	v_rcp_f32_e32 v132, v132
	v_rcp_f32_e32 v133, v133
	v_rcp_f32_e32 v136, v136
	v_rcp_f32_e32 v137, v137
	v_lshlrev_b32_e32 v134, 16, v156
	v_and_b32_e32 v135, 0xffff0000, v156
	v_lshlrev_b32_e32 v138, 16, v157
	v_and_b32_e32 v139, 0xffff0000, v157
	v_pk_mul_f32 v[132:133], v[132:133], v[134:135]
	v_pk_mul_f32 v[136:137], v[136:137], v[138:139]
	v_pk_mul_f32 v[12:13], v[12:13], v[132:133]
	v_pk_mul_f32 v[14:15], v[14:15], v[136:137]
	s_waitcnt vmcnt(2)
	v_lshlrev_b32_e32 v132, 16, v168
	v_and_b32_e32 v133, 0xffff0000, v168
	v_lshlrev_b32_e32 v136, 16, v169
	v_and_b32_e32 v137, 0xffff0000, v169
	v_rcp_f32_e32 v132, v132
	v_rcp_f32_e32 v133, v133
	v_rcp_f32_e32 v136, v136
	v_rcp_f32_e32 v137, v137
	v_lshlrev_b32_e32 v134, 16, v164
	v_and_b32_e32 v135, 0xffff0000, v164
	v_lshlrev_b32_e32 v138, 16, v165
	v_and_b32_e32 v139, 0xffff0000, v165
	v_pk_mul_f32 v[132:133], v[132:133], v[134:135]
	v_pk_mul_f32 v[136:137], v[136:137], v[138:139]
	v_pk_mul_f32 v[40:41], v[40:41], v[132:133]
	v_pk_mul_f32 v[42:43], v[42:43], v[136:137]
	v_lshlrev_b32_e32 v132, 16, v170
	v_and_b32_e32 v133, 0xffff0000, v170
	v_lshlrev_b32_e32 v136, 16, v171
	v_and_b32_e32 v137, 0xffff0000, v171
	v_rcp_f32_e32 v132, v132
	v_rcp_f32_e32 v133, v133
	v_rcp_f32_e32 v136, v136
	v_rcp_f32_e32 v137, v137
	v_lshlrev_b32_e32 v134, 16, v166
	v_and_b32_e32 v135, 0xffff0000, v166
	v_lshlrev_b32_e32 v138, 16, v167
	v_and_b32_e32 v139, 0xffff0000, v167
	v_pk_mul_f32 v[132:133], v[132:133], v[134:135]
	v_pk_mul_f32 v[136:137], v[136:137], v[138:139]
	v_pk_mul_f32 v[36:37], v[36:37], v[132:133]
	v_pk_mul_f32 v[38:39], v[38:39], v[136:137]
	s_waitcnt vmcnt(0)
	v_lshlrev_b32_e32 v132, 16, v176
	v_and_b32_e32 v133, 0xffff0000, v176
	v_lshlrev_b32_e32 v136, 16, v177
	v_and_b32_e32 v137, 0xffff0000, v177
	v_rcp_f32_e32 v132, v132
	v_rcp_f32_e32 v133, v133
	v_rcp_f32_e32 v136, v136
	v_rcp_f32_e32 v137, v137
	v_lshlrev_b32_e32 v134, 16, v172
	v_and_b32_e32 v135, 0xffff0000, v172
	v_lshlrev_b32_e32 v138, 16, v173
	v_and_b32_e32 v139, 0xffff0000, v173
	v_pk_mul_f32 v[132:133], v[132:133], v[134:135]
	v_pk_mul_f32 v[136:137], v[136:137], v[138:139]
	v_pk_mul_f32 v[8:9], v[8:9], v[132:133]
	v_pk_mul_f32 v[10:11], v[10:11], v[136:137]
	v_lshlrev_b32_e32 v132, 16, v178
	v_and_b32_e32 v133, 0xffff0000, v178
	v_lshlrev_b32_e32 v136, 16, v179
	v_and_b32_e32 v137, 0xffff0000, v179
	v_rcp_f32_e32 v132, v132
	v_rcp_f32_e32 v133, v133
	v_rcp_f32_e32 v136, v136
	v_rcp_f32_e32 v137, v137
	v_lshlrev_b32_e32 v134, 16, v174
	v_and_b32_e32 v135, 0xffff0000, v174
	v_lshlrev_b32_e32 v138, 16, v175
	v_and_b32_e32 v139, 0xffff0000, v175
	v_pk_mul_f32 v[132:133], v[132:133], v[134:135]
	v_pk_mul_f32 v[136:137], v[136:137], v[138:139]
	v_pk_mul_f32 v[4:5], v[4:5], v[132:133]
	v_pk_mul_f32 v[6:7], v[6:7], v[136:137]
	s_and_b64 vcc, exec, s[40:41]
	s_mov_b64 s[40:41], -1
	s_cbranch_vccnz .LBB0_604

.LBB0_700:
	v_mul_f32_e32 v150, v127, v127
	v_mul_f32_e32 v151, v129, v129
	v_fmac_f32_e32 v150, v126, v126
	v_fmac_f32_e32 v151, v128, v128
	v_add_f32_e32 v150, v150, v151
	v_mul_f32_e32 v151, v123, v123
	v_fmac_f32_e32 v151, v122, v122
	v_cvt_pk_bf16_f32 v126, v126, v127
	v_cvt_pk_bf16_f32 v127, v128, v129
	v_cvt_pk_bf16_f32 v128, v122, v123
	v_mul_f32_e32 v122, v119, v119
	v_mul_f32_e32 v123, v121, v121
	v_fmac_f32_e32 v122, v118, v118
	v_fmac_f32_e32 v123, v120, v120
	v_add_f32_e32 v122, v122, v123
	v_mul_f32_e32 v123, v115, v115
	v_fmac_f32_e32 v123, v114, v114
	v_add_f32_e32 v150, v150, v151
	v_mul_f32_e32 v151, v125, v125
	v_add_f32_e32 v122, v122, v123
	v_mul_f32_e32 v123, v117, v117
	v_fmac_f32_e32 v151, v124, v124
	v_fmac_f32_e32 v123, v116, v116
	v_add_f32_e32 v150, v151, v150
	v_cvt_pk_bf16_f32 v129, v124, v125
	v_add_f32_e32 v122, v123, v122
	v_and_b32_e32 v124, 64, v230
	v_add_f32_e32 v123, v150, v122
	v_xor_b32_e32 v122, 16, v230
	v_add_u32_e32 v150, 64, v124
	v_lshl_add_u32 v142, s30, 8, v144
	v_cmp_lt_i32_e32 vcc, v122, v150
	v_ashrrev_i32_e32 v143, 31, v142
	v_lshl_or_b32 v140, s75, 8, v146
	v_cndmask_b32_e32 v122, v230, v122, vcc
	v_lshlrev_b64 v[148:149], 11, v[142:143]
	v_lshlrev_b32_e32 v122, 2, v122
	v_ashrrev_i32_e32 v141, 31, v140
	ds_bpermute_b32 v151, v122, v123
	v_lshl_add_u64 v[124:125], s[28:29], 0, v[148:149]
	v_lshl_add_u64 v[148:149], v[140:141], 1, v[124:125]
	global_store_dwordx4 v[148:149], v[126:129], off sc1
	v_cvt_pk_bf16_f32 v124, v118, v119
	v_xor_b32_e32 v118, 32, v230
	v_cmp_lt_i32_e32 vcc, v118, v150
	s_waitcnt lgkmcnt(0)
	v_add_f32_e32 v119, v123, v151
	v_cvt_pk_bf16_f32 v125, v120, v121
	v_cvt_pk_bf16_f32 v126, v114, v115
	v_cvt_pk_bf16_f32 v127, v116, v117
	global_store_dwordx4 v[148:149], v[124:127], off offset:256 sc1
	v_cndmask_b32_e32 v118, v230, v118, vcc
	v_lshlrev_b32_e32 v118, 2, v118
	ds_bpermute_b32 v123, v118, v119
	s_and_saveexec_b64 s[64:65], s[38:39]
	s_cbranch_execz .LBB0_702
	s_lshl_b32 s66, s75, 2
	v_lshlrev_b64 v[114:115], 6, v[142:143]
	s_ashr_i32 s67, s66, 31
	v_lshl_add_u64 v[114:115], s[42:43], 0, v[114:115]
	v_lshl_add_u64 v[114:115], s[66:67], 2, v[114:115]
	s_lshl_b32 s30, s71, 2
	s_waitcnt lgkmcnt(0)
	v_add_f32_e32 v116, v119, v123
	v_lshl_add_u64 v[114:115], v[114:115], 0, s[30:31]
	global_store_dword v[114:115], v116, off
.LBB0_702:
	s_or_b64 exec, exec, s[64:65]
	v_mul_f32_e32 v119, v111, v111
	v_mul_f32_e32 v120, v113, v113
	v_fmac_f32_e32 v119, v110, v110
	v_fmac_f32_e32 v120, v112, v112
	v_add_f32_e32 v119, v119, v120
	v_mul_f32_e32 v120, v107, v107
	v_fmac_f32_e32 v120, v106, v106
	v_cvt_pk_bf16_f32 v110, v110, v111
	v_cvt_pk_bf16_f32 v111, v112, v113
	v_cvt_pk_bf16_f32 v112, v106, v107
	v_mul_f32_e32 v106, v103, v103
	v_mul_f32_e32 v107, v105, v105
	v_fmac_f32_e32 v106, v102, v102
	v_fmac_f32_e32 v107, v104, v104
	v_add_f32_e32 v106, v106, v107
	v_mul_f32_e32 v107, v99, v99
	v_fmac_f32_e32 v107, v98, v98
	v_add_f32_e32 v119, v119, v120
	v_mul_f32_e32 v120, v109, v109
	v_add_f32_e32 v106, v106, v107
	v_mul_f32_e32 v107, v101, v101
	v_fmac_f32_e32 v120, v108, v108
	v_fmac_f32_e32 v107, v100, v100
	v_add_f32_e32 v119, v120, v119
	v_add_f32_e32 v106, v107, v106
	v_cvt_pk_bf16_f32 v113, v108, v109
	v_add_f32_e32 v108, v119, v106
	v_or_b32_e32 v114, 16, v142
	ds_bpermute_b32 v109, v122, v108
	v_ashrrev_i32_e32 v115, 31, v114
	v_lshlrev_b64 v[116:117], 11, v[114:115]
	v_lshl_add_u64 v[106:107], s[28:29], 0, v[116:117]
	v_lshl_add_u64 v[116:117], v[140:141], 1, v[106:107]
	global_store_dwordx4 v[116:117], v[110:113], off sc1
	v_cvt_pk_bf16_f32 v106, v102, v103
	s_waitcnt lgkmcnt(0)
	v_add_f32_e32 v102, v108, v109
	ds_bpermute_b32 v103, v118, v102
	v_cvt_pk_bf16_f32 v107, v104, v105
	v_cvt_pk_bf16_f32 v108, v98, v99
	v_cvt_pk_bf16_f32 v109, v100, v101
	global_store_dwordx4 v[116:117], v[106:109], off offset:256 sc1
	s_and_saveexec_b64 s[64:65], s[38:39]
	s_cbranch_execz .LBB0_704
	s_lshl_b32 s66, s75, 2
	v_lshlrev_b64 v[98:99], 6, v[114:115]
	s_ashr_i32 s67, s66, 31
	v_lshl_add_u64 v[98:99], s[42:43], 0, v[98:99]
	v_lshl_add_u64 v[98:99], s[66:67], 2, v[98:99]
	s_lshl_b32 s30, s71, 2
	s_waitcnt lgkmcnt(0)
	v_add_f32_e32 v100, v102, v103
	v_lshl_add_u64 v[98:99], v[98:99], 0, s[30:31]
	global_store_dword v[98:99], v100, off
.LBB0_704:
	s_or_b64 exec, exec, s[64:65]
	v_mul_f32_e32 v102, v95, v95
	s_waitcnt lgkmcnt(0)
	v_mul_f32_e32 v103, v97, v97
	v_fmac_f32_e32 v102, v94, v94
	v_fmac_f32_e32 v103, v96, v96
	v_add_f32_e32 v102, v102, v103
	v_mul_f32_e32 v103, v91, v91
	v_fmac_f32_e32 v103, v90, v90
	v_cvt_pk_bf16_f32 v94, v94, v95
	v_cvt_pk_bf16_f32 v95, v96, v97
	v_cvt_pk_bf16_f32 v96, v90, v91
	v_mul_f32_e32 v90, v87, v87
	v_mul_f32_e32 v91, v89, v89
	v_fmac_f32_e32 v90, v86, v86
	v_fmac_f32_e32 v91, v88, v88
	v_add_f32_e32 v90, v90, v91
	v_mul_f32_e32 v91, v83, v83
	v_fmac_f32_e32 v91, v82, v82
	v_add_f32_e32 v102, v102, v103
	v_mul_f32_e32 v103, v93, v93
	v_add_f32_e32 v90, v90, v91
	v_mul_f32_e32 v91, v85, v85
	v_fmac_f32_e32 v103, v92, v92
	v_fmac_f32_e32 v91, v84, v84
	v_add_f32_e32 v102, v103, v102
	v_add_f32_e32 v90, v91, v90
	v_cvt_pk_bf16_f32 v97, v92, v93
	v_add_f32_e32 v92, v102, v90
	v_or_b32_e32 v98, 32, v142
	ds_bpermute_b32 v93, v122, v92
	v_ashrrev_i32_e32 v99, 31, v98
	v_lshlrev_b64 v[100:101], 11, v[98:99]
	v_lshl_add_u64 v[90:91], s[28:29], 0, v[100:101]
	v_lshl_add_u64 v[100:101], v[140:141], 1, v[90:91]
	global_store_dwordx4 v[100:101], v[94:97], off sc1
	v_cvt_pk_bf16_f32 v90, v86, v87
	s_waitcnt lgkmcnt(0)
	v_add_f32_e32 v86, v92, v93
	ds_bpermute_b32 v87, v118, v86
	v_cvt_pk_bf16_f32 v91, v88, v89
	v_cvt_pk_bf16_f32 v92, v82, v83
	v_cvt_pk_bf16_f32 v93, v84, v85
	global_store_dwordx4 v[100:101], v[90:93], off offset:256 sc1
	s_and_saveexec_b64 s[64:65], s[38:39]
	s_cbranch_execz .LBB0_706
	s_lshl_b32 s66, s75, 2
	v_lshlrev_b64 v[82:83], 6, v[98:99]
	s_ashr_i32 s67, s66, 31
	v_lshl_add_u64 v[82:83], s[42:43], 0, v[82:83]
	v_lshl_add_u64 v[82:83], s[66:67], 2, v[82:83]
	s_lshl_b32 s30, s71, 2
	s_waitcnt lgkmcnt(0)
	v_add_f32_e32 v84, v86, v87
	v_lshl_add_u64 v[82:83], v[82:83], 0, s[30:31]
	global_store_dword v[82:83], v84, off
.LBB0_706:
	s_or_b64 exec, exec, s[64:65]
	v_mul_f32_e32 v86, v79, v79
	s_waitcnt lgkmcnt(0)
	v_mul_f32_e32 v87, v81, v81
	v_fmac_f32_e32 v86, v78, v78
	v_fmac_f32_e32 v87, v80, v80
	v_add_f32_e32 v86, v86, v87
	v_mul_f32_e32 v87, v75, v75
	v_fmac_f32_e32 v87, v74, v74
	v_cvt_pk_bf16_f32 v78, v78, v79
	v_cvt_pk_bf16_f32 v79, v80, v81
	v_cvt_pk_bf16_f32 v80, v74, v75
	v_mul_f32_e32 v74, v71, v71
	v_mul_f32_e32 v75, v73, v73
	v_fmac_f32_e32 v74, v70, v70
	v_fmac_f32_e32 v75, v72, v72
	v_add_f32_e32 v74, v74, v75
	v_mul_f32_e32 v75, v67, v67
	v_fmac_f32_e32 v75, v66, v66
	v_add_f32_e32 v86, v86, v87
	v_mul_f32_e32 v87, v77, v77
	v_add_f32_e32 v74, v74, v75
	v_mul_f32_e32 v75, v69, v69
	v_fmac_f32_e32 v87, v76, v76
	v_fmac_f32_e32 v75, v68, v68
	v_add_f32_e32 v86, v87, v86
	v_add_f32_e32 v74, v75, v74
	v_cvt_pk_bf16_f32 v81, v76, v77
	v_add_f32_e32 v76, v86, v74
	v_or_b32_e32 v82, 48, v142
	ds_bpermute_b32 v77, v122, v76
	v_ashrrev_i32_e32 v83, 31, v82
	v_lshlrev_b64 v[84:85], 11, v[82:83]
	v_lshl_add_u64 v[74:75], s[28:29], 0, v[84:85]
	v_lshl_add_u64 v[84:85], v[140:141], 1, v[74:75]
	global_store_dwordx4 v[84:85], v[78:81], off sc1
	v_cvt_pk_bf16_f32 v74, v70, v71
	s_waitcnt lgkmcnt(0)
	v_add_f32_e32 v70, v76, v77
	ds_bpermute_b32 v71, v118, v70
	v_cvt_pk_bf16_f32 v75, v72, v73
	v_cvt_pk_bf16_f32 v76, v66, v67
	v_cvt_pk_bf16_f32 v77, v68, v69
	global_store_dwordx4 v[84:85], v[74:77], off offset:256 sc1
	s_and_saveexec_b64 s[64:65], s[38:39]
	s_cbranch_execz .LBB0_708
	s_lshl_b32 s66, s75, 2
	v_lshlrev_b64 v[66:67], 6, v[82:83]
	s_ashr_i32 s67, s66, 31
	v_lshl_add_u64 v[66:67], s[42:43], 0, v[66:67]
	v_lshl_add_u64 v[66:67], s[66:67], 2, v[66:67]
	s_lshl_b32 s30, s71, 2
	s_waitcnt lgkmcnt(0)
	v_add_f32_e32 v68, v70, v71
	v_lshl_add_u64 v[66:67], v[66:67], 0, s[30:31]
	global_store_dword v[66:67], v68, off
.LBB0_708:
	s_or_b64 exec, exec, s[64:65]
	v_mul_f32_e32 v70, v63, v63
	s_waitcnt lgkmcnt(0)
	v_mul_f32_e32 v71, v65, v65
	v_fmac_f32_e32 v70, v62, v62
	v_fmac_f32_e32 v71, v64, v64
	v_add_f32_e32 v70, v70, v71
	v_mul_f32_e32 v71, v59, v59
	v_fmac_f32_e32 v71, v58, v58
	v_cvt_pk_bf16_f32 v62, v62, v63
	v_cvt_pk_bf16_f32 v63, v64, v65
	v_cvt_pk_bf16_f32 v64, v58, v59
	v_mul_f32_e32 v58, v55, v55
	v_mul_f32_e32 v59, v57, v57
	v_fmac_f32_e32 v58, v54, v54
	v_fmac_f32_e32 v59, v56, v56
	v_add_f32_e32 v58, v58, v59
	v_mul_f32_e32 v59, v51, v51
	v_fmac_f32_e32 v59, v50, v50
	v_add_f32_e32 v70, v70, v71
	v_mul_f32_e32 v71, v61, v61
	v_add_f32_e32 v58, v58, v59
	v_mul_f32_e32 v59, v53, v53
	v_fmac_f32_e32 v71, v60, v60
	v_fmac_f32_e32 v59, v52, v52
	v_add_f32_e32 v70, v71, v70
	v_add_f32_e32 v58, v59, v58
	v_cvt_pk_bf16_f32 v65, v60, v61
	v_add_f32_e32 v60, v70, v58
	v_add_u32_e32 v66, 0x80, v142
	ds_bpermute_b32 v61, v122, v60
	v_ashrrev_i32_e32 v67, 31, v66
	v_lshlrev_b64 v[68:69], 11, v[66:67]
	v_lshl_add_u64 v[58:59], s[28:29], 0, v[68:69]
	v_lshl_add_u64 v[68:69], v[140:141], 1, v[58:59]
	global_store_dwordx4 v[68:69], v[62:65], off sc1
	v_cvt_pk_bf16_f32 v58, v54, v55
	s_waitcnt lgkmcnt(0)
	v_add_f32_e32 v54, v60, v61
	ds_bpermute_b32 v55, v118, v54
	v_cvt_pk_bf16_f32 v59, v56, v57
	v_cvt_pk_bf16_f32 v60, v50, v51
	v_cvt_pk_bf16_f32 v61, v52, v53
	global_store_dwordx4 v[68:69], v[58:61], off offset:256 sc1
	s_and_saveexec_b64 s[64:65], s[38:39]
	s_cbranch_execz .LBB0_710
	s_lshl_b32 s66, s75, 2
	v_lshlrev_b64 v[50:51], 6, v[66:67]
	s_ashr_i32 s67, s66, 31
	v_lshl_add_u64 v[50:51], s[42:43], 0, v[50:51]
	v_lshl_add_u64 v[50:51], s[66:67], 2, v[50:51]
	s_lshl_b32 s30, s71, 2
	s_waitcnt lgkmcnt(0)
	v_add_f32_e32 v52, v54, v55
	v_lshl_add_u64 v[50:51], v[50:51], 0, s[30:31]
	global_store_dword v[50:51], v52, off
.LBB0_710:
	s_or_b64 exec, exec, s[64:65]
	v_mul_f32_e32 v54, v47, v47
	s_waitcnt lgkmcnt(0)
	v_mul_f32_e32 v55, v49, v49
	v_fmac_f32_e32 v54, v46, v46
	v_fmac_f32_e32 v55, v48, v48
	v_add_f32_e32 v54, v54, v55
	v_mul_f32_e32 v55, v43, v43
	v_fmac_f32_e32 v55, v42, v42
	v_cvt_pk_bf16_f32 v46, v46, v47
	v_cvt_pk_bf16_f32 v47, v48, v49
	v_cvt_pk_bf16_f32 v48, v42, v43
	v_mul_f32_e32 v42, v39, v39
	v_mul_f32_e32 v43, v41, v41
	v_fmac_f32_e32 v42, v38, v38
	v_fmac_f32_e32 v43, v40, v40
	v_add_f32_e32 v42, v42, v43
	v_mul_f32_e32 v43, v35, v35
	v_fmac_f32_e32 v43, v34, v34
	v_add_f32_e32 v54, v54, v55
	v_mul_f32_e32 v55, v45, v45
	v_add_f32_e32 v42, v42, v43
	v_mul_f32_e32 v43, v37, v37
	v_fmac_f32_e32 v55, v44, v44
	v_fmac_f32_e32 v43, v36, v36
	v_add_f32_e32 v54, v55, v54
	v_add_f32_e32 v42, v43, v42
	v_cvt_pk_bf16_f32 v49, v44, v45
	v_add_f32_e32 v44, v54, v42
	v_add_u32_e32 v50, 0x90, v142
	ds_bpermute_b32 v45, v122, v44
	v_ashrrev_i32_e32 v51, 31, v50
	v_lshlrev_b64 v[52:53], 11, v[50:51]
	v_lshl_add_u64 v[42:43], s[28:29], 0, v[52:53]
	v_lshl_add_u64 v[52:53], v[140:141], 1, v[42:43]
	global_store_dwordx4 v[52:53], v[46:49], off sc1
	v_cvt_pk_bf16_f32 v42, v38, v39
	s_waitcnt lgkmcnt(0)
	v_add_f32_e32 v38, v44, v45
	ds_bpermute_b32 v39, v118, v38
	v_cvt_pk_bf16_f32 v43, v40, v41
	v_cvt_pk_bf16_f32 v44, v34, v35
	v_cvt_pk_bf16_f32 v45, v36, v37
	global_store_dwordx4 v[52:53], v[42:45], off offset:256 sc1
	s_and_saveexec_b64 s[64:65], s[38:39]
	s_cbranch_execz .LBB0_712
	s_lshl_b32 s66, s75, 2
	v_lshlrev_b64 v[34:35], 6, v[50:51]
	s_ashr_i32 s67, s66, 31
	v_lshl_add_u64 v[34:35], s[42:43], 0, v[34:35]
	v_lshl_add_u64 v[34:35], s[66:67], 2, v[34:35]
	s_lshl_b32 s30, s71, 2
	s_waitcnt lgkmcnt(0)
	v_add_f32_e32 v36, v38, v39
	v_lshl_add_u64 v[34:35], v[34:35], 0, s[30:31]
	global_store_dword v[34:35], v36, off
.LBB0_712:
	s_or_b64 exec, exec, s[64:65]
	v_mul_f32_e32 v38, v31, v31
	s_waitcnt lgkmcnt(0)
	v_mul_f32_e32 v39, v33, v33
	v_fmac_f32_e32 v38, v30, v30
	v_fmac_f32_e32 v39, v32, v32
	v_add_f32_e32 v38, v38, v39
	v_mul_f32_e32 v39, v27, v27
	v_fmac_f32_e32 v39, v26, v26
	v_cvt_pk_bf16_f32 v30, v30, v31
	v_cvt_pk_bf16_f32 v31, v32, v33
	v_cvt_pk_bf16_f32 v32, v26, v27
	v_mul_f32_e32 v26, v23, v23
	v_mul_f32_e32 v27, v25, v25
	v_fmac_f32_e32 v26, v22, v22
	v_fmac_f32_e32 v27, v24, v24
	v_add_f32_e32 v26, v26, v27
	v_mul_f32_e32 v27, v19, v19
	v_fmac_f32_e32 v27, v18, v18
	v_add_f32_e32 v38, v38, v39
	v_mul_f32_e32 v39, v29, v29
	v_add_f32_e32 v26, v26, v27
	v_mul_f32_e32 v27, v21, v21
	v_fmac_f32_e32 v39, v28, v28
	v_fmac_f32_e32 v27, v20, v20
	v_add_f32_e32 v38, v39, v38
	v_add_f32_e32 v26, v27, v26
	v_cvt_pk_bf16_f32 v33, v28, v29
	v_add_f32_e32 v28, v38, v26
	v_add_u32_e32 v34, 0xa0, v142
	ds_bpermute_b32 v29, v122, v28
	v_ashrrev_i32_e32 v35, 31, v34
	v_lshlrev_b64 v[36:37], 11, v[34:35]
	v_lshl_add_u64 v[26:27], s[28:29], 0, v[36:37]
	v_lshl_add_u64 v[36:37], v[140:141], 1, v[26:27]
	global_store_dwordx4 v[36:37], v[30:33], off sc1
	v_cvt_pk_bf16_f32 v26, v22, v23
	s_waitcnt lgkmcnt(0)
	v_add_f32_e32 v22, v28, v29
	ds_bpermute_b32 v23, v118, v22
	v_cvt_pk_bf16_f32 v27, v24, v25
	v_cvt_pk_bf16_f32 v28, v18, v19
	v_cvt_pk_bf16_f32 v29, v20, v21
	global_store_dwordx4 v[36:37], v[26:29], off offset:256 sc1
	s_and_saveexec_b64 s[64:65], s[38:39]
	s_cbranch_execz .LBB0_714
	s_lshl_b32 s66, s75, 2
	v_lshlrev_b64 v[18:19], 6, v[34:35]
	s_ashr_i32 s67, s66, 31
	v_lshl_add_u64 v[18:19], s[42:43], 0, v[18:19]
	v_lshl_add_u64 v[18:19], s[66:67], 2, v[18:19]
	s_lshl_b32 s30, s71, 2
	s_waitcnt lgkmcnt(0)
	v_add_f32_e32 v20, v22, v23
	v_lshl_add_u64 v[18:19], v[18:19], 0, s[30:31]
	global_store_dword v[18:19], v20, off
.LBB0_714:
	s_or_b64 exec, exec, s[64:65]
	v_mul_f32_e32 v22, v15, v15
	s_waitcnt lgkmcnt(0)
	v_mul_f32_e32 v23, v17, v17
	v_fmac_f32_e32 v22, v14, v14
	v_fmac_f32_e32 v23, v16, v16
	v_add_f32_e32 v22, v22, v23
	v_mul_f32_e32 v23, v11, v11
	v_fmac_f32_e32 v23, v10, v10
	v_cvt_pk_bf16_f32 v14, v14, v15
	v_cvt_pk_bf16_f32 v15, v16, v17
	v_cvt_pk_bf16_f32 v16, v10, v11
	v_mul_f32_e32 v10, v7, v7
	v_mul_f32_e32 v11, v9, v9
	v_fmac_f32_e32 v10, v6, v6
	v_fmac_f32_e32 v11, v8, v8
	v_add_f32_e32 v10, v10, v11
	v_mul_f32_e32 v11, v3, v3
	v_fmac_f32_e32 v11, v2, v2
	v_add_f32_e32 v22, v22, v23
	v_mul_f32_e32 v23, v13, v13
	v_add_f32_e32 v10, v10, v11
	v_mul_f32_e32 v11, v5, v5
	v_fmac_f32_e32 v23, v12, v12
	v_fmac_f32_e32 v11, v4, v4
	v_add_f32_e32 v22, v23, v22
	v_add_f32_e32 v10, v11, v10
	v_cvt_pk_bf16_f32 v17, v12, v13
	v_add_f32_e32 v12, v22, v10
	v_add_u32_e32 v18, 0xb0, v142
	ds_bpermute_b32 v13, v122, v12
	v_ashrrev_i32_e32 v19, 31, v18
	v_lshlrev_b64 v[20:21], 11, v[18:19]
	v_lshl_add_u64 v[10:11], s[28:29], 0, v[20:21]
	v_lshl_add_u64 v[20:21], v[140:141], 1, v[10:11]
	global_store_dwordx4 v[20:21], v[14:17], off sc1
	v_cvt_pk_bf16_f32 v10, v6, v7
	s_waitcnt lgkmcnt(0)
	v_add_f32_e32 v6, v12, v13
	ds_bpermute_b32 v7, v118, v6
	v_cvt_pk_bf16_f32 v11, v8, v9
	v_cvt_pk_bf16_f32 v12, v2, v3
	v_cvt_pk_bf16_f32 v13, v4, v5
	global_store_dwordx4 v[20:21], v[10:13], off offset:256 sc1
	s_and_saveexec_b64 s[64:65], s[38:39]
	s_cbranch_execz .LBB0_716
	s_lshl_b32 s66, s75, 2
	v_lshlrev_b64 v[2:3], 6, v[18:19]
	s_ashr_i32 s67, s66, 31
	v_lshl_add_u64 v[2:3], s[42:43], 0, v[2:3]
	v_lshl_add_u64 v[2:3], s[66:67], 2, v[2:3]
	s_lshl_b32 s30, s71, 2
	s_waitcnt lgkmcnt(0)
	v_add_f32_e32 v4, v6, v7
	v_lshl_add_u64 v[2:3], v[2:3], 0, s[30:31]
	global_store_dword v[2:3], v4, off

.LBB0_776:
	v_mov_b32_e32 v70, v31
	v_mov_b32_e32 v71, v32
	v_mov_b32_e32 v31, v33
	v_mov_b32_e32 v32, v27
	v_mov_b32_e32 v33, v28
	v_mov_b32_e32 v27, v29
	v_pk_add_f32 v[30:31], v[70:71], v[30:31]
	v_pk_add_f32 v[26:27], v[32:33], v[26:27]
	v_pk_add_f32 v[30:31], v[30:31], v[30:31] op_sel:[0,1] op_sel_hi:[1,0]
	v_pk_add_f32 v[26:27], v[26:27], v[26:27] op_sel:[0,1] op_sel_hi:[1,0]
	v_add_f32_e32 v22, v22, v23
	v_add_f32_e32 v24, v24, v25
	v_mov_b32_e32 v31, v18
	v_mov_b32_e32 v27, v19
	v_mov_b32_e32 v23, v20
	v_mov_b32_e32 v25, v21
	v_pk_add_f32 v[18:19], v[30:31], v[26:27]
	v_pk_add_f32 v[20:21], v[22:23], v[24:25]
	v_and_b32_e32 v23, 0xffff0000, v66
	v_pk_add_f32 v[18:19], v[18:19], v[20:21]
	v_lshlrev_b32_e32 v24, 16, v67
	v_add_f32_e32 v0, v18, v19
	v_fmamk_f32 v0, v0, 0x3a800000, v227
	v_mul_f32_e32 v18, 0x4f800000, v0
	v_cmp_gt_f32_e32 vcc, s7, v0
	v_and_b32_e32 v25, 0xffff0000, v67
	v_lshlrev_b32_e32 v26, 16, v62
	v_cndmask_b32_e32 v0, v0, v18, vcc
	v_sqrt_f32_e32 v18, v0
	v_and_b32_e32 v27, 0xffff0000, v62
	v_lshlrev_b32_e32 v28, 16, v63
	v_and_b32_e32 v29, 0xffff0000, v63
	v_add_u32_e32 v19, -1, v18
	v_fma_f32 v20, -v19, v18, v0
	v_cmp_ge_f32_e64 s[38:39], 0, v20
	v_add_u32_e32 v20, 1, v18
	v_lshlrev_b32_e32 v30, 16, v56
	v_cndmask_b32_e64 v19, v18, v19, s[38:39]
	v_fma_f32 v18, -v20, v18, v0
	v_cmp_lt_f32_e64 s[38:39], 0, v18
	v_and_b32_e32 v31, 0xffff0000, v56
	v_lshlrev_b32_e32 v32, 16, v57
	v_cndmask_b32_e64 v18, v19, v20, s[38:39]
	v_mul_f32_e32 v19, 0x37800000, v18
	v_cndmask_b32_e32 v18, v18, v19, vcc
	v_cmp_class_f32_e32 vcc, v0, v228
	v_and_b32_e32 v33, 0xffff0000, v57
	s_mov_b64 s[40:41], 0xc00
	v_cndmask_b32_e32 v0, v18, v0, vcc
	v_div_scale_f32 v18, s[38:39], v0, v0, 1.0
	v_rcp_f32_e32 v19, v18
	s_lshl_b64 s[38:39], s[42:43], 10
	v_lshl_add_u64 v[70:71], s[38:39], 2, v[50:51]
	v_fma_f32 v20, -v18, v19, 1.0
	v_fmac_f32_e32 v19, v20, v19
	v_div_scale_f32 v20, vcc, 1.0, v0, 1.0
	v_mul_f32_e32 v21, v20, v19
	v_fma_f32 v22, -v18, v21, v20
	v_fmac_f32_e32 v21, v22, v19
	v_fma_f32 v18, -v18, v21, v20
	v_div_fmas_f32 v18, v18, v19, v21
	v_div_fixup_f32 v0, v18, v0, 1.0
	s_waitcnt vmcnt(1)
	v_lshlrev_b32_e32 v18, 16, v68
	v_and_b32_e32 v19, 0xffff0000, v68
	v_lshlrev_b32_e32 v20, 16, v69
	v_and_b32_e32 v21, 0xffff0000, v69
	v_pk_mul_f32 v[18:19], v[0:1], v[18:19] op_sel_hi:[0,1]
	v_pk_mul_f32 v[20:21], v[0:1], v[20:21] op_sel_hi:[0,1]
	v_lshlrev_b32_e32 v22, 16, v66
	v_pk_fma_f32 v[20:21], v[16:17], v[20:21], v[24:25]
	v_pk_fma_f32 v[18:19], v[14:15], v[18:19], v[22:23]
	v_lshlrev_b32_e32 v22, 16, v64
	v_and_b32_e32 v23, 0xffff0000, v64
	v_lshlrev_b32_e32 v24, 16, v65
	v_and_b32_e32 v25, 0xffff0000, v65
	v_pk_mul_f32 v[22:23], v[0:1], v[22:23] op_sel_hi:[0,1]
	v_pk_mul_f32 v[24:25], v[0:1], v[24:25] op_sel_hi:[0,1]
	v_pk_fma_f32 v[24:25], v[12:13], v[24:25], v[28:29]
	v_pk_fma_f32 v[22:23], v[10:11], v[22:23], v[26:27]
	v_lshlrev_b32_e32 v26, 16, v58
	v_and_b32_e32 v27, 0xffff0000, v58
	v_lshlrev_b32_e32 v28, 16, v59
	v_and_b32_e32 v29, 0xffff0000, v59
	v_pk_mul_f32 v[26:27], v[0:1], v[26:27] op_sel_hi:[0,1]
	v_pk_mul_f32 v[28:29], v[0:1], v[28:29] op_sel_hi:[0,1]
	v_pk_fma_f32 v[28:29], v[8:9], v[28:29], v[32:33]
	v_pk_fma_f32 v[26:27], v[6:7], v[26:27], v[30:31]
	v_lshlrev_b32_e32 v30, 16, v54
	v_and_b32_e32 v31, 0xffff0000, v54
	v_lshlrev_b32_e32 v32, 16, v55
	v_and_b32_e32 v33, 0xffff0000, v55
	v_pk_mul_f32 v[30:31], v[0:1], v[30:31] op_sel_hi:[0,1]
	v_pk_mul_f32 v[32:33], v[0:1], v[32:33] op_sel_hi:[0,1]
	v_lshlrev_b32_e32 v54, 16, v52
	v_and_b32_e32 v55, 0xffff0000, v52
	v_lshlrev_b32_e32 v52, 16, v53
	v_and_b32_e32 v53, 0xffff0000, v53
	v_pk_fma_f32 v[32:33], v[4:5], v[32:33], v[52:53]
	v_pk_fma_f32 v[30:31], v[2:3], v[30:31], v[54:55]
	global_store_dwordx4 v[70:71], v[30:33], off sc1
	global_store_dwordx4 v[60:61], v[34:37], off offset:1024 sc1
	global_store_dwordx4 v[70:71], v[26:29], off offset:1024 sc1
	global_store_dwordx4 v[60:61], v[38:41], off offset:2048 sc1
	global_store_dwordx4 v[70:71], v[22:25], off offset:2048 sc1
	s_nop 0
	v_mov_b64_e32 v[38:39], v[42:43]
	v_mov_b64_e32 v[40:41], v[44:45]
	v_mov_b64_e32 v[44:45], v[20:21]
	v_mov_b64_e32 v[42:43], v[18:19]
.LBB0_777:
	v_lshl_add_u64 v[20:21], v[60:61], 0, s[40:41]
	s_add_i32 s40, s13, s56
	v_lshl_add_u64 v[18:19], s[38:39], 2, v[50:51]
	s_cmpk_lt_i32 s40, 0x4000
	global_store_dwordx4 v[20:21], v[38:41], off sc1
	global_store_dwordx4 v[18:19], v[42:45], off offset:3072 sc1
	s_cbranch_scc0 .LBB0_782
.LBB0_778:
	s_add_i32 s13, s40, s56
	s_cmpk_lt_i32 s13, 0x4000
	s_cselect_b32 s42, s13, s40
	s_ashr_i32 s41, s40, 31
	s_lshl_b64 s[38:39], s[40:41], 6
	s_add_u32 s44, s8, s38
	s_addc_u32 s45, s9, s39
	global_load_dwordx4 v[18:21], v1, s[44:45] offset:48
	global_load_dwordx4 v[22:25], v1, s[44:45] offset:32
	global_load_dwordx4 v[26:29], v1, s[44:45] offset:16
	global_load_dwordx4 v[30:33], v1, s[44:45]
	s_ashr_i32 s43, s42, 31
	s_lshl_b64 s[38:39], s[42:43], 6
	s_add_u32 s38, s8, s38
	s_addc_u32 s39, s9, s39
	s_lshl_b64 s[46:47], s[40:41], 11
	s_lshl_b64 s[50:51], s[42:43], 11
	v_lshl_add_u64 v[44:45], v[46:47], 0, s[46:47]
	v_lshl_add_u64 v[60:61], v[48:49], 0, s[46:47]
	v_lshl_add_u64 v[42:43], v[46:47], 0, s[50:51]
	v_lshl_add_u64 v[66:67], v[48:49], 0, s[50:51]
	s_lshl_b64 s[44:45], s[40:41], 12
	s_cmpk_gt_i32 s13, 0x3fff
	s_waitcnt vmcnt(0)
	v_add_f32_e32 v22, v22, v23
	v_add_f32_e32 v24, v24, v25
	v_mov_b32_e32 v34, v31
	v_mov_b32_e32 v35, v32
	v_mov_b32_e32 v31, v33
	v_mov_b32_e32 v32, v27
	v_mov_b32_e32 v33, v28
	v_mov_b32_e32 v27, v29
	v_pk_add_f32 v[30:31], v[34:35], v[30:31]
	v_pk_add_f32 v[26:27], v[32:33], v[26:27]
	v_pk_add_f32 v[30:31], v[30:31], v[30:31] op_sel:[0,1] op_sel_hi:[1,0]
	v_pk_add_f32 v[26:27], v[26:27], v[26:27] op_sel:[0,1] op_sel_hi:[1,0]
	v_mov_b32_e32 v31, v18
	v_mov_b32_e32 v27, v19
	v_mov_b32_e32 v23, v20
	v_mov_b32_e32 v25, v21
	v_pk_add_f32 v[18:19], v[30:31], v[26:27]
	v_pk_add_f32 v[20:21], v[22:23], v[24:25]
	s_nop 0
	v_pk_add_f32 v[18:19], v[18:19], v[20:21]
	s_nop 0
	v_add_f32_e32 v0, v18, v19
	v_fmamk_f32 v0, v0, 0x3a800000, v227
	v_cmp_gt_f32_e32 vcc, s7, v0
	v_mul_f32_e32 v18, 0x4f800000, v0
	s_nop 0
	v_cndmask_b32_e32 v0, v0, v18, vcc
	v_sqrt_f32_e32 v34, v0
	global_load_dwordx4 v[18:21], v1, s[38:39] offset:48
	global_load_dwordx4 v[22:25], v1, s[38:39] offset:32
	global_load_dwordx4 v[26:29], v1, s[38:39] offset:16
	global_load_dwordx4 v[30:33], v1, s[38:39]
	v_add_u32_e32 v36, -1, v34
	v_fma_f32 v37, -v36, v34, v0
	v_add_u32_e32 v35, 1, v34
	v_cmp_ge_f32_e64 s[38:39], 0, v37
	s_nop 1
	v_cndmask_b32_e64 v36, v34, v36, s[38:39]
	v_fma_f32 v34, -v35, v34, v0
	v_cmp_lt_f32_e64 s[38:39], 0, v34
	s_nop 1
	v_cndmask_b32_e64 v34, v36, v35, s[38:39]
	v_mul_f32_e32 v35, 0x37800000, v34
	v_cndmask_b32_e32 v34, v34, v35, vcc
	v_cmp_class_f32_e32 vcc, v0, v228
	s_nop 1
	v_cndmask_b32_e32 v0, v34, v0, vcc
	v_div_scale_f32 v34, s[38:39], v0, v0, 1.0
	v_rcp_f32_e32 v35, v34
	s_mov_b64 s[38:39], -1
	v_fma_f32 v36, -v34, v35, 1.0
	v_fmac_f32_e32 v35, v36, v35
	v_div_scale_f32 v36, vcc, 1.0, v0, 1.0
	v_mul_f32_e32 v37, v36, v35
	v_fma_f32 v38, -v34, v37, v36
	v_fmac_f32_e32 v37, v38, v35
	v_fma_f32 v34, -v34, v37, v36
	v_div_fmas_f32 v34, v34, v35, v37
	v_div_fixup_f32 v0, v34, v0, 1.0
	global_load_dwordx2 v[34:35], v[60:61], off
	global_load_dwordx2 v[52:53], v[66:67], off
	global_load_dwordx2 v[38:39], v[44:45], off
	global_load_dwordx2 v[54:55], v[42:43], off
	s_waitcnt vmcnt(3)
	v_lshlrev_b32_e32 v36, 16, v34
	s_waitcnt vmcnt(1)
	v_lshlrev_b32_e32 v40, 16, v38
	v_and_b32_e32 v41, 0xffff0000, v38
	v_lshlrev_b32_e32 v38, 16, v39
	v_and_b32_e32 v39, 0xffff0000, v39
	v_and_b32_e32 v37, 0xffff0000, v34
	v_lshlrev_b32_e32 v34, 16, v35
	v_and_b32_e32 v35, 0xffff0000, v35
	v_pk_mul_f32 v[56:57], v[0:1], v[40:41] op_sel_hi:[0,1]
	v_pk_mul_f32 v[38:39], v[0:1], v[38:39] op_sel_hi:[0,1]
	v_pk_fma_f32 v[40:41], v[4:5], v[38:39], v[34:35]
	v_pk_fma_f32 v[38:39], v[2:3], v[56:57], v[36:37]
	global_load_dwordx2 v[34:35], v[60:61], off offset:512
	global_load_dwordx2 v[56:57], v[66:67], off offset:512
	global_load_dwordx2 v[36:37], v[44:45], off offset:512
	global_load_dwordx2 v[58:59], v[42:43], off offset:512
	s_waitcnt vmcnt(3)
	v_lshlrev_b32_e32 v62, 16, v34
	s_waitcnt vmcnt(1)
	v_lshlrev_b32_e32 v64, 16, v36
	v_and_b32_e32 v65, 0xffff0000, v36
	v_lshlrev_b32_e32 v36, 16, v37
	v_and_b32_e32 v37, 0xffff0000, v37
	v_and_b32_e32 v63, 0xffff0000, v34
	v_lshlrev_b32_e32 v34, 16, v35
	v_and_b32_e32 v35, 0xffff0000, v35
	v_pk_mul_f32 v[64:65], v[0:1], v[64:65] op_sel_hi:[0,1]
	v_pk_mul_f32 v[36:37], v[0:1], v[36:37] op_sel_hi:[0,1]
	v_pk_fma_f32 v[36:37], v[8:9], v[36:37], v[34:35]
	v_pk_fma_f32 v[34:35], v[6:7], v[64:65], v[62:63]
	global_load_dwordx2 v[74:75], v[60:61], off offset:1024
	global_load_dwordx2 v[62:63], v[66:67], off offset:1024
	global_load_dwordx2 v[72:73], v[44:45], off offset:1024
	global_load_dwordx2 v[64:65], v[42:43], off offset:1024
	global_load_dwordx2 v[70:71], v[60:61], off offset:1536
	s_nop 0
	global_load_dwordx2 v[66:67], v[66:67], off offset:1536
	s_nop 0
	global_load_dwordx2 v[44:45], v[44:45], off offset:1536
	s_nop 0
	global_load_dwordx2 v[68:69], v[42:43], off offset:1536
	v_lshl_add_u64 v[60:61], v[50:51], 0, s[44:45]
	global_store_dwordx4 v[60:61], v[38:41], off sc1
	s_cbranch_scc0 .LBB0_780
	global_store_dwordx4 v[60:61], v[34:37], off offset:1024 sc1
	s_mov_b64 s[38:39], 0

	.amdhsa_kernel _Z10hybrid_fwd4Args
		.amdhsa_group_segment_fixed_size 0
		.amdhsa_private_segment_fixed_size 0
		.amdhsa_kernarg_size 440
		.amdhsa_user_sgpr_count 2
		.amdhsa_user_sgpr_dispatch_ptr 0
		.amdhsa_user_sgpr_queue_ptr 0
		.amdhsa_user_sgpr_kernarg_segment_ptr 1
		.amdhsa_user_sgpr_dispatch_id 0
		.amdhsa_user_sgpr_kernarg_preload_length 0
		.amdhsa_user_sgpr_kernarg_preload_offset 0
		.amdhsa_user_sgpr_private_segment_size 0
		.amdhsa_uses_dynamic_stack 0
		.amdhsa_enable_private_segment 0
		.amdhsa_system_sgpr_workgroup_id_x 1
		.amdhsa_system_sgpr_workgroup_id_y 0
		.amdhsa_system_sgpr_workgroup_id_z 0
		.amdhsa_system_sgpr_workgroup_info 0
		.amdhsa_system_vgpr_workitem_id 2
		.amdhsa_next_free_vgpr 243
		.amdhsa_next_free_sgpr 99
		.amdhsa_accum_offset 244
		.amdhsa_reserve_vcc 1
		.amdhsa_float_round_mode_32 0
		.amdhsa_float_round_mode_16_64 0
		.amdhsa_float_denorm_mode_32 3
		.amdhsa_float_denorm_mode_16_64 3
		.amdhsa_dx10_clamp 1
		.amdhsa_ieee_mode 1
		.amdhsa_fp16_overflow 0
		.amdhsa_tg_split 0
		.amdhsa_exception_fp_ieee_invalid_op 0
		.amdhsa_exception_fp_denorm_src 0
		.amdhsa_exception_fp_ieee_div_zero 0
		.amdhsa_exception_fp_ieee_overflow 0
		.amdhsa_exception_fp_ieee_underflow 0
		.amdhsa_exception_fp_ieee_inexact 0
		.amdhsa_exception_int_div_zero 0
	.end_amdhsa_kernel

amdhsa.kernels:
  - .agpr_count:     0
    .args:
      - .offset:         0
        .size:           184
        .value_kind:     by_value
      - .offset:         184
        .size:           4
        .value_kind:     hidden_block_count_x
      - .offset:         188
        .size:           4
        .value_kind:     hidden_block_count_y
      - .offset:         192
        .size:           4
        .value_kind:     hidden_block_count_z
      - .offset:         196
        .size:           2
        .value_kind:     hidden_group_size_x
      - .offset:         198
        .size:           2
        .value_kind:     hidden_group_size_y
      - .offset:         200
        .size:           2
        .value_kind:     hidden_group_size_z
      - .offset:         202
        .size:           2
        .value_kind:     hidden_remainder_x
      - .offset:         204
        .size:           2
        .value_kind:     hidden_remainder_y
      - .offset:         206
        .size:           2
        .value_kind:     hidden_remainder_z
      - .offset:         224
        .size:           8
        .value_kind:     hidden_global_offset_x
      - .offset:         232
        .size:           8
        .value_kind:     hidden_global_offset_y
      - .offset:         240
        .size:           8
        .value_kind:     hidden_global_offset_z
      - .offset:         248
        .size:           2
        .value_kind:     hidden_grid_dims
      - .offset:         272
        .size:           8
        .value_kind:     hidden_multigrid_sync_arg
      - .offset:         304
        .size:           4
        .value_kind:     hidden_dynamic_lds_size
    .group_segment_fixed_size: 0
    .kernarg_segment_align: 8
    .kernarg_segment_size: 440
    .language:       OpenCL C
    .language_version:
      - 2
      - 0
    .max_flat_workgroup_size: 512
    .name:           _Z10hybrid_fwd4Args
    .private_segment_fixed_size: 0
    .sgpr_count:     105
    .sgpr_spill_count: 139
    .symbol:         _Z10hybrid_fwd4Args.kd
    .uniform_work_group_size: 1
    .uses_dynamic_stack: false
    .vgpr_count:     243
    .vgpr_spill_count: 0
    .wavefront_size: 64
